# t0_item dot product with 32 strided weight loads in flight; RWW decay tile: w0 staged in LDS, results restaged in place and stored row-contiguous
# speedup vs baseline: 1.1049x; 1.0155x over previous
; DI float lo_bf(unsigned u) { bfx2 h = __builtin_bit_cast(bfx2, u); return (float)h[0]; }
; template <int MODE> DI uint4 load_a(const Params& p, int tm, int kv, int row, int kt, int c) {
;     ...
;     const float4* mu4 = (const float4*)(p.mu + (col - 1280));
;     const float4 m0 = mu4[0], m1 = mu4[1];
;     const unsigned cu[4] = {cur.x, cur.y, cur.z, cur.w}, pu[4] = {prv.x, prv.y, prv.z, prv.w};
;     const float mm[8] = {m0.x, m0.y, m0.z, m0.w, m1.x, m1.y, m1.z, m1.w};
;     unsigned o[4];
; #pragma unroll
;     for (int e = 0; e < 4; ++e) {
;       float c0 = lo_bf(cu[e]), c1 = hi_bf(cu[e]), p0 = lo_bf(pu[e]), p1 = hi_bf(pu[e]);
;       float z0 = c0 + (p0 - c0) * mm[2 * e], z1 = c1 + (p1 - c1) * mm[2 * e + 1];
;       if constexpr (MODE == G_RWG) { z0 = sigmoidf_(z0); z1 = sigmoidf_(z1); }
;       if constexpr (MODE == G_RWW) { z0 = tanhf(z0); z1 = tanhf(z1); }
;       o[e] = pack2(z0, z1);
;     }
;     return make_uint4(o[0], o[1], o[2], o[3]);
; template <int MODE, bool BIG = false> DI void gemm_tile(const Params& p, int tm, int tn, int kv, char* smem) {
;     ...
;     uint4 ra[4], rb[4];
; #pragma unroll
;     for (int i = 0; i < 4; ++i) { const int id = tid + 256 * i; ra[i] = load_a<MODE>(p, tma, kv, id >> 3, 0, id & 7); rb[i] = load_b<MODE>(p, tn, kv, id >> 3, 0, id & 7); }
;     for (int kt = 0; kt < KT; ++kt) {
;       __syncthreads();
; #pragma unroll
;       for (int i = 0; i < 4; ++i) {
;         const int id = tid + 256 * i;
;         *(uint4*)(As + (id >> 3) * 144 + (id & 7) * 16) = ra[i];
;         *(uint4*)(Bs + (id >> 3) * 144 + (id & 7) * 16) = rb[i];
;       }
;       __syncthreads();
;       if (kt + 1 < KT) {
; #pragma unroll
;         for (int i = 0; i < 4; ++i) { const int id = tid + 256 * i; ra[i] = load_a<MODE>(p, tma, kv, id >> 3, kt + 1, id & 7); rb[i] = load_b<MODE>(p, tn, kv, id >> 3, kt + 1, id & 7); }
;       }
; #pragma unroll
;       for (int s = 0; s < 4; ++s) {
;         bf16x8 af[2], bfr[2];
; #pragma unroll
;         for (int i = 0; i < 2; ++i) af[i] = *(const bf16x8*)(As + (wm * 64 + i * 32 + r) * 144 + s * 32 + hf * 16);
; #pragma unroll
;         for (int j = 0; j < 2; ++j) bfr[j] = *(const bf16x8*)(Bs + (wn * 64 + j * 32 + r) * 144 + s * 32 + hf * 16);
; #pragma unroll
;         for (int i = 0; i < 2; ++i)
; #pragma unroll
;           for (int j = 0; j < 2; ++j) acc[i][j] = MFMA(af[i], bfr[j], acc[i][j]);
;       }
.LBB0_205:
	s_or_b64 exec, exec, s[0:1]
	v_add_u32_e32 v56, s7, v84
	v_ashrrev_i32_e32 v57, 31, v56
	v_lshlrev_b64 v[56:57], 7, v[56:57]
	v_lshl_add_u64 v[38:39], v[38:39], 0, v[56:57]
	global_load_dwordx4 v[88:91], v[38:39], off
	s_brev_b32 s0, -2
	v_bfi_b32 v29, s0, v86, v55
	v_bfi_b32 v39, s0, v79, v49
	v_bfi_b32 v49, s0, v81, v51
	v_bfi_b32 v51, s0, v83, v53
	v_bfi_b32 v52, s0, v82, v52
	v_bfi_b32 v53, s0, v28, v5
	v_bfi_b32 v27, s0, v27, v3
	v_bfi_b32 v28, s0, v24, v2
	v_bfi_b32 v26, s0, v26, v13
	v_bfi_b32 v55, s0, v23, v12
	v_bfi_b32 v56, s0, v22, v11
	v_bfi_b32 v0, s0, v0, v10
	v_lshlrev_b32_e32 v57, 4, v66
	v_ashrrev_i32_e32 v82, 1, v66
	v_bfi_b32 v38, s0, v85, v54
	v_bfi_b32 v48, s0, v78, v48
	v_bfi_b32 v37, s0, v68, v37
	v_bfi_b32 v36, s0, v67, v36
	v_bfi_b32 v31, s0, v60, v31
	v_bfi_b32 v30, s0, v59, v30
	v_bfi_b32 v33, s0, v62, v33
	v_bfi_b32 v32, s0, v61, v32
	v_bfi_b32 v35, s0, v64, v35
	v_bfi_b32 v34, s0, v63, v34
	v_bfe_u32 v67, v66, 5, 1
	v_and_b32_e32 v83, 31, v66
	v_cvt_pk_f16_f32 v28, v28, v27
	v_cvt_pk_f16_f32 v27, v55, v26
	v_cvt_pk_f16_f32 v26, v0, v56
	v_and_b32_e32 v0, 0x70, v57
	v_and_b32_e32 v85, 0xffffffc0, v82
	v_bfi_b32 v50, s0, v80, v50
	v_bfi_b32 v47, s0, v77, v47
	v_bfi_b32 v46, s0, v76, v46
	v_bfi_b32 v41, s0, v70, v41
	v_bfi_b32 v40, s0, v69, v40
	v_bfi_b32 v43, s0, v72, v43
	v_bfi_b32 v42, s0, v71, v42
	v_bfi_b32 v45, s0, v74, v45
	v_bfi_b32 v44, s0, v73, v44
	v_bfi_b32 v54, s0, v25, v4
	v_cvt_pk_f16_f32 v5, v38, v29
	v_cvt_pk_f16_f32 v2, v48, v39
	v_cvt_pk_f16_f32 v25, v36, v37
	v_cvt_pk_f16_f32 v22, v30, v31
	v_cvt_pk_f16_f32 v23, v32, v33
	v_cvt_pk_f16_f32 v24, v34, v35
	v_lshlrev_b32_e32 v30, 4, v67
	v_mad_u64_u32 v[32:33], s[0:1], v58, s33, v[0:1]
	v_mad_u64_u32 v[34:35], s[0:1], v65, s33, v[0:1]
	v_mad_u64_u32 v[36:37], s[0:1], v75, s33, v[0:1]
	v_mad_u64_u32 v[38:39], s[0:1], v84, s33, v[0:1]
	v_or_b32_e32 v0, v85, v83
	v_cvt_pk_f16_f32 v3, v50, v49
	v_cvt_pk_f16_f32 v4, v52, v51
	v_mad_u64_u32 v[80:81], s[0:1], v0, s33, v[30:31]
	v_cvt_pk_f16_f32 v13, v46, v47
	v_cvt_pk_f16_f32 v10, v40, v41
	v_cvt_pk_f16_f32 v11, v42, v43
	v_cvt_pk_f16_f32 v12, v44, v45
	v_cvt_pk_f16_f32 v29, v54, v53
	s_barrier
	v_bfe_u32 v0, v66, 6, 1
	v_lshlrev_b32_e32 v66, 6, v66
	ds_write_b128 v32, v[22:25]
	ds_write_b128 v32, v[6:9] offset:18432
	ds_write_b128 v34, v[10:13]
	ds_write_b128 v34, v[14:17] offset:18432
	ds_write_b128 v36, v[2:5]
	ds_write_b128 v36, v[18:21] offset:18432
	ds_write_b128 v38, v[26:29]
	s_waitcnt vmcnt(0)
	ds_write_b128 v38, v[88:91] offset:18432
	s_waitcnt lgkmcnt(0)
	s_barrier
	ds_read_b128 v[2:5], v80
	ds_read_b128 v[22:25], v80 offset:4608
	v_lshl_or_b32 v6, v0, 6, v83
	v_mad_u32_u24 v81, v6, s33, v30
	ds_read_b128 v[6:9], v81 offset:18432
	ds_read_b128 v[18:21], v81 offset:23040
	s_waitcnt lgkmcnt(1)
	v_mfma_f32_32x32x16_f16 v[34:49], v[2:5], v[6:9], 0
	ds_read_b128 v[68:71], v80 offset:32
	ds_read_b128 v[72:75], v81 offset:18464
	ds_read_b128 v[76:79], v81 offset:23072
	v_lshlrev_b32_e32 v0, 8, v0
	v_lshl_or_b32 v67, v67, 2, v85
	v_lshl_or_b32 v0, v83, 2, v0
	s_mov_b32 s8, 0x3f2aaaab
	s_mov_b32 s9, 0x3f317218
	s_waitcnt lgkmcnt(3)
	v_mfma_f32_32x32x16_f16 v[50:65], v[2:5], v[18:21], 0
	s_mov_b32 s10, 0x33800000
	s_add_i32 s5, s5, s77
	s_add_i32 s4, s4, s87
	s_add_i32 s3, s3, s89
	s_cmp_ge_i32 s5, s84
	s_waitcnt lgkmcnt(1)
	v_mfma_f32_32x32x16_f16 v[34:49], v[68:71], v[72:75], v[34:49]
	s_waitcnt lgkmcnt(0)
	v_mfma_f32_32x32x16_f16 v[50:65], v[68:71], v[76:79], v[50:65]
	ds_read_b128 v[68:71], v80 offset:4640
	v_mfma_f32_32x32x16_f16 v[2:17], v[22:25], v[6:9], 0
	v_mfma_f32_32x32x16_f16 v[18:33], v[22:25], v[18:21], 0
	s_waitcnt lgkmcnt(0)
	v_mfma_f32_32x32x16_f16 v[2:17], v[68:71], v[72:75], v[2:17]
	v_mfma_f32_32x32x16_f16 v[18:33], v[68:71], v[76:79], v[18:33]
	ds_read_b128 v[68:71], v80 offset:64
	ds_read_b128 v[72:75], v81 offset:18496
	ds_read_b128 v[76:79], v81 offset:23104
	s_waitcnt lgkmcnt(1)
	v_mfma_f32_32x32x16_f16 v[34:49], v[68:71], v[72:75], v[34:49]
	s_waitcnt lgkmcnt(0)
	v_mfma_f32_32x32x16_f16 v[50:65], v[68:71], v[76:79], v[50:65]
	ds_read_b128 v[68:71], v80 offset:4672
	s_waitcnt lgkmcnt(0)
	v_mfma_f32_32x32x16_f16 v[2:17], v[68:71], v[72:75], v[2:17]
	v_mfma_f32_32x32x16_f16 v[18:33], v[68:71], v[76:79], v[18:33]
	ds_read_b128 v[68:71], v80 offset:96
	ds_read_b128 v[72:75], v81 offset:18528
	ds_read_b128 v[76:79], v81 offset:23136
	s_waitcnt lgkmcnt(1)
	v_mfma_f32_32x32x16_f16 v[34:49], v[68:71], v[72:75], v[34:49]
	s_waitcnt lgkmcnt(0)
	v_mfma_f32_32x32x16_f16 v[50:65], v[68:71], v[76:79], v[50:65]
	ds_read_b128 v[68:71], v80 offset:4704
	s_waitcnt lgkmcnt(0)
	s_barrier
; template <int MODE, bool BIG = false> DI void gemm_tile(const Params& p, int tm, int tn, int kv, char* smem) {
;     ...
;   __syncthreads();
;   if (!BIG || wm == hh) {
; #pragma unroll
;     for (int i = 0; i < MT; ++i)
; #pragma unroll
;       for (int j = 0; j < 2; ++j)
; #pragma unroll
;         for (int e = 0; e < 16; ++e) {
;           const int row = (BIG ? 0 : wm * 64) + i * 32 + 8 * (e >> 2) + 4 * hf + (e & 3);
;           const int col = wn * 64 + j * 32 + r;
;           Cs[row * 132 + col] = acc[i][j][e];
;         }
;     ...
;   } else if constexpr (MODE == G_RWW) {
;     float4* W4 = (float4*)((float*)(p.ws + OFF_BUFA) + (size_t)m * 512 + col0);
;     const float4* w04 = (const float4*)(p.w0 + col0);
; #pragma unroll
;     for (int c4 = 0; c4 < 16; ++c4) {
;       float4 v = crow4[c4], ww = w04[c4];
;       float u[4] = {v.x + ww.x, v.y + ww.y, v.z + ww.z, v.w + ww.w};
; #pragma unroll
;       for (int e = 0; e < 4; ++e) {
;         const float z = -u[e];
;         const float sp = fmaxf(z, 0.f) + log1pf(__expf(-fabsf(z)));
;         u[e] = __expf(-__expf(-sp - 0.5f));
;       }
	v_mfma_f32_32x32x16_f16 v[2:17], v[68:71], v[72:75], v[2:17]
	v_and_b32_e32 v72, 64, v66
	v_or_b32_e32 v73, s7, v72
	s_movk_i32 s7, 0x210
	v_mad_u64_u32 v[66:67], s[0:1], v67, s7, v[0:1]
	v_add_u32_e32 v0, 0x400, v66
	s_nop 2
	ds_write2_b32 v66, v34, v50 offset1:32
	ds_write2_b32 v66, v35, v51 offset0:132 offset1:164
	ds_write2_b32 v0, v36, v52 offset0:8 offset1:40
	ds_write2_b32 v0, v37, v53 offset0:140 offset1:172
	v_add_u32_e32 v0, 0x1000, v66
	v_mfma_f32_32x32x16_f16 v[18:33], v[68:71], v[76:79], v[18:33]
	ds_write2_b32 v0, v38, v54 offset0:32 offset1:64
	ds_write2_b32 v0, v39, v55 offset0:164 offset1:196
	v_add_u32_e32 v0, 0x1400, v66
	ds_write2_b32 v0, v40, v56 offset0:40 offset1:72
	ds_write2_b32 v0, v41, v57 offset0:172 offset1:204
	v_add_u32_e32 v0, 0x2000, v66
	ds_write2_b32 v0, v42, v58 offset0:64 offset1:96
	ds_write2_b32 v0, v43, v59 offset0:196 offset1:228
	v_add_u32_e32 v0, 0x2400, v66
	ds_write2_b32 v0, v44, v60 offset0:72 offset1:104
	ds_write2_b32 v0, v45, v61 offset0:204 offset1:236
	v_add_u32_e32 v0, 0x3000, v66
	ds_write2_b32 v0, v46, v62 offset0:96 offset1:128
	v_add_u32_e32 v0, 0x3200, v66
	ds_write2_b32 v0, v47, v63 offset0:100 offset1:132
	v_add_u32_e32 v0, 0x3400, v66
	ds_write2_b32 v0, v48, v64 offset0:104 offset1:136
	v_add_u32_e32 v0, 0x3600, v66
	ds_write2_b32 v0, v49, v65 offset0:108 offset1:140
	v_add_u32_e32 v0, 0x4000, v66
	ds_write2_b32 v0, v2, v18 offset0:128 offset1:160
	v_add_u32_e32 v0, 0x4400, v66
	ds_write2_b32 v0, v3, v19 offset0:4 offset1:36
	ds_write2_b32 v0, v4, v20 offset0:136 offset1:168
	v_add_u32_e32 v0, 0x4800, v66
	ds_write2_b32 v0, v5, v21 offset0:12 offset1:44
	v_add_u32_e32 v0, 0x5000, v66
	ds_write2_b32 v0, v6, v22 offset0:160 offset1:192
	v_add_u32_e32 v0, 0x5400, v66
	ds_write2_b32 v0, v7, v23 offset0:36 offset1:68
	ds_write2_b32 v0, v8, v24 offset0:168 offset1:200
	v_add_u32_e32 v0, 0x5800, v66
	ds_write2_b32 v0, v9, v25 offset0:44 offset1:76
	v_add_u32_e32 v0, 0x6000, v66
	ds_write2_b32 v0, v10, v26 offset0:192 offset1:224
	v_add_u32_e32 v0, 0x6400, v66
	ds_write2_b32 v0, v11, v27 offset0:68 offset1:100
	ds_write2_b32 v0, v12, v28 offset0:200 offset1:232
	v_add_u32_e32 v0, 0x6800, v66
	ds_write2_b32 v0, v13, v29 offset0:76 offset1:108
	v_add_u32_e32 v0, 0x7200, v66
	ds_write2_b32 v0, v14, v30 offset0:96 offset1:128
	v_add_u32_e32 v0, 0x7400, v66
	ds_write2_b32 v0, v15, v31 offset0:100 offset1:132
	v_add_u32_e32 v0, 0x7600, v66
	ds_write2_b32 v0, v16, v32 offset0:104 offset1:136
	v_add_u32_e32 v0, 0x7800, v66
	ds_write2_b32 v0, v17, v33 offset0:108 offset1:140
	s_waitcnt lgkmcnt(0)
	v_and_b32_e32 v74, 0xffffffbf, v73
	v_and_b32_e32 v75, 31, v173
	v_lshlrev_b32_e32 v74, 2, v74
	v_lshl_add_u32 v74, v75, 4, v74
	global_load_dwordx4 v[76:79], v74, s[74:75]
	v_lshlrev_b32_e32 v0, 4, v75
	v_add_u32_e32 v0, 0x10800, v0
	s_waitcnt vmcnt(0)
	ds_write_b128 v0, v[76:79]
	s_waitcnt lgkmcnt(0)
	v_lshlrev_b32_e32 v74, 2, v72
	v_add_u32_e32 v74, 0x10800, v74
	v_lshlrev_b32_e32 v0, 2, v73
	v_mul_u32_u24_e32 v75, 0x210, v82
	v_lshl_add_u32 v75, v72, 2, v75
	s_waitcnt lgkmcnt(0)
	s_barrier
	ds_read_b128 v[4:7], v74
	v_mul_lo_u32 v2, v82, s7
	v_lshl_add_u32 v12, v72, 2, v2
	ds_read_b128 v[8:11], v12
	s_mov_b32 s7, 0xbfb8aa3b
	v_add_u32_e32 v2, s6, v82
	s_mov_b32 s6, 0x7f800000
	v_ashrrev_i32_e32 v3, 31, v2
	v_readlane_b32 s0, v253, 4
	v_lshlrev_b64 v[2:3], 11, v[2:3]
	v_readlane_b32 s1, v253, 5
	s_waitcnt lgkmcnt(0)
	v_add_f32_e32 v4, v8, v4
	v_mul_f32_e64 v8, |v4|, s7
	v_exp_f32_e32 v8, v8
	v_add_f32_e32 v9, v9, v5
	v_add_f32_e32 v6, v10, v6
	v_max_f32_e64 v10, -v4, 0
	v_add_f32_e32 v13, 1.0, v8
	v_add_f32_e32 v14, -1.0, v13
	v_frexp_mant_f32_e32 v15, v13
	v_cvt_f64_f32_e32 v[4:5], v13
	v_sub_f32_e32 v16, v14, v13
	v_cmp_gt_f32_e32 vcc, s8, v15
	v_frexp_exp_i32_f64_e32 v4, v[4:5]
	v_sub_f32_e32 v14, v8, v14
	v_add_f32_e32 v5, 1.0, v16
	v_subbrev_co_u32_e32 v4, vcc, 0, v4, vcc
	v_add_f32_e32 v5, v14, v5
	v_sub_u32_e32 v14, 0, v4
	v_ldexp_f32 v13, v13, v14
	v_ldexp_f32 v5, v5, v14
	v_add_f32_e32 v14, -1.0, v13
	v_add_f32_e32 v15, 1.0, v13
	v_add_f32_e32 v16, 1.0, v14
	v_add_f32_e32 v18, -1.0, v15
	v_sub_f32_e32 v16, v13, v16
	v_sub_f32_e32 v13, v13, v18
	v_add_f32_e32 v16, v5, v16
	v_add_f32_e32 v5, v5, v13
	v_add_f32_e32 v13, v15, v5
	v_rcp_f32_e32 v18, v13
	v_add_f32_e32 v17, v14, v16
	v_sub_f32_e32 v15, v13, v15
	v_sub_f32_e32 v14, v17, v14
	v_sub_f32_e32 v5, v5, v15
	v_mul_f32_e32 v15, v17, v18
	v_sub_f32_e32 v14, v16, v14
	v_mul_f32_e32 v16, v13, v15
	v_fma_f32 v19, v15, v13, -v16
	v_fmac_f32_e32 v19, v15, v5
	v_add_f32_e32 v20, v16, v19
	v_sub_f32_e32 v21, v17, v20
	v_sub_f32_e32 v17, v17, v21
	v_sub_f32_e32 v16, v20, v16
	v_sub_f32_e32 v17, v17, v20
	v_add_f32_e32 v14, v14, v17
	v_sub_f32_e32 v16, v16, v19
	v_add_f32_e32 v14, v16, v14
	v_add_f32_e32 v16, v21, v14
	v_mul_f32_e32 v17, v18, v16
	v_mul_f32_e32 v19, v13, v17
	v_fma_f32 v13, v17, v13, -v19
	v_fmac_f32_e32 v13, v17, v5
	v_sub_f32_e32 v5, v21, v16
	v_add_f32_e32 v5, v14, v5
	v_add_f32_e32 v14, v19, v13
	v_sub_f32_e32 v20, v16, v14
	v_sub_f32_e32 v16, v16, v20
	v_sub_f32_e32 v19, v14, v19
	v_sub_f32_e32 v14, v16, v14
	v_add_f32_e32 v5, v5, v14
	v_sub_f32_e32 v13, v19, v13
	v_cvt_f32_i32_e32 v4, v4
	v_add_f32_e32 v5, v13, v5
	v_add_f32_e32 v13, v15, v17
	v_add_f32_e32 v5, v20, v5
	v_sub_f32_e32 v14, v13, v15
	v_mul_f32_e32 v5, v18, v5
	v_sub_f32_e32 v14, v17, v14
	v_add_f32_e32 v5, v14, v5
	v_mul_f32_e32 v17, 0x3f317218, v4
	v_add_f32_e32 v14, v13, v5
	v_fma_f32 v18, v4, s9, -v17
	v_mul_f32_e32 v15, v14, v14
	v_fmac_f32_e32 v18, 0xb102e308, v4
	v_sub_f32_e32 v4, v14, v13
	v_fmamk_f32 v16, v15, 0x3e9b6dac, v231
	v_sub_f32_e32 v4, v5, v4
; template <int MODE, bool BIG = false> DI void gemm_tile(const Params& p, int tm, int tn, int kv, char* smem) {
;     ...
; #pragma unroll
;       for (int e = 0; e < 4; ++e) {
;         const float z = -u[e];
;         const float sp = fmaxf(z, 0.f) + log1pf(__expf(-fabsf(z)));
;         u[e] = __expf(-__expf(-sp - 0.5f));
;       }
	v_add_f32_e32 v5, v17, v18
	v_fmaak_f32 v16, v15, v16, 0x3f2aaada
	v_sub_f32_e32 v13, v5, v17
	v_ldexp_f32 v17, v14, 1
	v_mul_f32_e32 v14, v14, v15
	v_mul_f32_e32 v14, v14, v16
	v_add_f32_e32 v15, v17, v14
	v_sub_f32_e32 v16, v15, v17
	v_ldexp_f32 v4, v4, 1
	v_sub_f32_e32 v14, v14, v16
	v_add_f32_e32 v4, v4, v14
	v_add_f32_e32 v14, v15, v4
	v_sub_f32_e32 v15, v14, v15
	v_sub_f32_e32 v4, v4, v15
	v_add_f32_e32 v15, v5, v14
	v_sub_f32_e32 v16, v15, v5
	v_sub_f32_e32 v17, v15, v16
	v_sub_f32_e32 v13, v18, v13
	v_sub_f32_e32 v5, v5, v17
	v_sub_f32_e32 v14, v14, v16
	v_add_f32_e32 v5, v14, v5
	v_add_f32_e32 v14, v13, v4
	v_sub_f32_e32 v16, v14, v13
	v_sub_f32_e32 v17, v14, v16
	v_sub_f32_e32 v13, v13, v17
	v_sub_f32_e32 v4, v4, v16
	v_add_f32_e32 v5, v14, v5
	v_add_f32_e32 v4, v4, v13
	v_add_f32_e32 v13, v15, v5
	v_sub_f32_e32 v14, v13, v15
	v_sub_f32_e32 v5, v5, v14
	v_add_f32_e32 v4, v4, v5
	v_add_f32_e32 v4, v13, v4
	v_cmp_neq_f32_e32 vcc, s6, v8
	v_mul_f32_e64 v5, |v9|, s7
	v_max_f32_e64 v9, -v9, 0
	v_cndmask_b32_e32 v4, v238, v4, vcc
	v_cmp_ngt_f32_e32 vcc, -1.0, v8
	v_lshl_add_u64 v[2:3], s[0:1], 0, v[2:3]
	s_nop 0
	v_cndmask_b32_e32 v4, v239, v4, vcc
	v_cmp_neq_f32_e32 vcc, -1.0, v8
	s_nop 1
	v_cndmask_b32_e32 v4, v240, v4, vcc
	v_cmp_lt_f32_e64 vcc, |v8|, s10
	s_nop 1
	v_cndmask_b32_e32 v4, v4, v8, vcc
	v_add_f32_e32 v4, v10, v4
	v_sub_f32_e32 v4, -0.5, v4
	v_mul_f32_e32 v4, 0x3fb8aa3b, v4
	v_exp_f32_e32 v8, v5
	v_exp_f32_e32 v4, v4
	v_add_f32_e32 v10, v11, v7
	v_add_f32_e32 v11, 1.0, v8
	v_mul_f32_e32 v7, 0xbfb8aa3b, v4
	v_add_f32_e32 v4, -1.0, v11
	v_sub_f32_e32 v5, v4, v11
	v_add_f32_e32 v5, 1.0, v5
	v_sub_f32_e32 v4, v8, v4
	v_add_f32_e32 v13, v4, v5
	v_frexp_mant_f32_e32 v4, v11
	v_cmp_gt_f32_e32 vcc, s8, v4
	v_cvt_f64_f32_e32 v[4:5], v11
	v_frexp_exp_i32_f64_e32 v4, v[4:5]
	v_subbrev_co_u32_e32 v4, vcc, 0, v4, vcc
	v_sub_u32_e32 v5, 0, v4
	v_ldexp_f32 v11, v11, v5
	v_ldexp_f32 v5, v13, v5
	v_add_f32_e32 v13, -1.0, v11
	v_add_f32_e32 v16, 1.0, v11
	v_add_f32_e32 v14, 1.0, v13
	v_add_f32_e32 v17, -1.0, v16
	v_sub_f32_e32 v14, v11, v14
	v_sub_f32_e32 v11, v11, v17
	v_add_f32_e32 v14, v5, v14
	v_add_f32_e32 v5, v5, v11
	v_add_f32_e32 v11, v16, v5
	v_rcp_f32_e32 v17, v11
	v_add_f32_e32 v15, v13, v14
	v_sub_f32_e32 v13, v15, v13
	v_sub_f32_e32 v13, v14, v13
	v_sub_f32_e32 v14, v11, v16
	v_sub_f32_e32 v5, v5, v14
	v_mul_f32_e32 v14, v15, v17
	v_mul_f32_e32 v16, v11, v14
	v_fma_f32 v18, v14, v11, -v16
	v_fmac_f32_e32 v18, v14, v5
	v_add_f32_e32 v19, v16, v18
	v_sub_f32_e32 v20, v15, v19
	v_sub_f32_e32 v15, v15, v20
	v_sub_f32_e32 v16, v19, v16
	v_sub_f32_e32 v15, v15, v19
	v_add_f32_e32 v13, v13, v15
	v_sub_f32_e32 v15, v16, v18
	v_add_f32_e32 v13, v15, v13
	v_add_f32_e32 v15, v20, v13
	v_mul_f32_e32 v16, v17, v15
	v_mul_f32_e32 v18, v11, v16
	v_fma_f32 v11, v16, v11, -v18
	v_fmac_f32_e32 v11, v16, v5
	v_sub_f32_e32 v5, v20, v15
	v_add_f32_e32 v5, v13, v5
	v_add_f32_e32 v13, v18, v11
	v_sub_f32_e32 v19, v15, v13
	v_sub_f32_e32 v15, v15, v19
	v_sub_f32_e32 v18, v13, v18
	v_sub_f32_e32 v13, v15, v13
	v_add_f32_e32 v5, v5, v13
	v_sub_f32_e32 v11, v18, v11
	v_cvt_f32_i32_e32 v4, v4
	v_add_f32_e32 v5, v11, v5
	v_add_f32_e32 v11, v14, v16
	v_add_f32_e32 v5, v19, v5
	v_sub_f32_e32 v13, v11, v14
	v_mul_f32_e32 v5, v17, v5
	v_sub_f32_e32 v13, v16, v13
	v_add_f32_e32 v5, v13, v5
	v_mul_f32_e32 v16, 0x3f317218, v4
	v_add_f32_e32 v13, v11, v5
	v_fma_f32 v17, v4, s9, -v16
	v_mul_f32_e32 v14, v13, v13
	v_fmac_f32_e32 v17, 0xb102e308, v4
	v_sub_f32_e32 v4, v13, v11
	v_fmamk_f32 v15, v14, 0x3e9b6dac, v231
	v_sub_f32_e32 v4, v5, v4
	v_add_f32_e32 v5, v16, v17
	v_fmaak_f32 v15, v14, v15, 0x3f2aaada
	v_sub_f32_e32 v11, v5, v16
	v_ldexp_f32 v16, v13, 1
	v_mul_f32_e32 v13, v13, v14
	v_mul_f32_e32 v13, v13, v15
	v_add_f32_e32 v14, v16, v13
	v_sub_f32_e32 v15, v14, v16
	v_ldexp_f32 v4, v4, 1
	v_sub_f32_e32 v13, v13, v15
	v_add_f32_e32 v4, v4, v13
	v_add_f32_e32 v13, v14, v4
	v_sub_f32_e32 v14, v13, v14
	v_sub_f32_e32 v4, v4, v14
	v_add_f32_e32 v14, v5, v13
	v_sub_f32_e32 v15, v14, v5
	v_sub_f32_e32 v16, v14, v15
	v_sub_f32_e32 v11, v17, v11
	v_sub_f32_e32 v5, v5, v16
	v_sub_f32_e32 v13, v13, v15
	v_add_f32_e32 v5, v13, v5
	v_add_f32_e32 v13, v11, v4
	v_sub_f32_e32 v15, v13, v11
	v_sub_f32_e32 v16, v13, v15
	v_sub_f32_e32 v11, v11, v16
	v_sub_f32_e32 v4, v4, v15
	v_add_f32_e32 v5, v13, v5
	v_add_f32_e32 v4, v4, v11
	v_add_f32_e32 v11, v14, v5
	v_sub_f32_e32 v13, v11, v14
	v_sub_f32_e32 v5, v5, v13
	v_add_f32_e32 v4, v4, v5
	v_add_f32_e32 v4, v11, v4
	v_cmp_neq_f32_e32 vcc, s6, v8
	s_nop 1
	v_cndmask_b32_e32 v4, v238, v4, vcc
	v_cmp_ngt_f32_e32 vcc, -1.0, v8
	s_nop 1
	v_cndmask_b32_e32 v4, v239, v4, vcc
	v_cmp_neq_f32_e32 vcc, -1.0, v8
	s_nop 1
	v_cndmask_b32_e32 v4, v240, v4, vcc
	v_cmp_lt_f32_e64 vcc, |v8|, s10
	s_nop 1
	v_cndmask_b32_e32 v4, v4, v8, vcc
	v_add_f32_e32 v4, v9, v4
	v_sub_f32_e32 v4, -0.5, v4
	v_mul_f32_e32 v4, 0x3fb8aa3b, v4
	v_exp_f32_e32 v5, v4
	v_mul_f32_e64 v4, |v6|, s7
	v_exp_f32_e32 v8, v4
	v_max_f32_e64 v9, -v6, 0
	v_exp_f32_e32 v4, v7
	v_mul_f32_e32 v5, 0xbfb8aa3b, v5
	v_add_f32_e32 v11, 1.0, v8
	v_add_f32_e32 v6, -1.0, v11
	v_sub_f32_e32 v7, v6, v11
	v_add_f32_e32 v7, 1.0, v7
	v_sub_f32_e32 v6, v8, v6
	v_add_f32_e32 v13, v6, v7
	v_frexp_mant_f32_e32 v6, v11
	v_cmp_gt_f32_e32 vcc, s8, v6
	v_cvt_f64_f32_e32 v[6:7], v11
	v_frexp_exp_i32_f64_e32 v6, v[6:7]
	v_subbrev_co_u32_e32 v6, vcc, 0, v6, vcc
	v_sub_u32_e32 v7, 0, v6
	v_ldexp_f32 v11, v11, v7
	v_ldexp_f32 v7, v13, v7
	v_add_f32_e32 v13, -1.0, v11
	v_add_f32_e32 v16, 1.0, v11
	v_add_f32_e32 v14, 1.0, v13
	v_add_f32_e32 v17, -1.0, v16
	v_sub_f32_e32 v14, v11, v14
	v_sub_f32_e32 v11, v11, v17
; template <int MODE, bool BIG = false> DI void gemm_tile(const Params& p, int tm, int tn, int kv, char* smem) {
;     ...
;     for (int c4 = 0; c4 < 16; ++c4) {
;       float4 v = crow4[c4], ww = w04[c4];
;       float u[4] = {v.x + ww.x, v.y + ww.y, v.z + ww.z, v.w + ww.w};
; #pragma unroll
;       for (int e = 0; e < 4; ++e) {
;         const float z = -u[e];
;         const float sp = fmaxf(z, 0.f) + log1pf(__expf(-fabsf(z)));
;         u[e] = __expf(-__expf(-sp - 0.5f));
;       }
;       W4[c4] = make_float4(u[0], u[1], u[2], u[3]);
	v_add_f32_e32 v14, v7, v14
	v_add_f32_e32 v7, v7, v11
	v_add_f32_e32 v11, v16, v7
	v_rcp_f32_e32 v17, v11
	v_add_f32_e32 v15, v13, v14
	v_sub_f32_e32 v13, v15, v13
	v_sub_f32_e32 v13, v14, v13
	v_sub_f32_e32 v14, v11, v16
	v_sub_f32_e32 v7, v7, v14
	v_mul_f32_e32 v14, v15, v17
	v_mul_f32_e32 v16, v11, v14
	v_fma_f32 v18, v14, v11, -v16
	v_fmac_f32_e32 v18, v14, v7
	v_add_f32_e32 v19, v16, v18
	v_sub_f32_e32 v20, v15, v19
	v_sub_f32_e32 v15, v15, v20
	v_sub_f32_e32 v16, v19, v16
	v_sub_f32_e32 v15, v15, v19
	v_add_f32_e32 v13, v13, v15
	v_sub_f32_e32 v15, v16, v18
	v_add_f32_e32 v13, v15, v13
	v_add_f32_e32 v15, v20, v13
	v_mul_f32_e32 v16, v17, v15
	v_mul_f32_e32 v18, v11, v16
	v_fma_f32 v11, v16, v11, -v18
	v_fmac_f32_e32 v11, v16, v7
	v_sub_f32_e32 v7, v20, v15
	v_add_f32_e32 v7, v13, v7
	v_add_f32_e32 v13, v18, v11
	v_sub_f32_e32 v19, v15, v13
	v_sub_f32_e32 v15, v15, v19
	v_sub_f32_e32 v18, v13, v18
	v_sub_f32_e32 v13, v15, v13
	v_add_f32_e32 v7, v7, v13
	v_sub_f32_e32 v11, v18, v11
	v_cvt_f32_i32_e32 v6, v6
	v_add_f32_e32 v7, v11, v7
	v_add_f32_e32 v11, v14, v16
	v_add_f32_e32 v7, v19, v7
	v_sub_f32_e32 v13, v11, v14
	v_mul_f32_e32 v7, v17, v7
	v_sub_f32_e32 v13, v16, v13
	v_add_f32_e32 v7, v13, v7
	v_mul_f32_e32 v16, 0x3f317218, v6
	v_add_f32_e32 v13, v11, v7
	v_fma_f32 v17, v6, s9, -v16
	v_mul_f32_e32 v14, v13, v13
	v_fmac_f32_e32 v17, 0xb102e308, v6
	v_sub_f32_e32 v6, v13, v11
	v_fmamk_f32 v15, v14, 0x3e9b6dac, v231
	v_sub_f32_e32 v6, v7, v6
	v_add_f32_e32 v7, v16, v17
	v_fmaak_f32 v15, v14, v15, 0x3f2aaada
	v_sub_f32_e32 v11, v7, v16
	v_ldexp_f32 v16, v13, 1
	v_mul_f32_e32 v13, v13, v14
	v_mul_f32_e32 v13, v13, v15
	v_add_f32_e32 v14, v16, v13
	v_sub_f32_e32 v15, v14, v16
	v_ldexp_f32 v6, v6, 1
	v_sub_f32_e32 v13, v13, v15
	v_add_f32_e32 v6, v6, v13
	v_add_f32_e32 v13, v14, v6
	v_sub_f32_e32 v14, v13, v14
	v_sub_f32_e32 v6, v6, v14
	v_add_f32_e32 v14, v7, v13
	v_sub_f32_e32 v15, v14, v7
	v_sub_f32_e32 v16, v14, v15
	v_sub_f32_e32 v11, v17, v11
	v_sub_f32_e32 v7, v7, v16
	v_sub_f32_e32 v13, v13, v15
	v_add_f32_e32 v7, v13, v7
	v_add_f32_e32 v13, v11, v6
	v_sub_f32_e32 v15, v13, v11
	v_sub_f32_e32 v16, v13, v15
	v_sub_f32_e32 v11, v11, v16
	v_sub_f32_e32 v6, v6, v15
	v_add_f32_e32 v7, v13, v7
	v_add_f32_e32 v6, v6, v11
	v_add_f32_e32 v11, v14, v7
	v_sub_f32_e32 v13, v11, v14
	v_sub_f32_e32 v7, v7, v13
	v_add_f32_e32 v6, v6, v7
	v_add_f32_e32 v6, v11, v6
	v_cmp_neq_f32_e32 vcc, s6, v8
	v_mul_f32_e64 v7, |v10|, s7
	v_max_f32_e64 v10, -v10, 0
	v_cndmask_b32_e32 v6, v238, v6, vcc
	v_cmp_ngt_f32_e32 vcc, -1.0, v8
	v_exp_f32_e32 v5, v5
	s_nop 0
	v_cndmask_b32_e32 v6, v239, v6, vcc
	v_cmp_neq_f32_e32 vcc, -1.0, v8
	s_nop 1
	v_cndmask_b32_e32 v6, v240, v6, vcc
	v_cmp_lt_f32_e64 vcc, |v8|, s10
	s_nop 1
	v_cndmask_b32_e32 v6, v6, v8, vcc
	v_exp_f32_e32 v8, v7
	v_add_f32_e32 v6, v9, v6
	v_sub_f32_e32 v6, -0.5, v6
	v_mul_f32_e32 v6, 0x3fb8aa3b, v6
	v_add_f32_e32 v11, 1.0, v8
	v_exp_f32_e32 v9, v6
	v_add_f32_e32 v6, -1.0, v11
	v_sub_f32_e32 v7, v6, v11
	v_add_f32_e32 v7, 1.0, v7
	v_sub_f32_e32 v6, v8, v6
	v_add_f32_e32 v13, v6, v7
	v_frexp_mant_f32_e32 v6, v11
	v_cmp_gt_f32_e32 vcc, s8, v6
	v_cvt_f64_f32_e32 v[6:7], v11
	v_frexp_exp_i32_f64_e32 v6, v[6:7]
	v_subbrev_co_u32_e32 v6, vcc, 0, v6, vcc
	v_sub_u32_e32 v7, 0, v6
	v_ldexp_f32 v11, v11, v7
	v_ldexp_f32 v7, v13, v7
	v_add_f32_e32 v13, -1.0, v11
	v_add_f32_e32 v16, 1.0, v11
	v_add_f32_e32 v14, 1.0, v13
	v_add_f32_e32 v17, -1.0, v16
	v_sub_f32_e32 v14, v11, v14
	v_sub_f32_e32 v11, v11, v17
	v_add_f32_e32 v14, v7, v14
	v_add_f32_e32 v7, v7, v11
	v_add_f32_e32 v11, v16, v7
	v_rcp_f32_e32 v17, v11
	v_add_f32_e32 v15, v13, v14
	v_sub_f32_e32 v13, v15, v13
	v_sub_f32_e32 v13, v14, v13
	v_sub_f32_e32 v14, v11, v16
	v_sub_f32_e32 v7, v7, v14
	v_mul_f32_e32 v14, v15, v17
	v_mul_f32_e32 v16, v11, v14
	v_fma_f32 v18, v14, v11, -v16
	v_fmac_f32_e32 v18, v14, v7
	v_add_f32_e32 v19, v16, v18
	v_sub_f32_e32 v20, v15, v19
	v_sub_f32_e32 v15, v15, v20
	v_sub_f32_e32 v16, v19, v16
	v_sub_f32_e32 v15, v15, v19
	v_add_f32_e32 v13, v13, v15
	v_sub_f32_e32 v15, v16, v18
	v_add_f32_e32 v13, v15, v13
	v_add_f32_e32 v15, v20, v13
	v_mul_f32_e32 v16, v17, v15
	v_mul_f32_e32 v18, v11, v16
	v_fma_f32 v11, v16, v11, -v18
	v_fmac_f32_e32 v11, v16, v7
	v_sub_f32_e32 v7, v20, v15
	v_add_f32_e32 v7, v13, v7
	v_add_f32_e32 v13, v18, v11
	v_sub_f32_e32 v19, v15, v13
	v_sub_f32_e32 v15, v15, v19
	v_sub_f32_e32 v18, v13, v18
	v_sub_f32_e32 v13, v15, v13
	v_add_f32_e32 v7, v7, v13
	v_sub_f32_e32 v11, v18, v11
	v_cvt_f32_i32_e32 v6, v6
	v_add_f32_e32 v7, v11, v7
	v_add_f32_e32 v11, v14, v16
	v_add_f32_e32 v7, v19, v7
	v_sub_f32_e32 v13, v11, v14
	v_mul_f32_e32 v7, v17, v7
	v_sub_f32_e32 v13, v16, v13
	v_add_f32_e32 v7, v13, v7
	v_mul_f32_e32 v16, 0x3f317218, v6
	v_add_f32_e32 v13, v11, v7
	v_fma_f32 v17, v6, s9, -v16
	v_mul_f32_e32 v14, v13, v13
	v_fmac_f32_e32 v17, 0xb102e308, v6
	v_sub_f32_e32 v6, v13, v11
	v_fmamk_f32 v15, v14, 0x3e9b6dac, v231
	v_sub_f32_e32 v6, v7, v6
	v_add_f32_e32 v7, v16, v17
	v_fmaak_f32 v15, v14, v15, 0x3f2aaada
	v_sub_f32_e32 v11, v7, v16
	v_ldexp_f32 v16, v13, 1
	v_mul_f32_e32 v13, v13, v14
	v_mul_f32_e32 v13, v13, v15
	v_add_f32_e32 v14, v16, v13
	v_sub_f32_e32 v15, v14, v16
	v_ldexp_f32 v6, v6, 1
	v_sub_f32_e32 v13, v13, v15
	v_add_f32_e32 v6, v6, v13
	v_add_f32_e32 v13, v14, v6
	v_sub_f32_e32 v14, v13, v14
	v_sub_f32_e32 v6, v6, v14
	v_add_f32_e32 v14, v7, v13
	v_sub_f32_e32 v15, v14, v7
	v_sub_f32_e32 v16, v14, v15
	v_sub_f32_e32 v11, v17, v11
	v_sub_f32_e32 v7, v7, v16
	v_sub_f32_e32 v13, v13, v15
	v_add_f32_e32 v7, v13, v7
	v_add_f32_e32 v13, v11, v6
	v_sub_f32_e32 v15, v13, v11
	v_sub_f32_e32 v16, v13, v15
	v_sub_f32_e32 v11, v11, v16
	v_sub_f32_e32 v6, v6, v15
	v_add_f32_e32 v7, v13, v7
	v_add_f32_e32 v6, v6, v11
	v_add_f32_e32 v11, v14, v7
	v_sub_f32_e32 v13, v11, v14
	v_sub_f32_e32 v7, v7, v13
	v_add_f32_e32 v6, v6, v7
	v_add_f32_e32 v6, v11, v6
	v_cmp_neq_f32_e32 vcc, s6, v8
	s_nop 1
	v_cndmask_b32_e32 v6, v238, v6, vcc
	v_cmp_ngt_f32_e32 vcc, -1.0, v8
	s_nop 1
	v_cndmask_b32_e32 v6, v239, v6, vcc
	v_cmp_neq_f32_e32 vcc, -1.0, v8
	s_nop 1
	v_cndmask_b32_e32 v6, v240, v6, vcc
	v_cmp_lt_f32_e64 vcc, |v8|, s10
	s_nop 1
	v_cndmask_b32_e32 v6, v6, v8, vcc
	v_add_f32_e32 v6, v10, v6
	v_sub_f32_e32 v6, -0.5, v6
	v_mul_f32_e32 v6, 0x3fb8aa3b, v6
	v_exp_f32_e32 v7, v6
	v_mul_f32_e32 v6, 0xbfb8aa3b, v9
	v_exp_f32_e32 v6, v6
	v_lshl_add_u64 v[10:11], v[2:3], 0, v[0:1]
	v_mul_f32_e32 v7, 0xbfb8aa3b, v7
	v_exp_f32_e32 v7, v7
	ds_write_b128 v75, v[4:7]
	ds_read_b128 v[2:5], v74 offset:16
	ds_read_b128 v[6:9], v12 offset:16
	s_waitcnt lgkmcnt(0)
; template <int MODE, bool BIG = false> DI void gemm_tile(const Params& p, int tm, int tn, int kv, char* smem) {
;     ...
; #pragma unroll
;       for (int e = 0; e < 4; ++e) {
;         const float z = -u[e];
;         const float sp = fmaxf(z, 0.f) + log1pf(__expf(-fabsf(z)));
;         u[e] = __expf(-__expf(-sp - 0.5f));
;       }
	v_add_f32_e32 v2, v6, v2
	v_mul_f32_e64 v6, |v2|, s7
	v_exp_f32_e32 v6, v6
	v_add_f32_e32 v4, v8, v4
	v_max_f32_e64 v8, -v2, 0
	v_add_f32_e32 v7, v7, v3
	v_add_f32_e32 v13, 1.0, v6
	v_add_f32_e32 v2, -1.0, v13
	v_sub_f32_e32 v3, v2, v13
	v_add_f32_e32 v3, 1.0, v3
	v_sub_f32_e32 v2, v6, v2
	v_add_f32_e32 v14, v2, v3
	v_frexp_mant_f32_e32 v2, v13
	v_cmp_gt_f32_e32 vcc, s8, v2
	v_cvt_f64_f32_e32 v[2:3], v13
	v_frexp_exp_i32_f64_e32 v2, v[2:3]
	v_subbrev_co_u32_e32 v2, vcc, 0, v2, vcc
	v_sub_u32_e32 v3, 0, v2
	v_ldexp_f32 v13, v13, v3
	v_ldexp_f32 v3, v14, v3
	v_add_f32_e32 v14, -1.0, v13
	v_add_f32_e32 v17, 1.0, v13
	v_add_f32_e32 v15, 1.0, v14
	v_add_f32_e32 v18, -1.0, v17
	v_sub_f32_e32 v15, v13, v15
	v_sub_f32_e32 v13, v13, v18
	v_add_f32_e32 v15, v3, v15
	v_add_f32_e32 v3, v3, v13
	v_add_f32_e32 v13, v17, v3
	v_rcp_f32_e32 v18, v13
	v_add_f32_e32 v16, v14, v15
	v_sub_f32_e32 v14, v16, v14
	v_sub_f32_e32 v14, v15, v14
	v_sub_f32_e32 v15, v13, v17
	v_sub_f32_e32 v3, v3, v15
	v_mul_f32_e32 v15, v16, v18
	v_mul_f32_e32 v17, v13, v15
	v_fma_f32 v19, v15, v13, -v17
	v_fmac_f32_e32 v19, v15, v3
	v_add_f32_e32 v20, v17, v19
	v_sub_f32_e32 v21, v16, v20
	v_sub_f32_e32 v16, v16, v21
	v_sub_f32_e32 v17, v20, v17
	v_sub_f32_e32 v16, v16, v20
	v_add_f32_e32 v14, v14, v16
	v_sub_f32_e32 v16, v17, v19
	v_add_f32_e32 v14, v16, v14
	v_add_f32_e32 v16, v21, v14
	v_mul_f32_e32 v17, v18, v16
	v_mul_f32_e32 v19, v13, v17
	v_fma_f32 v13, v17, v13, -v19
	v_fmac_f32_e32 v13, v17, v3
	v_sub_f32_e32 v3, v21, v16
	v_add_f32_e32 v3, v14, v3
	v_add_f32_e32 v14, v19, v13
	v_sub_f32_e32 v20, v16, v14
	v_sub_f32_e32 v16, v16, v20
	v_sub_f32_e32 v19, v14, v19
	v_sub_f32_e32 v14, v16, v14
	v_add_f32_e32 v3, v3, v14
	v_sub_f32_e32 v13, v19, v13
	v_cvt_f32_i32_e32 v2, v2
	v_add_f32_e32 v3, v13, v3
	v_add_f32_e32 v13, v15, v17
	v_add_f32_e32 v3, v20, v3
	v_sub_f32_e32 v14, v13, v15
	v_mul_f32_e32 v3, v18, v3
	v_sub_f32_e32 v14, v17, v14
	v_add_f32_e32 v3, v14, v3
	v_mul_f32_e32 v17, 0x3f317218, v2
	v_add_f32_e32 v14, v13, v3
	v_fma_f32 v18, v2, s9, -v17
	v_mul_f32_e32 v15, v14, v14
	v_fmac_f32_e32 v18, 0xb102e308, v2
	v_sub_f32_e32 v2, v14, v13
	v_fmamk_f32 v16, v15, 0x3e9b6dac, v231
	v_sub_f32_e32 v2, v3, v2
	v_add_f32_e32 v3, v17, v18
	v_fmaak_f32 v16, v15, v16, 0x3f2aaada
	v_sub_f32_e32 v13, v3, v17
	v_ldexp_f32 v17, v14, 1
	v_mul_f32_e32 v14, v14, v15
	v_mul_f32_e32 v14, v14, v16
	v_add_f32_e32 v15, v17, v14
	v_sub_f32_e32 v16, v15, v17
	v_ldexp_f32 v2, v2, 1
	v_sub_f32_e32 v14, v14, v16
	v_add_f32_e32 v2, v2, v14
	v_add_f32_e32 v14, v15, v2
	v_sub_f32_e32 v15, v14, v15
	v_sub_f32_e32 v2, v2, v15
	v_add_f32_e32 v15, v3, v14
	v_sub_f32_e32 v16, v15, v3
	v_sub_f32_e32 v17, v15, v16
	v_sub_f32_e32 v13, v18, v13
	v_sub_f32_e32 v3, v3, v17
	v_sub_f32_e32 v14, v14, v16
	v_add_f32_e32 v3, v14, v3
	v_add_f32_e32 v14, v13, v2
	v_sub_f32_e32 v16, v14, v13
	v_sub_f32_e32 v17, v14, v16
	v_sub_f32_e32 v13, v13, v17
	v_sub_f32_e32 v2, v2, v16
	v_add_f32_e32 v3, v14, v3
	v_add_f32_e32 v2, v2, v13
	v_add_f32_e32 v13, v15, v3
	v_sub_f32_e32 v14, v13, v15
	v_sub_f32_e32 v3, v3, v14
	v_add_f32_e32 v2, v2, v3
	v_add_f32_e32 v2, v13, v2
	v_cmp_neq_f32_e32 vcc, s6, v6
	v_mul_f32_e64 v3, |v7|, s7
	v_max_f32_e64 v7, -v7, 0
	v_cndmask_b32_e32 v2, v238, v2, vcc
	v_cmp_ngt_f32_e32 vcc, -1.0, v6
	s_nop 1
	v_cndmask_b32_e32 v2, v239, v2, vcc
	v_cmp_neq_f32_e32 vcc, -1.0, v6
	s_nop 1
	v_cndmask_b32_e32 v2, v240, v2, vcc
	v_cmp_lt_f32_e64 vcc, |v6|, s10
	s_nop 1
	v_cndmask_b32_e32 v2, v2, v6, vcc
	v_add_f32_e32 v2, v8, v2
	v_sub_f32_e32 v2, -0.5, v2
	v_mul_f32_e32 v2, 0x3fb8aa3b, v2
	v_exp_f32_e32 v6, v3
	v_exp_f32_e32 v2, v2
	v_add_f32_e32 v8, v9, v5
	v_add_f32_e32 v9, 1.0, v6
	v_mul_f32_e32 v5, 0xbfb8aa3b, v2
	v_add_f32_e32 v2, -1.0, v9
	v_sub_f32_e32 v3, v2, v9
	v_add_f32_e32 v3, 1.0, v3
	v_sub_f32_e32 v2, v6, v2
	v_add_f32_e32 v13, v2, v3
	v_frexp_mant_f32_e32 v2, v9
	v_cmp_gt_f32_e32 vcc, s8, v2
	v_cvt_f64_f32_e32 v[2:3], v9
	v_frexp_exp_i32_f64_e32 v2, v[2:3]
	v_subbrev_co_u32_e32 v2, vcc, 0, v2, vcc
	v_sub_u32_e32 v3, 0, v2
	v_ldexp_f32 v9, v9, v3
	v_ldexp_f32 v3, v13, v3
	v_add_f32_e32 v13, -1.0, v9
	v_add_f32_e32 v16, 1.0, v9
	v_add_f32_e32 v14, 1.0, v13
	v_add_f32_e32 v17, -1.0, v16
	v_sub_f32_e32 v14, v9, v14
	v_sub_f32_e32 v9, v9, v17
	v_add_f32_e32 v14, v3, v14
	v_add_f32_e32 v3, v3, v9
	v_add_f32_e32 v9, v16, v3
	v_rcp_f32_e32 v17, v9
	v_add_f32_e32 v15, v13, v14
	v_sub_f32_e32 v13, v15, v13
	v_sub_f32_e32 v13, v14, v13
	v_sub_f32_e32 v14, v9, v16
	v_sub_f32_e32 v3, v3, v14
	v_mul_f32_e32 v14, v15, v17
	v_mul_f32_e32 v16, v9, v14
	v_fma_f32 v18, v14, v9, -v16
	v_fmac_f32_e32 v18, v14, v3
	v_add_f32_e32 v19, v16, v18
	v_sub_f32_e32 v20, v15, v19
	v_sub_f32_e32 v15, v15, v20
	v_sub_f32_e32 v16, v19, v16
	v_sub_f32_e32 v15, v15, v19
	v_add_f32_e32 v13, v13, v15
	v_sub_f32_e32 v15, v16, v18
	v_add_f32_e32 v13, v15, v13
	v_add_f32_e32 v15, v20, v13
	v_mul_f32_e32 v16, v17, v15
	v_mul_f32_e32 v18, v9, v16
	v_fma_f32 v9, v16, v9, -v18
	v_fmac_f32_e32 v9, v16, v3
	v_sub_f32_e32 v3, v20, v15
	v_add_f32_e32 v3, v13, v3
	v_add_f32_e32 v13, v18, v9
	v_sub_f32_e32 v19, v15, v13
	v_sub_f32_e32 v15, v15, v19
	v_sub_f32_e32 v18, v13, v18
	v_sub_f32_e32 v13, v15, v13
	v_add_f32_e32 v3, v3, v13
	v_sub_f32_e32 v9, v18, v9
	v_cvt_f32_i32_e32 v2, v2
	v_add_f32_e32 v3, v9, v3
	v_add_f32_e32 v9, v14, v16
	v_add_f32_e32 v3, v19, v3
	v_sub_f32_e32 v13, v9, v14
	v_mul_f32_e32 v3, v17, v3
	v_sub_f32_e32 v13, v16, v13
	v_add_f32_e32 v3, v13, v3
	v_mul_f32_e32 v16, 0x3f317218, v2
	v_add_f32_e32 v13, v9, v3
	v_fma_f32 v17, v2, s9, -v16
	v_mul_f32_e32 v14, v13, v13
	v_fmac_f32_e32 v17, 0xb102e308, v2
; template <int MODE, bool BIG = false> DI void gemm_tile(const Params& p, int tm, int tn, int kv, char* smem) {
;     ...
; #pragma unroll
;       for (int e = 0; e < 4; ++e) {
;         const float z = -u[e];
;         const float sp = fmaxf(z, 0.f) + log1pf(__expf(-fabsf(z)));
;         u[e] = __expf(-__expf(-sp - 0.5f));
;       }
	v_sub_f32_e32 v2, v13, v9
	v_fmamk_f32 v15, v14, 0x3e9b6dac, v231
	v_sub_f32_e32 v2, v3, v2
	v_add_f32_e32 v3, v16, v17
	v_fmaak_f32 v15, v14, v15, 0x3f2aaada
	v_sub_f32_e32 v9, v3, v16
	v_ldexp_f32 v16, v13, 1
	v_mul_f32_e32 v13, v13, v14
	v_mul_f32_e32 v13, v13, v15
	v_add_f32_e32 v14, v16, v13
	v_sub_f32_e32 v15, v14, v16
	v_ldexp_f32 v2, v2, 1
	v_sub_f32_e32 v13, v13, v15
	v_add_f32_e32 v2, v2, v13
	v_add_f32_e32 v13, v14, v2
	v_sub_f32_e32 v14, v13, v14
	v_sub_f32_e32 v2, v2, v14
	v_add_f32_e32 v14, v3, v13
	v_sub_f32_e32 v15, v14, v3
	v_sub_f32_e32 v16, v14, v15
	v_sub_f32_e32 v9, v17, v9
	v_sub_f32_e32 v3, v3, v16
	v_sub_f32_e32 v13, v13, v15
	v_add_f32_e32 v3, v13, v3
	v_add_f32_e32 v13, v9, v2
	v_sub_f32_e32 v15, v13, v9
	v_sub_f32_e32 v16, v13, v15
	v_sub_f32_e32 v9, v9, v16
	v_sub_f32_e32 v2, v2, v15
	v_add_f32_e32 v3, v13, v3
	v_add_f32_e32 v2, v2, v9
	v_add_f32_e32 v9, v14, v3
	v_sub_f32_e32 v13, v9, v14
	v_sub_f32_e32 v3, v3, v13
	v_add_f32_e32 v2, v2, v3
	v_add_f32_e32 v2, v9, v2
	v_cmp_neq_f32_e32 vcc, s6, v6
	s_nop 1
	v_cndmask_b32_e32 v2, v238, v2, vcc
	v_cmp_ngt_f32_e32 vcc, -1.0, v6
	s_nop 1
	v_cndmask_b32_e32 v2, v239, v2, vcc
	v_cmp_neq_f32_e32 vcc, -1.0, v6
	s_nop 1
	v_cndmask_b32_e32 v2, v240, v2, vcc
	v_cmp_lt_f32_e64 vcc, |v6|, s10
	s_nop 1
	v_cndmask_b32_e32 v2, v2, v6, vcc
	v_add_f32_e32 v2, v7, v2
	v_sub_f32_e32 v2, -0.5, v2
	v_mul_f32_e32 v2, 0x3fb8aa3b, v2
	v_exp_f32_e32 v3, v2
	v_mul_f32_e64 v2, |v4|, s7
	v_exp_f32_e32 v6, v2
	v_max_f32_e64 v7, -v4, 0
	v_exp_f32_e32 v2, v5
	v_mul_f32_e32 v3, 0xbfb8aa3b, v3
	v_add_f32_e32 v9, 1.0, v6
	v_add_f32_e32 v4, -1.0, v9
	v_sub_f32_e32 v5, v4, v9
	v_add_f32_e32 v5, 1.0, v5
	v_sub_f32_e32 v4, v6, v4
	v_add_f32_e32 v13, v4, v5
	v_frexp_mant_f32_e32 v4, v9
	v_cmp_gt_f32_e32 vcc, s8, v4
	v_cvt_f64_f32_e32 v[4:5], v9
	v_frexp_exp_i32_f64_e32 v4, v[4:5]
	v_subbrev_co_u32_e32 v4, vcc, 0, v4, vcc
	v_sub_u32_e32 v5, 0, v4
	v_ldexp_f32 v9, v9, v5
	v_ldexp_f32 v5, v13, v5
	v_add_f32_e32 v13, -1.0, v9
	v_add_f32_e32 v16, 1.0, v9
	v_add_f32_e32 v14, 1.0, v13
	v_add_f32_e32 v17, -1.0, v16
	v_sub_f32_e32 v14, v9, v14
	v_sub_f32_e32 v9, v9, v17
	v_add_f32_e32 v14, v5, v14
	v_add_f32_e32 v5, v5, v9
	v_add_f32_e32 v9, v16, v5
	v_rcp_f32_e32 v17, v9
	v_add_f32_e32 v15, v13, v14
	v_sub_f32_e32 v13, v15, v13
	v_sub_f32_e32 v13, v14, v13
	v_sub_f32_e32 v14, v9, v16
	v_sub_f32_e32 v5, v5, v14
	v_mul_f32_e32 v14, v15, v17
	v_mul_f32_e32 v16, v9, v14
	v_fma_f32 v18, v14, v9, -v16
	v_fmac_f32_e32 v18, v14, v5
	v_add_f32_e32 v19, v16, v18
	v_sub_f32_e32 v20, v15, v19
	v_sub_f32_e32 v15, v15, v20
	v_sub_f32_e32 v16, v19, v16
	v_sub_f32_e32 v15, v15, v19
	v_add_f32_e32 v13, v13, v15
	v_sub_f32_e32 v15, v16, v18
	v_add_f32_e32 v13, v15, v13
	v_add_f32_e32 v15, v20, v13
	v_mul_f32_e32 v16, v17, v15
	v_mul_f32_e32 v18, v9, v16
	v_fma_f32 v9, v16, v9, -v18
	v_fmac_f32_e32 v9, v16, v5
	v_sub_f32_e32 v5, v20, v15
	v_add_f32_e32 v5, v13, v5
	v_add_f32_e32 v13, v18, v9
	v_sub_f32_e32 v19, v15, v13
	v_sub_f32_e32 v15, v15, v19
	v_sub_f32_e32 v18, v13, v18
	v_sub_f32_e32 v13, v15, v13
	v_add_f32_e32 v5, v5, v13
	v_sub_f32_e32 v9, v18, v9
	v_cvt_f32_i32_e32 v4, v4
	v_add_f32_e32 v5, v9, v5
	v_add_f32_e32 v9, v14, v16
	v_add_f32_e32 v5, v19, v5
	v_sub_f32_e32 v13, v9, v14
	v_mul_f32_e32 v5, v17, v5
	v_sub_f32_e32 v13, v16, v13
	v_add_f32_e32 v5, v13, v5
	v_mul_f32_e32 v16, 0x3f317218, v4
	v_add_f32_e32 v13, v9, v5
	v_fma_f32 v17, v4, s9, -v16
	v_mul_f32_e32 v14, v13, v13
	v_fmac_f32_e32 v17, 0xb102e308, v4
	v_sub_f32_e32 v4, v13, v9
	v_fmamk_f32 v15, v14, 0x3e9b6dac, v231
	v_sub_f32_e32 v4, v5, v4
	v_add_f32_e32 v5, v16, v17
	v_fmaak_f32 v15, v14, v15, 0x3f2aaada
	v_sub_f32_e32 v9, v5, v16
	v_ldexp_f32 v16, v13, 1
	v_mul_f32_e32 v13, v13, v14
	v_mul_f32_e32 v13, v13, v15
	v_add_f32_e32 v14, v16, v13
	v_sub_f32_e32 v15, v14, v16
	v_ldexp_f32 v4, v4, 1
	v_sub_f32_e32 v13, v13, v15
	v_add_f32_e32 v4, v4, v13
	v_add_f32_e32 v13, v14, v4
	v_sub_f32_e32 v14, v13, v14
	v_sub_f32_e32 v4, v4, v14
	v_add_f32_e32 v14, v5, v13
	v_sub_f32_e32 v15, v14, v5
	v_sub_f32_e32 v16, v14, v15
	v_sub_f32_e32 v9, v17, v9
	v_sub_f32_e32 v5, v5, v16
	v_sub_f32_e32 v13, v13, v15
	v_add_f32_e32 v5, v13, v5
	v_add_f32_e32 v13, v9, v4
	v_sub_f32_e32 v15, v13, v9
	v_sub_f32_e32 v16, v13, v15
	v_sub_f32_e32 v9, v9, v16
	v_sub_f32_e32 v4, v4, v15
	v_add_f32_e32 v5, v13, v5
	v_add_f32_e32 v4, v4, v9
	v_add_f32_e32 v9, v14, v5
	v_sub_f32_e32 v13, v9, v14
	v_sub_f32_e32 v5, v5, v13
	v_add_f32_e32 v4, v4, v5
	v_add_f32_e32 v4, v9, v4
	v_cmp_neq_f32_e32 vcc, s6, v6
	v_mul_f32_e64 v5, |v8|, s7
	v_max_f32_e64 v8, -v8, 0
	v_cndmask_b32_e32 v4, v238, v4, vcc
	v_cmp_ngt_f32_e32 vcc, -1.0, v6
	v_exp_f32_e32 v3, v3
	s_nop 0
	v_cndmask_b32_e32 v4, v239, v4, vcc
	v_cmp_neq_f32_e32 vcc, -1.0, v6
	s_nop 1
	v_cndmask_b32_e32 v4, v240, v4, vcc
	v_cmp_lt_f32_e64 vcc, |v6|, s10
	s_nop 1
	v_cndmask_b32_e32 v4, v4, v6, vcc
	v_exp_f32_e32 v6, v5
	v_add_f32_e32 v4, v7, v4
	v_sub_f32_e32 v4, -0.5, v4
	v_mul_f32_e32 v4, 0x3fb8aa3b, v4
	v_add_f32_e32 v9, 1.0, v6
	v_exp_f32_e32 v7, v4
	v_add_f32_e32 v4, -1.0, v9
	v_sub_f32_e32 v5, v4, v9
	v_add_f32_e32 v5, 1.0, v5
	v_sub_f32_e32 v4, v6, v4
	v_add_f32_e32 v13, v4, v5
	v_frexp_mant_f32_e32 v4, v9
	v_cmp_gt_f32_e32 vcc, s8, v4
	v_cvt_f64_f32_e32 v[4:5], v9
	v_frexp_exp_i32_f64_e32 v4, v[4:5]
	v_subbrev_co_u32_e32 v4, vcc, 0, v4, vcc
	v_sub_u32_e32 v5, 0, v4
	v_ldexp_f32 v9, v9, v5
	v_ldexp_f32 v5, v13, v5
	v_add_f32_e32 v13, -1.0, v9
	v_add_f32_e32 v16, 1.0, v9
	v_add_f32_e32 v14, 1.0, v13
	v_add_f32_e32 v17, -1.0, v16
	v_sub_f32_e32 v14, v9, v14
	v_sub_f32_e32 v9, v9, v17
	v_add_f32_e32 v14, v5, v14
	v_add_f32_e32 v5, v5, v9
; template <int MODE, bool BIG = false> DI void gemm_tile(const Params& p, int tm, int tn, int kv, char* smem) {
;     ...
;     for (int c4 = 0; c4 < 16; ++c4) {
;       float4 v = crow4[c4], ww = w04[c4];
;       float u[4] = {v.x + ww.x, v.y + ww.y, v.z + ww.z, v.w + ww.w};
; #pragma unroll
;       for (int e = 0; e < 4; ++e) {
;         const float z = -u[e];
;         const float sp = fmaxf(z, 0.f) + log1pf(__expf(-fabsf(z)));
;         u[e] = __expf(-__expf(-sp - 0.5f));
;       }
;       W4[c4] = make_float4(u[0], u[1], u[2], u[3]);
	v_add_f32_e32 v9, v16, v5
	v_rcp_f32_e32 v17, v9
	v_add_f32_e32 v15, v13, v14
	v_sub_f32_e32 v13, v15, v13
	v_sub_f32_e32 v13, v14, v13
	v_sub_f32_e32 v14, v9, v16
	v_sub_f32_e32 v5, v5, v14
	v_mul_f32_e32 v14, v15, v17
	v_mul_f32_e32 v16, v9, v14
	v_fma_f32 v18, v14, v9, -v16
	v_fmac_f32_e32 v18, v14, v5
	v_add_f32_e32 v19, v16, v18
	v_sub_f32_e32 v20, v15, v19
	v_sub_f32_e32 v15, v15, v20
	v_sub_f32_e32 v16, v19, v16
	v_sub_f32_e32 v15, v15, v19
	v_add_f32_e32 v13, v13, v15
	v_sub_f32_e32 v15, v16, v18
	v_add_f32_e32 v13, v15, v13
	v_add_f32_e32 v15, v20, v13
	v_mul_f32_e32 v16, v17, v15
	v_mul_f32_e32 v18, v9, v16
	v_fma_f32 v9, v16, v9, -v18
	v_fmac_f32_e32 v9, v16, v5
	v_sub_f32_e32 v5, v20, v15
	v_add_f32_e32 v5, v13, v5
	v_add_f32_e32 v13, v18, v9
	v_sub_f32_e32 v19, v15, v13
	v_sub_f32_e32 v15, v15, v19
	v_sub_f32_e32 v18, v13, v18
	v_sub_f32_e32 v13, v15, v13
	v_add_f32_e32 v5, v5, v13
	v_sub_f32_e32 v9, v18, v9
	v_cvt_f32_i32_e32 v4, v4
	v_add_f32_e32 v5, v9, v5
	v_add_f32_e32 v9, v14, v16
	v_add_f32_e32 v5, v19, v5
	v_sub_f32_e32 v13, v9, v14
	v_mul_f32_e32 v5, v17, v5
	v_sub_f32_e32 v13, v16, v13
	v_add_f32_e32 v5, v13, v5
	v_mul_f32_e32 v16, 0x3f317218, v4
	v_add_f32_e32 v13, v9, v5
	v_fma_f32 v17, v4, s9, -v16
	v_mul_f32_e32 v14, v13, v13
	v_fmac_f32_e32 v17, 0xb102e308, v4
	v_sub_f32_e32 v4, v13, v9
	v_fmamk_f32 v15, v14, 0x3e9b6dac, v231
	v_sub_f32_e32 v4, v5, v4
	v_add_f32_e32 v5, v16, v17
	v_fmaak_f32 v15, v14, v15, 0x3f2aaada
	v_sub_f32_e32 v9, v5, v16
	v_ldexp_f32 v16, v13, 1
	v_mul_f32_e32 v13, v13, v14
	v_mul_f32_e32 v13, v13, v15
	v_add_f32_e32 v14, v16, v13
	v_sub_f32_e32 v15, v14, v16
	v_ldexp_f32 v4, v4, 1
	v_sub_f32_e32 v13, v13, v15
	v_add_f32_e32 v4, v4, v13
	v_add_f32_e32 v13, v14, v4
	v_sub_f32_e32 v14, v13, v14
	v_sub_f32_e32 v4, v4, v14
	v_add_f32_e32 v14, v5, v13
	v_sub_f32_e32 v15, v14, v5
	v_sub_f32_e32 v16, v14, v15
	v_sub_f32_e32 v9, v17, v9
	v_sub_f32_e32 v5, v5, v16
	v_sub_f32_e32 v13, v13, v15
	v_add_f32_e32 v5, v13, v5
	v_add_f32_e32 v13, v9, v4
	v_sub_f32_e32 v15, v13, v9
	v_sub_f32_e32 v16, v13, v15
	v_sub_f32_e32 v9, v9, v16
	v_sub_f32_e32 v4, v4, v15
	v_add_f32_e32 v5, v13, v5
	v_add_f32_e32 v4, v4, v9
	v_add_f32_e32 v9, v14, v5
	v_sub_f32_e32 v13, v9, v14
	v_sub_f32_e32 v5, v5, v13
	v_add_f32_e32 v4, v4, v5
	v_add_f32_e32 v4, v9, v4
	v_cmp_neq_f32_e32 vcc, s6, v6
	s_nop 1
	v_cndmask_b32_e32 v4, v238, v4, vcc
	v_cmp_ngt_f32_e32 vcc, -1.0, v6
	s_nop 1
	v_cndmask_b32_e32 v4, v239, v4, vcc
	v_cmp_neq_f32_e32 vcc, -1.0, v6
	s_nop 1
	v_cndmask_b32_e32 v4, v240, v4, vcc
	v_cmp_lt_f32_e64 vcc, |v6|, s10
	s_nop 1
	v_cndmask_b32_e32 v4, v4, v6, vcc
	v_add_f32_e32 v4, v8, v4
	v_sub_f32_e32 v4, -0.5, v4
	v_mul_f32_e32 v4, 0x3fb8aa3b, v4
	v_exp_f32_e32 v5, v4
	v_mul_f32_e32 v4, 0xbfb8aa3b, v7
	v_exp_f32_e32 v4, v4
	ds_read_b128 v[6:9], v12 offset:32
	v_mul_f32_e32 v5, 0xbfb8aa3b, v5
	v_exp_f32_e32 v5, v5
	ds_write_b128 v75, v[2:5] offset:16
	ds_read_b128 v[2:5], v74 offset:32
	s_waitcnt lgkmcnt(0)
	v_add_f32_e32 v2, v6, v2
	v_mul_f32_e64 v6, |v2|, s7
	v_exp_f32_e32 v6, v6
	v_add_f32_e32 v4, v8, v4
	v_max_f32_e64 v8, -v2, 0
	v_add_f32_e32 v7, v7, v3
	v_add_f32_e32 v13, 1.0, v6
	v_add_f32_e32 v2, -1.0, v13
	v_sub_f32_e32 v3, v2, v13
	v_add_f32_e32 v3, 1.0, v3
	v_sub_f32_e32 v2, v6, v2
	v_add_f32_e32 v14, v2, v3
	v_frexp_mant_f32_e32 v2, v13
	v_cmp_gt_f32_e32 vcc, s8, v2
	v_cvt_f64_f32_e32 v[2:3], v13
	v_frexp_exp_i32_f64_e32 v2, v[2:3]
	v_subbrev_co_u32_e32 v2, vcc, 0, v2, vcc
	v_sub_u32_e32 v3, 0, v2
	v_ldexp_f32 v13, v13, v3
	v_ldexp_f32 v3, v14, v3
	v_add_f32_e32 v14, -1.0, v13
	v_add_f32_e32 v17, 1.0, v13
	v_add_f32_e32 v15, 1.0, v14
	v_add_f32_e32 v18, -1.0, v17
	v_sub_f32_e32 v15, v13, v15
	v_sub_f32_e32 v13, v13, v18
	v_add_f32_e32 v15, v3, v15
	v_add_f32_e32 v3, v3, v13
	v_add_f32_e32 v13, v17, v3
	v_rcp_f32_e32 v18, v13
	v_add_f32_e32 v16, v14, v15
	v_sub_f32_e32 v14, v16, v14
	v_sub_f32_e32 v14, v15, v14
	v_sub_f32_e32 v15, v13, v17
	v_sub_f32_e32 v3, v3, v15
	v_mul_f32_e32 v15, v16, v18
	v_mul_f32_e32 v17, v13, v15
	v_fma_f32 v19, v15, v13, -v17
	v_fmac_f32_e32 v19, v15, v3
	v_add_f32_e32 v20, v17, v19
	v_sub_f32_e32 v21, v16, v20
	v_sub_f32_e32 v16, v16, v21
	v_sub_f32_e32 v17, v20, v17
	v_sub_f32_e32 v16, v16, v20
	v_add_f32_e32 v14, v14, v16
	v_sub_f32_e32 v16, v17, v19
	v_add_f32_e32 v14, v16, v14
	v_add_f32_e32 v16, v21, v14
	v_mul_f32_e32 v17, v18, v16
	v_mul_f32_e32 v19, v13, v17
	v_fma_f32 v13, v17, v13, -v19
	v_fmac_f32_e32 v13, v17, v3
	v_sub_f32_e32 v3, v21, v16
	v_add_f32_e32 v3, v14, v3
	v_add_f32_e32 v14, v19, v13
	v_sub_f32_e32 v20, v16, v14
	v_sub_f32_e32 v16, v16, v20
	v_sub_f32_e32 v19, v14, v19
	v_sub_f32_e32 v14, v16, v14
	v_add_f32_e32 v3, v3, v14
	v_sub_f32_e32 v13, v19, v13
	v_cvt_f32_i32_e32 v2, v2
	v_add_f32_e32 v3, v13, v3
	v_add_f32_e32 v13, v15, v17
	v_add_f32_e32 v3, v20, v3
	v_sub_f32_e32 v14, v13, v15
	v_mul_f32_e32 v3, v18, v3
	v_sub_f32_e32 v14, v17, v14
	v_add_f32_e32 v3, v14, v3
	v_mul_f32_e32 v17, 0x3f317218, v2
	v_add_f32_e32 v14, v13, v3
	v_fma_f32 v18, v2, s9, -v17
	v_mul_f32_e32 v15, v14, v14
	v_fmac_f32_e32 v18, 0xb102e308, v2
	v_sub_f32_e32 v2, v14, v13
	v_fmamk_f32 v16, v15, 0x3e9b6dac, v231
	v_sub_f32_e32 v2, v3, v2
	v_add_f32_e32 v3, v17, v18
	v_fmaak_f32 v16, v15, v16, 0x3f2aaada
	v_sub_f32_e32 v13, v3, v17
	v_ldexp_f32 v17, v14, 1
	v_mul_f32_e32 v14, v14, v15
	v_mul_f32_e32 v14, v14, v16
	v_add_f32_e32 v15, v17, v14
	v_sub_f32_e32 v16, v15, v17
	v_ldexp_f32 v2, v2, 1
	v_sub_f32_e32 v14, v14, v16
	v_add_f32_e32 v2, v2, v14
	v_add_f32_e32 v14, v15, v2
	v_sub_f32_e32 v15, v14, v15
	v_sub_f32_e32 v2, v2, v15
	v_add_f32_e32 v15, v3, v14
; template <int MODE, bool BIG = false> DI void gemm_tile(const Params& p, int tm, int tn, int kv, char* smem) {
;     ...
; #pragma unroll
;       for (int e = 0; e < 4; ++e) {
;         const float z = -u[e];
;         const float sp = fmaxf(z, 0.f) + log1pf(__expf(-fabsf(z)));
;         u[e] = __expf(-__expf(-sp - 0.5f));
;       }
	v_sub_f32_e32 v16, v15, v3
	v_sub_f32_e32 v17, v15, v16
	v_sub_f32_e32 v13, v18, v13
	v_sub_f32_e32 v3, v3, v17
	v_sub_f32_e32 v14, v14, v16
	v_add_f32_e32 v3, v14, v3
	v_add_f32_e32 v14, v13, v2
	v_sub_f32_e32 v16, v14, v13
	v_sub_f32_e32 v17, v14, v16
	v_sub_f32_e32 v13, v13, v17
	v_sub_f32_e32 v2, v2, v16
	v_add_f32_e32 v3, v14, v3
	v_add_f32_e32 v2, v2, v13
	v_add_f32_e32 v13, v15, v3
	v_sub_f32_e32 v14, v13, v15
	v_sub_f32_e32 v3, v3, v14
	v_add_f32_e32 v2, v2, v3
	v_add_f32_e32 v2, v13, v2
	v_cmp_neq_f32_e32 vcc, s6, v6
	v_mul_f32_e64 v3, |v7|, s7
	v_max_f32_e64 v7, -v7, 0
	v_cndmask_b32_e32 v2, v238, v2, vcc
	v_cmp_ngt_f32_e32 vcc, -1.0, v6
	s_nop 1
	v_cndmask_b32_e32 v2, v239, v2, vcc
	v_cmp_neq_f32_e32 vcc, -1.0, v6
	s_nop 1
	v_cndmask_b32_e32 v2, v240, v2, vcc
	v_cmp_lt_f32_e64 vcc, |v6|, s10
	s_nop 1
	v_cndmask_b32_e32 v2, v2, v6, vcc
	v_add_f32_e32 v2, v8, v2
	v_sub_f32_e32 v2, -0.5, v2
	v_mul_f32_e32 v2, 0x3fb8aa3b, v2
	v_exp_f32_e32 v6, v3
	v_exp_f32_e32 v2, v2
	v_add_f32_e32 v8, v9, v5
	v_add_f32_e32 v9, 1.0, v6
	v_mul_f32_e32 v5, 0xbfb8aa3b, v2
	v_add_f32_e32 v2, -1.0, v9
	v_sub_f32_e32 v3, v2, v9
	v_add_f32_e32 v3, 1.0, v3
	v_sub_f32_e32 v2, v6, v2
	v_add_f32_e32 v13, v2, v3
	v_frexp_mant_f32_e32 v2, v9
	v_cmp_gt_f32_e32 vcc, s8, v2
	v_cvt_f64_f32_e32 v[2:3], v9
	v_frexp_exp_i32_f64_e32 v2, v[2:3]
	v_subbrev_co_u32_e32 v2, vcc, 0, v2, vcc
	v_sub_u32_e32 v3, 0, v2
	v_ldexp_f32 v9, v9, v3
	v_ldexp_f32 v3, v13, v3
	v_add_f32_e32 v13, -1.0, v9
	v_add_f32_e32 v16, 1.0, v9
	v_add_f32_e32 v14, 1.0, v13
	v_add_f32_e32 v17, -1.0, v16
	v_sub_f32_e32 v14, v9, v14
	v_sub_f32_e32 v9, v9, v17
	v_add_f32_e32 v14, v3, v14
	v_add_f32_e32 v3, v3, v9
	v_add_f32_e32 v9, v16, v3
	v_rcp_f32_e32 v17, v9
	v_add_f32_e32 v15, v13, v14
	v_sub_f32_e32 v13, v15, v13
	v_sub_f32_e32 v13, v14, v13
	v_sub_f32_e32 v14, v9, v16
	v_sub_f32_e32 v3, v3, v14
	v_mul_f32_e32 v14, v15, v17
	v_mul_f32_e32 v16, v9, v14
	v_fma_f32 v18, v14, v9, -v16
	v_fmac_f32_e32 v18, v14, v3
	v_add_f32_e32 v19, v16, v18
	v_sub_f32_e32 v20, v15, v19
	v_sub_f32_e32 v15, v15, v20
	v_sub_f32_e32 v16, v19, v16
	v_sub_f32_e32 v15, v15, v19
	v_add_f32_e32 v13, v13, v15
	v_sub_f32_e32 v15, v16, v18
	v_add_f32_e32 v13, v15, v13
	v_add_f32_e32 v15, v20, v13
	v_mul_f32_e32 v16, v17, v15
	v_mul_f32_e32 v18, v9, v16
	v_fma_f32 v9, v16, v9, -v18
	v_fmac_f32_e32 v9, v16, v3
	v_sub_f32_e32 v3, v20, v15
	v_add_f32_e32 v3, v13, v3
	v_add_f32_e32 v13, v18, v9
	v_sub_f32_e32 v19, v15, v13
	v_sub_f32_e32 v15, v15, v19
	v_sub_f32_e32 v18, v13, v18
	v_sub_f32_e32 v13, v15, v13
	v_add_f32_e32 v3, v3, v13
	v_sub_f32_e32 v9, v18, v9
	v_cvt_f32_i32_e32 v2, v2
	v_add_f32_e32 v3, v9, v3
	v_add_f32_e32 v9, v14, v16
	v_add_f32_e32 v3, v19, v3
	v_sub_f32_e32 v13, v9, v14
	v_mul_f32_e32 v3, v17, v3
	v_sub_f32_e32 v13, v16, v13
	v_add_f32_e32 v3, v13, v3
	v_mul_f32_e32 v16, 0x3f317218, v2
	v_add_f32_e32 v13, v9, v3
	v_fma_f32 v17, v2, s9, -v16
	v_mul_f32_e32 v14, v13, v13
	v_fmac_f32_e32 v17, 0xb102e308, v2
	v_sub_f32_e32 v2, v13, v9
	v_fmamk_f32 v15, v14, 0x3e9b6dac, v231
	v_sub_f32_e32 v2, v3, v2
	v_add_f32_e32 v3, v16, v17
	v_fmaak_f32 v15, v14, v15, 0x3f2aaada
	v_sub_f32_e32 v9, v3, v16
	v_ldexp_f32 v16, v13, 1
	v_mul_f32_e32 v13, v13, v14
	v_mul_f32_e32 v13, v13, v15
	v_add_f32_e32 v14, v16, v13
	v_sub_f32_e32 v15, v14, v16
	v_ldexp_f32 v2, v2, 1
	v_sub_f32_e32 v13, v13, v15
	v_add_f32_e32 v2, v2, v13
	v_add_f32_e32 v13, v14, v2
	v_sub_f32_e32 v14, v13, v14
	v_sub_f32_e32 v2, v2, v14
	v_add_f32_e32 v14, v3, v13
	v_sub_f32_e32 v15, v14, v3
	v_sub_f32_e32 v16, v14, v15
	v_sub_f32_e32 v9, v17, v9
	v_sub_f32_e32 v3, v3, v16
	v_sub_f32_e32 v13, v13, v15
	v_add_f32_e32 v3, v13, v3
	v_add_f32_e32 v13, v9, v2
	v_sub_f32_e32 v15, v13, v9
	v_sub_f32_e32 v16, v13, v15
	v_sub_f32_e32 v9, v9, v16
	v_sub_f32_e32 v2, v2, v15
	v_add_f32_e32 v3, v13, v3
	v_add_f32_e32 v2, v2, v9
	v_add_f32_e32 v9, v14, v3
	v_sub_f32_e32 v13, v9, v14
	v_sub_f32_e32 v3, v3, v13
	v_add_f32_e32 v2, v2, v3
	v_add_f32_e32 v2, v9, v2
	v_cmp_neq_f32_e32 vcc, s6, v6
	s_nop 1
	v_cndmask_b32_e32 v2, v238, v2, vcc
	v_cmp_ngt_f32_e32 vcc, -1.0, v6
	s_nop 1
	v_cndmask_b32_e32 v2, v239, v2, vcc
	v_cmp_neq_f32_e32 vcc, -1.0, v6
	s_nop 1
	v_cndmask_b32_e32 v2, v240, v2, vcc
	v_cmp_lt_f32_e64 vcc, |v6|, s10
	s_nop 1
	v_cndmask_b32_e32 v2, v2, v6, vcc
	v_add_f32_e32 v2, v7, v2
	v_sub_f32_e32 v2, -0.5, v2
	v_mul_f32_e32 v2, 0x3fb8aa3b, v2
	v_exp_f32_e32 v3, v2
	v_mul_f32_e64 v2, |v4|, s7
	v_exp_f32_e32 v6, v2
	v_max_f32_e64 v7, -v4, 0
	v_exp_f32_e32 v2, v5
	v_mul_f32_e32 v3, 0xbfb8aa3b, v3
	v_add_f32_e32 v9, 1.0, v6
	v_add_f32_e32 v4, -1.0, v9
	v_sub_f32_e32 v5, v4, v9
	v_add_f32_e32 v5, 1.0, v5
	v_sub_f32_e32 v4, v6, v4
	v_add_f32_e32 v13, v4, v5
	v_frexp_mant_f32_e32 v4, v9
	v_cmp_gt_f32_e32 vcc, s8, v4
	v_cvt_f64_f32_e32 v[4:5], v9
	v_frexp_exp_i32_f64_e32 v4, v[4:5]
	v_subbrev_co_u32_e32 v4, vcc, 0, v4, vcc
	v_sub_u32_e32 v5, 0, v4
	v_ldexp_f32 v9, v9, v5
	v_ldexp_f32 v5, v13, v5
	v_add_f32_e32 v13, -1.0, v9
	v_add_f32_e32 v16, 1.0, v9
	v_add_f32_e32 v14, 1.0, v13
	v_add_f32_e32 v17, -1.0, v16
	v_sub_f32_e32 v14, v9, v14
	v_sub_f32_e32 v9, v9, v17
	v_add_f32_e32 v14, v5, v14
	v_add_f32_e32 v5, v5, v9
	v_add_f32_e32 v9, v16, v5
	v_rcp_f32_e32 v17, v9
	v_add_f32_e32 v15, v13, v14
	v_sub_f32_e32 v13, v15, v13
	v_sub_f32_e32 v13, v14, v13
	v_sub_f32_e32 v14, v9, v16
	v_sub_f32_e32 v5, v5, v14
	v_mul_f32_e32 v14, v15, v17
	v_mul_f32_e32 v16, v9, v14
	v_fma_f32 v18, v14, v9, -v16
	v_fmac_f32_e32 v18, v14, v5
	v_add_f32_e32 v19, v16, v18
	v_sub_f32_e32 v20, v15, v19
	v_sub_f32_e32 v15, v15, v20
	v_sub_f32_e32 v16, v19, v16
	v_sub_f32_e32 v15, v15, v19
; template <int MODE, bool BIG = false> DI void gemm_tile(const Params& p, int tm, int tn, int kv, char* smem) {
;     ...
;     for (int c4 = 0; c4 < 16; ++c4) {
;       float4 v = crow4[c4], ww = w04[c4];
;       float u[4] = {v.x + ww.x, v.y + ww.y, v.z + ww.z, v.w + ww.w};
; #pragma unroll
;       for (int e = 0; e < 4; ++e) {
;         const float z = -u[e];
;         const float sp = fmaxf(z, 0.f) + log1pf(__expf(-fabsf(z)));
;         u[e] = __expf(-__expf(-sp - 0.5f));
;       }
;       W4[c4] = make_float4(u[0], u[1], u[2], u[3]);
	v_add_f32_e32 v13, v13, v15
	v_sub_f32_e32 v15, v16, v18
	v_add_f32_e32 v13, v15, v13
	v_add_f32_e32 v15, v20, v13
	v_mul_f32_e32 v16, v17, v15
	v_mul_f32_e32 v18, v9, v16
	v_fma_f32 v9, v16, v9, -v18
	v_fmac_f32_e32 v9, v16, v5
	v_sub_f32_e32 v5, v20, v15
	v_add_f32_e32 v5, v13, v5
	v_add_f32_e32 v13, v18, v9
	v_sub_f32_e32 v19, v15, v13
	v_sub_f32_e32 v15, v15, v19
	v_sub_f32_e32 v18, v13, v18
	v_sub_f32_e32 v13, v15, v13
	v_add_f32_e32 v5, v5, v13
	v_sub_f32_e32 v9, v18, v9
	v_cvt_f32_i32_e32 v4, v4
	v_add_f32_e32 v5, v9, v5
	v_add_f32_e32 v9, v14, v16
	v_add_f32_e32 v5, v19, v5
	v_sub_f32_e32 v13, v9, v14
	v_mul_f32_e32 v5, v17, v5
	v_sub_f32_e32 v13, v16, v13
	v_add_f32_e32 v5, v13, v5
	v_mul_f32_e32 v16, 0x3f317218, v4
	v_add_f32_e32 v13, v9, v5
	v_fma_f32 v17, v4, s9, -v16
	v_mul_f32_e32 v14, v13, v13
	v_fmac_f32_e32 v17, 0xb102e308, v4
	v_sub_f32_e32 v4, v13, v9
	v_fmamk_f32 v15, v14, 0x3e9b6dac, v231
	v_sub_f32_e32 v4, v5, v4
	v_add_f32_e32 v5, v16, v17
	v_fmaak_f32 v15, v14, v15, 0x3f2aaada
	v_sub_f32_e32 v9, v5, v16
	v_ldexp_f32 v16, v13, 1
	v_mul_f32_e32 v13, v13, v14
	v_mul_f32_e32 v13, v13, v15
	v_add_f32_e32 v14, v16, v13
	v_sub_f32_e32 v15, v14, v16
	v_ldexp_f32 v4, v4, 1
	v_sub_f32_e32 v13, v13, v15
	v_add_f32_e32 v4, v4, v13
	v_add_f32_e32 v13, v14, v4
	v_sub_f32_e32 v14, v13, v14
	v_sub_f32_e32 v4, v4, v14
	v_add_f32_e32 v14, v5, v13
	v_sub_f32_e32 v15, v14, v5
	v_sub_f32_e32 v16, v14, v15
	v_sub_f32_e32 v9, v17, v9
	v_sub_f32_e32 v5, v5, v16
	v_sub_f32_e32 v13, v13, v15
	v_add_f32_e32 v5, v13, v5
	v_add_f32_e32 v13, v9, v4
	v_sub_f32_e32 v15, v13, v9
	v_sub_f32_e32 v16, v13, v15
	v_sub_f32_e32 v9, v9, v16
	v_sub_f32_e32 v4, v4, v15
	v_add_f32_e32 v5, v13, v5
	v_add_f32_e32 v4, v4, v9
	v_add_f32_e32 v9, v14, v5
	v_sub_f32_e32 v13, v9, v14
	v_sub_f32_e32 v5, v5, v13
	v_add_f32_e32 v4, v4, v5
	v_add_f32_e32 v4, v9, v4
	v_cmp_neq_f32_e32 vcc, s6, v6
	v_mul_f32_e64 v5, |v8|, s7
	v_max_f32_e64 v8, -v8, 0
	v_cndmask_b32_e32 v4, v238, v4, vcc
	v_cmp_ngt_f32_e32 vcc, -1.0, v6
	v_exp_f32_e32 v3, v3
	s_nop 0
	v_cndmask_b32_e32 v4, v239, v4, vcc
	v_cmp_neq_f32_e32 vcc, -1.0, v6
	s_nop 1
	v_cndmask_b32_e32 v4, v240, v4, vcc
	v_cmp_lt_f32_e64 vcc, |v6|, s10
	s_nop 1
	v_cndmask_b32_e32 v4, v4, v6, vcc
	v_exp_f32_e32 v6, v5
	v_add_f32_e32 v4, v7, v4
	v_sub_f32_e32 v4, -0.5, v4
	v_mul_f32_e32 v4, 0x3fb8aa3b, v4
	v_add_f32_e32 v9, 1.0, v6
	v_exp_f32_e32 v7, v4
	v_add_f32_e32 v4, -1.0, v9
	v_sub_f32_e32 v5, v4, v9
	v_add_f32_e32 v5, 1.0, v5
	v_sub_f32_e32 v4, v6, v4
	v_add_f32_e32 v13, v4, v5
	v_frexp_mant_f32_e32 v4, v9
	v_cmp_gt_f32_e32 vcc, s8, v4
	v_cvt_f64_f32_e32 v[4:5], v9
	v_frexp_exp_i32_f64_e32 v4, v[4:5]
	v_subbrev_co_u32_e32 v4, vcc, 0, v4, vcc
	v_sub_u32_e32 v5, 0, v4
	v_ldexp_f32 v9, v9, v5
	v_ldexp_f32 v5, v13, v5
	v_add_f32_e32 v13, -1.0, v9
	v_add_f32_e32 v16, 1.0, v9
	v_add_f32_e32 v14, 1.0, v13
	v_add_f32_e32 v17, -1.0, v16
	v_sub_f32_e32 v14, v9, v14
	v_sub_f32_e32 v9, v9, v17
	v_add_f32_e32 v14, v5, v14
	v_add_f32_e32 v5, v5, v9
	v_add_f32_e32 v9, v16, v5
	v_rcp_f32_e32 v17, v9
	v_add_f32_e32 v15, v13, v14
	v_sub_f32_e32 v13, v15, v13
	v_sub_f32_e32 v13, v14, v13
	v_sub_f32_e32 v14, v9, v16
	v_sub_f32_e32 v5, v5, v14
	v_mul_f32_e32 v14, v15, v17
	v_mul_f32_e32 v16, v9, v14
	v_fma_f32 v18, v14, v9, -v16
	v_fmac_f32_e32 v18, v14, v5
	v_add_f32_e32 v19, v16, v18
	v_sub_f32_e32 v20, v15, v19
	v_sub_f32_e32 v15, v15, v20
	v_sub_f32_e32 v16, v19, v16
	v_sub_f32_e32 v15, v15, v19
	v_add_f32_e32 v13, v13, v15
	v_sub_f32_e32 v15, v16, v18
	v_add_f32_e32 v13, v15, v13
	v_add_f32_e32 v15, v20, v13
	v_mul_f32_e32 v16, v17, v15
	v_mul_f32_e32 v18, v9, v16
	v_fma_f32 v9, v16, v9, -v18
	v_fmac_f32_e32 v9, v16, v5
	v_sub_f32_e32 v5, v20, v15
	v_add_f32_e32 v5, v13, v5
	v_add_f32_e32 v13, v18, v9
	v_sub_f32_e32 v19, v15, v13
	v_sub_f32_e32 v15, v15, v19
	v_sub_f32_e32 v18, v13, v18
	v_sub_f32_e32 v13, v15, v13
	v_add_f32_e32 v5, v5, v13
	v_sub_f32_e32 v9, v18, v9
	v_cvt_f32_i32_e32 v4, v4
	v_add_f32_e32 v5, v9, v5
	v_add_f32_e32 v9, v14, v16
	v_add_f32_e32 v5, v19, v5
	v_sub_f32_e32 v13, v9, v14
	v_mul_f32_e32 v5, v17, v5
	v_sub_f32_e32 v13, v16, v13
	v_add_f32_e32 v5, v13, v5
	v_mul_f32_e32 v16, 0x3f317218, v4
	v_add_f32_e32 v13, v9, v5
	v_fma_f32 v17, v4, s9, -v16
	v_mul_f32_e32 v14, v13, v13
	v_fmac_f32_e32 v17, 0xb102e308, v4
	v_sub_f32_e32 v4, v13, v9
	v_fmamk_f32 v15, v14, 0x3e9b6dac, v231
	v_sub_f32_e32 v4, v5, v4
	v_add_f32_e32 v5, v16, v17
	v_fmaak_f32 v15, v14, v15, 0x3f2aaada
	v_sub_f32_e32 v9, v5, v16
	v_ldexp_f32 v16, v13, 1
	v_mul_f32_e32 v13, v13, v14
	v_mul_f32_e32 v13, v13, v15
	v_add_f32_e32 v14, v16, v13
	v_sub_f32_e32 v15, v14, v16
	v_ldexp_f32 v4, v4, 1
	v_sub_f32_e32 v13, v13, v15
	v_add_f32_e32 v4, v4, v13
	v_add_f32_e32 v13, v14, v4
	v_sub_f32_e32 v14, v13, v14
	v_sub_f32_e32 v4, v4, v14
	v_add_f32_e32 v14, v5, v13
	v_sub_f32_e32 v15, v14, v5
	v_sub_f32_e32 v16, v14, v15
	v_sub_f32_e32 v9, v17, v9
	v_sub_f32_e32 v5, v5, v16
	v_sub_f32_e32 v13, v13, v15
	v_add_f32_e32 v5, v13, v5
	v_add_f32_e32 v13, v9, v4
	v_sub_f32_e32 v15, v13, v9
	v_sub_f32_e32 v16, v13, v15
	v_sub_f32_e32 v9, v9, v16
	v_sub_f32_e32 v4, v4, v15
	v_add_f32_e32 v5, v13, v5
	v_add_f32_e32 v4, v4, v9
	v_add_f32_e32 v9, v14, v5
	v_sub_f32_e32 v13, v9, v14
	v_sub_f32_e32 v5, v5, v13
	v_add_f32_e32 v4, v4, v5
	v_add_f32_e32 v4, v9, v4
	v_cmp_neq_f32_e32 vcc, s6, v6
	s_nop 1
	v_cndmask_b32_e32 v4, v238, v4, vcc
	v_cmp_ngt_f32_e32 vcc, -1.0, v6
	s_nop 1
	v_cndmask_b32_e32 v4, v239, v4, vcc
	v_cmp_neq_f32_e32 vcc, -1.0, v6
	s_nop 1
	v_cndmask_b32_e32 v4, v240, v4, vcc
	v_cmp_lt_f32_e64 vcc, |v6|, s10
	s_nop 1
	v_cndmask_b32_e32 v4, v4, v6, vcc
	v_add_f32_e32 v4, v8, v4
	v_sub_f32_e32 v4, -0.5, v4
	v_mul_f32_e32 v4, 0x3fb8aa3b, v4
	v_exp_f32_e32 v5, v4
	v_mul_f32_e32 v4, 0xbfb8aa3b, v7
	v_exp_f32_e32 v4, v4
	ds_read_b128 v[6:9], v12 offset:48
	v_mul_f32_e32 v5, 0xbfb8aa3b, v5
	v_exp_f32_e32 v5, v5
	ds_write_b128 v75, v[2:5] offset:32
	ds_read_b128 v[2:5], v74 offset:48
	s_waitcnt lgkmcnt(0)
; template <int MODE, bool BIG = false> DI void gemm_tile(const Params& p, int tm, int tn, int kv, char* smem) {
;     ...
;     for (int c4 = 0; c4 < 16; ++c4) {
;       float4 v = crow4[c4], ww = w04[c4];
;       float u[4] = {v.x + ww.x, v.y + ww.y, v.z + ww.z, v.w + ww.w};
; #pragma unroll
;       for (int e = 0; e < 4; ++e) {
;         const float z = -u[e];
;         const float sp = fmaxf(z, 0.f) + log1pf(__expf(-fabsf(z)));
;         u[e] = __expf(-__expf(-sp - 0.5f));
;       }
;       W4[c4] = make_float4(u[0], u[1], u[2], u[3]);
	v_add_f32_e32 v2, v6, v2
	v_mul_f32_e64 v6, |v2|, s7
	v_exp_f32_e32 v6, v6
	v_add_f32_e32 v4, v8, v4
	v_max_f32_e64 v8, -v2, 0
	v_add_f32_e32 v7, v7, v3
	v_add_f32_e32 v13, 1.0, v6
	v_add_f32_e32 v2, -1.0, v13
	v_sub_f32_e32 v3, v2, v13
	v_add_f32_e32 v3, 1.0, v3
	v_sub_f32_e32 v2, v6, v2
	v_add_f32_e32 v14, v2, v3
	v_frexp_mant_f32_e32 v2, v13
	v_cmp_gt_f32_e32 vcc, s8, v2
	v_cvt_f64_f32_e32 v[2:3], v13
	v_frexp_exp_i32_f64_e32 v2, v[2:3]
	v_subbrev_co_u32_e32 v2, vcc, 0, v2, vcc
	v_sub_u32_e32 v3, 0, v2
	v_ldexp_f32 v13, v13, v3
	v_ldexp_f32 v3, v14, v3
	v_add_f32_e32 v14, -1.0, v13
	v_add_f32_e32 v17, 1.0, v13
	v_add_f32_e32 v15, 1.0, v14
	v_add_f32_e32 v18, -1.0, v17
	v_sub_f32_e32 v15, v13, v15
	v_sub_f32_e32 v13, v13, v18
	v_add_f32_e32 v15, v3, v15
	v_add_f32_e32 v3, v3, v13
	v_add_f32_e32 v13, v17, v3
	v_rcp_f32_e32 v18, v13
	v_add_f32_e32 v16, v14, v15
	v_sub_f32_e32 v14, v16, v14
	v_sub_f32_e32 v14, v15, v14
	v_sub_f32_e32 v15, v13, v17
	v_sub_f32_e32 v3, v3, v15
	v_mul_f32_e32 v15, v16, v18
	v_mul_f32_e32 v17, v13, v15
	v_fma_f32 v19, v15, v13, -v17
	v_fmac_f32_e32 v19, v15, v3
	v_add_f32_e32 v20, v17, v19
	v_sub_f32_e32 v21, v16, v20
	v_sub_f32_e32 v16, v16, v21
	v_sub_f32_e32 v17, v20, v17
	v_sub_f32_e32 v16, v16, v20
	v_add_f32_e32 v14, v14, v16
	v_sub_f32_e32 v16, v17, v19
	v_add_f32_e32 v14, v16, v14
	v_add_f32_e32 v16, v21, v14
	v_mul_f32_e32 v17, v18, v16
	v_mul_f32_e32 v19, v13, v17
	v_fma_f32 v13, v17, v13, -v19
	v_fmac_f32_e32 v13, v17, v3
	v_sub_f32_e32 v3, v21, v16
	v_add_f32_e32 v3, v14, v3
	v_add_f32_e32 v14, v19, v13
	v_sub_f32_e32 v20, v16, v14
	v_sub_f32_e32 v16, v16, v20
	v_sub_f32_e32 v19, v14, v19
	v_sub_f32_e32 v14, v16, v14
	v_add_f32_e32 v3, v3, v14
	v_sub_f32_e32 v13, v19, v13
	v_cvt_f32_i32_e32 v2, v2
	v_add_f32_e32 v3, v13, v3
	v_add_f32_e32 v13, v15, v17
	v_add_f32_e32 v3, v20, v3
	v_sub_f32_e32 v14, v13, v15
	v_mul_f32_e32 v3, v18, v3
	v_sub_f32_e32 v14, v17, v14
	v_add_f32_e32 v3, v14, v3
	v_mul_f32_e32 v17, 0x3f317218, v2
	v_add_f32_e32 v14, v13, v3
	v_fma_f32 v18, v2, s9, -v17
	v_mul_f32_e32 v15, v14, v14
	v_fmac_f32_e32 v18, 0xb102e308, v2
	v_sub_f32_e32 v2, v14, v13
	v_fmamk_f32 v16, v15, 0x3e9b6dac, v231
	v_sub_f32_e32 v2, v3, v2
	v_add_f32_e32 v3, v17, v18
	v_fmaak_f32 v16, v15, v16, 0x3f2aaada
	v_sub_f32_e32 v13, v3, v17
	v_ldexp_f32 v17, v14, 1
	v_mul_f32_e32 v14, v14, v15
	v_mul_f32_e32 v14, v14, v16
	v_add_f32_e32 v15, v17, v14
	v_sub_f32_e32 v16, v15, v17
	v_ldexp_f32 v2, v2, 1
	v_sub_f32_e32 v14, v14, v16
	v_add_f32_e32 v2, v2, v14
	v_add_f32_e32 v14, v15, v2
	v_sub_f32_e32 v15, v14, v15
	v_sub_f32_e32 v2, v2, v15
	v_add_f32_e32 v15, v3, v14
	v_sub_f32_e32 v16, v15, v3
	v_sub_f32_e32 v17, v15, v16
	v_sub_f32_e32 v13, v18, v13
	v_sub_f32_e32 v3, v3, v17
	v_sub_f32_e32 v14, v14, v16
	v_add_f32_e32 v3, v14, v3
	v_add_f32_e32 v14, v13, v2
	v_sub_f32_e32 v16, v14, v13
	v_sub_f32_e32 v17, v14, v16
	v_sub_f32_e32 v13, v13, v17
	v_sub_f32_e32 v2, v2, v16
	v_add_f32_e32 v3, v14, v3
	v_add_f32_e32 v2, v2, v13
	v_add_f32_e32 v13, v15, v3
	v_sub_f32_e32 v14, v13, v15
	v_sub_f32_e32 v3, v3, v14
	v_add_f32_e32 v2, v2, v3
	v_add_f32_e32 v2, v13, v2
	v_cmp_neq_f32_e32 vcc, s6, v6
	v_mul_f32_e64 v3, |v7|, s7
	v_max_f32_e64 v7, -v7, 0
	v_cndmask_b32_e32 v2, v238, v2, vcc
	v_cmp_ngt_f32_e32 vcc, -1.0, v6
	s_nop 1
	v_cndmask_b32_e32 v2, v239, v2, vcc
	v_cmp_neq_f32_e32 vcc, -1.0, v6
	s_nop 1
	v_cndmask_b32_e32 v2, v240, v2, vcc
	v_cmp_lt_f32_e64 vcc, |v6|, s10
	s_nop 1
	v_cndmask_b32_e32 v2, v2, v6, vcc
	v_add_f32_e32 v2, v8, v2
	v_sub_f32_e32 v2, -0.5, v2
	v_mul_f32_e32 v2, 0x3fb8aa3b, v2
	v_exp_f32_e32 v6, v3
	v_exp_f32_e32 v2, v2
	v_add_f32_e32 v8, v9, v5
	v_add_f32_e32 v9, 1.0, v6
	v_mul_f32_e32 v5, 0xbfb8aa3b, v2
	v_add_f32_e32 v2, -1.0, v9
	v_sub_f32_e32 v3, v2, v9
	v_add_f32_e32 v3, 1.0, v3
	v_sub_f32_e32 v2, v6, v2
	v_add_f32_e32 v13, v2, v3
	v_frexp_mant_f32_e32 v2, v9
	v_cmp_gt_f32_e32 vcc, s8, v2
	v_cvt_f64_f32_e32 v[2:3], v9
	v_frexp_exp_i32_f64_e32 v2, v[2:3]
	v_subbrev_co_u32_e32 v2, vcc, 0, v2, vcc
	v_sub_u32_e32 v3, 0, v2
	v_ldexp_f32 v9, v9, v3
	v_ldexp_f32 v3, v13, v3
	v_add_f32_e32 v13, -1.0, v9
	v_add_f32_e32 v16, 1.0, v9
	v_add_f32_e32 v14, 1.0, v13
	v_add_f32_e32 v17, -1.0, v16
	v_sub_f32_e32 v14, v9, v14
	v_sub_f32_e32 v9, v9, v17
	v_add_f32_e32 v14, v3, v14
	v_add_f32_e32 v3, v3, v9
	v_add_f32_e32 v9, v16, v3
	v_rcp_f32_e32 v17, v9
	v_add_f32_e32 v15, v13, v14
	v_sub_f32_e32 v13, v15, v13
	v_sub_f32_e32 v13, v14, v13
	v_sub_f32_e32 v14, v9, v16
	v_sub_f32_e32 v3, v3, v14
	v_mul_f32_e32 v14, v15, v17
	v_mul_f32_e32 v16, v9, v14
	v_fma_f32 v18, v14, v9, -v16
	v_fmac_f32_e32 v18, v14, v3
	v_add_f32_e32 v19, v16, v18
	v_sub_f32_e32 v20, v15, v19
	v_sub_f32_e32 v15, v15, v20
	v_sub_f32_e32 v16, v19, v16
	v_sub_f32_e32 v15, v15, v19
	v_add_f32_e32 v13, v13, v15
	v_sub_f32_e32 v15, v16, v18
	v_add_f32_e32 v13, v15, v13
	v_add_f32_e32 v15, v20, v13
	v_mul_f32_e32 v16, v17, v15
	v_mul_f32_e32 v18, v9, v16
	v_fma_f32 v9, v16, v9, -v18
	v_fmac_f32_e32 v9, v16, v3
	v_sub_f32_e32 v3, v20, v15
	v_add_f32_e32 v3, v13, v3
	v_add_f32_e32 v13, v18, v9
	v_sub_f32_e32 v19, v15, v13
	v_sub_f32_e32 v15, v15, v19
	v_sub_f32_e32 v18, v13, v18
	v_sub_f32_e32 v13, v15, v13
	v_add_f32_e32 v3, v3, v13
	v_sub_f32_e32 v9, v18, v9
	v_cvt_f32_i32_e32 v2, v2
	v_add_f32_e32 v3, v9, v3
	v_add_f32_e32 v9, v14, v16
	v_add_f32_e32 v3, v19, v3
	v_sub_f32_e32 v13, v9, v14
	v_mul_f32_e32 v3, v17, v3
	v_sub_f32_e32 v13, v16, v13
	v_add_f32_e32 v3, v13, v3
	v_mul_f32_e32 v16, 0x3f317218, v2
	v_add_f32_e32 v13, v9, v3
	v_fma_f32 v17, v2, s9, -v16
	v_mul_f32_e32 v14, v13, v13
	v_fmac_f32_e32 v17, 0xb102e308, v2
; template <int MODE, bool BIG = false> DI void gemm_tile(const Params& p, int tm, int tn, int kv, char* smem) {
;     ...
;     for (int c4 = 0; c4 < 16; ++c4) {
;       float4 v = crow4[c4], ww = w04[c4];
;       float u[4] = {v.x + ww.x, v.y + ww.y, v.z + ww.z, v.w + ww.w};
; #pragma unroll
;       for (int e = 0; e < 4; ++e) {
;         const float z = -u[e];
;         const float sp = fmaxf(z, 0.f) + log1pf(__expf(-fabsf(z)));
;         u[e] = __expf(-__expf(-sp - 0.5f));
;       }
;       W4[c4] = make_float4(u[0], u[1], u[2], u[3]);
	v_sub_f32_e32 v2, v13, v9
	v_fmamk_f32 v15, v14, 0x3e9b6dac, v231
	v_sub_f32_e32 v2, v3, v2
	v_add_f32_e32 v3, v16, v17
	v_fmaak_f32 v15, v14, v15, 0x3f2aaada
	v_sub_f32_e32 v9, v3, v16
	v_ldexp_f32 v16, v13, 1
	v_mul_f32_e32 v13, v13, v14
	v_mul_f32_e32 v13, v13, v15
	v_add_f32_e32 v14, v16, v13
	v_sub_f32_e32 v15, v14, v16
	v_ldexp_f32 v2, v2, 1
	v_sub_f32_e32 v13, v13, v15
	v_add_f32_e32 v2, v2, v13
	v_add_f32_e32 v13, v14, v2
	v_sub_f32_e32 v14, v13, v14
	v_sub_f32_e32 v2, v2, v14
	v_add_f32_e32 v14, v3, v13
	v_sub_f32_e32 v15, v14, v3
	v_sub_f32_e32 v16, v14, v15
	v_sub_f32_e32 v9, v17, v9
	v_sub_f32_e32 v3, v3, v16
	v_sub_f32_e32 v13, v13, v15
	v_add_f32_e32 v3, v13, v3
	v_add_f32_e32 v13, v9, v2
	v_sub_f32_e32 v15, v13, v9
	v_sub_f32_e32 v16, v13, v15
	v_sub_f32_e32 v9, v9, v16
	v_sub_f32_e32 v2, v2, v15
	v_add_f32_e32 v3, v13, v3
	v_add_f32_e32 v2, v2, v9
	v_add_f32_e32 v9, v14, v3
	v_sub_f32_e32 v13, v9, v14
	v_sub_f32_e32 v3, v3, v13
	v_add_f32_e32 v2, v2, v3
	v_add_f32_e32 v2, v9, v2
	v_cmp_neq_f32_e32 vcc, s6, v6
	s_nop 1
	v_cndmask_b32_e32 v2, v238, v2, vcc
	v_cmp_ngt_f32_e32 vcc, -1.0, v6
	s_nop 1
	v_cndmask_b32_e32 v2, v239, v2, vcc
	v_cmp_neq_f32_e32 vcc, -1.0, v6
	s_nop 1
	v_cndmask_b32_e32 v2, v240, v2, vcc
	v_cmp_lt_f32_e64 vcc, |v6|, s10
	s_nop 1
	v_cndmask_b32_e32 v2, v2, v6, vcc
	v_add_f32_e32 v2, v7, v2
	v_sub_f32_e32 v2, -0.5, v2
	v_mul_f32_e32 v2, 0x3fb8aa3b, v2
	v_exp_f32_e32 v3, v2
	v_mul_f32_e64 v2, |v4|, s7
	v_exp_f32_e32 v6, v2
	v_max_f32_e64 v7, -v4, 0
	v_exp_f32_e32 v2, v5
	v_mul_f32_e32 v3, 0xbfb8aa3b, v3
	v_add_f32_e32 v9, 1.0, v6
	v_add_f32_e32 v4, -1.0, v9
	v_sub_f32_e32 v5, v4, v9
	v_add_f32_e32 v5, 1.0, v5
	v_sub_f32_e32 v4, v6, v4
	v_add_f32_e32 v13, v4, v5
	v_frexp_mant_f32_e32 v4, v9
	v_cmp_gt_f32_e32 vcc, s8, v4
	v_cvt_f64_f32_e32 v[4:5], v9
	v_frexp_exp_i32_f64_e32 v4, v[4:5]
	v_subbrev_co_u32_e32 v4, vcc, 0, v4, vcc
	v_sub_u32_e32 v5, 0, v4
	v_ldexp_f32 v9, v9, v5
	v_ldexp_f32 v5, v13, v5
	v_add_f32_e32 v13, -1.0, v9
	v_add_f32_e32 v16, 1.0, v9
	v_add_f32_e32 v14, 1.0, v13
	v_add_f32_e32 v17, -1.0, v16
	v_sub_f32_e32 v14, v9, v14
	v_sub_f32_e32 v9, v9, v17
	v_add_f32_e32 v14, v5, v14
	v_add_f32_e32 v5, v5, v9
	v_add_f32_e32 v9, v16, v5
	v_rcp_f32_e32 v17, v9
	v_add_f32_e32 v15, v13, v14
	v_sub_f32_e32 v13, v15, v13
	v_sub_f32_e32 v13, v14, v13
	v_sub_f32_e32 v14, v9, v16
	v_sub_f32_e32 v5, v5, v14
	v_mul_f32_e32 v14, v15, v17
	v_mul_f32_e32 v16, v9, v14
	v_fma_f32 v18, v14, v9, -v16
	v_fmac_f32_e32 v18, v14, v5
	v_add_f32_e32 v19, v16, v18
	v_sub_f32_e32 v20, v15, v19
	v_sub_f32_e32 v15, v15, v20
	v_sub_f32_e32 v16, v19, v16
	v_sub_f32_e32 v15, v15, v19
	v_add_f32_e32 v13, v13, v15
	v_sub_f32_e32 v15, v16, v18
	v_add_f32_e32 v13, v15, v13
	v_add_f32_e32 v15, v20, v13
	v_mul_f32_e32 v16, v17, v15
	v_mul_f32_e32 v18, v9, v16
	v_fma_f32 v9, v16, v9, -v18
	v_fmac_f32_e32 v9, v16, v5
	v_sub_f32_e32 v5, v20, v15
	v_add_f32_e32 v5, v13, v5
	v_add_f32_e32 v13, v18, v9
	v_sub_f32_e32 v19, v15, v13
	v_sub_f32_e32 v15, v15, v19
	v_sub_f32_e32 v18, v13, v18
	v_sub_f32_e32 v13, v15, v13
	v_add_f32_e32 v5, v5, v13
	v_sub_f32_e32 v9, v18, v9
	v_cvt_f32_i32_e32 v4, v4
	v_add_f32_e32 v5, v9, v5
	v_add_f32_e32 v9, v14, v16
	v_add_f32_e32 v5, v19, v5
	v_sub_f32_e32 v13, v9, v14
	v_mul_f32_e32 v5, v17, v5
	v_sub_f32_e32 v13, v16, v13
	v_add_f32_e32 v5, v13, v5
	v_mul_f32_e32 v16, 0x3f317218, v4
	v_add_f32_e32 v13, v9, v5
	v_fma_f32 v17, v4, s9, -v16
	v_mul_f32_e32 v14, v13, v13
	v_fmac_f32_e32 v17, 0xb102e308, v4
	v_sub_f32_e32 v4, v13, v9
	v_fmamk_f32 v15, v14, 0x3e9b6dac, v231
	v_sub_f32_e32 v4, v5, v4
	v_add_f32_e32 v5, v16, v17
	v_fmaak_f32 v15, v14, v15, 0x3f2aaada
	v_sub_f32_e32 v9, v5, v16
	v_ldexp_f32 v16, v13, 1
	v_mul_f32_e32 v13, v13, v14
	v_mul_f32_e32 v13, v13, v15
	v_add_f32_e32 v14, v16, v13
	v_sub_f32_e32 v15, v14, v16
	v_ldexp_f32 v4, v4, 1
	v_sub_f32_e32 v13, v13, v15
	v_add_f32_e32 v4, v4, v13
	v_add_f32_e32 v13, v14, v4
	v_sub_f32_e32 v14, v13, v14
	v_sub_f32_e32 v4, v4, v14
	v_add_f32_e32 v14, v5, v13
	v_sub_f32_e32 v15, v14, v5
	v_sub_f32_e32 v16, v14, v15
	v_sub_f32_e32 v9, v17, v9
	v_sub_f32_e32 v5, v5, v16
	v_sub_f32_e32 v13, v13, v15
	v_add_f32_e32 v5, v13, v5
	v_add_f32_e32 v13, v9, v4
	v_sub_f32_e32 v15, v13, v9
	v_sub_f32_e32 v16, v13, v15
	v_sub_f32_e32 v9, v9, v16
	v_sub_f32_e32 v4, v4, v15
	v_add_f32_e32 v5, v13, v5
	v_add_f32_e32 v4, v4, v9
	v_add_f32_e32 v9, v14, v5
	v_sub_f32_e32 v13, v9, v14
	v_sub_f32_e32 v5, v5, v13
	v_add_f32_e32 v4, v4, v5
	v_add_f32_e32 v4, v9, v4
	v_cmp_neq_f32_e32 vcc, s6, v6
	v_mul_f32_e64 v5, |v8|, s7
	v_max_f32_e64 v8, -v8, 0
	v_cndmask_b32_e32 v4, v238, v4, vcc
	v_cmp_ngt_f32_e32 vcc, -1.0, v6
	v_exp_f32_e32 v3, v3
	s_nop 0
	v_cndmask_b32_e32 v4, v239, v4, vcc
	v_cmp_neq_f32_e32 vcc, -1.0, v6
	s_nop 1
	v_cndmask_b32_e32 v4, v240, v4, vcc
	v_cmp_lt_f32_e64 vcc, |v6|, s10
	s_nop 1
	v_cndmask_b32_e32 v4, v4, v6, vcc
	v_exp_f32_e32 v6, v5
	v_add_f32_e32 v4, v7, v4
	v_sub_f32_e32 v4, -0.5, v4
	v_mul_f32_e32 v4, 0x3fb8aa3b, v4
	v_add_f32_e32 v9, 1.0, v6
	v_exp_f32_e32 v7, v4
	v_add_f32_e32 v4, -1.0, v9
	v_sub_f32_e32 v5, v4, v9
	v_add_f32_e32 v5, 1.0, v5
	v_sub_f32_e32 v4, v6, v4
	v_add_f32_e32 v13, v4, v5
	v_frexp_mant_f32_e32 v4, v9
	v_cmp_gt_f32_e32 vcc, s8, v4
	v_cvt_f64_f32_e32 v[4:5], v9
	v_frexp_exp_i32_f64_e32 v4, v[4:5]
	v_subbrev_co_u32_e32 v4, vcc, 0, v4, vcc
	v_sub_u32_e32 v5, 0, v4
	v_ldexp_f32 v9, v9, v5
	v_ldexp_f32 v5, v13, v5
	v_add_f32_e32 v13, -1.0, v9
	v_add_f32_e32 v16, 1.0, v9
	v_add_f32_e32 v14, 1.0, v13
	v_add_f32_e32 v17, -1.0, v16
	v_sub_f32_e32 v14, v9, v14
	v_sub_f32_e32 v9, v9, v17
	v_add_f32_e32 v14, v5, v14
	v_add_f32_e32 v5, v5, v9
; template <int MODE, bool BIG = false> DI void gemm_tile(const Params& p, int tm, int tn, int kv, char* smem) {
;     ...
;     for (int c4 = 0; c4 < 16; ++c4) {
;       float4 v = crow4[c4], ww = w04[c4];
;       float u[4] = {v.x + ww.x, v.y + ww.y, v.z + ww.z, v.w + ww.w};
; #pragma unroll
;       for (int e = 0; e < 4; ++e) {
;         const float z = -u[e];
;         const float sp = fmaxf(z, 0.f) + log1pf(__expf(-fabsf(z)));
;         u[e] = __expf(-__expf(-sp - 0.5f));
;       }
;       W4[c4] = make_float4(u[0], u[1], u[2], u[3]);
	v_add_f32_e32 v9, v16, v5
	v_rcp_f32_e32 v17, v9
	v_add_f32_e32 v15, v13, v14
	v_sub_f32_e32 v13, v15, v13
	v_sub_f32_e32 v13, v14, v13
	v_sub_f32_e32 v14, v9, v16
	v_sub_f32_e32 v5, v5, v14
	v_mul_f32_e32 v14, v15, v17
	v_mul_f32_e32 v16, v9, v14
	v_fma_f32 v18, v14, v9, -v16
	v_fmac_f32_e32 v18, v14, v5
	v_add_f32_e32 v19, v16, v18
	v_sub_f32_e32 v20, v15, v19
	v_sub_f32_e32 v15, v15, v20
	v_sub_f32_e32 v16, v19, v16
	v_sub_f32_e32 v15, v15, v19
	v_add_f32_e32 v13, v13, v15
	v_sub_f32_e32 v15, v16, v18
	v_add_f32_e32 v13, v15, v13
	v_add_f32_e32 v15, v20, v13
	v_mul_f32_e32 v16, v17, v15
	v_mul_f32_e32 v18, v9, v16
	v_fma_f32 v9, v16, v9, -v18
	v_fmac_f32_e32 v9, v16, v5
	v_sub_f32_e32 v5, v20, v15
	v_add_f32_e32 v5, v13, v5
	v_add_f32_e32 v13, v18, v9
	v_sub_f32_e32 v19, v15, v13
	v_sub_f32_e32 v15, v15, v19
	v_sub_f32_e32 v18, v13, v18
	v_sub_f32_e32 v13, v15, v13
	v_add_f32_e32 v5, v5, v13
	v_sub_f32_e32 v9, v18, v9
	v_cvt_f32_i32_e32 v4, v4
	v_add_f32_e32 v5, v9, v5
	v_add_f32_e32 v9, v14, v16
	v_add_f32_e32 v5, v19, v5
	v_sub_f32_e32 v13, v9, v14
	v_mul_f32_e32 v5, v17, v5
	v_sub_f32_e32 v13, v16, v13
	v_add_f32_e32 v5, v13, v5
	v_mul_f32_e32 v16, 0x3f317218, v4
	v_add_f32_e32 v13, v9, v5
	v_fma_f32 v17, v4, s9, -v16
	v_mul_f32_e32 v14, v13, v13
	v_fmac_f32_e32 v17, 0xb102e308, v4
	v_sub_f32_e32 v4, v13, v9
	v_fmamk_f32 v15, v14, 0x3e9b6dac, v231
	v_sub_f32_e32 v4, v5, v4
	v_add_f32_e32 v5, v16, v17
	v_fmaak_f32 v15, v14, v15, 0x3f2aaada
	v_sub_f32_e32 v9, v5, v16
	v_ldexp_f32 v16, v13, 1
	v_mul_f32_e32 v13, v13, v14
	v_mul_f32_e32 v13, v13, v15
	v_add_f32_e32 v14, v16, v13
	v_sub_f32_e32 v15, v14, v16
	v_ldexp_f32 v4, v4, 1
	v_sub_f32_e32 v13, v13, v15
	v_add_f32_e32 v4, v4, v13
	v_add_f32_e32 v13, v14, v4
	v_sub_f32_e32 v14, v13, v14
	v_sub_f32_e32 v4, v4, v14
	v_add_f32_e32 v14, v5, v13
	v_sub_f32_e32 v15, v14, v5
	v_sub_f32_e32 v16, v14, v15
	v_sub_f32_e32 v9, v17, v9
	v_sub_f32_e32 v5, v5, v16
	v_sub_f32_e32 v13, v13, v15
	v_add_f32_e32 v5, v13, v5
	v_add_f32_e32 v13, v9, v4
	v_sub_f32_e32 v15, v13, v9
	v_sub_f32_e32 v16, v13, v15
	v_sub_f32_e32 v9, v9, v16
	v_sub_f32_e32 v4, v4, v15
	v_add_f32_e32 v5, v13, v5
	v_add_f32_e32 v4, v4, v9
	v_add_f32_e32 v9, v14, v5
	v_sub_f32_e32 v13, v9, v14
	v_sub_f32_e32 v5, v5, v13
	v_add_f32_e32 v4, v4, v5
	v_add_f32_e32 v4, v9, v4
	v_cmp_neq_f32_e32 vcc, s6, v6
	s_nop 1
	v_cndmask_b32_e32 v4, v238, v4, vcc
	v_cmp_ngt_f32_e32 vcc, -1.0, v6
	s_nop 1
	v_cndmask_b32_e32 v4, v239, v4, vcc
	v_cmp_neq_f32_e32 vcc, -1.0, v6
	s_nop 1
	v_cndmask_b32_e32 v4, v240, v4, vcc
	v_cmp_lt_f32_e64 vcc, |v6|, s10
	s_nop 1
	v_cndmask_b32_e32 v4, v4, v6, vcc
	v_add_f32_e32 v4, v8, v4
	v_sub_f32_e32 v4, -0.5, v4
	v_mul_f32_e32 v4, 0x3fb8aa3b, v4
	v_exp_f32_e32 v5, v4
	v_mul_f32_e32 v4, 0xbfb8aa3b, v7
	v_exp_f32_e32 v4, v4
	ds_read_b128 v[6:9], v12 offset:64
	v_mul_f32_e32 v5, 0xbfb8aa3b, v5
	v_exp_f32_e32 v5, v5
	ds_write_b128 v75, v[2:5] offset:48
	ds_read_b128 v[2:5], v74 offset:64
	s_waitcnt lgkmcnt(0)
	v_add_f32_e32 v2, v6, v2
	v_mul_f32_e64 v6, |v2|, s7
	v_exp_f32_e32 v6, v6
	v_add_f32_e32 v4, v8, v4
	v_max_f32_e64 v8, -v2, 0
	v_add_f32_e32 v7, v7, v3
	v_add_f32_e32 v13, 1.0, v6
	v_add_f32_e32 v2, -1.0, v13
	v_sub_f32_e32 v3, v2, v13
	v_add_f32_e32 v3, 1.0, v3
	v_sub_f32_e32 v2, v6, v2
	v_add_f32_e32 v14, v2, v3
	v_frexp_mant_f32_e32 v2, v13
	v_cmp_gt_f32_e32 vcc, s8, v2
	v_cvt_f64_f32_e32 v[2:3], v13
	v_frexp_exp_i32_f64_e32 v2, v[2:3]
	v_subbrev_co_u32_e32 v2, vcc, 0, v2, vcc
	v_sub_u32_e32 v3, 0, v2
	v_ldexp_f32 v13, v13, v3
	v_ldexp_f32 v3, v14, v3
	v_add_f32_e32 v14, -1.0, v13
	v_add_f32_e32 v17, 1.0, v13
	v_add_f32_e32 v15, 1.0, v14
	v_add_f32_e32 v18, -1.0, v17
	v_sub_f32_e32 v15, v13, v15
	v_sub_f32_e32 v13, v13, v18
	v_add_f32_e32 v15, v3, v15
	v_add_f32_e32 v3, v3, v13
	v_add_f32_e32 v13, v17, v3
	v_rcp_f32_e32 v18, v13
	v_add_f32_e32 v16, v14, v15
	v_sub_f32_e32 v14, v16, v14
	v_sub_f32_e32 v14, v15, v14
	v_sub_f32_e32 v15, v13, v17
	v_sub_f32_e32 v3, v3, v15
	v_mul_f32_e32 v15, v16, v18
	v_mul_f32_e32 v17, v13, v15
	v_fma_f32 v19, v15, v13, -v17
	v_fmac_f32_e32 v19, v15, v3
	v_add_f32_e32 v20, v17, v19
	v_sub_f32_e32 v21, v16, v20
	v_sub_f32_e32 v16, v16, v21
	v_sub_f32_e32 v17, v20, v17
	v_sub_f32_e32 v16, v16, v20
	v_add_f32_e32 v14, v14, v16
	v_sub_f32_e32 v16, v17, v19
	v_add_f32_e32 v14, v16, v14
	v_add_f32_e32 v16, v21, v14
	v_mul_f32_e32 v17, v18, v16
	v_mul_f32_e32 v19, v13, v17
	v_fma_f32 v13, v17, v13, -v19
	v_fmac_f32_e32 v13, v17, v3
	v_sub_f32_e32 v3, v21, v16
	v_add_f32_e32 v3, v14, v3
	v_add_f32_e32 v14, v19, v13
	v_sub_f32_e32 v20, v16, v14
	v_sub_f32_e32 v16, v16, v20
	v_sub_f32_e32 v19, v14, v19
	v_sub_f32_e32 v14, v16, v14
	v_add_f32_e32 v3, v3, v14
	v_sub_f32_e32 v13, v19, v13
	v_cvt_f32_i32_e32 v2, v2
	v_add_f32_e32 v3, v13, v3
	v_add_f32_e32 v13, v15, v17
	v_add_f32_e32 v3, v20, v3
	v_sub_f32_e32 v14, v13, v15
	v_mul_f32_e32 v3, v18, v3
	v_sub_f32_e32 v14, v17, v14
	v_add_f32_e32 v3, v14, v3
	v_mul_f32_e32 v17, 0x3f317218, v2
	v_add_f32_e32 v14, v13, v3
	v_fma_f32 v18, v2, s9, -v17
	v_mul_f32_e32 v15, v14, v14
	v_fmac_f32_e32 v18, 0xb102e308, v2
	v_sub_f32_e32 v2, v14, v13
	v_fmamk_f32 v16, v15, 0x3e9b6dac, v231
	v_sub_f32_e32 v2, v3, v2
	v_add_f32_e32 v3, v17, v18
	v_fmaak_f32 v16, v15, v16, 0x3f2aaada
	v_sub_f32_e32 v13, v3, v17
	v_ldexp_f32 v17, v14, 1
	v_mul_f32_e32 v14, v14, v15
	v_mul_f32_e32 v14, v14, v16
	v_add_f32_e32 v15, v17, v14
	v_sub_f32_e32 v16, v15, v17
	v_ldexp_f32 v2, v2, 1
	v_sub_f32_e32 v14, v14, v16
	v_add_f32_e32 v2, v2, v14
	v_add_f32_e32 v14, v15, v2
	v_sub_f32_e32 v15, v14, v15
	v_sub_f32_e32 v2, v2, v15
	v_add_f32_e32 v15, v3, v14
; template <int MODE, bool BIG = false> DI void gemm_tile(const Params& p, int tm, int tn, int kv, char* smem) {
;     ...
;     for (int c4 = 0; c4 < 16; ++c4) {
;       float4 v = crow4[c4], ww = w04[c4];
;       float u[4] = {v.x + ww.x, v.y + ww.y, v.z + ww.z, v.w + ww.w};
; #pragma unroll
;       for (int e = 0; e < 4; ++e) {
;         const float z = -u[e];
;         const float sp = fmaxf(z, 0.f) + log1pf(__expf(-fabsf(z)));
;         u[e] = __expf(-__expf(-sp - 0.5f));
;       }
;       W4[c4] = make_float4(u[0], u[1], u[2], u[3]);
	v_sub_f32_e32 v16, v15, v3
	v_sub_f32_e32 v17, v15, v16
	v_sub_f32_e32 v13, v18, v13
	v_sub_f32_e32 v3, v3, v17
	v_sub_f32_e32 v14, v14, v16
	v_add_f32_e32 v3, v14, v3
	v_add_f32_e32 v14, v13, v2
	v_sub_f32_e32 v16, v14, v13
	v_sub_f32_e32 v17, v14, v16
	v_sub_f32_e32 v13, v13, v17
	v_sub_f32_e32 v2, v2, v16
	v_add_f32_e32 v3, v14, v3
	v_add_f32_e32 v2, v2, v13
	v_add_f32_e32 v13, v15, v3
	v_sub_f32_e32 v14, v13, v15
	v_sub_f32_e32 v3, v3, v14
	v_add_f32_e32 v2, v2, v3
	v_add_f32_e32 v2, v13, v2
	v_cmp_neq_f32_e32 vcc, s6, v6
	v_mul_f32_e64 v3, |v7|, s7
	v_max_f32_e64 v7, -v7, 0
	v_cndmask_b32_e32 v2, v238, v2, vcc
	v_cmp_ngt_f32_e32 vcc, -1.0, v6
	s_nop 1
	v_cndmask_b32_e32 v2, v239, v2, vcc
	v_cmp_neq_f32_e32 vcc, -1.0, v6
	s_nop 1
	v_cndmask_b32_e32 v2, v240, v2, vcc
	v_cmp_lt_f32_e64 vcc, |v6|, s10
	s_nop 1
	v_cndmask_b32_e32 v2, v2, v6, vcc
	v_add_f32_e32 v2, v8, v2
	v_sub_f32_e32 v2, -0.5, v2
	v_mul_f32_e32 v2, 0x3fb8aa3b, v2
	v_exp_f32_e32 v6, v3
	v_exp_f32_e32 v2, v2
	v_add_f32_e32 v8, v9, v5
	v_add_f32_e32 v9, 1.0, v6
	v_mul_f32_e32 v5, 0xbfb8aa3b, v2
	v_add_f32_e32 v2, -1.0, v9
	v_sub_f32_e32 v3, v2, v9
	v_add_f32_e32 v3, 1.0, v3
	v_sub_f32_e32 v2, v6, v2
	v_add_f32_e32 v13, v2, v3
	v_frexp_mant_f32_e32 v2, v9
	v_cmp_gt_f32_e32 vcc, s8, v2
	v_cvt_f64_f32_e32 v[2:3], v9
	v_frexp_exp_i32_f64_e32 v2, v[2:3]
	v_subbrev_co_u32_e32 v2, vcc, 0, v2, vcc
	v_sub_u32_e32 v3, 0, v2
	v_ldexp_f32 v9, v9, v3
	v_ldexp_f32 v3, v13, v3
	v_add_f32_e32 v13, -1.0, v9
	v_add_f32_e32 v16, 1.0, v9
	v_add_f32_e32 v14, 1.0, v13
	v_add_f32_e32 v17, -1.0, v16
	v_sub_f32_e32 v14, v9, v14
	v_sub_f32_e32 v9, v9, v17
	v_add_f32_e32 v14, v3, v14
	v_add_f32_e32 v3, v3, v9
	v_add_f32_e32 v9, v16, v3
	v_rcp_f32_e32 v17, v9
	v_add_f32_e32 v15, v13, v14
	v_sub_f32_e32 v13, v15, v13
	v_sub_f32_e32 v13, v14, v13
	v_sub_f32_e32 v14, v9, v16
	v_sub_f32_e32 v3, v3, v14
	v_mul_f32_e32 v14, v15, v17
	v_mul_f32_e32 v16, v9, v14
	v_fma_f32 v18, v14, v9, -v16
	v_fmac_f32_e32 v18, v14, v3
	v_add_f32_e32 v19, v16, v18
	v_sub_f32_e32 v20, v15, v19
	v_sub_f32_e32 v15, v15, v20
	v_sub_f32_e32 v16, v19, v16
	v_sub_f32_e32 v15, v15, v19
	v_add_f32_e32 v13, v13, v15
	v_sub_f32_e32 v15, v16, v18
	v_add_f32_e32 v13, v15, v13
	v_add_f32_e32 v15, v20, v13
	v_mul_f32_e32 v16, v17, v15
	v_mul_f32_e32 v18, v9, v16
	v_fma_f32 v9, v16, v9, -v18
	v_fmac_f32_e32 v9, v16, v3
	v_sub_f32_e32 v3, v20, v15
	v_add_f32_e32 v3, v13, v3
	v_add_f32_e32 v13, v18, v9
	v_sub_f32_e32 v19, v15, v13
	v_sub_f32_e32 v15, v15, v19
	v_sub_f32_e32 v18, v13, v18
	v_sub_f32_e32 v13, v15, v13
	v_add_f32_e32 v3, v3, v13
	v_sub_f32_e32 v9, v18, v9
	v_cvt_f32_i32_e32 v2, v2
	v_add_f32_e32 v3, v9, v3
	v_add_f32_e32 v9, v14, v16
	v_add_f32_e32 v3, v19, v3
	v_sub_f32_e32 v13, v9, v14
	v_mul_f32_e32 v3, v17, v3
	v_sub_f32_e32 v13, v16, v13
	v_add_f32_e32 v3, v13, v3
	v_mul_f32_e32 v16, 0x3f317218, v2
	v_add_f32_e32 v13, v9, v3
	v_fma_f32 v17, v2, s9, -v16
	v_mul_f32_e32 v14, v13, v13
	v_fmac_f32_e32 v17, 0xb102e308, v2
	v_sub_f32_e32 v2, v13, v9
	v_fmamk_f32 v15, v14, 0x3e9b6dac, v231
	v_sub_f32_e32 v2, v3, v2
	v_add_f32_e32 v3, v16, v17
	v_fmaak_f32 v15, v14, v15, 0x3f2aaada
	v_sub_f32_e32 v9, v3, v16
	v_ldexp_f32 v16, v13, 1
	v_mul_f32_e32 v13, v13, v14
	v_mul_f32_e32 v13, v13, v15
	v_add_f32_e32 v14, v16, v13
	v_sub_f32_e32 v15, v14, v16
	v_ldexp_f32 v2, v2, 1
	v_sub_f32_e32 v13, v13, v15
	v_add_f32_e32 v2, v2, v13
	v_add_f32_e32 v13, v14, v2
	v_sub_f32_e32 v14, v13, v14
	v_sub_f32_e32 v2, v2, v14
	v_add_f32_e32 v14, v3, v13
	v_sub_f32_e32 v15, v14, v3
	v_sub_f32_e32 v16, v14, v15
	v_sub_f32_e32 v9, v17, v9
	v_sub_f32_e32 v3, v3, v16
	v_sub_f32_e32 v13, v13, v15
	v_add_f32_e32 v3, v13, v3
	v_add_f32_e32 v13, v9, v2
	v_sub_f32_e32 v15, v13, v9
	v_sub_f32_e32 v16, v13, v15
	v_sub_f32_e32 v9, v9, v16
	v_sub_f32_e32 v2, v2, v15
	v_add_f32_e32 v3, v13, v3
	v_add_f32_e32 v2, v2, v9
	v_add_f32_e32 v9, v14, v3
	v_sub_f32_e32 v13, v9, v14
	v_sub_f32_e32 v3, v3, v13
	v_add_f32_e32 v2, v2, v3
	v_add_f32_e32 v2, v9, v2
	v_cmp_neq_f32_e32 vcc, s6, v6
	s_nop 1
	v_cndmask_b32_e32 v2, v238, v2, vcc
	v_cmp_ngt_f32_e32 vcc, -1.0, v6
	s_nop 1
	v_cndmask_b32_e32 v2, v239, v2, vcc
	v_cmp_neq_f32_e32 vcc, -1.0, v6
	s_nop 1
	v_cndmask_b32_e32 v2, v240, v2, vcc
	v_cmp_lt_f32_e64 vcc, |v6|, s10
	s_nop 1
	v_cndmask_b32_e32 v2, v2, v6, vcc
	v_add_f32_e32 v2, v7, v2
	v_sub_f32_e32 v2, -0.5, v2
	v_mul_f32_e32 v2, 0x3fb8aa3b, v2
	v_exp_f32_e32 v3, v2
	v_mul_f32_e64 v2, |v4|, s7
	v_exp_f32_e32 v6, v2
	v_max_f32_e64 v7, -v4, 0
	v_exp_f32_e32 v2, v5
	v_mul_f32_e32 v3, 0xbfb8aa3b, v3
	v_add_f32_e32 v9, 1.0, v6
	v_add_f32_e32 v4, -1.0, v9
	v_sub_f32_e32 v5, v4, v9
	v_add_f32_e32 v5, 1.0, v5
	v_sub_f32_e32 v4, v6, v4
	v_add_f32_e32 v13, v4, v5
	v_frexp_mant_f32_e32 v4, v9
	v_cmp_gt_f32_e32 vcc, s8, v4
	v_cvt_f64_f32_e32 v[4:5], v9
	v_frexp_exp_i32_f64_e32 v4, v[4:5]
	v_subbrev_co_u32_e32 v4, vcc, 0, v4, vcc
	v_sub_u32_e32 v5, 0, v4
	v_ldexp_f32 v9, v9, v5
	v_ldexp_f32 v5, v13, v5
	v_add_f32_e32 v13, -1.0, v9
	v_add_f32_e32 v16, 1.0, v9
	v_add_f32_e32 v14, 1.0, v13
	v_add_f32_e32 v17, -1.0, v16
	v_sub_f32_e32 v14, v9, v14
	v_sub_f32_e32 v9, v9, v17
	v_add_f32_e32 v14, v5, v14
	v_add_f32_e32 v5, v5, v9
	v_add_f32_e32 v9, v16, v5
	v_rcp_f32_e32 v17, v9
	v_add_f32_e32 v15, v13, v14
	v_sub_f32_e32 v13, v15, v13
	v_sub_f32_e32 v13, v14, v13
	v_sub_f32_e32 v14, v9, v16
	v_sub_f32_e32 v5, v5, v14
	v_mul_f32_e32 v14, v15, v17
	v_mul_f32_e32 v16, v9, v14
	v_fma_f32 v18, v14, v9, -v16
	v_fmac_f32_e32 v18, v14, v5
	v_add_f32_e32 v19, v16, v18
	v_sub_f32_e32 v20, v15, v19
	v_sub_f32_e32 v15, v15, v20
	v_sub_f32_e32 v16, v19, v16
	v_sub_f32_e32 v15, v15, v19
; template <int MODE, bool BIG = false> DI void gemm_tile(const Params& p, int tm, int tn, int kv, char* smem) {
;     ...
;     for (int c4 = 0; c4 < 16; ++c4) {
;       float4 v = crow4[c4], ww = w04[c4];
;       float u[4] = {v.x + ww.x, v.y + ww.y, v.z + ww.z, v.w + ww.w};
; #pragma unroll
;       for (int e = 0; e < 4; ++e) {
;         const float z = -u[e];
;         const float sp = fmaxf(z, 0.f) + log1pf(__expf(-fabsf(z)));
;         u[e] = __expf(-__expf(-sp - 0.5f));
;       }
;       W4[c4] = make_float4(u[0], u[1], u[2], u[3]);
	v_add_f32_e32 v13, v13, v15
	v_sub_f32_e32 v15, v16, v18
	v_add_f32_e32 v13, v15, v13
	v_add_f32_e32 v15, v20, v13
	v_mul_f32_e32 v16, v17, v15
	v_mul_f32_e32 v18, v9, v16
	v_fma_f32 v9, v16, v9, -v18
	v_fmac_f32_e32 v9, v16, v5
	v_sub_f32_e32 v5, v20, v15
	v_add_f32_e32 v5, v13, v5
	v_add_f32_e32 v13, v18, v9
	v_sub_f32_e32 v19, v15, v13
	v_sub_f32_e32 v15, v15, v19
	v_sub_f32_e32 v18, v13, v18
	v_sub_f32_e32 v13, v15, v13
	v_add_f32_e32 v5, v5, v13
	v_sub_f32_e32 v9, v18, v9
	v_cvt_f32_i32_e32 v4, v4
	v_add_f32_e32 v5, v9, v5
	v_add_f32_e32 v9, v14, v16
	v_add_f32_e32 v5, v19, v5
	v_sub_f32_e32 v13, v9, v14
	v_mul_f32_e32 v5, v17, v5
	v_sub_f32_e32 v13, v16, v13
	v_add_f32_e32 v5, v13, v5
	v_mul_f32_e32 v16, 0x3f317218, v4
	v_add_f32_e32 v13, v9, v5
	v_fma_f32 v17, v4, s9, -v16
	v_mul_f32_e32 v14, v13, v13
	v_fmac_f32_e32 v17, 0xb102e308, v4
	v_sub_f32_e32 v4, v13, v9
	v_fmamk_f32 v15, v14, 0x3e9b6dac, v231
	v_sub_f32_e32 v4, v5, v4
	v_add_f32_e32 v5, v16, v17
	v_fmaak_f32 v15, v14, v15, 0x3f2aaada
	v_sub_f32_e32 v9, v5, v16
	v_ldexp_f32 v16, v13, 1
	v_mul_f32_e32 v13, v13, v14
	v_mul_f32_e32 v13, v13, v15
	v_add_f32_e32 v14, v16, v13
	v_sub_f32_e32 v15, v14, v16
	v_ldexp_f32 v4, v4, 1
	v_sub_f32_e32 v13, v13, v15
	v_add_f32_e32 v4, v4, v13
	v_add_f32_e32 v13, v14, v4
	v_sub_f32_e32 v14, v13, v14
	v_sub_f32_e32 v4, v4, v14
	v_add_f32_e32 v14, v5, v13
	v_sub_f32_e32 v15, v14, v5
	v_sub_f32_e32 v16, v14, v15
	v_sub_f32_e32 v9, v17, v9
	v_sub_f32_e32 v5, v5, v16
	v_sub_f32_e32 v13, v13, v15
	v_add_f32_e32 v5, v13, v5
	v_add_f32_e32 v13, v9, v4
	v_sub_f32_e32 v15, v13, v9
	v_sub_f32_e32 v16, v13, v15
	v_sub_f32_e32 v9, v9, v16
	v_sub_f32_e32 v4, v4, v15
	v_add_f32_e32 v5, v13, v5
	v_add_f32_e32 v4, v4, v9
	v_add_f32_e32 v9, v14, v5
	v_sub_f32_e32 v13, v9, v14
	v_sub_f32_e32 v5, v5, v13
	v_add_f32_e32 v4, v4, v5
	v_add_f32_e32 v4, v9, v4
	v_cmp_neq_f32_e32 vcc, s6, v6
	v_mul_f32_e64 v5, |v8|, s7
	v_max_f32_e64 v8, -v8, 0
	v_cndmask_b32_e32 v4, v238, v4, vcc
	v_cmp_ngt_f32_e32 vcc, -1.0, v6
	v_exp_f32_e32 v3, v3
	s_nop 0
	v_cndmask_b32_e32 v4, v239, v4, vcc
	v_cmp_neq_f32_e32 vcc, -1.0, v6
	s_nop 1
	v_cndmask_b32_e32 v4, v240, v4, vcc
	v_cmp_lt_f32_e64 vcc, |v6|, s10
	s_nop 1
	v_cndmask_b32_e32 v4, v4, v6, vcc
	v_exp_f32_e32 v6, v5
	v_add_f32_e32 v4, v7, v4
	v_sub_f32_e32 v4, -0.5, v4
	v_mul_f32_e32 v4, 0x3fb8aa3b, v4
	v_add_f32_e32 v9, 1.0, v6
	v_exp_f32_e32 v7, v4
	v_add_f32_e32 v4, -1.0, v9
	v_sub_f32_e32 v5, v4, v9
	v_add_f32_e32 v5, 1.0, v5
	v_sub_f32_e32 v4, v6, v4
	v_add_f32_e32 v13, v4, v5
	v_frexp_mant_f32_e32 v4, v9
	v_cmp_gt_f32_e32 vcc, s8, v4
	v_cvt_f64_f32_e32 v[4:5], v9
	v_frexp_exp_i32_f64_e32 v4, v[4:5]
	v_subbrev_co_u32_e32 v4, vcc, 0, v4, vcc
	v_sub_u32_e32 v5, 0, v4
	v_ldexp_f32 v9, v9, v5
	v_ldexp_f32 v5, v13, v5
	v_add_f32_e32 v13, -1.0, v9
	v_add_f32_e32 v16, 1.0, v9
	v_add_f32_e32 v14, 1.0, v13
	v_add_f32_e32 v17, -1.0, v16
	v_sub_f32_e32 v14, v9, v14
	v_sub_f32_e32 v9, v9, v17
	v_add_f32_e32 v14, v5, v14
	v_add_f32_e32 v5, v5, v9
	v_add_f32_e32 v9, v16, v5
	v_rcp_f32_e32 v17, v9
	v_add_f32_e32 v15, v13, v14
	v_sub_f32_e32 v13, v15, v13
	v_sub_f32_e32 v13, v14, v13
	v_sub_f32_e32 v14, v9, v16
	v_sub_f32_e32 v5, v5, v14
	v_mul_f32_e32 v14, v15, v17
	v_mul_f32_e32 v16, v9, v14
	v_fma_f32 v18, v14, v9, -v16
	v_fmac_f32_e32 v18, v14, v5
	v_add_f32_e32 v19, v16, v18
	v_sub_f32_e32 v20, v15, v19
	v_sub_f32_e32 v15, v15, v20
	v_sub_f32_e32 v16, v19, v16
	v_sub_f32_e32 v15, v15, v19
	v_add_f32_e32 v13, v13, v15
	v_sub_f32_e32 v15, v16, v18
	v_add_f32_e32 v13, v15, v13
	v_add_f32_e32 v15, v20, v13
	v_mul_f32_e32 v16, v17, v15
	v_mul_f32_e32 v18, v9, v16
	v_fma_f32 v9, v16, v9, -v18
	v_fmac_f32_e32 v9, v16, v5
	v_sub_f32_e32 v5, v20, v15
	v_add_f32_e32 v5, v13, v5
	v_add_f32_e32 v13, v18, v9
	v_sub_f32_e32 v19, v15, v13
	v_sub_f32_e32 v15, v15, v19
	v_sub_f32_e32 v18, v13, v18
	v_sub_f32_e32 v13, v15, v13
	v_add_f32_e32 v5, v5, v13
	v_sub_f32_e32 v9, v18, v9
	v_cvt_f32_i32_e32 v4, v4
	v_add_f32_e32 v5, v9, v5
	v_add_f32_e32 v9, v14, v16
	v_add_f32_e32 v5, v19, v5
	v_sub_f32_e32 v13, v9, v14
	v_mul_f32_e32 v5, v17, v5
	v_sub_f32_e32 v13, v16, v13
	v_add_f32_e32 v5, v13, v5
	v_mul_f32_e32 v16, 0x3f317218, v4
	v_add_f32_e32 v13, v9, v5
	v_fma_f32 v17, v4, s9, -v16
	v_mul_f32_e32 v14, v13, v13
	v_fmac_f32_e32 v17, 0xb102e308, v4
	v_sub_f32_e32 v4, v13, v9
	v_fmamk_f32 v15, v14, 0x3e9b6dac, v231
	v_sub_f32_e32 v4, v5, v4
	v_add_f32_e32 v5, v16, v17
	v_fmaak_f32 v15, v14, v15, 0x3f2aaada
	v_sub_f32_e32 v9, v5, v16
	v_ldexp_f32 v16, v13, 1
	v_mul_f32_e32 v13, v13, v14
	v_mul_f32_e32 v13, v13, v15
	v_add_f32_e32 v14, v16, v13
	v_sub_f32_e32 v15, v14, v16
	v_ldexp_f32 v4, v4, 1
	v_sub_f32_e32 v13, v13, v15
	v_add_f32_e32 v4, v4, v13
	v_add_f32_e32 v13, v14, v4
	v_sub_f32_e32 v14, v13, v14
	v_sub_f32_e32 v4, v4, v14
	v_add_f32_e32 v14, v5, v13
	v_sub_f32_e32 v15, v14, v5
	v_sub_f32_e32 v16, v14, v15
	v_sub_f32_e32 v9, v17, v9
	v_sub_f32_e32 v5, v5, v16
	v_sub_f32_e32 v13, v13, v15
	v_add_f32_e32 v5, v13, v5
	v_add_f32_e32 v13, v9, v4
	v_sub_f32_e32 v15, v13, v9
	v_sub_f32_e32 v16, v13, v15
	v_sub_f32_e32 v9, v9, v16
	v_sub_f32_e32 v4, v4, v15
	v_add_f32_e32 v5, v13, v5
	v_add_f32_e32 v4, v4, v9
	v_add_f32_e32 v9, v14, v5
	v_sub_f32_e32 v13, v9, v14
	v_sub_f32_e32 v5, v5, v13
	v_add_f32_e32 v4, v4, v5
	v_add_f32_e32 v4, v9, v4
	v_cmp_neq_f32_e32 vcc, s6, v6
	s_nop 1
	v_cndmask_b32_e32 v4, v238, v4, vcc
	v_cmp_ngt_f32_e32 vcc, -1.0, v6
	s_nop 1
	v_cndmask_b32_e32 v4, v239, v4, vcc
	v_cmp_neq_f32_e32 vcc, -1.0, v6
	s_nop 1
	v_cndmask_b32_e32 v4, v240, v4, vcc
	v_cmp_lt_f32_e64 vcc, |v6|, s10
	s_nop 1
	v_cndmask_b32_e32 v4, v4, v6, vcc
	v_add_f32_e32 v4, v8, v4
	v_sub_f32_e32 v4, -0.5, v4
	v_mul_f32_e32 v4, 0x3fb8aa3b, v4
	v_exp_f32_e32 v5, v4
	v_mul_f32_e32 v4, 0xbfb8aa3b, v7
	v_exp_f32_e32 v4, v4
	ds_read_b128 v[6:9], v12 offset:80
	v_mul_f32_e32 v5, 0xbfb8aa3b, v5
	v_exp_f32_e32 v5, v5
	ds_write_b128 v75, v[2:5] offset:64
	ds_read_b128 v[2:5], v74 offset:80
	s_waitcnt lgkmcnt(0)
; template <int MODE, bool BIG = false> DI void gemm_tile(const Params& p, int tm, int tn, int kv, char* smem) {
;     ...
;     for (int c4 = 0; c4 < 16; ++c4) {
;       float4 v = crow4[c4], ww = w04[c4];
;       float u[4] = {v.x + ww.x, v.y + ww.y, v.z + ww.z, v.w + ww.w};
; #pragma unroll
;       for (int e = 0; e < 4; ++e) {
;         const float z = -u[e];
;         const float sp = fmaxf(z, 0.f) + log1pf(__expf(-fabsf(z)));
;         u[e] = __expf(-__expf(-sp - 0.5f));
;       }
;       W4[c4] = make_float4(u[0], u[1], u[2], u[3]);
	v_add_f32_e32 v2, v6, v2
	v_mul_f32_e64 v6, |v2|, s7
	v_exp_f32_e32 v6, v6
	v_add_f32_e32 v4, v8, v4
	v_max_f32_e64 v8, -v2, 0
	v_add_f32_e32 v7, v7, v3
	v_add_f32_e32 v13, 1.0, v6
	v_add_f32_e32 v2, -1.0, v13
	v_sub_f32_e32 v3, v2, v13
	v_add_f32_e32 v3, 1.0, v3
	v_sub_f32_e32 v2, v6, v2
	v_add_f32_e32 v14, v2, v3
	v_frexp_mant_f32_e32 v2, v13
	v_cmp_gt_f32_e32 vcc, s8, v2
	v_cvt_f64_f32_e32 v[2:3], v13
	v_frexp_exp_i32_f64_e32 v2, v[2:3]
	v_subbrev_co_u32_e32 v2, vcc, 0, v2, vcc
	v_sub_u32_e32 v3, 0, v2
	v_ldexp_f32 v13, v13, v3
	v_ldexp_f32 v3, v14, v3
	v_add_f32_e32 v14, -1.0, v13
	v_add_f32_e32 v17, 1.0, v13
	v_add_f32_e32 v15, 1.0, v14
	v_add_f32_e32 v18, -1.0, v17
	v_sub_f32_e32 v15, v13, v15
	v_sub_f32_e32 v13, v13, v18
	v_add_f32_e32 v15, v3, v15
	v_add_f32_e32 v3, v3, v13
	v_add_f32_e32 v13, v17, v3
	v_rcp_f32_e32 v18, v13
	v_add_f32_e32 v16, v14, v15
	v_sub_f32_e32 v14, v16, v14
	v_sub_f32_e32 v14, v15, v14
	v_sub_f32_e32 v15, v13, v17
	v_sub_f32_e32 v3, v3, v15
	v_mul_f32_e32 v15, v16, v18
	v_mul_f32_e32 v17, v13, v15
	v_fma_f32 v19, v15, v13, -v17
	v_fmac_f32_e32 v19, v15, v3
	v_add_f32_e32 v20, v17, v19
	v_sub_f32_e32 v21, v16, v20
	v_sub_f32_e32 v16, v16, v21
	v_sub_f32_e32 v17, v20, v17
	v_sub_f32_e32 v16, v16, v20
	v_add_f32_e32 v14, v14, v16
	v_sub_f32_e32 v16, v17, v19
	v_add_f32_e32 v14, v16, v14
	v_add_f32_e32 v16, v21, v14
	v_mul_f32_e32 v17, v18, v16
	v_mul_f32_e32 v19, v13, v17
	v_fma_f32 v13, v17, v13, -v19
	v_fmac_f32_e32 v13, v17, v3
	v_sub_f32_e32 v3, v21, v16
	v_add_f32_e32 v3, v14, v3
	v_add_f32_e32 v14, v19, v13
	v_sub_f32_e32 v20, v16, v14
	v_sub_f32_e32 v16, v16, v20
	v_sub_f32_e32 v19, v14, v19
	v_sub_f32_e32 v14, v16, v14
	v_add_f32_e32 v3, v3, v14
	v_sub_f32_e32 v13, v19, v13
	v_cvt_f32_i32_e32 v2, v2
	v_add_f32_e32 v3, v13, v3
	v_add_f32_e32 v13, v15, v17
	v_add_f32_e32 v3, v20, v3
	v_sub_f32_e32 v14, v13, v15
	v_mul_f32_e32 v3, v18, v3
	v_sub_f32_e32 v14, v17, v14
	v_add_f32_e32 v3, v14, v3
	v_mul_f32_e32 v17, 0x3f317218, v2
	v_add_f32_e32 v14, v13, v3
	v_fma_f32 v18, v2, s9, -v17
	v_mul_f32_e32 v15, v14, v14
	v_fmac_f32_e32 v18, 0xb102e308, v2
	v_sub_f32_e32 v2, v14, v13
	v_fmamk_f32 v16, v15, 0x3e9b6dac, v231
	v_sub_f32_e32 v2, v3, v2
	v_add_f32_e32 v3, v17, v18
	v_fmaak_f32 v16, v15, v16, 0x3f2aaada
	v_sub_f32_e32 v13, v3, v17
	v_ldexp_f32 v17, v14, 1
	v_mul_f32_e32 v14, v14, v15
	v_mul_f32_e32 v14, v14, v16
	v_add_f32_e32 v15, v17, v14
	v_sub_f32_e32 v16, v15, v17
	v_ldexp_f32 v2, v2, 1
	v_sub_f32_e32 v14, v14, v16
	v_add_f32_e32 v2, v2, v14
	v_add_f32_e32 v14, v15, v2
	v_sub_f32_e32 v15, v14, v15
	v_sub_f32_e32 v2, v2, v15
	v_add_f32_e32 v15, v3, v14
	v_sub_f32_e32 v16, v15, v3
	v_sub_f32_e32 v17, v15, v16
	v_sub_f32_e32 v13, v18, v13
	v_sub_f32_e32 v3, v3, v17
	v_sub_f32_e32 v14, v14, v16
	v_add_f32_e32 v3, v14, v3
	v_add_f32_e32 v14, v13, v2
	v_sub_f32_e32 v16, v14, v13
	v_sub_f32_e32 v17, v14, v16
	v_sub_f32_e32 v13, v13, v17
	v_sub_f32_e32 v2, v2, v16
	v_add_f32_e32 v3, v14, v3
	v_add_f32_e32 v2, v2, v13
	v_add_f32_e32 v13, v15, v3
	v_sub_f32_e32 v14, v13, v15
	v_sub_f32_e32 v3, v3, v14
	v_add_f32_e32 v2, v2, v3
	v_add_f32_e32 v2, v13, v2
	v_cmp_neq_f32_e32 vcc, s6, v6
	v_mul_f32_e64 v3, |v7|, s7
	v_max_f32_e64 v7, -v7, 0
	v_cndmask_b32_e32 v2, v238, v2, vcc
	v_cmp_ngt_f32_e32 vcc, -1.0, v6
	s_nop 1
	v_cndmask_b32_e32 v2, v239, v2, vcc
	v_cmp_neq_f32_e32 vcc, -1.0, v6
	s_nop 1
	v_cndmask_b32_e32 v2, v240, v2, vcc
	v_cmp_lt_f32_e64 vcc, |v6|, s10
	s_nop 1
	v_cndmask_b32_e32 v2, v2, v6, vcc
	v_add_f32_e32 v2, v8, v2
	v_sub_f32_e32 v2, -0.5, v2
	v_mul_f32_e32 v2, 0x3fb8aa3b, v2
	v_exp_f32_e32 v6, v3
	v_exp_f32_e32 v2, v2
	v_add_f32_e32 v8, v9, v5
	v_add_f32_e32 v9, 1.0, v6
	v_mul_f32_e32 v5, 0xbfb8aa3b, v2
	v_add_f32_e32 v2, -1.0, v9
	v_sub_f32_e32 v3, v2, v9
	v_add_f32_e32 v3, 1.0, v3
	v_sub_f32_e32 v2, v6, v2
	v_add_f32_e32 v13, v2, v3
	v_frexp_mant_f32_e32 v2, v9
	v_cmp_gt_f32_e32 vcc, s8, v2
	v_cvt_f64_f32_e32 v[2:3], v9
	v_frexp_exp_i32_f64_e32 v2, v[2:3]
	v_subbrev_co_u32_e32 v2, vcc, 0, v2, vcc
	v_sub_u32_e32 v3, 0, v2
	v_ldexp_f32 v9, v9, v3
	v_ldexp_f32 v3, v13, v3
	v_add_f32_e32 v13, -1.0, v9
	v_add_f32_e32 v16, 1.0, v9
	v_add_f32_e32 v14, 1.0, v13
	v_add_f32_e32 v17, -1.0, v16
	v_sub_f32_e32 v14, v9, v14
	v_sub_f32_e32 v9, v9, v17
	v_add_f32_e32 v14, v3, v14
	v_add_f32_e32 v3, v3, v9
	v_add_f32_e32 v9, v16, v3
	v_rcp_f32_e32 v17, v9
	v_add_f32_e32 v15, v13, v14
	v_sub_f32_e32 v13, v15, v13
	v_sub_f32_e32 v13, v14, v13
	v_sub_f32_e32 v14, v9, v16
	v_sub_f32_e32 v3, v3, v14
	v_mul_f32_e32 v14, v15, v17
	v_mul_f32_e32 v16, v9, v14
	v_fma_f32 v18, v14, v9, -v16
	v_fmac_f32_e32 v18, v14, v3
	v_add_f32_e32 v19, v16, v18
	v_sub_f32_e32 v20, v15, v19
	v_sub_f32_e32 v15, v15, v20
	v_sub_f32_e32 v16, v19, v16
	v_sub_f32_e32 v15, v15, v19
	v_add_f32_e32 v13, v13, v15
	v_sub_f32_e32 v15, v16, v18
	v_add_f32_e32 v13, v15, v13
	v_add_f32_e32 v15, v20, v13
	v_mul_f32_e32 v16, v17, v15
	v_mul_f32_e32 v18, v9, v16
	v_fma_f32 v9, v16, v9, -v18
	v_fmac_f32_e32 v9, v16, v3
	v_sub_f32_e32 v3, v20, v15
	v_add_f32_e32 v3, v13, v3
	v_add_f32_e32 v13, v18, v9
	v_sub_f32_e32 v19, v15, v13
	v_sub_f32_e32 v15, v15, v19
	v_sub_f32_e32 v18, v13, v18
	v_sub_f32_e32 v13, v15, v13
	v_add_f32_e32 v3, v3, v13
	v_sub_f32_e32 v9, v18, v9
	v_cvt_f32_i32_e32 v2, v2
	v_add_f32_e32 v3, v9, v3
	v_add_f32_e32 v9, v14, v16
	v_add_f32_e32 v3, v19, v3
	v_sub_f32_e32 v13, v9, v14
	v_mul_f32_e32 v3, v17, v3
	v_sub_f32_e32 v13, v16, v13
	v_add_f32_e32 v3, v13, v3
	v_mul_f32_e32 v16, 0x3f317218, v2
	v_add_f32_e32 v13, v9, v3
	v_fma_f32 v17, v2, s9, -v16
	v_mul_f32_e32 v14, v13, v13
	v_fmac_f32_e32 v17, 0xb102e308, v2
; template <int MODE, bool BIG = false> DI void gemm_tile(const Params& p, int tm, int tn, int kv, char* smem) {
;     ...
;     for (int c4 = 0; c4 < 16; ++c4) {
;       float4 v = crow4[c4], ww = w04[c4];
;       float u[4] = {v.x + ww.x, v.y + ww.y, v.z + ww.z, v.w + ww.w};
; #pragma unroll
;       for (int e = 0; e < 4; ++e) {
;         const float z = -u[e];
;         const float sp = fmaxf(z, 0.f) + log1pf(__expf(-fabsf(z)));
;         u[e] = __expf(-__expf(-sp - 0.5f));
;       }
;       W4[c4] = make_float4(u[0], u[1], u[2], u[3]);
	v_sub_f32_e32 v2, v13, v9
	v_fmamk_f32 v15, v14, 0x3e9b6dac, v231
	v_sub_f32_e32 v2, v3, v2
	v_add_f32_e32 v3, v16, v17
	v_fmaak_f32 v15, v14, v15, 0x3f2aaada
	v_sub_f32_e32 v9, v3, v16
	v_ldexp_f32 v16, v13, 1
	v_mul_f32_e32 v13, v13, v14
	v_mul_f32_e32 v13, v13, v15
	v_add_f32_e32 v14, v16, v13
	v_sub_f32_e32 v15, v14, v16
	v_ldexp_f32 v2, v2, 1
	v_sub_f32_e32 v13, v13, v15
	v_add_f32_e32 v2, v2, v13
	v_add_f32_e32 v13, v14, v2
	v_sub_f32_e32 v14, v13, v14
	v_sub_f32_e32 v2, v2, v14
	v_add_f32_e32 v14, v3, v13
	v_sub_f32_e32 v15, v14, v3
	v_sub_f32_e32 v16, v14, v15
	v_sub_f32_e32 v9, v17, v9
	v_sub_f32_e32 v3, v3, v16
	v_sub_f32_e32 v13, v13, v15
	v_add_f32_e32 v3, v13, v3
	v_add_f32_e32 v13, v9, v2
	v_sub_f32_e32 v15, v13, v9
	v_sub_f32_e32 v16, v13, v15
	v_sub_f32_e32 v9, v9, v16
	v_sub_f32_e32 v2, v2, v15
	v_add_f32_e32 v3, v13, v3
	v_add_f32_e32 v2, v2, v9
	v_add_f32_e32 v9, v14, v3
	v_sub_f32_e32 v13, v9, v14
	v_sub_f32_e32 v3, v3, v13
	v_add_f32_e32 v2, v2, v3
	v_add_f32_e32 v2, v9, v2
	v_cmp_neq_f32_e32 vcc, s6, v6
	s_nop 1
	v_cndmask_b32_e32 v2, v238, v2, vcc
	v_cmp_ngt_f32_e32 vcc, -1.0, v6
	s_nop 1
	v_cndmask_b32_e32 v2, v239, v2, vcc
	v_cmp_neq_f32_e32 vcc, -1.0, v6
	s_nop 1
	v_cndmask_b32_e32 v2, v240, v2, vcc
	v_cmp_lt_f32_e64 vcc, |v6|, s10
	s_nop 1
	v_cndmask_b32_e32 v2, v2, v6, vcc
	v_add_f32_e32 v2, v7, v2
	v_sub_f32_e32 v2, -0.5, v2
	v_mul_f32_e32 v2, 0x3fb8aa3b, v2
	v_exp_f32_e32 v3, v2
	v_mul_f32_e64 v2, |v4|, s7
	v_exp_f32_e32 v6, v2
	v_max_f32_e64 v7, -v4, 0
	v_exp_f32_e32 v2, v5
	v_mul_f32_e32 v3, 0xbfb8aa3b, v3
	v_add_f32_e32 v9, 1.0, v6
	v_add_f32_e32 v4, -1.0, v9
	v_sub_f32_e32 v5, v4, v9
	v_add_f32_e32 v5, 1.0, v5
	v_sub_f32_e32 v4, v6, v4
	v_add_f32_e32 v13, v4, v5
	v_frexp_mant_f32_e32 v4, v9
	v_cmp_gt_f32_e32 vcc, s8, v4
	v_cvt_f64_f32_e32 v[4:5], v9
	v_frexp_exp_i32_f64_e32 v4, v[4:5]
	v_subbrev_co_u32_e32 v4, vcc, 0, v4, vcc
	v_sub_u32_e32 v5, 0, v4
	v_ldexp_f32 v9, v9, v5
	v_ldexp_f32 v5, v13, v5
	v_add_f32_e32 v13, -1.0, v9
	v_add_f32_e32 v16, 1.0, v9
	v_add_f32_e32 v14, 1.0, v13
	v_add_f32_e32 v17, -1.0, v16
	v_sub_f32_e32 v14, v9, v14
	v_sub_f32_e32 v9, v9, v17
	v_add_f32_e32 v14, v5, v14
	v_add_f32_e32 v5, v5, v9
	v_add_f32_e32 v9, v16, v5
	v_rcp_f32_e32 v17, v9
	v_add_f32_e32 v15, v13, v14
	v_sub_f32_e32 v13, v15, v13
	v_sub_f32_e32 v13, v14, v13
	v_sub_f32_e32 v14, v9, v16
	v_sub_f32_e32 v5, v5, v14
	v_mul_f32_e32 v14, v15, v17
	v_mul_f32_e32 v16, v9, v14
	v_fma_f32 v18, v14, v9, -v16
	v_fmac_f32_e32 v18, v14, v5
	v_add_f32_e32 v19, v16, v18
	v_sub_f32_e32 v20, v15, v19
	v_sub_f32_e32 v15, v15, v20
	v_sub_f32_e32 v16, v19, v16
	v_sub_f32_e32 v15, v15, v19
	v_add_f32_e32 v13, v13, v15
	v_sub_f32_e32 v15, v16, v18
	v_add_f32_e32 v13, v15, v13
	v_add_f32_e32 v15, v20, v13
	v_mul_f32_e32 v16, v17, v15
	v_mul_f32_e32 v18, v9, v16
	v_fma_f32 v9, v16, v9, -v18
	v_fmac_f32_e32 v9, v16, v5
	v_sub_f32_e32 v5, v20, v15
	v_add_f32_e32 v5, v13, v5
	v_add_f32_e32 v13, v18, v9
	v_sub_f32_e32 v19, v15, v13
	v_sub_f32_e32 v15, v15, v19
	v_sub_f32_e32 v18, v13, v18
	v_sub_f32_e32 v13, v15, v13
	v_add_f32_e32 v5, v5, v13
	v_sub_f32_e32 v9, v18, v9
	v_cvt_f32_i32_e32 v4, v4
	v_add_f32_e32 v5, v9, v5
	v_add_f32_e32 v9, v14, v16
	v_add_f32_e32 v5, v19, v5
	v_sub_f32_e32 v13, v9, v14
	v_mul_f32_e32 v5, v17, v5
	v_sub_f32_e32 v13, v16, v13
	v_add_f32_e32 v5, v13, v5
	v_mul_f32_e32 v16, 0x3f317218, v4
	v_add_f32_e32 v13, v9, v5
	v_fma_f32 v17, v4, s9, -v16
	v_mul_f32_e32 v14, v13, v13
	v_fmac_f32_e32 v17, 0xb102e308, v4
	v_sub_f32_e32 v4, v13, v9
	v_fmamk_f32 v15, v14, 0x3e9b6dac, v231
	v_sub_f32_e32 v4, v5, v4
	v_add_f32_e32 v5, v16, v17
	v_fmaak_f32 v15, v14, v15, 0x3f2aaada
	v_sub_f32_e32 v9, v5, v16
	v_ldexp_f32 v16, v13, 1
	v_mul_f32_e32 v13, v13, v14
	v_mul_f32_e32 v13, v13, v15
	v_add_f32_e32 v14, v16, v13
	v_sub_f32_e32 v15, v14, v16
	v_ldexp_f32 v4, v4, 1
	v_sub_f32_e32 v13, v13, v15
	v_add_f32_e32 v4, v4, v13
	v_add_f32_e32 v13, v14, v4
	v_sub_f32_e32 v14, v13, v14
	v_sub_f32_e32 v4, v4, v14
	v_add_f32_e32 v14, v5, v13
	v_sub_f32_e32 v15, v14, v5
	v_sub_f32_e32 v16, v14, v15
	v_sub_f32_e32 v9, v17, v9
	v_sub_f32_e32 v5, v5, v16
	v_sub_f32_e32 v13, v13, v15
	v_add_f32_e32 v5, v13, v5
	v_add_f32_e32 v13, v9, v4
	v_sub_f32_e32 v15, v13, v9
	v_sub_f32_e32 v16, v13, v15
	v_sub_f32_e32 v9, v9, v16
	v_sub_f32_e32 v4, v4, v15
	v_add_f32_e32 v5, v13, v5
	v_add_f32_e32 v4, v4, v9
	v_add_f32_e32 v9, v14, v5
	v_sub_f32_e32 v13, v9, v14
	v_sub_f32_e32 v5, v5, v13
	v_add_f32_e32 v4, v4, v5
	v_add_f32_e32 v4, v9, v4
	v_cmp_neq_f32_e32 vcc, s6, v6
	v_mul_f32_e64 v5, |v8|, s7
	v_max_f32_e64 v8, -v8, 0
	v_cndmask_b32_e32 v4, v238, v4, vcc
	v_cmp_ngt_f32_e32 vcc, -1.0, v6
	v_exp_f32_e32 v3, v3
	s_nop 0
	v_cndmask_b32_e32 v4, v239, v4, vcc
	v_cmp_neq_f32_e32 vcc, -1.0, v6
	s_nop 1
	v_cndmask_b32_e32 v4, v240, v4, vcc
	v_cmp_lt_f32_e64 vcc, |v6|, s10
	s_nop 1
	v_cndmask_b32_e32 v4, v4, v6, vcc
	v_exp_f32_e32 v6, v5
	v_add_f32_e32 v4, v7, v4
	v_sub_f32_e32 v4, -0.5, v4
	v_mul_f32_e32 v4, 0x3fb8aa3b, v4
	v_add_f32_e32 v9, 1.0, v6
	v_exp_f32_e32 v7, v4
	v_add_f32_e32 v4, -1.0, v9
	v_sub_f32_e32 v5, v4, v9
	v_add_f32_e32 v5, 1.0, v5
	v_sub_f32_e32 v4, v6, v4
	v_add_f32_e32 v13, v4, v5
	v_frexp_mant_f32_e32 v4, v9
	v_cmp_gt_f32_e32 vcc, s8, v4
	v_cvt_f64_f32_e32 v[4:5], v9
	v_frexp_exp_i32_f64_e32 v4, v[4:5]
	v_subbrev_co_u32_e32 v4, vcc, 0, v4, vcc
	v_sub_u32_e32 v5, 0, v4
	v_ldexp_f32 v9, v9, v5
	v_ldexp_f32 v5, v13, v5
	v_add_f32_e32 v13, -1.0, v9
	v_add_f32_e32 v16, 1.0, v9
	v_add_f32_e32 v14, 1.0, v13
	v_add_f32_e32 v17, -1.0, v16
	v_sub_f32_e32 v14, v9, v14
	v_sub_f32_e32 v9, v9, v17
	v_add_f32_e32 v14, v5, v14
	v_add_f32_e32 v5, v5, v9
; template <int MODE, bool BIG = false> DI void gemm_tile(const Params& p, int tm, int tn, int kv, char* smem) {
;     ...
;     for (int c4 = 0; c4 < 16; ++c4) {
;       float4 v = crow4[c4], ww = w04[c4];
;       float u[4] = {v.x + ww.x, v.y + ww.y, v.z + ww.z, v.w + ww.w};
; #pragma unroll
;       for (int e = 0; e < 4; ++e) {
;         const float z = -u[e];
;         const float sp = fmaxf(z, 0.f) + log1pf(__expf(-fabsf(z)));
;         u[e] = __expf(-__expf(-sp - 0.5f));
;       }
;       W4[c4] = make_float4(u[0], u[1], u[2], u[3]);
	v_add_f32_e32 v9, v16, v5
	v_rcp_f32_e32 v17, v9
	v_add_f32_e32 v15, v13, v14
	v_sub_f32_e32 v13, v15, v13
	v_sub_f32_e32 v13, v14, v13
	v_sub_f32_e32 v14, v9, v16
	v_sub_f32_e32 v5, v5, v14
	v_mul_f32_e32 v14, v15, v17
	v_mul_f32_e32 v16, v9, v14
	v_fma_f32 v18, v14, v9, -v16
	v_fmac_f32_e32 v18, v14, v5
	v_add_f32_e32 v19, v16, v18
	v_sub_f32_e32 v20, v15, v19
	v_sub_f32_e32 v15, v15, v20
	v_sub_f32_e32 v16, v19, v16
	v_sub_f32_e32 v15, v15, v19
	v_add_f32_e32 v13, v13, v15
	v_sub_f32_e32 v15, v16, v18
	v_add_f32_e32 v13, v15, v13
	v_add_f32_e32 v15, v20, v13
	v_mul_f32_e32 v16, v17, v15
	v_mul_f32_e32 v18, v9, v16
	v_fma_f32 v9, v16, v9, -v18
	v_fmac_f32_e32 v9, v16, v5
	v_sub_f32_e32 v5, v20, v15
	v_add_f32_e32 v5, v13, v5
	v_add_f32_e32 v13, v18, v9
	v_sub_f32_e32 v19, v15, v13
	v_sub_f32_e32 v15, v15, v19
	v_sub_f32_e32 v18, v13, v18
	v_sub_f32_e32 v13, v15, v13
	v_add_f32_e32 v5, v5, v13
	v_sub_f32_e32 v9, v18, v9
	v_cvt_f32_i32_e32 v4, v4
	v_add_f32_e32 v5, v9, v5
	v_add_f32_e32 v9, v14, v16
	v_add_f32_e32 v5, v19, v5
	v_sub_f32_e32 v13, v9, v14
	v_mul_f32_e32 v5, v17, v5
	v_sub_f32_e32 v13, v16, v13
	v_add_f32_e32 v5, v13, v5
	v_mul_f32_e32 v16, 0x3f317218, v4
	v_add_f32_e32 v13, v9, v5
	v_fma_f32 v17, v4, s9, -v16
	v_mul_f32_e32 v14, v13, v13
	v_fmac_f32_e32 v17, 0xb102e308, v4
	v_sub_f32_e32 v4, v13, v9
	v_fmamk_f32 v15, v14, 0x3e9b6dac, v231
	v_sub_f32_e32 v4, v5, v4
	v_add_f32_e32 v5, v16, v17
	v_fmaak_f32 v15, v14, v15, 0x3f2aaada
	v_sub_f32_e32 v9, v5, v16
	v_ldexp_f32 v16, v13, 1
	v_mul_f32_e32 v13, v13, v14
	v_mul_f32_e32 v13, v13, v15
	v_add_f32_e32 v14, v16, v13
	v_sub_f32_e32 v15, v14, v16
	v_ldexp_f32 v4, v4, 1
	v_sub_f32_e32 v13, v13, v15
	v_add_f32_e32 v4, v4, v13
	v_add_f32_e32 v13, v14, v4
	v_sub_f32_e32 v14, v13, v14
	v_sub_f32_e32 v4, v4, v14
	v_add_f32_e32 v14, v5, v13
	v_sub_f32_e32 v15, v14, v5
	v_sub_f32_e32 v16, v14, v15
	v_sub_f32_e32 v9, v17, v9
	v_sub_f32_e32 v5, v5, v16
	v_sub_f32_e32 v13, v13, v15
	v_add_f32_e32 v5, v13, v5
	v_add_f32_e32 v13, v9, v4
	v_sub_f32_e32 v15, v13, v9
	v_sub_f32_e32 v16, v13, v15
	v_sub_f32_e32 v9, v9, v16
	v_sub_f32_e32 v4, v4, v15
	v_add_f32_e32 v5, v13, v5
	v_add_f32_e32 v4, v4, v9
	v_add_f32_e32 v9, v14, v5
	v_sub_f32_e32 v13, v9, v14
	v_sub_f32_e32 v5, v5, v13
	v_add_f32_e32 v4, v4, v5
	v_add_f32_e32 v4, v9, v4
	v_cmp_neq_f32_e32 vcc, s6, v6
	s_nop 1
	v_cndmask_b32_e32 v4, v238, v4, vcc
	v_cmp_ngt_f32_e32 vcc, -1.0, v6
	s_nop 1
	v_cndmask_b32_e32 v4, v239, v4, vcc
	v_cmp_neq_f32_e32 vcc, -1.0, v6
	s_nop 1
	v_cndmask_b32_e32 v4, v240, v4, vcc
	v_cmp_lt_f32_e64 vcc, |v6|, s10
	s_nop 1
	v_cndmask_b32_e32 v4, v4, v6, vcc
	v_add_f32_e32 v4, v8, v4
	v_sub_f32_e32 v4, -0.5, v4
	v_mul_f32_e32 v4, 0x3fb8aa3b, v4
	v_exp_f32_e32 v5, v4
	v_mul_f32_e32 v4, 0xbfb8aa3b, v7
	v_exp_f32_e32 v4, v4
	ds_read_b128 v[6:9], v12 offset:96
	v_mul_f32_e32 v5, 0xbfb8aa3b, v5
	v_exp_f32_e32 v5, v5
	ds_write_b128 v75, v[2:5] offset:80
	ds_read_b128 v[2:5], v74 offset:96
	s_waitcnt lgkmcnt(0)
	v_add_f32_e32 v2, v6, v2
	v_mul_f32_e64 v6, |v2|, s7
	v_exp_f32_e32 v6, v6
	v_add_f32_e32 v4, v8, v4
	v_max_f32_e64 v8, -v2, 0
	v_add_f32_e32 v7, v7, v3
	v_add_f32_e32 v13, 1.0, v6
	v_add_f32_e32 v2, -1.0, v13
	v_sub_f32_e32 v3, v2, v13
	v_add_f32_e32 v3, 1.0, v3
	v_sub_f32_e32 v2, v6, v2
	v_add_f32_e32 v14, v2, v3
	v_frexp_mant_f32_e32 v2, v13
	v_cmp_gt_f32_e32 vcc, s8, v2
	v_cvt_f64_f32_e32 v[2:3], v13
	v_frexp_exp_i32_f64_e32 v2, v[2:3]
	v_subbrev_co_u32_e32 v2, vcc, 0, v2, vcc
	v_sub_u32_e32 v3, 0, v2
	v_ldexp_f32 v13, v13, v3
	v_ldexp_f32 v3, v14, v3
	v_add_f32_e32 v14, -1.0, v13
	v_add_f32_e32 v17, 1.0, v13
	v_add_f32_e32 v15, 1.0, v14
	v_add_f32_e32 v18, -1.0, v17
	v_sub_f32_e32 v15, v13, v15
	v_sub_f32_e32 v13, v13, v18
	v_add_f32_e32 v15, v3, v15
	v_add_f32_e32 v3, v3, v13
	v_add_f32_e32 v13, v17, v3
	v_rcp_f32_e32 v18, v13
	v_add_f32_e32 v16, v14, v15
	v_sub_f32_e32 v14, v16, v14
	v_sub_f32_e32 v14, v15, v14
	v_sub_f32_e32 v15, v13, v17
	v_sub_f32_e32 v3, v3, v15
	v_mul_f32_e32 v15, v16, v18
	v_mul_f32_e32 v17, v13, v15
	v_fma_f32 v19, v15, v13, -v17
	v_fmac_f32_e32 v19, v15, v3
	v_add_f32_e32 v20, v17, v19
	v_sub_f32_e32 v21, v16, v20
	v_sub_f32_e32 v16, v16, v21
	v_sub_f32_e32 v17, v20, v17
	v_sub_f32_e32 v16, v16, v20
	v_add_f32_e32 v14, v14, v16
	v_sub_f32_e32 v16, v17, v19
	v_add_f32_e32 v14, v16, v14
	v_add_f32_e32 v16, v21, v14
	v_mul_f32_e32 v17, v18, v16
	v_mul_f32_e32 v19, v13, v17
	v_fma_f32 v13, v17, v13, -v19
	v_fmac_f32_e32 v13, v17, v3
	v_sub_f32_e32 v3, v21, v16
	v_add_f32_e32 v3, v14, v3
	v_add_f32_e32 v14, v19, v13
	v_sub_f32_e32 v20, v16, v14
	v_sub_f32_e32 v16, v16, v20
	v_sub_f32_e32 v19, v14, v19
	v_sub_f32_e32 v14, v16, v14
	v_add_f32_e32 v3, v3, v14
	v_sub_f32_e32 v13, v19, v13
	v_cvt_f32_i32_e32 v2, v2
	v_add_f32_e32 v3, v13, v3
	v_add_f32_e32 v13, v15, v17
	v_add_f32_e32 v3, v20, v3
	v_sub_f32_e32 v14, v13, v15
	v_mul_f32_e32 v3, v18, v3
	v_sub_f32_e32 v14, v17, v14
	v_add_f32_e32 v3, v14, v3
	v_mul_f32_e32 v17, 0x3f317218, v2
	v_add_f32_e32 v14, v13, v3
	v_fma_f32 v18, v2, s9, -v17
	v_mul_f32_e32 v15, v14, v14
	v_fmac_f32_e32 v18, 0xb102e308, v2
	v_sub_f32_e32 v2, v14, v13
	v_fmamk_f32 v16, v15, 0x3e9b6dac, v231
	v_sub_f32_e32 v2, v3, v2
	v_add_f32_e32 v3, v17, v18
	v_fmaak_f32 v16, v15, v16, 0x3f2aaada
	v_sub_f32_e32 v13, v3, v17
	v_ldexp_f32 v17, v14, 1
	v_mul_f32_e32 v14, v14, v15
	v_mul_f32_e32 v14, v14, v16
	v_add_f32_e32 v15, v17, v14
	v_sub_f32_e32 v16, v15, v17
	v_ldexp_f32 v2, v2, 1
	v_sub_f32_e32 v14, v14, v16
	v_add_f32_e32 v2, v2, v14
	v_add_f32_e32 v14, v15, v2
	v_sub_f32_e32 v15, v14, v15
	v_sub_f32_e32 v2, v2, v15
	v_add_f32_e32 v15, v3, v14
; template <int MODE, bool BIG = false> DI void gemm_tile(const Params& p, int tm, int tn, int kv, char* smem) {
;     ...
;     for (int c4 = 0; c4 < 16; ++c4) {
;       float4 v = crow4[c4], ww = w04[c4];
;       float u[4] = {v.x + ww.x, v.y + ww.y, v.z + ww.z, v.w + ww.w};
; #pragma unroll
;       for (int e = 0; e < 4; ++e) {
;         const float z = -u[e];
;         const float sp = fmaxf(z, 0.f) + log1pf(__expf(-fabsf(z)));
;         u[e] = __expf(-__expf(-sp - 0.5f));
;       }
;       W4[c4] = make_float4(u[0], u[1], u[2], u[3]);
	v_sub_f32_e32 v16, v15, v3
	v_sub_f32_e32 v17, v15, v16
	v_sub_f32_e32 v13, v18, v13
	v_sub_f32_e32 v3, v3, v17
	v_sub_f32_e32 v14, v14, v16
	v_add_f32_e32 v3, v14, v3
	v_add_f32_e32 v14, v13, v2
	v_sub_f32_e32 v16, v14, v13
	v_sub_f32_e32 v17, v14, v16
	v_sub_f32_e32 v13, v13, v17
	v_sub_f32_e32 v2, v2, v16
	v_add_f32_e32 v3, v14, v3
	v_add_f32_e32 v2, v2, v13
	v_add_f32_e32 v13, v15, v3
	v_sub_f32_e32 v14, v13, v15
	v_sub_f32_e32 v3, v3, v14
	v_add_f32_e32 v2, v2, v3
	v_add_f32_e32 v2, v13, v2
	v_cmp_neq_f32_e32 vcc, s6, v6
	v_mul_f32_e64 v3, |v7|, s7
	v_max_f32_e64 v7, -v7, 0
	v_cndmask_b32_e32 v2, v238, v2, vcc
	v_cmp_ngt_f32_e32 vcc, -1.0, v6
	s_nop 1
	v_cndmask_b32_e32 v2, v239, v2, vcc
	v_cmp_neq_f32_e32 vcc, -1.0, v6
	s_nop 1
	v_cndmask_b32_e32 v2, v240, v2, vcc
	v_cmp_lt_f32_e64 vcc, |v6|, s10
	s_nop 1
	v_cndmask_b32_e32 v2, v2, v6, vcc
	v_add_f32_e32 v2, v8, v2
	v_sub_f32_e32 v2, -0.5, v2
	v_mul_f32_e32 v2, 0x3fb8aa3b, v2
	v_exp_f32_e32 v6, v3
	v_exp_f32_e32 v2, v2
	v_add_f32_e32 v8, v9, v5
	v_add_f32_e32 v9, 1.0, v6
	v_mul_f32_e32 v5, 0xbfb8aa3b, v2
	v_add_f32_e32 v2, -1.0, v9
	v_sub_f32_e32 v3, v2, v9
	v_add_f32_e32 v3, 1.0, v3
	v_sub_f32_e32 v2, v6, v2
	v_add_f32_e32 v13, v2, v3
	v_frexp_mant_f32_e32 v2, v9
	v_cmp_gt_f32_e32 vcc, s8, v2
	v_cvt_f64_f32_e32 v[2:3], v9
	v_frexp_exp_i32_f64_e32 v2, v[2:3]
	v_subbrev_co_u32_e32 v2, vcc, 0, v2, vcc
	v_sub_u32_e32 v3, 0, v2
	v_ldexp_f32 v9, v9, v3
	v_ldexp_f32 v3, v13, v3
	v_add_f32_e32 v13, -1.0, v9
	v_add_f32_e32 v16, 1.0, v9
	v_add_f32_e32 v14, 1.0, v13
	v_add_f32_e32 v17, -1.0, v16
	v_sub_f32_e32 v14, v9, v14
	v_sub_f32_e32 v9, v9, v17
	v_add_f32_e32 v14, v3, v14
	v_add_f32_e32 v3, v3, v9
	v_add_f32_e32 v9, v16, v3
	v_rcp_f32_e32 v17, v9
	v_add_f32_e32 v15, v13, v14
	v_sub_f32_e32 v13, v15, v13
	v_sub_f32_e32 v13, v14, v13
	v_sub_f32_e32 v14, v9, v16
	v_sub_f32_e32 v3, v3, v14
	v_mul_f32_e32 v14, v15, v17
	v_mul_f32_e32 v16, v9, v14
	v_fma_f32 v18, v14, v9, -v16
	v_fmac_f32_e32 v18, v14, v3
	v_add_f32_e32 v19, v16, v18
	v_sub_f32_e32 v20, v15, v19
	v_sub_f32_e32 v15, v15, v20
	v_sub_f32_e32 v16, v19, v16
	v_sub_f32_e32 v15, v15, v19
	v_add_f32_e32 v13, v13, v15
	v_sub_f32_e32 v15, v16, v18
	v_add_f32_e32 v13, v15, v13
	v_add_f32_e32 v15, v20, v13
	v_mul_f32_e32 v16, v17, v15
	v_mul_f32_e32 v18, v9, v16
	v_fma_f32 v9, v16, v9, -v18
	v_fmac_f32_e32 v9, v16, v3
	v_sub_f32_e32 v3, v20, v15
	v_add_f32_e32 v3, v13, v3
	v_add_f32_e32 v13, v18, v9
	v_sub_f32_e32 v19, v15, v13
	v_sub_f32_e32 v15, v15, v19
	v_sub_f32_e32 v18, v13, v18
	v_sub_f32_e32 v13, v15, v13
	v_add_f32_e32 v3, v3, v13
	v_sub_f32_e32 v9, v18, v9
	v_cvt_f32_i32_e32 v2, v2
	v_add_f32_e32 v3, v9, v3
	v_add_f32_e32 v9, v14, v16
	v_add_f32_e32 v3, v19, v3
	v_sub_f32_e32 v13, v9, v14
	v_mul_f32_e32 v3, v17, v3
	v_sub_f32_e32 v13, v16, v13
	v_add_f32_e32 v3, v13, v3
	v_mul_f32_e32 v16, 0x3f317218, v2
	v_add_f32_e32 v13, v9, v3
	v_fma_f32 v17, v2, s9, -v16
	v_mul_f32_e32 v14, v13, v13
	v_fmac_f32_e32 v17, 0xb102e308, v2
	v_sub_f32_e32 v2, v13, v9
	v_fmamk_f32 v15, v14, 0x3e9b6dac, v231
	v_sub_f32_e32 v2, v3, v2
	v_add_f32_e32 v3, v16, v17
	v_fmaak_f32 v15, v14, v15, 0x3f2aaada
	v_sub_f32_e32 v9, v3, v16
	v_ldexp_f32 v16, v13, 1
	v_mul_f32_e32 v13, v13, v14
	v_mul_f32_e32 v13, v13, v15
	v_add_f32_e32 v14, v16, v13
	v_sub_f32_e32 v15, v14, v16
	v_ldexp_f32 v2, v2, 1
	v_sub_f32_e32 v13, v13, v15
	v_add_f32_e32 v2, v2, v13
	v_add_f32_e32 v13, v14, v2
	v_sub_f32_e32 v14, v13, v14
	v_sub_f32_e32 v2, v2, v14
	v_add_f32_e32 v14, v3, v13
	v_sub_f32_e32 v15, v14, v3
	v_sub_f32_e32 v16, v14, v15
	v_sub_f32_e32 v9, v17, v9
	v_sub_f32_e32 v3, v3, v16
	v_sub_f32_e32 v13, v13, v15
	v_add_f32_e32 v3, v13, v3
	v_add_f32_e32 v13, v9, v2
	v_sub_f32_e32 v15, v13, v9
	v_sub_f32_e32 v16, v13, v15
	v_sub_f32_e32 v9, v9, v16
	v_sub_f32_e32 v2, v2, v15
	v_add_f32_e32 v3, v13, v3
	v_add_f32_e32 v2, v2, v9
	v_add_f32_e32 v9, v14, v3
	v_sub_f32_e32 v13, v9, v14
	v_sub_f32_e32 v3, v3, v13
	v_add_f32_e32 v2, v2, v3
	v_add_f32_e32 v2, v9, v2
	v_cmp_neq_f32_e32 vcc, s6, v6
	s_nop 1
	v_cndmask_b32_e32 v2, v238, v2, vcc
	v_cmp_ngt_f32_e32 vcc, -1.0, v6
	s_nop 1
	v_cndmask_b32_e32 v2, v239, v2, vcc
	v_cmp_neq_f32_e32 vcc, -1.0, v6
	s_nop 1
	v_cndmask_b32_e32 v2, v240, v2, vcc
	v_cmp_lt_f32_e64 vcc, |v6|, s10
	s_nop 1
	v_cndmask_b32_e32 v2, v2, v6, vcc
	v_add_f32_e32 v2, v7, v2
	v_sub_f32_e32 v2, -0.5, v2
	v_mul_f32_e32 v2, 0x3fb8aa3b, v2
	v_exp_f32_e32 v3, v2
	v_mul_f32_e64 v2, |v4|, s7
	v_exp_f32_e32 v6, v2
	v_max_f32_e64 v7, -v4, 0
	v_exp_f32_e32 v2, v5
	v_mul_f32_e32 v3, 0xbfb8aa3b, v3
	v_add_f32_e32 v9, 1.0, v6
	v_add_f32_e32 v4, -1.0, v9
	v_sub_f32_e32 v5, v4, v9
	v_add_f32_e32 v5, 1.0, v5
	v_sub_f32_e32 v4, v6, v4
	v_add_f32_e32 v13, v4, v5
	v_frexp_mant_f32_e32 v4, v9
	v_cmp_gt_f32_e32 vcc, s8, v4
	v_cvt_f64_f32_e32 v[4:5], v9
	v_frexp_exp_i32_f64_e32 v4, v[4:5]
	v_subbrev_co_u32_e32 v4, vcc, 0, v4, vcc
	v_sub_u32_e32 v5, 0, v4
	v_ldexp_f32 v9, v9, v5
	v_ldexp_f32 v5, v13, v5
	v_add_f32_e32 v13, -1.0, v9
	v_add_f32_e32 v16, 1.0, v9
	v_add_f32_e32 v14, 1.0, v13
	v_add_f32_e32 v17, -1.0, v16
	v_sub_f32_e32 v14, v9, v14
	v_sub_f32_e32 v9, v9, v17
	v_add_f32_e32 v14, v5, v14
	v_add_f32_e32 v5, v5, v9
	v_add_f32_e32 v9, v16, v5
	v_rcp_f32_e32 v17, v9
	v_add_f32_e32 v15, v13, v14
	v_sub_f32_e32 v13, v15, v13
	v_sub_f32_e32 v13, v14, v13
	v_sub_f32_e32 v14, v9, v16
	v_sub_f32_e32 v5, v5, v14
	v_mul_f32_e32 v14, v15, v17
	v_mul_f32_e32 v16, v9, v14
	v_fma_f32 v18, v14, v9, -v16
	v_fmac_f32_e32 v18, v14, v5
	v_add_f32_e32 v19, v16, v18
	v_sub_f32_e32 v20, v15, v19
	v_sub_f32_e32 v15, v15, v20
	v_sub_f32_e32 v16, v19, v16
	v_sub_f32_e32 v15, v15, v19
; template <int MODE, bool BIG = false> DI void gemm_tile(const Params& p, int tm, int tn, int kv, char* smem) {
;     ...
;     for (int c4 = 0; c4 < 16; ++c4) {
;       float4 v = crow4[c4], ww = w04[c4];
;       float u[4] = {v.x + ww.x, v.y + ww.y, v.z + ww.z, v.w + ww.w};
; #pragma unroll
;       for (int e = 0; e < 4; ++e) {
;         const float z = -u[e];
;         const float sp = fmaxf(z, 0.f) + log1pf(__expf(-fabsf(z)));
;         u[e] = __expf(-__expf(-sp - 0.5f));
;       }
;       W4[c4] = make_float4(u[0], u[1], u[2], u[3]);
	v_add_f32_e32 v13, v13, v15
	v_sub_f32_e32 v15, v16, v18
	v_add_f32_e32 v13, v15, v13
	v_add_f32_e32 v15, v20, v13
	v_mul_f32_e32 v16, v17, v15
	v_mul_f32_e32 v18, v9, v16
	v_fma_f32 v9, v16, v9, -v18
	v_fmac_f32_e32 v9, v16, v5
	v_sub_f32_e32 v5, v20, v15
	v_add_f32_e32 v5, v13, v5
	v_add_f32_e32 v13, v18, v9
	v_sub_f32_e32 v19, v15, v13
	v_sub_f32_e32 v15, v15, v19
	v_sub_f32_e32 v18, v13, v18
	v_sub_f32_e32 v13, v15, v13
	v_add_f32_e32 v5, v5, v13
	v_sub_f32_e32 v9, v18, v9
	v_cvt_f32_i32_e32 v4, v4
	v_add_f32_e32 v5, v9, v5
	v_add_f32_e32 v9, v14, v16
	v_add_f32_e32 v5, v19, v5
	v_sub_f32_e32 v13, v9, v14
	v_mul_f32_e32 v5, v17, v5
	v_sub_f32_e32 v13, v16, v13
	v_add_f32_e32 v5, v13, v5
	v_mul_f32_e32 v16, 0x3f317218, v4
	v_add_f32_e32 v13, v9, v5
	v_fma_f32 v17, v4, s9, -v16
	v_mul_f32_e32 v14, v13, v13
	v_fmac_f32_e32 v17, 0xb102e308, v4
	v_sub_f32_e32 v4, v13, v9
	v_fmamk_f32 v15, v14, 0x3e9b6dac, v231
	v_sub_f32_e32 v4, v5, v4
	v_add_f32_e32 v5, v16, v17
	v_fmaak_f32 v15, v14, v15, 0x3f2aaada
	v_sub_f32_e32 v9, v5, v16
	v_ldexp_f32 v16, v13, 1
	v_mul_f32_e32 v13, v13, v14
	v_mul_f32_e32 v13, v13, v15
	v_add_f32_e32 v14, v16, v13
	v_sub_f32_e32 v15, v14, v16
	v_ldexp_f32 v4, v4, 1
	v_sub_f32_e32 v13, v13, v15
	v_add_f32_e32 v4, v4, v13
	v_add_f32_e32 v13, v14, v4
	v_sub_f32_e32 v14, v13, v14
	v_sub_f32_e32 v4, v4, v14
	v_add_f32_e32 v14, v5, v13
	v_sub_f32_e32 v15, v14, v5
	v_sub_f32_e32 v16, v14, v15
	v_sub_f32_e32 v9, v17, v9
	v_sub_f32_e32 v5, v5, v16
	v_sub_f32_e32 v13, v13, v15
	v_add_f32_e32 v5, v13, v5
	v_add_f32_e32 v13, v9, v4
	v_sub_f32_e32 v15, v13, v9
	v_sub_f32_e32 v16, v13, v15
	v_sub_f32_e32 v9, v9, v16
	v_sub_f32_e32 v4, v4, v15
	v_add_f32_e32 v5, v13, v5
	v_add_f32_e32 v4, v4, v9
	v_add_f32_e32 v9, v14, v5
	v_sub_f32_e32 v13, v9, v14
	v_sub_f32_e32 v5, v5, v13
	v_add_f32_e32 v4, v4, v5
	v_add_f32_e32 v4, v9, v4
	v_cmp_neq_f32_e32 vcc, s6, v6
	v_mul_f32_e64 v5, |v8|, s7
	v_max_f32_e64 v8, -v8, 0
	v_cndmask_b32_e32 v4, v238, v4, vcc
	v_cmp_ngt_f32_e32 vcc, -1.0, v6
	v_exp_f32_e32 v3, v3
	s_nop 0
	v_cndmask_b32_e32 v4, v239, v4, vcc
	v_cmp_neq_f32_e32 vcc, -1.0, v6
	s_nop 1
	v_cndmask_b32_e32 v4, v240, v4, vcc
	v_cmp_lt_f32_e64 vcc, |v6|, s10
	s_nop 1
	v_cndmask_b32_e32 v4, v4, v6, vcc
	v_exp_f32_e32 v6, v5
	v_add_f32_e32 v4, v7, v4
	v_sub_f32_e32 v4, -0.5, v4
	v_mul_f32_e32 v4, 0x3fb8aa3b, v4
	v_add_f32_e32 v9, 1.0, v6
	v_exp_f32_e32 v7, v4
	v_add_f32_e32 v4, -1.0, v9
	v_sub_f32_e32 v5, v4, v9
	v_add_f32_e32 v5, 1.0, v5
	v_sub_f32_e32 v4, v6, v4
	v_add_f32_e32 v13, v4, v5
	v_frexp_mant_f32_e32 v4, v9
	v_cmp_gt_f32_e32 vcc, s8, v4
	v_cvt_f64_f32_e32 v[4:5], v9
	v_frexp_exp_i32_f64_e32 v4, v[4:5]
	v_subbrev_co_u32_e32 v4, vcc, 0, v4, vcc
	v_sub_u32_e32 v5, 0, v4
	v_ldexp_f32 v9, v9, v5
	v_ldexp_f32 v5, v13, v5
	v_add_f32_e32 v13, -1.0, v9
	v_add_f32_e32 v16, 1.0, v9
	v_add_f32_e32 v14, 1.0, v13
	v_add_f32_e32 v17, -1.0, v16
	v_sub_f32_e32 v14, v9, v14
	v_sub_f32_e32 v9, v9, v17
	v_add_f32_e32 v14, v5, v14
	v_add_f32_e32 v5, v5, v9
	v_add_f32_e32 v9, v16, v5
	v_rcp_f32_e32 v17, v9
	v_add_f32_e32 v15, v13, v14
	v_sub_f32_e32 v13, v15, v13
	v_sub_f32_e32 v13, v14, v13
	v_sub_f32_e32 v14, v9, v16
	v_sub_f32_e32 v5, v5, v14
	v_mul_f32_e32 v14, v15, v17
	v_mul_f32_e32 v16, v9, v14
	v_fma_f32 v18, v14, v9, -v16
	v_fmac_f32_e32 v18, v14, v5
	v_add_f32_e32 v19, v16, v18
	v_sub_f32_e32 v20, v15, v19
	v_sub_f32_e32 v15, v15, v20
	v_sub_f32_e32 v16, v19, v16
	v_sub_f32_e32 v15, v15, v19
	v_add_f32_e32 v13, v13, v15
	v_sub_f32_e32 v15, v16, v18
	v_add_f32_e32 v13, v15, v13
	v_add_f32_e32 v15, v20, v13
	v_mul_f32_e32 v16, v17, v15
	v_mul_f32_e32 v18, v9, v16
	v_fma_f32 v9, v16, v9, -v18
	v_fmac_f32_e32 v9, v16, v5
	v_sub_f32_e32 v5, v20, v15
	v_add_f32_e32 v5, v13, v5
	v_add_f32_e32 v13, v18, v9
	v_sub_f32_e32 v19, v15, v13
	v_sub_f32_e32 v15, v15, v19
	v_sub_f32_e32 v18, v13, v18
	v_sub_f32_e32 v13, v15, v13
	v_add_f32_e32 v5, v5, v13
	v_sub_f32_e32 v9, v18, v9
	v_cvt_f32_i32_e32 v4, v4
	v_add_f32_e32 v5, v9, v5
	v_add_f32_e32 v9, v14, v16
	v_add_f32_e32 v5, v19, v5
	v_sub_f32_e32 v13, v9, v14
	v_mul_f32_e32 v5, v17, v5
	v_sub_f32_e32 v13, v16, v13
	v_add_f32_e32 v5, v13, v5
	v_mul_f32_e32 v16, 0x3f317218, v4
	v_add_f32_e32 v13, v9, v5
	v_fma_f32 v17, v4, s9, -v16
	v_mul_f32_e32 v14, v13, v13
	v_fmac_f32_e32 v17, 0xb102e308, v4
	v_sub_f32_e32 v4, v13, v9
	v_fmamk_f32 v15, v14, 0x3e9b6dac, v231
	v_sub_f32_e32 v4, v5, v4
	v_add_f32_e32 v5, v16, v17
	v_fmaak_f32 v15, v14, v15, 0x3f2aaada
	v_sub_f32_e32 v9, v5, v16
	v_ldexp_f32 v16, v13, 1
	v_mul_f32_e32 v13, v13, v14
	v_mul_f32_e32 v13, v13, v15
	v_add_f32_e32 v14, v16, v13
	v_sub_f32_e32 v15, v14, v16
	v_ldexp_f32 v4, v4, 1
	v_sub_f32_e32 v13, v13, v15
	v_add_f32_e32 v4, v4, v13
	v_add_f32_e32 v13, v14, v4
	v_sub_f32_e32 v14, v13, v14
	v_sub_f32_e32 v4, v4, v14
	v_add_f32_e32 v14, v5, v13
	v_sub_f32_e32 v15, v14, v5
	v_sub_f32_e32 v16, v14, v15
	v_sub_f32_e32 v9, v17, v9
	v_sub_f32_e32 v5, v5, v16
	v_sub_f32_e32 v13, v13, v15
	v_add_f32_e32 v5, v13, v5
	v_add_f32_e32 v13, v9, v4
	v_sub_f32_e32 v15, v13, v9
	v_sub_f32_e32 v16, v13, v15
	v_sub_f32_e32 v9, v9, v16
	v_sub_f32_e32 v4, v4, v15
	v_add_f32_e32 v5, v13, v5
	v_add_f32_e32 v4, v4, v9
	v_add_f32_e32 v9, v14, v5
	v_sub_f32_e32 v13, v9, v14
	v_sub_f32_e32 v5, v5, v13
	v_add_f32_e32 v4, v4, v5
	v_add_f32_e32 v4, v9, v4
	v_cmp_neq_f32_e32 vcc, s6, v6
	s_nop 1
	v_cndmask_b32_e32 v4, v238, v4, vcc
	v_cmp_ngt_f32_e32 vcc, -1.0, v6
	s_nop 1
	v_cndmask_b32_e32 v4, v239, v4, vcc
	v_cmp_neq_f32_e32 vcc, -1.0, v6
	s_nop 1
	v_cndmask_b32_e32 v4, v240, v4, vcc
	v_cmp_lt_f32_e64 vcc, |v6|, s10
	s_nop 1
	v_cndmask_b32_e32 v4, v4, v6, vcc
	v_add_f32_e32 v4, v8, v4
	v_sub_f32_e32 v4, -0.5, v4
	v_mul_f32_e32 v4, 0x3fb8aa3b, v4
	v_exp_f32_e32 v5, v4
	v_mul_f32_e32 v4, 0xbfb8aa3b, v7
	v_exp_f32_e32 v4, v4
	ds_read_b128 v[6:9], v12 offset:112
	v_mul_f32_e32 v5, 0xbfb8aa3b, v5
	v_exp_f32_e32 v5, v5
	ds_write_b128 v75, v[2:5] offset:96
	ds_read_b128 v[2:5], v74 offset:112
	s_waitcnt lgkmcnt(0)
; template <int MODE, bool BIG = false> DI void gemm_tile(const Params& p, int tm, int tn, int kv, char* smem) {
;     ...
;     for (int c4 = 0; c4 < 16; ++c4) {
;       float4 v = crow4[c4], ww = w04[c4];
;       float u[4] = {v.x + ww.x, v.y + ww.y, v.z + ww.z, v.w + ww.w};
; #pragma unroll
;       for (int e = 0; e < 4; ++e) {
;         const float z = -u[e];
;         const float sp = fmaxf(z, 0.f) + log1pf(__expf(-fabsf(z)));
;         u[e] = __expf(-__expf(-sp - 0.5f));
;       }
;       W4[c4] = make_float4(u[0], u[1], u[2], u[3]);
	v_add_f32_e32 v2, v6, v2
	v_mul_f32_e64 v6, |v2|, s7
	v_exp_f32_e32 v6, v6
	v_add_f32_e32 v4, v8, v4
	v_max_f32_e64 v8, -v2, 0
	v_add_f32_e32 v7, v7, v3
	v_add_f32_e32 v13, 1.0, v6
	v_add_f32_e32 v2, -1.0, v13
	v_sub_f32_e32 v3, v2, v13
	v_add_f32_e32 v3, 1.0, v3
	v_sub_f32_e32 v2, v6, v2
	v_add_f32_e32 v14, v2, v3
	v_frexp_mant_f32_e32 v2, v13
	v_cmp_gt_f32_e32 vcc, s8, v2
	v_cvt_f64_f32_e32 v[2:3], v13
	v_frexp_exp_i32_f64_e32 v2, v[2:3]
	v_subbrev_co_u32_e32 v2, vcc, 0, v2, vcc
	v_sub_u32_e32 v3, 0, v2
	v_ldexp_f32 v13, v13, v3
	v_ldexp_f32 v3, v14, v3
	v_add_f32_e32 v14, -1.0, v13
	v_add_f32_e32 v17, 1.0, v13
	v_add_f32_e32 v15, 1.0, v14
	v_add_f32_e32 v18, -1.0, v17
	v_sub_f32_e32 v15, v13, v15
	v_sub_f32_e32 v13, v13, v18
	v_add_f32_e32 v15, v3, v15
	v_add_f32_e32 v3, v3, v13
	v_add_f32_e32 v13, v17, v3
	v_rcp_f32_e32 v18, v13
	v_add_f32_e32 v16, v14, v15
	v_sub_f32_e32 v14, v16, v14
	v_sub_f32_e32 v14, v15, v14
	v_sub_f32_e32 v15, v13, v17
	v_sub_f32_e32 v3, v3, v15
	v_mul_f32_e32 v15, v16, v18
	v_mul_f32_e32 v17, v13, v15
	v_fma_f32 v19, v15, v13, -v17
	v_fmac_f32_e32 v19, v15, v3
	v_add_f32_e32 v20, v17, v19
	v_sub_f32_e32 v21, v16, v20
	v_sub_f32_e32 v16, v16, v21
	v_sub_f32_e32 v17, v20, v17
	v_sub_f32_e32 v16, v16, v20
	v_add_f32_e32 v14, v14, v16
	v_sub_f32_e32 v16, v17, v19
	v_add_f32_e32 v14, v16, v14
	v_add_f32_e32 v16, v21, v14
	v_mul_f32_e32 v17, v18, v16
	v_mul_f32_e32 v19, v13, v17
	v_fma_f32 v13, v17, v13, -v19
	v_fmac_f32_e32 v13, v17, v3
	v_sub_f32_e32 v3, v21, v16
	v_add_f32_e32 v3, v14, v3
	v_add_f32_e32 v14, v19, v13
	v_sub_f32_e32 v20, v16, v14
	v_sub_f32_e32 v16, v16, v20
	v_sub_f32_e32 v19, v14, v19
	v_sub_f32_e32 v14, v16, v14
	v_add_f32_e32 v3, v3, v14
	v_sub_f32_e32 v13, v19, v13
	v_cvt_f32_i32_e32 v2, v2
	v_add_f32_e32 v3, v13, v3
	v_add_f32_e32 v13, v15, v17
	v_add_f32_e32 v3, v20, v3
	v_sub_f32_e32 v14, v13, v15
	v_mul_f32_e32 v3, v18, v3
	v_sub_f32_e32 v14, v17, v14
	v_add_f32_e32 v3, v14, v3
	v_mul_f32_e32 v17, 0x3f317218, v2
	v_add_f32_e32 v14, v13, v3
	v_fma_f32 v18, v2, s9, -v17
	v_mul_f32_e32 v15, v14, v14
	v_fmac_f32_e32 v18, 0xb102e308, v2
	v_sub_f32_e32 v2, v14, v13
	v_fmamk_f32 v16, v15, 0x3e9b6dac, v231
	v_sub_f32_e32 v2, v3, v2
	v_add_f32_e32 v3, v17, v18
	v_fmaak_f32 v16, v15, v16, 0x3f2aaada
	v_sub_f32_e32 v13, v3, v17
	v_ldexp_f32 v17, v14, 1
	v_mul_f32_e32 v14, v14, v15
	v_mul_f32_e32 v14, v14, v16
	v_add_f32_e32 v15, v17, v14
	v_sub_f32_e32 v16, v15, v17
	v_ldexp_f32 v2, v2, 1
	v_sub_f32_e32 v14, v14, v16
	v_add_f32_e32 v2, v2, v14
	v_add_f32_e32 v14, v15, v2
	v_sub_f32_e32 v15, v14, v15
	v_sub_f32_e32 v2, v2, v15
	v_add_f32_e32 v15, v3, v14
	v_sub_f32_e32 v16, v15, v3
	v_sub_f32_e32 v17, v15, v16
	v_sub_f32_e32 v13, v18, v13
	v_sub_f32_e32 v3, v3, v17
	v_sub_f32_e32 v14, v14, v16
	v_add_f32_e32 v3, v14, v3
	v_add_f32_e32 v14, v13, v2
	v_sub_f32_e32 v16, v14, v13
	v_sub_f32_e32 v17, v14, v16
	v_sub_f32_e32 v13, v13, v17
	v_sub_f32_e32 v2, v2, v16
	v_add_f32_e32 v3, v14, v3
	v_add_f32_e32 v2, v2, v13
	v_add_f32_e32 v13, v15, v3
	v_sub_f32_e32 v14, v13, v15
	v_sub_f32_e32 v3, v3, v14
	v_add_f32_e32 v2, v2, v3
	v_add_f32_e32 v2, v13, v2
	v_cmp_neq_f32_e32 vcc, s6, v6
	v_mul_f32_e64 v3, |v7|, s7
	v_max_f32_e64 v7, -v7, 0
	v_cndmask_b32_e32 v2, v238, v2, vcc
	v_cmp_ngt_f32_e32 vcc, -1.0, v6
	s_nop 1
	v_cndmask_b32_e32 v2, v239, v2, vcc
	v_cmp_neq_f32_e32 vcc, -1.0, v6
	s_nop 1
	v_cndmask_b32_e32 v2, v240, v2, vcc
	v_cmp_lt_f32_e64 vcc, |v6|, s10
	s_nop 1
	v_cndmask_b32_e32 v2, v2, v6, vcc
	v_add_f32_e32 v2, v8, v2
	v_sub_f32_e32 v2, -0.5, v2
	v_mul_f32_e32 v2, 0x3fb8aa3b, v2
	v_exp_f32_e32 v6, v3
	v_exp_f32_e32 v2, v2
	v_add_f32_e32 v8, v9, v5
	v_add_f32_e32 v9, 1.0, v6
	v_mul_f32_e32 v5, 0xbfb8aa3b, v2
	v_add_f32_e32 v2, -1.0, v9
	v_sub_f32_e32 v3, v2, v9
	v_add_f32_e32 v3, 1.0, v3
	v_sub_f32_e32 v2, v6, v2
	v_add_f32_e32 v13, v2, v3
	v_frexp_mant_f32_e32 v2, v9
	v_cmp_gt_f32_e32 vcc, s8, v2
	v_cvt_f64_f32_e32 v[2:3], v9
	v_frexp_exp_i32_f64_e32 v2, v[2:3]
	v_subbrev_co_u32_e32 v2, vcc, 0, v2, vcc
	v_sub_u32_e32 v3, 0, v2
	v_ldexp_f32 v9, v9, v3
	v_ldexp_f32 v3, v13, v3
	v_add_f32_e32 v13, -1.0, v9
	v_add_f32_e32 v16, 1.0, v9
	v_add_f32_e32 v14, 1.0, v13
	v_add_f32_e32 v17, -1.0, v16
	v_sub_f32_e32 v14, v9, v14
	v_sub_f32_e32 v9, v9, v17
	v_add_f32_e32 v14, v3, v14
	v_add_f32_e32 v3, v3, v9
	v_add_f32_e32 v9, v16, v3
	v_rcp_f32_e32 v17, v9
	v_add_f32_e32 v15, v13, v14
	v_sub_f32_e32 v13, v15, v13
	v_sub_f32_e32 v13, v14, v13
	v_sub_f32_e32 v14, v9, v16
	v_sub_f32_e32 v3, v3, v14
	v_mul_f32_e32 v14, v15, v17
	v_mul_f32_e32 v16, v9, v14
	v_fma_f32 v18, v14, v9, -v16
	v_fmac_f32_e32 v18, v14, v3
	v_add_f32_e32 v19, v16, v18
	v_sub_f32_e32 v20, v15, v19
	v_sub_f32_e32 v15, v15, v20
	v_sub_f32_e32 v16, v19, v16
	v_sub_f32_e32 v15, v15, v19
	v_add_f32_e32 v13, v13, v15
	v_sub_f32_e32 v15, v16, v18
	v_add_f32_e32 v13, v15, v13
	v_add_f32_e32 v15, v20, v13
	v_mul_f32_e32 v16, v17, v15
	v_mul_f32_e32 v18, v9, v16
	v_fma_f32 v9, v16, v9, -v18
	v_fmac_f32_e32 v9, v16, v3
	v_sub_f32_e32 v3, v20, v15
	v_add_f32_e32 v3, v13, v3
	v_add_f32_e32 v13, v18, v9
	v_sub_f32_e32 v19, v15, v13
	v_sub_f32_e32 v15, v15, v19
	v_sub_f32_e32 v18, v13, v18
	v_sub_f32_e32 v13, v15, v13
	v_add_f32_e32 v3, v3, v13
	v_sub_f32_e32 v9, v18, v9
	v_cvt_f32_i32_e32 v2, v2
	v_add_f32_e32 v3, v9, v3
	v_add_f32_e32 v9, v14, v16
	v_add_f32_e32 v3, v19, v3
	v_sub_f32_e32 v13, v9, v14
	v_mul_f32_e32 v3, v17, v3
	v_sub_f32_e32 v13, v16, v13
	v_add_f32_e32 v3, v13, v3
	v_mul_f32_e32 v16, 0x3f317218, v2
	v_add_f32_e32 v13, v9, v3
	v_fma_f32 v17, v2, s9, -v16
	v_mul_f32_e32 v14, v13, v13
	v_fmac_f32_e32 v17, 0xb102e308, v2
; template <int MODE, bool BIG = false> DI void gemm_tile(const Params& p, int tm, int tn, int kv, char* smem) {
;     ...
;     for (int c4 = 0; c4 < 16; ++c4) {
;       float4 v = crow4[c4], ww = w04[c4];
;       float u[4] = {v.x + ww.x, v.y + ww.y, v.z + ww.z, v.w + ww.w};
; #pragma unroll
;       for (int e = 0; e < 4; ++e) {
;         const float z = -u[e];
;         const float sp = fmaxf(z, 0.f) + log1pf(__expf(-fabsf(z)));
;         u[e] = __expf(-__expf(-sp - 0.5f));
;       }
;       W4[c4] = make_float4(u[0], u[1], u[2], u[3]);
	v_sub_f32_e32 v2, v13, v9
	v_fmamk_f32 v15, v14, 0x3e9b6dac, v231
	v_sub_f32_e32 v2, v3, v2
	v_add_f32_e32 v3, v16, v17
	v_fmaak_f32 v15, v14, v15, 0x3f2aaada
	v_sub_f32_e32 v9, v3, v16
	v_ldexp_f32 v16, v13, 1
	v_mul_f32_e32 v13, v13, v14
	v_mul_f32_e32 v13, v13, v15
	v_add_f32_e32 v14, v16, v13
	v_sub_f32_e32 v15, v14, v16
	v_ldexp_f32 v2, v2, 1
	v_sub_f32_e32 v13, v13, v15
	v_add_f32_e32 v2, v2, v13
	v_add_f32_e32 v13, v14, v2
	v_sub_f32_e32 v14, v13, v14
	v_sub_f32_e32 v2, v2, v14
	v_add_f32_e32 v14, v3, v13
	v_sub_f32_e32 v15, v14, v3
	v_sub_f32_e32 v16, v14, v15
	v_sub_f32_e32 v9, v17, v9
	v_sub_f32_e32 v3, v3, v16
	v_sub_f32_e32 v13, v13, v15
	v_add_f32_e32 v3, v13, v3
	v_add_f32_e32 v13, v9, v2
	v_sub_f32_e32 v15, v13, v9
	v_sub_f32_e32 v16, v13, v15
	v_sub_f32_e32 v9, v9, v16
	v_sub_f32_e32 v2, v2, v15
	v_add_f32_e32 v3, v13, v3
	v_add_f32_e32 v2, v2, v9
	v_add_f32_e32 v9, v14, v3
	v_sub_f32_e32 v13, v9, v14
	v_sub_f32_e32 v3, v3, v13
	v_add_f32_e32 v2, v2, v3
	v_add_f32_e32 v2, v9, v2
	v_cmp_neq_f32_e32 vcc, s6, v6
	s_nop 1
	v_cndmask_b32_e32 v2, v238, v2, vcc
	v_cmp_ngt_f32_e32 vcc, -1.0, v6
	s_nop 1
	v_cndmask_b32_e32 v2, v239, v2, vcc
	v_cmp_neq_f32_e32 vcc, -1.0, v6
	s_nop 1
	v_cndmask_b32_e32 v2, v240, v2, vcc
	v_cmp_lt_f32_e64 vcc, |v6|, s10
	s_nop 1
	v_cndmask_b32_e32 v2, v2, v6, vcc
	v_add_f32_e32 v2, v7, v2
	v_sub_f32_e32 v2, -0.5, v2
	v_mul_f32_e32 v2, 0x3fb8aa3b, v2
	v_exp_f32_e32 v3, v2
	v_mul_f32_e64 v2, |v4|, s7
	v_exp_f32_e32 v6, v2
	v_max_f32_e64 v7, -v4, 0
	v_exp_f32_e32 v2, v5
	v_mul_f32_e32 v3, 0xbfb8aa3b, v3
	v_add_f32_e32 v9, 1.0, v6
	v_add_f32_e32 v4, -1.0, v9
	v_sub_f32_e32 v5, v4, v9
	v_add_f32_e32 v5, 1.0, v5
	v_sub_f32_e32 v4, v6, v4
	v_add_f32_e32 v13, v4, v5
	v_frexp_mant_f32_e32 v4, v9
	v_cmp_gt_f32_e32 vcc, s8, v4
	v_cvt_f64_f32_e32 v[4:5], v9
	v_frexp_exp_i32_f64_e32 v4, v[4:5]
	v_subbrev_co_u32_e32 v4, vcc, 0, v4, vcc
	v_sub_u32_e32 v5, 0, v4
	v_ldexp_f32 v9, v9, v5
	v_ldexp_f32 v5, v13, v5
	v_add_f32_e32 v13, -1.0, v9
	v_add_f32_e32 v16, 1.0, v9
	v_add_f32_e32 v14, 1.0, v13
	v_add_f32_e32 v17, -1.0, v16
	v_sub_f32_e32 v14, v9, v14
	v_sub_f32_e32 v9, v9, v17
	v_add_f32_e32 v14, v5, v14
	v_add_f32_e32 v5, v5, v9
	v_add_f32_e32 v9, v16, v5
	v_rcp_f32_e32 v17, v9
	v_add_f32_e32 v15, v13, v14
	v_sub_f32_e32 v13, v15, v13
	v_sub_f32_e32 v13, v14, v13
	v_sub_f32_e32 v14, v9, v16
	v_sub_f32_e32 v5, v5, v14
	v_mul_f32_e32 v14, v15, v17
	v_mul_f32_e32 v16, v9, v14
	v_fma_f32 v18, v14, v9, -v16
	v_fmac_f32_e32 v18, v14, v5
	v_add_f32_e32 v19, v16, v18
	v_sub_f32_e32 v20, v15, v19
	v_sub_f32_e32 v15, v15, v20
	v_sub_f32_e32 v16, v19, v16
	v_sub_f32_e32 v15, v15, v19
	v_add_f32_e32 v13, v13, v15
	v_sub_f32_e32 v15, v16, v18
	v_add_f32_e32 v13, v15, v13
	v_add_f32_e32 v15, v20, v13
	v_mul_f32_e32 v16, v17, v15
	v_mul_f32_e32 v18, v9, v16
	v_fma_f32 v9, v16, v9, -v18
	v_fmac_f32_e32 v9, v16, v5
	v_sub_f32_e32 v5, v20, v15
	v_add_f32_e32 v5, v13, v5
	v_add_f32_e32 v13, v18, v9
	v_sub_f32_e32 v19, v15, v13
	v_sub_f32_e32 v15, v15, v19
	v_sub_f32_e32 v18, v13, v18
	v_sub_f32_e32 v13, v15, v13
	v_add_f32_e32 v5, v5, v13
	v_sub_f32_e32 v9, v18, v9
	v_cvt_f32_i32_e32 v4, v4
	v_add_f32_e32 v5, v9, v5
	v_add_f32_e32 v9, v14, v16
	v_add_f32_e32 v5, v19, v5
	v_sub_f32_e32 v13, v9, v14
	v_mul_f32_e32 v5, v17, v5
	v_sub_f32_e32 v13, v16, v13
	v_add_f32_e32 v5, v13, v5
	v_mul_f32_e32 v16, 0x3f317218, v4
	v_add_f32_e32 v13, v9, v5
	v_fma_f32 v17, v4, s9, -v16
	v_mul_f32_e32 v14, v13, v13
	v_fmac_f32_e32 v17, 0xb102e308, v4
	v_sub_f32_e32 v4, v13, v9
	v_fmamk_f32 v15, v14, 0x3e9b6dac, v231
	v_sub_f32_e32 v4, v5, v4
	v_add_f32_e32 v5, v16, v17
	v_fmaak_f32 v15, v14, v15, 0x3f2aaada
	v_sub_f32_e32 v9, v5, v16
	v_ldexp_f32 v16, v13, 1
	v_mul_f32_e32 v13, v13, v14
	v_mul_f32_e32 v13, v13, v15
	v_add_f32_e32 v14, v16, v13
	v_sub_f32_e32 v15, v14, v16
	v_ldexp_f32 v4, v4, 1
	v_sub_f32_e32 v13, v13, v15
	v_add_f32_e32 v4, v4, v13
	v_add_f32_e32 v13, v14, v4
	v_sub_f32_e32 v14, v13, v14
	v_sub_f32_e32 v4, v4, v14
	v_add_f32_e32 v14, v5, v13
	v_sub_f32_e32 v15, v14, v5
	v_sub_f32_e32 v16, v14, v15
	v_sub_f32_e32 v9, v17, v9
	v_sub_f32_e32 v5, v5, v16
	v_sub_f32_e32 v13, v13, v15
	v_add_f32_e32 v5, v13, v5
	v_add_f32_e32 v13, v9, v4
	v_sub_f32_e32 v15, v13, v9
	v_sub_f32_e32 v16, v13, v15
	v_sub_f32_e32 v9, v9, v16
	v_sub_f32_e32 v4, v4, v15
	v_add_f32_e32 v5, v13, v5
	v_add_f32_e32 v4, v4, v9
	v_add_f32_e32 v9, v14, v5
	v_sub_f32_e32 v13, v9, v14
	v_sub_f32_e32 v5, v5, v13
	v_add_f32_e32 v4, v4, v5
	v_add_f32_e32 v4, v9, v4
	v_cmp_neq_f32_e32 vcc, s6, v6
	v_mul_f32_e64 v5, |v8|, s7
	v_max_f32_e64 v8, -v8, 0
	v_cndmask_b32_e32 v4, v238, v4, vcc
	v_cmp_ngt_f32_e32 vcc, -1.0, v6
	v_exp_f32_e32 v3, v3
	s_nop 0
	v_cndmask_b32_e32 v4, v239, v4, vcc
	v_cmp_neq_f32_e32 vcc, -1.0, v6
	s_nop 1
	v_cndmask_b32_e32 v4, v240, v4, vcc
	v_cmp_lt_f32_e64 vcc, |v6|, s10
	s_nop 1
	v_cndmask_b32_e32 v4, v4, v6, vcc
	v_exp_f32_e32 v6, v5
	v_add_f32_e32 v4, v7, v4
	v_sub_f32_e32 v4, -0.5, v4
	v_mul_f32_e32 v4, 0x3fb8aa3b, v4
	v_add_f32_e32 v9, 1.0, v6
	v_exp_f32_e32 v7, v4
	v_add_f32_e32 v4, -1.0, v9
	v_sub_f32_e32 v5, v4, v9
	v_add_f32_e32 v5, 1.0, v5
	v_sub_f32_e32 v4, v6, v4
	v_add_f32_e32 v13, v4, v5
	v_frexp_mant_f32_e32 v4, v9
	v_cmp_gt_f32_e32 vcc, s8, v4
	v_cvt_f64_f32_e32 v[4:5], v9
	v_frexp_exp_i32_f64_e32 v4, v[4:5]
	v_subbrev_co_u32_e32 v4, vcc, 0, v4, vcc
	v_sub_u32_e32 v5, 0, v4
	v_ldexp_f32 v9, v9, v5
	v_ldexp_f32 v5, v13, v5
	v_add_f32_e32 v13, -1.0, v9
	v_add_f32_e32 v16, 1.0, v9
	v_add_f32_e32 v14, 1.0, v13
	v_add_f32_e32 v17, -1.0, v16
	v_sub_f32_e32 v14, v9, v14
	v_sub_f32_e32 v9, v9, v17
	v_add_f32_e32 v14, v5, v14
	v_add_f32_e32 v5, v5, v9
; template <int MODE, bool BIG = false> DI void gemm_tile(const Params& p, int tm, int tn, int kv, char* smem) {
;     ...
;     for (int c4 = 0; c4 < 16; ++c4) {
;       float4 v = crow4[c4], ww = w04[c4];
;       float u[4] = {v.x + ww.x, v.y + ww.y, v.z + ww.z, v.w + ww.w};
; #pragma unroll
;       for (int e = 0; e < 4; ++e) {
;         const float z = -u[e];
;         const float sp = fmaxf(z, 0.f) + log1pf(__expf(-fabsf(z)));
;         u[e] = __expf(-__expf(-sp - 0.5f));
;       }
;       W4[c4] = make_float4(u[0], u[1], u[2], u[3]);
	v_add_f32_e32 v9, v16, v5
	v_rcp_f32_e32 v17, v9
	v_add_f32_e32 v15, v13, v14
	v_sub_f32_e32 v13, v15, v13
	v_sub_f32_e32 v13, v14, v13
	v_sub_f32_e32 v14, v9, v16
	v_sub_f32_e32 v5, v5, v14
	v_mul_f32_e32 v14, v15, v17
	v_mul_f32_e32 v16, v9, v14
	v_fma_f32 v18, v14, v9, -v16
	v_fmac_f32_e32 v18, v14, v5
	v_add_f32_e32 v19, v16, v18
	v_sub_f32_e32 v20, v15, v19
	v_sub_f32_e32 v15, v15, v20
	v_sub_f32_e32 v16, v19, v16
	v_sub_f32_e32 v15, v15, v19
	v_add_f32_e32 v13, v13, v15
	v_sub_f32_e32 v15, v16, v18
	v_add_f32_e32 v13, v15, v13
	v_add_f32_e32 v15, v20, v13
	v_mul_f32_e32 v16, v17, v15
	v_mul_f32_e32 v18, v9, v16
	v_fma_f32 v9, v16, v9, -v18
	v_fmac_f32_e32 v9, v16, v5
	v_sub_f32_e32 v5, v20, v15
	v_add_f32_e32 v5, v13, v5
	v_add_f32_e32 v13, v18, v9
	v_sub_f32_e32 v19, v15, v13
	v_sub_f32_e32 v15, v15, v19
	v_sub_f32_e32 v18, v13, v18
	v_sub_f32_e32 v13, v15, v13
	v_add_f32_e32 v5, v5, v13
	v_sub_f32_e32 v9, v18, v9
	v_cvt_f32_i32_e32 v4, v4
	v_add_f32_e32 v5, v9, v5
	v_add_f32_e32 v9, v14, v16
	v_add_f32_e32 v5, v19, v5
	v_sub_f32_e32 v13, v9, v14
	v_mul_f32_e32 v5, v17, v5
	v_sub_f32_e32 v13, v16, v13
	v_add_f32_e32 v5, v13, v5
	v_mul_f32_e32 v16, 0x3f317218, v4
	v_add_f32_e32 v13, v9, v5
	v_fma_f32 v17, v4, s9, -v16
	v_mul_f32_e32 v14, v13, v13
	v_fmac_f32_e32 v17, 0xb102e308, v4
	v_sub_f32_e32 v4, v13, v9
	v_fmamk_f32 v15, v14, 0x3e9b6dac, v231
	v_sub_f32_e32 v4, v5, v4
	v_add_f32_e32 v5, v16, v17
	v_fmaak_f32 v15, v14, v15, 0x3f2aaada
	v_sub_f32_e32 v9, v5, v16
	v_ldexp_f32 v16, v13, 1
	v_mul_f32_e32 v13, v13, v14
	v_mul_f32_e32 v13, v13, v15
	v_add_f32_e32 v14, v16, v13
	v_sub_f32_e32 v15, v14, v16
	v_ldexp_f32 v4, v4, 1
	v_sub_f32_e32 v13, v13, v15
	v_add_f32_e32 v4, v4, v13
	v_add_f32_e32 v13, v14, v4
	v_sub_f32_e32 v14, v13, v14
	v_sub_f32_e32 v4, v4, v14
	v_add_f32_e32 v14, v5, v13
	v_sub_f32_e32 v15, v14, v5
	v_sub_f32_e32 v16, v14, v15
	v_sub_f32_e32 v9, v17, v9
	v_sub_f32_e32 v5, v5, v16
	v_sub_f32_e32 v13, v13, v15
	v_add_f32_e32 v5, v13, v5
	v_add_f32_e32 v13, v9, v4
	v_sub_f32_e32 v15, v13, v9
	v_sub_f32_e32 v16, v13, v15
	v_sub_f32_e32 v9, v9, v16
	v_sub_f32_e32 v4, v4, v15
	v_add_f32_e32 v5, v13, v5
	v_add_f32_e32 v4, v4, v9
	v_add_f32_e32 v9, v14, v5
	v_sub_f32_e32 v13, v9, v14
	v_sub_f32_e32 v5, v5, v13
	v_add_f32_e32 v4, v4, v5
	v_add_f32_e32 v4, v9, v4
	v_cmp_neq_f32_e32 vcc, s6, v6
	s_nop 1
	v_cndmask_b32_e32 v4, v238, v4, vcc
	v_cmp_ngt_f32_e32 vcc, -1.0, v6
	s_nop 1
	v_cndmask_b32_e32 v4, v239, v4, vcc
	v_cmp_neq_f32_e32 vcc, -1.0, v6
	s_nop 1
	v_cndmask_b32_e32 v4, v240, v4, vcc
	v_cmp_lt_f32_e64 vcc, |v6|, s10
	s_nop 1
	v_cndmask_b32_e32 v4, v4, v6, vcc
	v_add_f32_e32 v4, v8, v4
	v_sub_f32_e32 v4, -0.5, v4
	v_mul_f32_e32 v4, 0x3fb8aa3b, v4
	v_exp_f32_e32 v5, v4
	v_mul_f32_e32 v4, 0xbfb8aa3b, v7
	v_exp_f32_e32 v4, v4
	ds_read_b128 v[6:9], v12 offset:128
	v_mul_f32_e32 v5, 0xbfb8aa3b, v5
	v_exp_f32_e32 v5, v5
	ds_write_b128 v75, v[2:5] offset:112
	ds_read_b128 v[2:5], v74 offset:128
	s_waitcnt lgkmcnt(0)
	v_add_f32_e32 v2, v6, v2
	v_mul_f32_e64 v6, |v2|, s7
	v_exp_f32_e32 v6, v6
	v_add_f32_e32 v4, v8, v4
	v_max_f32_e64 v8, -v2, 0
	v_add_f32_e32 v7, v7, v3
	v_add_f32_e32 v13, 1.0, v6
	v_add_f32_e32 v2, -1.0, v13
	v_sub_f32_e32 v3, v2, v13
	v_add_f32_e32 v3, 1.0, v3
	v_sub_f32_e32 v2, v6, v2
	v_add_f32_e32 v14, v2, v3
	v_frexp_mant_f32_e32 v2, v13
	v_cmp_gt_f32_e32 vcc, s8, v2
	v_cvt_f64_f32_e32 v[2:3], v13
	v_frexp_exp_i32_f64_e32 v2, v[2:3]
	v_subbrev_co_u32_e32 v2, vcc, 0, v2, vcc
	v_sub_u32_e32 v3, 0, v2
	v_ldexp_f32 v13, v13, v3
	v_ldexp_f32 v3, v14, v3
	v_add_f32_e32 v14, -1.0, v13
	v_add_f32_e32 v17, 1.0, v13
	v_add_f32_e32 v15, 1.0, v14
	v_add_f32_e32 v18, -1.0, v17
	v_sub_f32_e32 v15, v13, v15
	v_sub_f32_e32 v13, v13, v18
	v_add_f32_e32 v15, v3, v15
	v_add_f32_e32 v3, v3, v13
	v_add_f32_e32 v13, v17, v3
	v_rcp_f32_e32 v18, v13
	v_add_f32_e32 v16, v14, v15
	v_sub_f32_e32 v14, v16, v14
	v_sub_f32_e32 v14, v15, v14
	v_sub_f32_e32 v15, v13, v17
	v_sub_f32_e32 v3, v3, v15
	v_mul_f32_e32 v15, v16, v18
	v_mul_f32_e32 v17, v13, v15
	v_fma_f32 v19, v15, v13, -v17
	v_fmac_f32_e32 v19, v15, v3
	v_add_f32_e32 v20, v17, v19
	v_sub_f32_e32 v21, v16, v20
	v_sub_f32_e32 v16, v16, v21
	v_sub_f32_e32 v17, v20, v17
	v_sub_f32_e32 v16, v16, v20
	v_add_f32_e32 v14, v14, v16
	v_sub_f32_e32 v16, v17, v19
	v_add_f32_e32 v14, v16, v14
	v_add_f32_e32 v16, v21, v14
	v_mul_f32_e32 v17, v18, v16
	v_mul_f32_e32 v19, v13, v17
	v_fma_f32 v13, v17, v13, -v19
	v_fmac_f32_e32 v13, v17, v3
	v_sub_f32_e32 v3, v21, v16
	v_add_f32_e32 v3, v14, v3
	v_add_f32_e32 v14, v19, v13
	v_sub_f32_e32 v20, v16, v14
	v_sub_f32_e32 v16, v16, v20
	v_sub_f32_e32 v19, v14, v19
	v_sub_f32_e32 v14, v16, v14
	v_add_f32_e32 v3, v3, v14
	v_sub_f32_e32 v13, v19, v13
	v_cvt_f32_i32_e32 v2, v2
	v_add_f32_e32 v3, v13, v3
	v_add_f32_e32 v13, v15, v17
	v_add_f32_e32 v3, v20, v3
	v_sub_f32_e32 v14, v13, v15
	v_mul_f32_e32 v3, v18, v3
	v_sub_f32_e32 v14, v17, v14
	v_add_f32_e32 v3, v14, v3
	v_mul_f32_e32 v17, 0x3f317218, v2
	v_add_f32_e32 v14, v13, v3
	v_fma_f32 v18, v2, s9, -v17
	v_mul_f32_e32 v15, v14, v14
	v_fmac_f32_e32 v18, 0xb102e308, v2
	v_sub_f32_e32 v2, v14, v13
	v_fmamk_f32 v16, v15, 0x3e9b6dac, v231
	v_sub_f32_e32 v2, v3, v2
	v_add_f32_e32 v3, v17, v18
	v_fmaak_f32 v16, v15, v16, 0x3f2aaada
	v_sub_f32_e32 v13, v3, v17
	v_ldexp_f32 v17, v14, 1
	v_mul_f32_e32 v14, v14, v15
	v_mul_f32_e32 v14, v14, v16
	v_add_f32_e32 v15, v17, v14
	v_sub_f32_e32 v16, v15, v17
	v_ldexp_f32 v2, v2, 1
	v_sub_f32_e32 v14, v14, v16
	v_add_f32_e32 v2, v2, v14
	v_add_f32_e32 v14, v15, v2
	v_sub_f32_e32 v15, v14, v15
	v_sub_f32_e32 v2, v2, v15
	v_add_f32_e32 v15, v3, v14
; template <int MODE, bool BIG = false> DI void gemm_tile(const Params& p, int tm, int tn, int kv, char* smem) {
;     ...
;     for (int c4 = 0; c4 < 16; ++c4) {
;       float4 v = crow4[c4], ww = w04[c4];
;       float u[4] = {v.x + ww.x, v.y + ww.y, v.z + ww.z, v.w + ww.w};
; #pragma unroll
;       for (int e = 0; e < 4; ++e) {
;         const float z = -u[e];
;         const float sp = fmaxf(z, 0.f) + log1pf(__expf(-fabsf(z)));
;         u[e] = __expf(-__expf(-sp - 0.5f));
;       }
;       W4[c4] = make_float4(u[0], u[1], u[2], u[3]);
	v_sub_f32_e32 v16, v15, v3
	v_sub_f32_e32 v17, v15, v16
	v_sub_f32_e32 v13, v18, v13
	v_sub_f32_e32 v3, v3, v17
	v_sub_f32_e32 v14, v14, v16
	v_add_f32_e32 v3, v14, v3
	v_add_f32_e32 v14, v13, v2
	v_sub_f32_e32 v16, v14, v13
	v_sub_f32_e32 v17, v14, v16
	v_sub_f32_e32 v13, v13, v17
	v_sub_f32_e32 v2, v2, v16
	v_add_f32_e32 v3, v14, v3
	v_add_f32_e32 v2, v2, v13
	v_add_f32_e32 v13, v15, v3
	v_sub_f32_e32 v14, v13, v15
	v_sub_f32_e32 v3, v3, v14
	v_add_f32_e32 v2, v2, v3
	v_add_f32_e32 v2, v13, v2
	v_cmp_neq_f32_e32 vcc, s6, v6
	v_mul_f32_e64 v3, |v7|, s7
	v_max_f32_e64 v7, -v7, 0
	v_cndmask_b32_e32 v2, v238, v2, vcc
	v_cmp_ngt_f32_e32 vcc, -1.0, v6
	s_nop 1
	v_cndmask_b32_e32 v2, v239, v2, vcc
	v_cmp_neq_f32_e32 vcc, -1.0, v6
	s_nop 1
	v_cndmask_b32_e32 v2, v240, v2, vcc
	v_cmp_lt_f32_e64 vcc, |v6|, s10
	s_nop 1
	v_cndmask_b32_e32 v2, v2, v6, vcc
	v_add_f32_e32 v2, v8, v2
	v_sub_f32_e32 v2, -0.5, v2
	v_mul_f32_e32 v2, 0x3fb8aa3b, v2
	v_exp_f32_e32 v6, v3
	v_exp_f32_e32 v2, v2
	v_add_f32_e32 v8, v9, v5
	v_add_f32_e32 v9, 1.0, v6
	v_mul_f32_e32 v5, 0xbfb8aa3b, v2
	v_add_f32_e32 v2, -1.0, v9
	v_sub_f32_e32 v3, v2, v9
	v_add_f32_e32 v3, 1.0, v3
	v_sub_f32_e32 v2, v6, v2
	v_add_f32_e32 v13, v2, v3
	v_frexp_mant_f32_e32 v2, v9
	v_cmp_gt_f32_e32 vcc, s8, v2
	v_cvt_f64_f32_e32 v[2:3], v9
	v_frexp_exp_i32_f64_e32 v2, v[2:3]
	v_subbrev_co_u32_e32 v2, vcc, 0, v2, vcc
	v_sub_u32_e32 v3, 0, v2
	v_ldexp_f32 v9, v9, v3
	v_ldexp_f32 v3, v13, v3
	v_add_f32_e32 v13, -1.0, v9
	v_add_f32_e32 v16, 1.0, v9
	v_add_f32_e32 v14, 1.0, v13
	v_add_f32_e32 v17, -1.0, v16
	v_sub_f32_e32 v14, v9, v14
	v_sub_f32_e32 v9, v9, v17
	v_add_f32_e32 v14, v3, v14
	v_add_f32_e32 v3, v3, v9
	v_add_f32_e32 v9, v16, v3
	v_rcp_f32_e32 v17, v9
	v_add_f32_e32 v15, v13, v14
	v_sub_f32_e32 v13, v15, v13
	v_sub_f32_e32 v13, v14, v13
	v_sub_f32_e32 v14, v9, v16
	v_sub_f32_e32 v3, v3, v14
	v_mul_f32_e32 v14, v15, v17
	v_mul_f32_e32 v16, v9, v14
	v_fma_f32 v18, v14, v9, -v16
	v_fmac_f32_e32 v18, v14, v3
	v_add_f32_e32 v19, v16, v18
	v_sub_f32_e32 v20, v15, v19
	v_sub_f32_e32 v15, v15, v20
	v_sub_f32_e32 v16, v19, v16
	v_sub_f32_e32 v15, v15, v19
	v_add_f32_e32 v13, v13, v15
	v_sub_f32_e32 v15, v16, v18
	v_add_f32_e32 v13, v15, v13
	v_add_f32_e32 v15, v20, v13
	v_mul_f32_e32 v16, v17, v15
	v_mul_f32_e32 v18, v9, v16
	v_fma_f32 v9, v16, v9, -v18
	v_fmac_f32_e32 v9, v16, v3
	v_sub_f32_e32 v3, v20, v15
	v_add_f32_e32 v3, v13, v3
	v_add_f32_e32 v13, v18, v9
	v_sub_f32_e32 v19, v15, v13
	v_sub_f32_e32 v15, v15, v19
	v_sub_f32_e32 v18, v13, v18
	v_sub_f32_e32 v13, v15, v13
	v_add_f32_e32 v3, v3, v13
	v_sub_f32_e32 v9, v18, v9
	v_cvt_f32_i32_e32 v2, v2
	v_add_f32_e32 v3, v9, v3
	v_add_f32_e32 v9, v14, v16
	v_add_f32_e32 v3, v19, v3
	v_sub_f32_e32 v13, v9, v14
	v_mul_f32_e32 v3, v17, v3
	v_sub_f32_e32 v13, v16, v13
	v_add_f32_e32 v3, v13, v3
	v_mul_f32_e32 v16, 0x3f317218, v2
	v_add_f32_e32 v13, v9, v3
	v_fma_f32 v17, v2, s9, -v16
	v_mul_f32_e32 v14, v13, v13
	v_fmac_f32_e32 v17, 0xb102e308, v2
	v_sub_f32_e32 v2, v13, v9
	v_fmamk_f32 v15, v14, 0x3e9b6dac, v231
	v_sub_f32_e32 v2, v3, v2
	v_add_f32_e32 v3, v16, v17
	v_fmaak_f32 v15, v14, v15, 0x3f2aaada
	v_sub_f32_e32 v9, v3, v16
	v_ldexp_f32 v16, v13, 1
	v_mul_f32_e32 v13, v13, v14
	v_mul_f32_e32 v13, v13, v15
	v_add_f32_e32 v14, v16, v13
	v_sub_f32_e32 v15, v14, v16
	v_ldexp_f32 v2, v2, 1
	v_sub_f32_e32 v13, v13, v15
	v_add_f32_e32 v2, v2, v13
	v_add_f32_e32 v13, v14, v2
	v_sub_f32_e32 v14, v13, v14
	v_sub_f32_e32 v2, v2, v14
	v_add_f32_e32 v14, v3, v13
	v_sub_f32_e32 v15, v14, v3
	v_sub_f32_e32 v16, v14, v15
	v_sub_f32_e32 v9, v17, v9
	v_sub_f32_e32 v3, v3, v16
	v_sub_f32_e32 v13, v13, v15
	v_add_f32_e32 v3, v13, v3
	v_add_f32_e32 v13, v9, v2
	v_sub_f32_e32 v15, v13, v9
	v_sub_f32_e32 v16, v13, v15
	v_sub_f32_e32 v9, v9, v16
	v_sub_f32_e32 v2, v2, v15
	v_add_f32_e32 v3, v13, v3
	v_add_f32_e32 v2, v2, v9
	v_add_f32_e32 v9, v14, v3
	v_sub_f32_e32 v13, v9, v14
	v_sub_f32_e32 v3, v3, v13
	v_add_f32_e32 v2, v2, v3
	v_add_f32_e32 v2, v9, v2
	v_cmp_neq_f32_e32 vcc, s6, v6
	s_nop 1
	v_cndmask_b32_e32 v2, v238, v2, vcc
	v_cmp_ngt_f32_e32 vcc, -1.0, v6
	s_nop 1
	v_cndmask_b32_e32 v2, v239, v2, vcc
	v_cmp_neq_f32_e32 vcc, -1.0, v6
	s_nop 1
	v_cndmask_b32_e32 v2, v240, v2, vcc
	v_cmp_lt_f32_e64 vcc, |v6|, s10
	s_nop 1
	v_cndmask_b32_e32 v2, v2, v6, vcc
	v_add_f32_e32 v2, v7, v2
	v_sub_f32_e32 v2, -0.5, v2
	v_mul_f32_e32 v2, 0x3fb8aa3b, v2
	v_exp_f32_e32 v3, v2
	v_mul_f32_e64 v2, |v4|, s7
	v_exp_f32_e32 v6, v2
	v_max_f32_e64 v7, -v4, 0
	v_exp_f32_e32 v2, v5
	v_mul_f32_e32 v3, 0xbfb8aa3b, v3
	v_add_f32_e32 v9, 1.0, v6
	v_add_f32_e32 v4, -1.0, v9
	v_sub_f32_e32 v5, v4, v9
	v_add_f32_e32 v5, 1.0, v5
	v_sub_f32_e32 v4, v6, v4
	v_add_f32_e32 v13, v4, v5
	v_frexp_mant_f32_e32 v4, v9
	v_cmp_gt_f32_e32 vcc, s8, v4
	v_cvt_f64_f32_e32 v[4:5], v9
	v_frexp_exp_i32_f64_e32 v4, v[4:5]
	v_subbrev_co_u32_e32 v4, vcc, 0, v4, vcc
	v_sub_u32_e32 v5, 0, v4
	v_ldexp_f32 v9, v9, v5
	v_ldexp_f32 v5, v13, v5
	v_add_f32_e32 v13, -1.0, v9
	v_add_f32_e32 v16, 1.0, v9
	v_add_f32_e32 v14, 1.0, v13
	v_add_f32_e32 v17, -1.0, v16
	v_sub_f32_e32 v14, v9, v14
	v_sub_f32_e32 v9, v9, v17
	v_add_f32_e32 v14, v5, v14
	v_add_f32_e32 v5, v5, v9
	v_add_f32_e32 v9, v16, v5
	v_rcp_f32_e32 v17, v9
	v_add_f32_e32 v15, v13, v14
	v_sub_f32_e32 v13, v15, v13
	v_sub_f32_e32 v13, v14, v13
	v_sub_f32_e32 v14, v9, v16
	v_sub_f32_e32 v5, v5, v14
	v_mul_f32_e32 v14, v15, v17
	v_mul_f32_e32 v16, v9, v14
	v_fma_f32 v18, v14, v9, -v16
	v_fmac_f32_e32 v18, v14, v5
	v_add_f32_e32 v19, v16, v18
	v_sub_f32_e32 v20, v15, v19
	v_sub_f32_e32 v15, v15, v20
	v_sub_f32_e32 v16, v19, v16
	v_sub_f32_e32 v15, v15, v19
; template <int MODE, bool BIG = false> DI void gemm_tile(const Params& p, int tm, int tn, int kv, char* smem) {
;     ...
;     for (int c4 = 0; c4 < 16; ++c4) {
;       float4 v = crow4[c4], ww = w04[c4];
;       float u[4] = {v.x + ww.x, v.y + ww.y, v.z + ww.z, v.w + ww.w};
; #pragma unroll
;       for (int e = 0; e < 4; ++e) {
;         const float z = -u[e];
;         const float sp = fmaxf(z, 0.f) + log1pf(__expf(-fabsf(z)));
;         u[e] = __expf(-__expf(-sp - 0.5f));
;       }
;       W4[c4] = make_float4(u[0], u[1], u[2], u[3]);
	v_add_f32_e32 v13, v13, v15
	v_sub_f32_e32 v15, v16, v18
	v_add_f32_e32 v13, v15, v13
	v_add_f32_e32 v15, v20, v13
	v_mul_f32_e32 v16, v17, v15
	v_mul_f32_e32 v18, v9, v16
	v_fma_f32 v9, v16, v9, -v18
	v_fmac_f32_e32 v9, v16, v5
	v_sub_f32_e32 v5, v20, v15
	v_add_f32_e32 v5, v13, v5
	v_add_f32_e32 v13, v18, v9
	v_sub_f32_e32 v19, v15, v13
	v_sub_f32_e32 v15, v15, v19
	v_sub_f32_e32 v18, v13, v18
	v_sub_f32_e32 v13, v15, v13
	v_add_f32_e32 v5, v5, v13
	v_sub_f32_e32 v9, v18, v9
	v_cvt_f32_i32_e32 v4, v4
	v_add_f32_e32 v5, v9, v5
	v_add_f32_e32 v9, v14, v16
	v_add_f32_e32 v5, v19, v5
	v_sub_f32_e32 v13, v9, v14
	v_mul_f32_e32 v5, v17, v5
	v_sub_f32_e32 v13, v16, v13
	v_add_f32_e32 v5, v13, v5
	v_mul_f32_e32 v16, 0x3f317218, v4
	v_add_f32_e32 v13, v9, v5
	v_fma_f32 v17, v4, s9, -v16
	v_mul_f32_e32 v14, v13, v13
	v_fmac_f32_e32 v17, 0xb102e308, v4
	v_sub_f32_e32 v4, v13, v9
	v_fmamk_f32 v15, v14, 0x3e9b6dac, v231
	v_sub_f32_e32 v4, v5, v4
	v_add_f32_e32 v5, v16, v17
	v_fmaak_f32 v15, v14, v15, 0x3f2aaada
	v_sub_f32_e32 v9, v5, v16
	v_ldexp_f32 v16, v13, 1
	v_mul_f32_e32 v13, v13, v14
	v_mul_f32_e32 v13, v13, v15
	v_add_f32_e32 v14, v16, v13
	v_sub_f32_e32 v15, v14, v16
	v_ldexp_f32 v4, v4, 1
	v_sub_f32_e32 v13, v13, v15
	v_add_f32_e32 v4, v4, v13
	v_add_f32_e32 v13, v14, v4
	v_sub_f32_e32 v14, v13, v14
	v_sub_f32_e32 v4, v4, v14
	v_add_f32_e32 v14, v5, v13
	v_sub_f32_e32 v15, v14, v5
	v_sub_f32_e32 v16, v14, v15
	v_sub_f32_e32 v9, v17, v9
	v_sub_f32_e32 v5, v5, v16
	v_sub_f32_e32 v13, v13, v15
	v_add_f32_e32 v5, v13, v5
	v_add_f32_e32 v13, v9, v4
	v_sub_f32_e32 v15, v13, v9
	v_sub_f32_e32 v16, v13, v15
	v_sub_f32_e32 v9, v9, v16
	v_sub_f32_e32 v4, v4, v15
	v_add_f32_e32 v5, v13, v5
	v_add_f32_e32 v4, v4, v9
	v_add_f32_e32 v9, v14, v5
	v_sub_f32_e32 v13, v9, v14
	v_sub_f32_e32 v5, v5, v13
	v_add_f32_e32 v4, v4, v5
	v_add_f32_e32 v4, v9, v4
	v_cmp_neq_f32_e32 vcc, s6, v6
	v_mul_f32_e64 v5, |v8|, s7
	v_max_f32_e64 v8, -v8, 0
	v_cndmask_b32_e32 v4, v238, v4, vcc
	v_cmp_ngt_f32_e32 vcc, -1.0, v6
	v_exp_f32_e32 v3, v3
	s_nop 0
	v_cndmask_b32_e32 v4, v239, v4, vcc
	v_cmp_neq_f32_e32 vcc, -1.0, v6
	s_nop 1
	v_cndmask_b32_e32 v4, v240, v4, vcc
	v_cmp_lt_f32_e64 vcc, |v6|, s10
	s_nop 1
	v_cndmask_b32_e32 v4, v4, v6, vcc
	v_exp_f32_e32 v6, v5
	v_add_f32_e32 v4, v7, v4
	v_sub_f32_e32 v4, -0.5, v4
	v_mul_f32_e32 v4, 0x3fb8aa3b, v4
	v_add_f32_e32 v9, 1.0, v6
	v_exp_f32_e32 v7, v4
	v_add_f32_e32 v4, -1.0, v9
	v_sub_f32_e32 v5, v4, v9
	v_add_f32_e32 v5, 1.0, v5
	v_sub_f32_e32 v4, v6, v4
	v_add_f32_e32 v13, v4, v5
	v_frexp_mant_f32_e32 v4, v9
	v_cmp_gt_f32_e32 vcc, s8, v4
	v_cvt_f64_f32_e32 v[4:5], v9
	v_frexp_exp_i32_f64_e32 v4, v[4:5]
	v_subbrev_co_u32_e32 v4, vcc, 0, v4, vcc
	v_sub_u32_e32 v5, 0, v4
	v_ldexp_f32 v9, v9, v5
	v_ldexp_f32 v5, v13, v5
	v_add_f32_e32 v13, -1.0, v9
	v_add_f32_e32 v16, 1.0, v9
	v_add_f32_e32 v14, 1.0, v13
	v_add_f32_e32 v17, -1.0, v16
	v_sub_f32_e32 v14, v9, v14
	v_sub_f32_e32 v9, v9, v17
	v_add_f32_e32 v14, v5, v14
	v_add_f32_e32 v5, v5, v9
	v_add_f32_e32 v9, v16, v5
	v_rcp_f32_e32 v17, v9
	v_add_f32_e32 v15, v13, v14
	v_sub_f32_e32 v13, v15, v13
	v_sub_f32_e32 v13, v14, v13
	v_sub_f32_e32 v14, v9, v16
	v_sub_f32_e32 v5, v5, v14
	v_mul_f32_e32 v14, v15, v17
	v_mul_f32_e32 v16, v9, v14
	v_fma_f32 v18, v14, v9, -v16
	v_fmac_f32_e32 v18, v14, v5
	v_add_f32_e32 v19, v16, v18
	v_sub_f32_e32 v20, v15, v19
	v_sub_f32_e32 v15, v15, v20
	v_sub_f32_e32 v16, v19, v16
	v_sub_f32_e32 v15, v15, v19
	v_add_f32_e32 v13, v13, v15
	v_sub_f32_e32 v15, v16, v18
	v_add_f32_e32 v13, v15, v13
	v_add_f32_e32 v15, v20, v13
	v_mul_f32_e32 v16, v17, v15
	v_mul_f32_e32 v18, v9, v16
	v_fma_f32 v9, v16, v9, -v18
	v_fmac_f32_e32 v9, v16, v5
	v_sub_f32_e32 v5, v20, v15
	v_add_f32_e32 v5, v13, v5
	v_add_f32_e32 v13, v18, v9
	v_sub_f32_e32 v19, v15, v13
	v_sub_f32_e32 v15, v15, v19
	v_sub_f32_e32 v18, v13, v18
	v_sub_f32_e32 v13, v15, v13
	v_add_f32_e32 v5, v5, v13
	v_sub_f32_e32 v9, v18, v9
	v_cvt_f32_i32_e32 v4, v4
	v_add_f32_e32 v5, v9, v5
	v_add_f32_e32 v9, v14, v16
	v_add_f32_e32 v5, v19, v5
	v_sub_f32_e32 v13, v9, v14
	v_mul_f32_e32 v5, v17, v5
	v_sub_f32_e32 v13, v16, v13
	v_add_f32_e32 v5, v13, v5
	v_mul_f32_e32 v16, 0x3f317218, v4
	v_add_f32_e32 v13, v9, v5
	v_fma_f32 v17, v4, s9, -v16
	v_mul_f32_e32 v14, v13, v13
	v_fmac_f32_e32 v17, 0xb102e308, v4
	v_sub_f32_e32 v4, v13, v9
	v_fmamk_f32 v15, v14, 0x3e9b6dac, v231
	v_sub_f32_e32 v4, v5, v4
	v_add_f32_e32 v5, v16, v17
	v_fmaak_f32 v15, v14, v15, 0x3f2aaada
	v_sub_f32_e32 v9, v5, v16
	v_ldexp_f32 v16, v13, 1
	v_mul_f32_e32 v13, v13, v14
	v_mul_f32_e32 v13, v13, v15
	v_add_f32_e32 v14, v16, v13
	v_sub_f32_e32 v15, v14, v16
	v_ldexp_f32 v4, v4, 1
	v_sub_f32_e32 v13, v13, v15
	v_add_f32_e32 v4, v4, v13
	v_add_f32_e32 v13, v14, v4
	v_sub_f32_e32 v14, v13, v14
	v_sub_f32_e32 v4, v4, v14
	v_add_f32_e32 v14, v5, v13
	v_sub_f32_e32 v15, v14, v5
	v_sub_f32_e32 v16, v14, v15
	v_sub_f32_e32 v9, v17, v9
	v_sub_f32_e32 v5, v5, v16
	v_sub_f32_e32 v13, v13, v15
	v_add_f32_e32 v5, v13, v5
	v_add_f32_e32 v13, v9, v4
	v_sub_f32_e32 v15, v13, v9
	v_sub_f32_e32 v16, v13, v15
	v_sub_f32_e32 v9, v9, v16
	v_sub_f32_e32 v4, v4, v15
	v_add_f32_e32 v5, v13, v5
	v_add_f32_e32 v4, v4, v9
	v_add_f32_e32 v9, v14, v5
	v_sub_f32_e32 v13, v9, v14
	v_sub_f32_e32 v5, v5, v13
	v_add_f32_e32 v4, v4, v5
	v_add_f32_e32 v4, v9, v4
	v_cmp_neq_f32_e32 vcc, s6, v6
	s_nop 1
	v_cndmask_b32_e32 v4, v238, v4, vcc
	v_cmp_ngt_f32_e32 vcc, -1.0, v6
	s_nop 1
	v_cndmask_b32_e32 v4, v239, v4, vcc
	v_cmp_neq_f32_e32 vcc, -1.0, v6
	s_nop 1
	v_cndmask_b32_e32 v4, v240, v4, vcc
	v_cmp_lt_f32_e64 vcc, |v6|, s10
	s_nop 1
	v_cndmask_b32_e32 v4, v4, v6, vcc
	v_add_f32_e32 v4, v8, v4
	v_sub_f32_e32 v4, -0.5, v4
	v_mul_f32_e32 v4, 0x3fb8aa3b, v4
	v_exp_f32_e32 v5, v4
	v_mul_f32_e32 v4, 0xbfb8aa3b, v7
	v_exp_f32_e32 v4, v4
	ds_read_b128 v[6:9], v12 offset:144
	v_mul_f32_e32 v5, 0xbfb8aa3b, v5
	v_exp_f32_e32 v5, v5
	ds_write_b128 v75, v[2:5] offset:128
	ds_read_b128 v[2:5], v74 offset:144
	s_waitcnt lgkmcnt(0)
; template <int MODE, bool BIG = false> DI void gemm_tile(const Params& p, int tm, int tn, int kv, char* smem) {
;     ...
;     for (int c4 = 0; c4 < 16; ++c4) {
;       float4 v = crow4[c4], ww = w04[c4];
;       float u[4] = {v.x + ww.x, v.y + ww.y, v.z + ww.z, v.w + ww.w};
; #pragma unroll
;       for (int e = 0; e < 4; ++e) {
;         const float z = -u[e];
;         const float sp = fmaxf(z, 0.f) + log1pf(__expf(-fabsf(z)));
;         u[e] = __expf(-__expf(-sp - 0.5f));
;       }
;       W4[c4] = make_float4(u[0], u[1], u[2], u[3]);
	v_add_f32_e32 v2, v6, v2
	v_mul_f32_e64 v6, |v2|, s7
	v_exp_f32_e32 v6, v6
	v_add_f32_e32 v4, v8, v4
	v_max_f32_e64 v8, -v2, 0
	v_add_f32_e32 v7, v7, v3
	v_add_f32_e32 v13, 1.0, v6
	v_add_f32_e32 v2, -1.0, v13
	v_sub_f32_e32 v3, v2, v13
	v_add_f32_e32 v3, 1.0, v3
	v_sub_f32_e32 v2, v6, v2
	v_add_f32_e32 v14, v2, v3
	v_frexp_mant_f32_e32 v2, v13
	v_cmp_gt_f32_e32 vcc, s8, v2
	v_cvt_f64_f32_e32 v[2:3], v13
	v_frexp_exp_i32_f64_e32 v2, v[2:3]
	v_subbrev_co_u32_e32 v2, vcc, 0, v2, vcc
	v_sub_u32_e32 v3, 0, v2
	v_ldexp_f32 v13, v13, v3
	v_ldexp_f32 v3, v14, v3
	v_add_f32_e32 v14, -1.0, v13
	v_add_f32_e32 v17, 1.0, v13
	v_add_f32_e32 v15, 1.0, v14
	v_add_f32_e32 v18, -1.0, v17
	v_sub_f32_e32 v15, v13, v15
	v_sub_f32_e32 v13, v13, v18
	v_add_f32_e32 v15, v3, v15
	v_add_f32_e32 v3, v3, v13
	v_add_f32_e32 v13, v17, v3
	v_rcp_f32_e32 v18, v13
	v_add_f32_e32 v16, v14, v15
	v_sub_f32_e32 v14, v16, v14
	v_sub_f32_e32 v14, v15, v14
	v_sub_f32_e32 v15, v13, v17
	v_sub_f32_e32 v3, v3, v15
	v_mul_f32_e32 v15, v16, v18
	v_mul_f32_e32 v17, v13, v15
	v_fma_f32 v19, v15, v13, -v17
	v_fmac_f32_e32 v19, v15, v3
	v_add_f32_e32 v20, v17, v19
	v_sub_f32_e32 v21, v16, v20
	v_sub_f32_e32 v16, v16, v21
	v_sub_f32_e32 v17, v20, v17
	v_sub_f32_e32 v16, v16, v20
	v_add_f32_e32 v14, v14, v16
	v_sub_f32_e32 v16, v17, v19
	v_add_f32_e32 v14, v16, v14
	v_add_f32_e32 v16, v21, v14
	v_mul_f32_e32 v17, v18, v16
	v_mul_f32_e32 v19, v13, v17
	v_fma_f32 v13, v17, v13, -v19
	v_fmac_f32_e32 v13, v17, v3
	v_sub_f32_e32 v3, v21, v16
	v_add_f32_e32 v3, v14, v3
	v_add_f32_e32 v14, v19, v13
	v_sub_f32_e32 v20, v16, v14
	v_sub_f32_e32 v16, v16, v20
	v_sub_f32_e32 v19, v14, v19
	v_sub_f32_e32 v14, v16, v14
	v_add_f32_e32 v3, v3, v14
	v_sub_f32_e32 v13, v19, v13
	v_cvt_f32_i32_e32 v2, v2
	v_add_f32_e32 v3, v13, v3
	v_add_f32_e32 v13, v15, v17
	v_add_f32_e32 v3, v20, v3
	v_sub_f32_e32 v14, v13, v15
	v_mul_f32_e32 v3, v18, v3
	v_sub_f32_e32 v14, v17, v14
	v_add_f32_e32 v3, v14, v3
	v_mul_f32_e32 v17, 0x3f317218, v2
	v_add_f32_e32 v14, v13, v3
	v_fma_f32 v18, v2, s9, -v17
	v_mul_f32_e32 v15, v14, v14
	v_fmac_f32_e32 v18, 0xb102e308, v2
	v_sub_f32_e32 v2, v14, v13
	v_fmamk_f32 v16, v15, 0x3e9b6dac, v231
	v_sub_f32_e32 v2, v3, v2
	v_add_f32_e32 v3, v17, v18
	v_fmaak_f32 v16, v15, v16, 0x3f2aaada
	v_sub_f32_e32 v13, v3, v17
	v_ldexp_f32 v17, v14, 1
	v_mul_f32_e32 v14, v14, v15
	v_mul_f32_e32 v14, v14, v16
	v_add_f32_e32 v15, v17, v14
	v_sub_f32_e32 v16, v15, v17
	v_ldexp_f32 v2, v2, 1
	v_sub_f32_e32 v14, v14, v16
	v_add_f32_e32 v2, v2, v14
	v_add_f32_e32 v14, v15, v2
	v_sub_f32_e32 v15, v14, v15
	v_sub_f32_e32 v2, v2, v15
	v_add_f32_e32 v15, v3, v14
	v_sub_f32_e32 v16, v15, v3
	v_sub_f32_e32 v17, v15, v16
	v_sub_f32_e32 v13, v18, v13
	v_sub_f32_e32 v3, v3, v17
	v_sub_f32_e32 v14, v14, v16
	v_add_f32_e32 v3, v14, v3
	v_add_f32_e32 v14, v13, v2
	v_sub_f32_e32 v16, v14, v13
	v_sub_f32_e32 v17, v14, v16
	v_sub_f32_e32 v13, v13, v17
	v_sub_f32_e32 v2, v2, v16
	v_add_f32_e32 v3, v14, v3
	v_add_f32_e32 v2, v2, v13
	v_add_f32_e32 v13, v15, v3
	v_sub_f32_e32 v14, v13, v15
	v_sub_f32_e32 v3, v3, v14
	v_add_f32_e32 v2, v2, v3
	v_add_f32_e32 v2, v13, v2
	v_cmp_neq_f32_e32 vcc, s6, v6
	v_mul_f32_e64 v3, |v7|, s7
	v_max_f32_e64 v7, -v7, 0
	v_cndmask_b32_e32 v2, v238, v2, vcc
	v_cmp_ngt_f32_e32 vcc, -1.0, v6
	s_nop 1
	v_cndmask_b32_e32 v2, v239, v2, vcc
	v_cmp_neq_f32_e32 vcc, -1.0, v6
	s_nop 1
	v_cndmask_b32_e32 v2, v240, v2, vcc
	v_cmp_lt_f32_e64 vcc, |v6|, s10
	s_nop 1
	v_cndmask_b32_e32 v2, v2, v6, vcc
	v_add_f32_e32 v2, v8, v2
	v_sub_f32_e32 v2, -0.5, v2
	v_mul_f32_e32 v2, 0x3fb8aa3b, v2
	v_exp_f32_e32 v6, v3
	v_exp_f32_e32 v2, v2
	v_add_f32_e32 v8, v9, v5
	v_add_f32_e32 v9, 1.0, v6
	v_mul_f32_e32 v5, 0xbfb8aa3b, v2
	v_add_f32_e32 v2, -1.0, v9
	v_sub_f32_e32 v3, v2, v9
	v_add_f32_e32 v3, 1.0, v3
	v_sub_f32_e32 v2, v6, v2
	v_add_f32_e32 v13, v2, v3
	v_frexp_mant_f32_e32 v2, v9
	v_cmp_gt_f32_e32 vcc, s8, v2
	v_cvt_f64_f32_e32 v[2:3], v9
	v_frexp_exp_i32_f64_e32 v2, v[2:3]
	v_subbrev_co_u32_e32 v2, vcc, 0, v2, vcc
	v_sub_u32_e32 v3, 0, v2
	v_ldexp_f32 v9, v9, v3
	v_ldexp_f32 v3, v13, v3
	v_add_f32_e32 v13, -1.0, v9
	v_add_f32_e32 v16, 1.0, v9
	v_add_f32_e32 v14, 1.0, v13
	v_add_f32_e32 v17, -1.0, v16
	v_sub_f32_e32 v14, v9, v14
	v_sub_f32_e32 v9, v9, v17
	v_add_f32_e32 v14, v3, v14
	v_add_f32_e32 v3, v3, v9
	v_add_f32_e32 v9, v16, v3
	v_rcp_f32_e32 v17, v9
	v_add_f32_e32 v15, v13, v14
	v_sub_f32_e32 v13, v15, v13
	v_sub_f32_e32 v13, v14, v13
	v_sub_f32_e32 v14, v9, v16
	v_sub_f32_e32 v3, v3, v14
	v_mul_f32_e32 v14, v15, v17
	v_mul_f32_e32 v16, v9, v14
	v_fma_f32 v18, v14, v9, -v16
	v_fmac_f32_e32 v18, v14, v3
	v_add_f32_e32 v19, v16, v18
	v_sub_f32_e32 v20, v15, v19
	v_sub_f32_e32 v15, v15, v20
	v_sub_f32_e32 v16, v19, v16
	v_sub_f32_e32 v15, v15, v19
	v_add_f32_e32 v13, v13, v15
	v_sub_f32_e32 v15, v16, v18
	v_add_f32_e32 v13, v15, v13
	v_add_f32_e32 v15, v20, v13
	v_mul_f32_e32 v16, v17, v15
	v_mul_f32_e32 v18, v9, v16
	v_fma_f32 v9, v16, v9, -v18
	v_fmac_f32_e32 v9, v16, v3
	v_sub_f32_e32 v3, v20, v15
	v_add_f32_e32 v3, v13, v3
	v_add_f32_e32 v13, v18, v9
	v_sub_f32_e32 v19, v15, v13
	v_sub_f32_e32 v15, v15, v19
	v_sub_f32_e32 v18, v13, v18
	v_sub_f32_e32 v13, v15, v13
	v_add_f32_e32 v3, v3, v13
	v_sub_f32_e32 v9, v18, v9
	v_cvt_f32_i32_e32 v2, v2
	v_add_f32_e32 v3, v9, v3
	v_add_f32_e32 v9, v14, v16
	v_add_f32_e32 v3, v19, v3
	v_sub_f32_e32 v13, v9, v14
	v_mul_f32_e32 v3, v17, v3
	v_sub_f32_e32 v13, v16, v13
	v_add_f32_e32 v3, v13, v3
	v_mul_f32_e32 v16, 0x3f317218, v2
	v_add_f32_e32 v13, v9, v3
	v_fma_f32 v17, v2, s9, -v16
	v_mul_f32_e32 v14, v13, v13
	v_fmac_f32_e32 v17, 0xb102e308, v2
; template <int MODE, bool BIG = false> DI void gemm_tile(const Params& p, int tm, int tn, int kv, char* smem) {
;     ...
;     for (int c4 = 0; c4 < 16; ++c4) {
;       float4 v = crow4[c4], ww = w04[c4];
;       float u[4] = {v.x + ww.x, v.y + ww.y, v.z + ww.z, v.w + ww.w};
; #pragma unroll
;       for (int e = 0; e < 4; ++e) {
;         const float z = -u[e];
;         const float sp = fmaxf(z, 0.f) + log1pf(__expf(-fabsf(z)));
;         u[e] = __expf(-__expf(-sp - 0.5f));
;       }
;       W4[c4] = make_float4(u[0], u[1], u[2], u[3]);
	v_sub_f32_e32 v2, v13, v9
	v_fmamk_f32 v15, v14, 0x3e9b6dac, v231
	v_sub_f32_e32 v2, v3, v2
	v_add_f32_e32 v3, v16, v17
	v_fmaak_f32 v15, v14, v15, 0x3f2aaada
	v_sub_f32_e32 v9, v3, v16
	v_ldexp_f32 v16, v13, 1
	v_mul_f32_e32 v13, v13, v14
	v_mul_f32_e32 v13, v13, v15
	v_add_f32_e32 v14, v16, v13
	v_sub_f32_e32 v15, v14, v16
	v_ldexp_f32 v2, v2, 1
	v_sub_f32_e32 v13, v13, v15
	v_add_f32_e32 v2, v2, v13
	v_add_f32_e32 v13, v14, v2
	v_sub_f32_e32 v14, v13, v14
	v_sub_f32_e32 v2, v2, v14
	v_add_f32_e32 v14, v3, v13
	v_sub_f32_e32 v15, v14, v3
	v_sub_f32_e32 v16, v14, v15
	v_sub_f32_e32 v9, v17, v9
	v_sub_f32_e32 v3, v3, v16
	v_sub_f32_e32 v13, v13, v15
	v_add_f32_e32 v3, v13, v3
	v_add_f32_e32 v13, v9, v2
	v_sub_f32_e32 v15, v13, v9
	v_sub_f32_e32 v16, v13, v15
	v_sub_f32_e32 v9, v9, v16
	v_sub_f32_e32 v2, v2, v15
	v_add_f32_e32 v3, v13, v3
	v_add_f32_e32 v2, v2, v9
	v_add_f32_e32 v9, v14, v3
	v_sub_f32_e32 v13, v9, v14
	v_sub_f32_e32 v3, v3, v13
	v_add_f32_e32 v2, v2, v3
	v_add_f32_e32 v2, v9, v2
	v_cmp_neq_f32_e32 vcc, s6, v6
	s_nop 1
	v_cndmask_b32_e32 v2, v238, v2, vcc
	v_cmp_ngt_f32_e32 vcc, -1.0, v6
	s_nop 1
	v_cndmask_b32_e32 v2, v239, v2, vcc
	v_cmp_neq_f32_e32 vcc, -1.0, v6
	s_nop 1
	v_cndmask_b32_e32 v2, v240, v2, vcc
	v_cmp_lt_f32_e64 vcc, |v6|, s10
	s_nop 1
	v_cndmask_b32_e32 v2, v2, v6, vcc
	v_add_f32_e32 v2, v7, v2
	v_sub_f32_e32 v2, -0.5, v2
	v_mul_f32_e32 v2, 0x3fb8aa3b, v2
	v_exp_f32_e32 v3, v2
	v_mul_f32_e64 v2, |v4|, s7
	v_exp_f32_e32 v6, v2
	v_max_f32_e64 v7, -v4, 0
	v_exp_f32_e32 v2, v5
	v_mul_f32_e32 v3, 0xbfb8aa3b, v3
	v_add_f32_e32 v9, 1.0, v6
	v_add_f32_e32 v4, -1.0, v9
	v_sub_f32_e32 v5, v4, v9
	v_add_f32_e32 v5, 1.0, v5
	v_sub_f32_e32 v4, v6, v4
	v_add_f32_e32 v13, v4, v5
	v_frexp_mant_f32_e32 v4, v9
	v_cmp_gt_f32_e32 vcc, s8, v4
	v_cvt_f64_f32_e32 v[4:5], v9
	v_frexp_exp_i32_f64_e32 v4, v[4:5]
	v_subbrev_co_u32_e32 v4, vcc, 0, v4, vcc
	v_sub_u32_e32 v5, 0, v4
	v_ldexp_f32 v9, v9, v5
	v_ldexp_f32 v5, v13, v5
	v_add_f32_e32 v13, -1.0, v9
	v_add_f32_e32 v16, 1.0, v9
	v_add_f32_e32 v14, 1.0, v13
	v_add_f32_e32 v17, -1.0, v16
	v_sub_f32_e32 v14, v9, v14
	v_sub_f32_e32 v9, v9, v17
	v_add_f32_e32 v14, v5, v14
	v_add_f32_e32 v5, v5, v9
	v_add_f32_e32 v9, v16, v5
	v_rcp_f32_e32 v17, v9
	v_add_f32_e32 v15, v13, v14
	v_sub_f32_e32 v13, v15, v13
	v_sub_f32_e32 v13, v14, v13
	v_sub_f32_e32 v14, v9, v16
	v_sub_f32_e32 v5, v5, v14
	v_mul_f32_e32 v14, v15, v17
	v_mul_f32_e32 v16, v9, v14
	v_fma_f32 v18, v14, v9, -v16
	v_fmac_f32_e32 v18, v14, v5
	v_add_f32_e32 v19, v16, v18
	v_sub_f32_e32 v20, v15, v19
	v_sub_f32_e32 v15, v15, v20
	v_sub_f32_e32 v16, v19, v16
	v_sub_f32_e32 v15, v15, v19
	v_add_f32_e32 v13, v13, v15
	v_sub_f32_e32 v15, v16, v18
	v_add_f32_e32 v13, v15, v13
	v_add_f32_e32 v15, v20, v13
	v_mul_f32_e32 v16, v17, v15
	v_mul_f32_e32 v18, v9, v16
	v_fma_f32 v9, v16, v9, -v18
	v_fmac_f32_e32 v9, v16, v5
	v_sub_f32_e32 v5, v20, v15
	v_add_f32_e32 v5, v13, v5
	v_add_f32_e32 v13, v18, v9
	v_sub_f32_e32 v19, v15, v13
	v_sub_f32_e32 v15, v15, v19
	v_sub_f32_e32 v18, v13, v18
	v_sub_f32_e32 v13, v15, v13
	v_add_f32_e32 v5, v5, v13
	v_sub_f32_e32 v9, v18, v9
	v_cvt_f32_i32_e32 v4, v4
	v_add_f32_e32 v5, v9, v5
	v_add_f32_e32 v9, v14, v16
	v_add_f32_e32 v5, v19, v5
	v_sub_f32_e32 v13, v9, v14
	v_mul_f32_e32 v5, v17, v5
	v_sub_f32_e32 v13, v16, v13
	v_add_f32_e32 v5, v13, v5
	v_mul_f32_e32 v16, 0x3f317218, v4
	v_add_f32_e32 v13, v9, v5
	v_fma_f32 v17, v4, s9, -v16
	v_mul_f32_e32 v14, v13, v13
	v_fmac_f32_e32 v17, 0xb102e308, v4
	v_sub_f32_e32 v4, v13, v9
	v_fmamk_f32 v15, v14, 0x3e9b6dac, v231
	v_sub_f32_e32 v4, v5, v4
	v_add_f32_e32 v5, v16, v17
	v_fmaak_f32 v15, v14, v15, 0x3f2aaada
	v_sub_f32_e32 v9, v5, v16
	v_ldexp_f32 v16, v13, 1
	v_mul_f32_e32 v13, v13, v14
	v_mul_f32_e32 v13, v13, v15
	v_add_f32_e32 v14, v16, v13
	v_sub_f32_e32 v15, v14, v16
	v_ldexp_f32 v4, v4, 1
	v_sub_f32_e32 v13, v13, v15
	v_add_f32_e32 v4, v4, v13
	v_add_f32_e32 v13, v14, v4
	v_sub_f32_e32 v14, v13, v14
	v_sub_f32_e32 v4, v4, v14
	v_add_f32_e32 v14, v5, v13
	v_sub_f32_e32 v15, v14, v5
	v_sub_f32_e32 v16, v14, v15
	v_sub_f32_e32 v9, v17, v9
	v_sub_f32_e32 v5, v5, v16
	v_sub_f32_e32 v13, v13, v15
	v_add_f32_e32 v5, v13, v5
	v_add_f32_e32 v13, v9, v4
	v_sub_f32_e32 v15, v13, v9
	v_sub_f32_e32 v16, v13, v15
	v_sub_f32_e32 v9, v9, v16
	v_sub_f32_e32 v4, v4, v15
	v_add_f32_e32 v5, v13, v5
	v_add_f32_e32 v4, v4, v9
	v_add_f32_e32 v9, v14, v5
	v_sub_f32_e32 v13, v9, v14
	v_sub_f32_e32 v5, v5, v13
	v_add_f32_e32 v4, v4, v5
	v_add_f32_e32 v4, v9, v4
	v_cmp_neq_f32_e32 vcc, s6, v6
	v_mul_f32_e64 v5, |v8|, s7
	v_max_f32_e64 v8, -v8, 0
	v_cndmask_b32_e32 v4, v238, v4, vcc
	v_cmp_ngt_f32_e32 vcc, -1.0, v6
	v_exp_f32_e32 v3, v3
	s_nop 0
	v_cndmask_b32_e32 v4, v239, v4, vcc
	v_cmp_neq_f32_e32 vcc, -1.0, v6
	s_nop 1
	v_cndmask_b32_e32 v4, v240, v4, vcc
	v_cmp_lt_f32_e64 vcc, |v6|, s10
	s_nop 1
	v_cndmask_b32_e32 v4, v4, v6, vcc
	v_exp_f32_e32 v6, v5
	v_add_f32_e32 v4, v7, v4
	v_sub_f32_e32 v4, -0.5, v4
	v_mul_f32_e32 v4, 0x3fb8aa3b, v4
	v_add_f32_e32 v9, 1.0, v6
	v_exp_f32_e32 v7, v4
	v_add_f32_e32 v4, -1.0, v9
	v_sub_f32_e32 v5, v4, v9
	v_add_f32_e32 v5, 1.0, v5
	v_sub_f32_e32 v4, v6, v4
	v_add_f32_e32 v13, v4, v5
	v_frexp_mant_f32_e32 v4, v9
	v_cmp_gt_f32_e32 vcc, s8, v4
	v_cvt_f64_f32_e32 v[4:5], v9
	v_frexp_exp_i32_f64_e32 v4, v[4:5]
	v_subbrev_co_u32_e32 v4, vcc, 0, v4, vcc
	v_sub_u32_e32 v5, 0, v4
	v_ldexp_f32 v9, v9, v5
	v_ldexp_f32 v5, v13, v5
	v_add_f32_e32 v13, -1.0, v9
	v_add_f32_e32 v16, 1.0, v9
	v_add_f32_e32 v14, 1.0, v13
	v_add_f32_e32 v17, -1.0, v16
	v_sub_f32_e32 v14, v9, v14
	v_sub_f32_e32 v9, v9, v17
	v_add_f32_e32 v14, v5, v14
	v_add_f32_e32 v5, v5, v9
; template <int MODE, bool BIG = false> DI void gemm_tile(const Params& p, int tm, int tn, int kv, char* smem) {
;     ...
;     for (int c4 = 0; c4 < 16; ++c4) {
;       float4 v = crow4[c4], ww = w04[c4];
;       float u[4] = {v.x + ww.x, v.y + ww.y, v.z + ww.z, v.w + ww.w};
; #pragma unroll
;       for (int e = 0; e < 4; ++e) {
;         const float z = -u[e];
;         const float sp = fmaxf(z, 0.f) + log1pf(__expf(-fabsf(z)));
;         u[e] = __expf(-__expf(-sp - 0.5f));
;       }
;       W4[c4] = make_float4(u[0], u[1], u[2], u[3]);
	v_add_f32_e32 v9, v16, v5
	v_rcp_f32_e32 v17, v9
	v_add_f32_e32 v15, v13, v14
	v_sub_f32_e32 v13, v15, v13
	v_sub_f32_e32 v13, v14, v13
	v_sub_f32_e32 v14, v9, v16
	v_sub_f32_e32 v5, v5, v14
	v_mul_f32_e32 v14, v15, v17
	v_mul_f32_e32 v16, v9, v14
	v_fma_f32 v18, v14, v9, -v16
	v_fmac_f32_e32 v18, v14, v5
	v_add_f32_e32 v19, v16, v18
	v_sub_f32_e32 v20, v15, v19
	v_sub_f32_e32 v15, v15, v20
	v_sub_f32_e32 v16, v19, v16
	v_sub_f32_e32 v15, v15, v19
	v_add_f32_e32 v13, v13, v15
	v_sub_f32_e32 v15, v16, v18
	v_add_f32_e32 v13, v15, v13
	v_add_f32_e32 v15, v20, v13
	v_mul_f32_e32 v16, v17, v15
	v_mul_f32_e32 v18, v9, v16
	v_fma_f32 v9, v16, v9, -v18
	v_fmac_f32_e32 v9, v16, v5
	v_sub_f32_e32 v5, v20, v15
	v_add_f32_e32 v5, v13, v5
	v_add_f32_e32 v13, v18, v9
	v_sub_f32_e32 v19, v15, v13
	v_sub_f32_e32 v15, v15, v19
	v_sub_f32_e32 v18, v13, v18
	v_sub_f32_e32 v13, v15, v13
	v_add_f32_e32 v5, v5, v13
	v_sub_f32_e32 v9, v18, v9
	v_cvt_f32_i32_e32 v4, v4
	v_add_f32_e32 v5, v9, v5
	v_add_f32_e32 v9, v14, v16
	v_add_f32_e32 v5, v19, v5
	v_sub_f32_e32 v13, v9, v14
	v_mul_f32_e32 v5, v17, v5
	v_sub_f32_e32 v13, v16, v13
	v_add_f32_e32 v5, v13, v5
	v_mul_f32_e32 v16, 0x3f317218, v4
	v_add_f32_e32 v13, v9, v5
	v_fma_f32 v17, v4, s9, -v16
	v_mul_f32_e32 v14, v13, v13
	v_fmac_f32_e32 v17, 0xb102e308, v4
	v_sub_f32_e32 v4, v13, v9
	v_fmamk_f32 v15, v14, 0x3e9b6dac, v231
	v_sub_f32_e32 v4, v5, v4
	v_add_f32_e32 v5, v16, v17
	v_fmaak_f32 v15, v14, v15, 0x3f2aaada
	v_sub_f32_e32 v9, v5, v16
	v_ldexp_f32 v16, v13, 1
	v_mul_f32_e32 v13, v13, v14
	v_mul_f32_e32 v13, v13, v15
	v_add_f32_e32 v14, v16, v13
	v_sub_f32_e32 v15, v14, v16
	v_ldexp_f32 v4, v4, 1
	v_sub_f32_e32 v13, v13, v15
	v_add_f32_e32 v4, v4, v13
	v_add_f32_e32 v13, v14, v4
	v_sub_f32_e32 v14, v13, v14
	v_sub_f32_e32 v4, v4, v14
	v_add_f32_e32 v14, v5, v13
	v_sub_f32_e32 v15, v14, v5
	v_sub_f32_e32 v16, v14, v15
	v_sub_f32_e32 v9, v17, v9
	v_sub_f32_e32 v5, v5, v16
	v_sub_f32_e32 v13, v13, v15
	v_add_f32_e32 v5, v13, v5
	v_add_f32_e32 v13, v9, v4
	v_sub_f32_e32 v15, v13, v9
	v_sub_f32_e32 v16, v13, v15
	v_sub_f32_e32 v9, v9, v16
	v_sub_f32_e32 v4, v4, v15
	v_add_f32_e32 v5, v13, v5
	v_add_f32_e32 v4, v4, v9
	v_add_f32_e32 v9, v14, v5
	v_sub_f32_e32 v13, v9, v14
	v_sub_f32_e32 v5, v5, v13
	v_add_f32_e32 v4, v4, v5
	v_add_f32_e32 v4, v9, v4
	v_cmp_neq_f32_e32 vcc, s6, v6
	s_nop 1
	v_cndmask_b32_e32 v4, v238, v4, vcc
	v_cmp_ngt_f32_e32 vcc, -1.0, v6
	s_nop 1
	v_cndmask_b32_e32 v4, v239, v4, vcc
	v_cmp_neq_f32_e32 vcc, -1.0, v6
	s_nop 1
	v_cndmask_b32_e32 v4, v240, v4, vcc
	v_cmp_lt_f32_e64 vcc, |v6|, s10
	s_nop 1
	v_cndmask_b32_e32 v4, v4, v6, vcc
	v_add_f32_e32 v4, v8, v4
	v_sub_f32_e32 v4, -0.5, v4
	v_mul_f32_e32 v4, 0x3fb8aa3b, v4
	v_exp_f32_e32 v5, v4
	v_mul_f32_e32 v4, 0xbfb8aa3b, v7
	v_exp_f32_e32 v4, v4
	ds_read_b128 v[6:9], v12 offset:160
	v_mul_f32_e32 v5, 0xbfb8aa3b, v5
	v_exp_f32_e32 v5, v5
	ds_write_b128 v75, v[2:5] offset:144
	ds_read_b128 v[2:5], v74 offset:160
	s_waitcnt lgkmcnt(0)
	v_add_f32_e32 v2, v6, v2
	v_mul_f32_e64 v6, |v2|, s7
	v_exp_f32_e32 v6, v6
	v_add_f32_e32 v4, v8, v4
	v_max_f32_e64 v8, -v2, 0
	v_add_f32_e32 v7, v7, v3
	v_add_f32_e32 v13, 1.0, v6
	v_add_f32_e32 v2, -1.0, v13
	v_sub_f32_e32 v3, v2, v13
	v_add_f32_e32 v3, 1.0, v3
	v_sub_f32_e32 v2, v6, v2
	v_add_f32_e32 v14, v2, v3
	v_frexp_mant_f32_e32 v2, v13
	v_cmp_gt_f32_e32 vcc, s8, v2
	v_cvt_f64_f32_e32 v[2:3], v13
	v_frexp_exp_i32_f64_e32 v2, v[2:3]
	v_subbrev_co_u32_e32 v2, vcc, 0, v2, vcc
	v_sub_u32_e32 v3, 0, v2
	v_ldexp_f32 v13, v13, v3
	v_ldexp_f32 v3, v14, v3
	v_add_f32_e32 v14, -1.0, v13
	v_add_f32_e32 v17, 1.0, v13
	v_add_f32_e32 v15, 1.0, v14
	v_add_f32_e32 v18, -1.0, v17
	v_sub_f32_e32 v15, v13, v15
	v_sub_f32_e32 v13, v13, v18
	v_add_f32_e32 v15, v3, v15
	v_add_f32_e32 v3, v3, v13
	v_add_f32_e32 v13, v17, v3
	v_rcp_f32_e32 v18, v13
	v_add_f32_e32 v16, v14, v15
	v_sub_f32_e32 v14, v16, v14
	v_sub_f32_e32 v14, v15, v14
	v_sub_f32_e32 v15, v13, v17
	v_sub_f32_e32 v3, v3, v15
	v_mul_f32_e32 v15, v16, v18
	v_mul_f32_e32 v17, v13, v15
	v_fma_f32 v19, v15, v13, -v17
	v_fmac_f32_e32 v19, v15, v3
	v_add_f32_e32 v20, v17, v19
	v_sub_f32_e32 v21, v16, v20
	v_sub_f32_e32 v16, v16, v21
	v_sub_f32_e32 v17, v20, v17
	v_sub_f32_e32 v16, v16, v20
	v_add_f32_e32 v14, v14, v16
	v_sub_f32_e32 v16, v17, v19
	v_add_f32_e32 v14, v16, v14
	v_add_f32_e32 v16, v21, v14
	v_mul_f32_e32 v17, v18, v16
	v_mul_f32_e32 v19, v13, v17
	v_fma_f32 v13, v17, v13, -v19
	v_fmac_f32_e32 v13, v17, v3
	v_sub_f32_e32 v3, v21, v16
	v_add_f32_e32 v3, v14, v3
	v_add_f32_e32 v14, v19, v13
	v_sub_f32_e32 v20, v16, v14
	v_sub_f32_e32 v16, v16, v20
	v_sub_f32_e32 v19, v14, v19
	v_sub_f32_e32 v14, v16, v14
	v_add_f32_e32 v3, v3, v14
	v_sub_f32_e32 v13, v19, v13
	v_cvt_f32_i32_e32 v2, v2
	v_add_f32_e32 v3, v13, v3
	v_add_f32_e32 v13, v15, v17
	v_add_f32_e32 v3, v20, v3
	v_sub_f32_e32 v14, v13, v15
	v_mul_f32_e32 v3, v18, v3
	v_sub_f32_e32 v14, v17, v14
	v_add_f32_e32 v3, v14, v3
	v_mul_f32_e32 v17, 0x3f317218, v2
	v_add_f32_e32 v14, v13, v3
	v_fma_f32 v18, v2, s9, -v17
	v_mul_f32_e32 v15, v14, v14
	v_fmac_f32_e32 v18, 0xb102e308, v2
	v_sub_f32_e32 v2, v14, v13
	v_fmamk_f32 v16, v15, 0x3e9b6dac, v231
	v_sub_f32_e32 v2, v3, v2
	v_add_f32_e32 v3, v17, v18
	v_fmaak_f32 v16, v15, v16, 0x3f2aaada
	v_sub_f32_e32 v13, v3, v17
	v_ldexp_f32 v17, v14, 1
	v_mul_f32_e32 v14, v14, v15
	v_mul_f32_e32 v14, v14, v16
	v_add_f32_e32 v15, v17, v14
	v_sub_f32_e32 v16, v15, v17
	v_ldexp_f32 v2, v2, 1
	v_sub_f32_e32 v14, v14, v16
	v_add_f32_e32 v2, v2, v14
	v_add_f32_e32 v14, v15, v2
	v_sub_f32_e32 v15, v14, v15
	v_sub_f32_e32 v2, v2, v15
	v_add_f32_e32 v15, v3, v14
; template <int MODE, bool BIG = false> DI void gemm_tile(const Params& p, int tm, int tn, int kv, char* smem) {
;     ...
;     for (int c4 = 0; c4 < 16; ++c4) {
;       float4 v = crow4[c4], ww = w04[c4];
;       float u[4] = {v.x + ww.x, v.y + ww.y, v.z + ww.z, v.w + ww.w};
; #pragma unroll
;       for (int e = 0; e < 4; ++e) {
;         const float z = -u[e];
;         const float sp = fmaxf(z, 0.f) + log1pf(__expf(-fabsf(z)));
;         u[e] = __expf(-__expf(-sp - 0.5f));
;       }
;       W4[c4] = make_float4(u[0], u[1], u[2], u[3]);
	v_sub_f32_e32 v16, v15, v3
	v_sub_f32_e32 v17, v15, v16
	v_sub_f32_e32 v13, v18, v13
	v_sub_f32_e32 v3, v3, v17
	v_sub_f32_e32 v14, v14, v16
	v_add_f32_e32 v3, v14, v3
	v_add_f32_e32 v14, v13, v2
	v_sub_f32_e32 v16, v14, v13
	v_sub_f32_e32 v17, v14, v16
	v_sub_f32_e32 v13, v13, v17
	v_sub_f32_e32 v2, v2, v16
	v_add_f32_e32 v3, v14, v3
	v_add_f32_e32 v2, v2, v13
	v_add_f32_e32 v13, v15, v3
	v_sub_f32_e32 v14, v13, v15
	v_sub_f32_e32 v3, v3, v14
	v_add_f32_e32 v2, v2, v3
	v_add_f32_e32 v2, v13, v2
	v_cmp_neq_f32_e32 vcc, s6, v6
	v_mul_f32_e64 v3, |v7|, s7
	v_max_f32_e64 v7, -v7, 0
	v_cndmask_b32_e32 v2, v238, v2, vcc
	v_cmp_ngt_f32_e32 vcc, -1.0, v6
	s_nop 1
	v_cndmask_b32_e32 v2, v239, v2, vcc
	v_cmp_neq_f32_e32 vcc, -1.0, v6
	s_nop 1
	v_cndmask_b32_e32 v2, v240, v2, vcc
	v_cmp_lt_f32_e64 vcc, |v6|, s10
	s_nop 1
	v_cndmask_b32_e32 v2, v2, v6, vcc
	v_add_f32_e32 v2, v8, v2
	v_sub_f32_e32 v2, -0.5, v2
	v_mul_f32_e32 v2, 0x3fb8aa3b, v2
	v_exp_f32_e32 v6, v3
	v_exp_f32_e32 v2, v2
	v_add_f32_e32 v8, v9, v5
	v_add_f32_e32 v9, 1.0, v6
	v_mul_f32_e32 v5, 0xbfb8aa3b, v2
	v_add_f32_e32 v2, -1.0, v9
	v_sub_f32_e32 v3, v2, v9
	v_add_f32_e32 v3, 1.0, v3
	v_sub_f32_e32 v2, v6, v2
	v_add_f32_e32 v13, v2, v3
	v_frexp_mant_f32_e32 v2, v9
	v_cmp_gt_f32_e32 vcc, s8, v2
	v_cvt_f64_f32_e32 v[2:3], v9
	v_frexp_exp_i32_f64_e32 v2, v[2:3]
	v_subbrev_co_u32_e32 v2, vcc, 0, v2, vcc
	v_sub_u32_e32 v3, 0, v2
	v_ldexp_f32 v9, v9, v3
	v_ldexp_f32 v3, v13, v3
	v_add_f32_e32 v13, -1.0, v9
	v_add_f32_e32 v16, 1.0, v9
	v_add_f32_e32 v14, 1.0, v13
	v_add_f32_e32 v17, -1.0, v16
	v_sub_f32_e32 v14, v9, v14
	v_sub_f32_e32 v9, v9, v17
	v_add_f32_e32 v14, v3, v14
	v_add_f32_e32 v3, v3, v9
	v_add_f32_e32 v9, v16, v3
	v_rcp_f32_e32 v17, v9
	v_add_f32_e32 v15, v13, v14
	v_sub_f32_e32 v13, v15, v13
	v_sub_f32_e32 v13, v14, v13
	v_sub_f32_e32 v14, v9, v16
	v_sub_f32_e32 v3, v3, v14
	v_mul_f32_e32 v14, v15, v17
	v_mul_f32_e32 v16, v9, v14
	v_fma_f32 v18, v14, v9, -v16
	v_fmac_f32_e32 v18, v14, v3
	v_add_f32_e32 v19, v16, v18
	v_sub_f32_e32 v20, v15, v19
	v_sub_f32_e32 v15, v15, v20
	v_sub_f32_e32 v16, v19, v16
	v_sub_f32_e32 v15, v15, v19
	v_add_f32_e32 v13, v13, v15
	v_sub_f32_e32 v15, v16, v18
	v_add_f32_e32 v13, v15, v13
	v_add_f32_e32 v15, v20, v13
	v_mul_f32_e32 v16, v17, v15
	v_mul_f32_e32 v18, v9, v16
	v_fma_f32 v9, v16, v9, -v18
	v_fmac_f32_e32 v9, v16, v3
	v_sub_f32_e32 v3, v20, v15
	v_add_f32_e32 v3, v13, v3
	v_add_f32_e32 v13, v18, v9
	v_sub_f32_e32 v19, v15, v13
	v_sub_f32_e32 v15, v15, v19
	v_sub_f32_e32 v18, v13, v18
	v_sub_f32_e32 v13, v15, v13
	v_add_f32_e32 v3, v3, v13
	v_sub_f32_e32 v9, v18, v9
	v_cvt_f32_i32_e32 v2, v2
	v_add_f32_e32 v3, v9, v3
	v_add_f32_e32 v9, v14, v16
	v_add_f32_e32 v3, v19, v3
	v_sub_f32_e32 v13, v9, v14
	v_mul_f32_e32 v3, v17, v3
	v_sub_f32_e32 v13, v16, v13
	v_add_f32_e32 v3, v13, v3
	v_mul_f32_e32 v16, 0x3f317218, v2
	v_add_f32_e32 v13, v9, v3
	v_fma_f32 v17, v2, s9, -v16
	v_mul_f32_e32 v14, v13, v13
	v_fmac_f32_e32 v17, 0xb102e308, v2
	v_sub_f32_e32 v2, v13, v9
	v_fmamk_f32 v15, v14, 0x3e9b6dac, v231
	v_sub_f32_e32 v2, v3, v2
	v_add_f32_e32 v3, v16, v17
	v_fmaak_f32 v15, v14, v15, 0x3f2aaada
	v_sub_f32_e32 v9, v3, v16
	v_ldexp_f32 v16, v13, 1
	v_mul_f32_e32 v13, v13, v14
	v_mul_f32_e32 v13, v13, v15
	v_add_f32_e32 v14, v16, v13
	v_sub_f32_e32 v15, v14, v16
	v_ldexp_f32 v2, v2, 1
	v_sub_f32_e32 v13, v13, v15
	v_add_f32_e32 v2, v2, v13
	v_add_f32_e32 v13, v14, v2
	v_sub_f32_e32 v14, v13, v14
	v_sub_f32_e32 v2, v2, v14
	v_add_f32_e32 v14, v3, v13
	v_sub_f32_e32 v15, v14, v3
	v_sub_f32_e32 v16, v14, v15
	v_sub_f32_e32 v9, v17, v9
	v_sub_f32_e32 v3, v3, v16
	v_sub_f32_e32 v13, v13, v15
	v_add_f32_e32 v3, v13, v3
	v_add_f32_e32 v13, v9, v2
	v_sub_f32_e32 v15, v13, v9
	v_sub_f32_e32 v16, v13, v15
	v_sub_f32_e32 v9, v9, v16
	v_sub_f32_e32 v2, v2, v15
	v_add_f32_e32 v3, v13, v3
	v_add_f32_e32 v2, v2, v9
	v_add_f32_e32 v9, v14, v3
	v_sub_f32_e32 v13, v9, v14
	v_sub_f32_e32 v3, v3, v13
	v_add_f32_e32 v2, v2, v3
	v_add_f32_e32 v2, v9, v2
	v_cmp_neq_f32_e32 vcc, s6, v6
	s_nop 1
	v_cndmask_b32_e32 v2, v238, v2, vcc
	v_cmp_ngt_f32_e32 vcc, -1.0, v6
	s_nop 1
	v_cndmask_b32_e32 v2, v239, v2, vcc
	v_cmp_neq_f32_e32 vcc, -1.0, v6
	s_nop 1
	v_cndmask_b32_e32 v2, v240, v2, vcc
	v_cmp_lt_f32_e64 vcc, |v6|, s10
	s_nop 1
	v_cndmask_b32_e32 v2, v2, v6, vcc
	v_add_f32_e32 v2, v7, v2
	v_sub_f32_e32 v2, -0.5, v2
	v_mul_f32_e32 v2, 0x3fb8aa3b, v2
	v_exp_f32_e32 v3, v2
	v_mul_f32_e64 v2, |v4|, s7
	v_exp_f32_e32 v6, v2
	v_max_f32_e64 v7, -v4, 0
	v_exp_f32_e32 v2, v5
	v_mul_f32_e32 v3, 0xbfb8aa3b, v3
	v_add_f32_e32 v9, 1.0, v6
	v_add_f32_e32 v4, -1.0, v9
	v_sub_f32_e32 v5, v4, v9
	v_add_f32_e32 v5, 1.0, v5
	v_sub_f32_e32 v4, v6, v4
	v_add_f32_e32 v13, v4, v5
	v_frexp_mant_f32_e32 v4, v9
	v_cmp_gt_f32_e32 vcc, s8, v4
	v_cvt_f64_f32_e32 v[4:5], v9
	v_frexp_exp_i32_f64_e32 v4, v[4:5]
	v_subbrev_co_u32_e32 v4, vcc, 0, v4, vcc
	v_sub_u32_e32 v5, 0, v4
	v_ldexp_f32 v9, v9, v5
	v_ldexp_f32 v5, v13, v5
	v_add_f32_e32 v13, -1.0, v9
	v_add_f32_e32 v16, 1.0, v9
	v_add_f32_e32 v14, 1.0, v13
	v_add_f32_e32 v17, -1.0, v16
	v_sub_f32_e32 v14, v9, v14
	v_sub_f32_e32 v9, v9, v17
	v_add_f32_e32 v14, v5, v14
	v_add_f32_e32 v5, v5, v9
	v_add_f32_e32 v9, v16, v5
	v_rcp_f32_e32 v17, v9
	v_add_f32_e32 v15, v13, v14
	v_sub_f32_e32 v13, v15, v13
	v_sub_f32_e32 v13, v14, v13
	v_sub_f32_e32 v14, v9, v16
	v_sub_f32_e32 v5, v5, v14
	v_mul_f32_e32 v14, v15, v17
	v_mul_f32_e32 v16, v9, v14
	v_fma_f32 v18, v14, v9, -v16
	v_fmac_f32_e32 v18, v14, v5
	v_add_f32_e32 v19, v16, v18
	v_sub_f32_e32 v20, v15, v19
	v_sub_f32_e32 v15, v15, v20
	v_sub_f32_e32 v16, v19, v16
	v_sub_f32_e32 v15, v15, v19
; template <int MODE, bool BIG = false> DI void gemm_tile(const Params& p, int tm, int tn, int kv, char* smem) {
;     ...
;     for (int c4 = 0; c4 < 16; ++c4) {
;       float4 v = crow4[c4], ww = w04[c4];
;       float u[4] = {v.x + ww.x, v.y + ww.y, v.z + ww.z, v.w + ww.w};
; #pragma unroll
;       for (int e = 0; e < 4; ++e) {
;         const float z = -u[e];
;         const float sp = fmaxf(z, 0.f) + log1pf(__expf(-fabsf(z)));
;         u[e] = __expf(-__expf(-sp - 0.5f));
;       }
;       W4[c4] = make_float4(u[0], u[1], u[2], u[3]);
	v_add_f32_e32 v13, v13, v15
	v_sub_f32_e32 v15, v16, v18
	v_add_f32_e32 v13, v15, v13
	v_add_f32_e32 v15, v20, v13
	v_mul_f32_e32 v16, v17, v15
	v_mul_f32_e32 v18, v9, v16
	v_fma_f32 v9, v16, v9, -v18
	v_fmac_f32_e32 v9, v16, v5
	v_sub_f32_e32 v5, v20, v15
	v_add_f32_e32 v5, v13, v5
	v_add_f32_e32 v13, v18, v9
	v_sub_f32_e32 v19, v15, v13
	v_sub_f32_e32 v15, v15, v19
	v_sub_f32_e32 v18, v13, v18
	v_sub_f32_e32 v13, v15, v13
	v_add_f32_e32 v5, v5, v13
	v_sub_f32_e32 v9, v18, v9
	v_cvt_f32_i32_e32 v4, v4
	v_add_f32_e32 v5, v9, v5
	v_add_f32_e32 v9, v14, v16
	v_add_f32_e32 v5, v19, v5
	v_sub_f32_e32 v13, v9, v14
	v_mul_f32_e32 v5, v17, v5
	v_sub_f32_e32 v13, v16, v13
	v_add_f32_e32 v5, v13, v5
	v_mul_f32_e32 v16, 0x3f317218, v4
	v_add_f32_e32 v13, v9, v5
	v_fma_f32 v17, v4, s9, -v16
	v_mul_f32_e32 v14, v13, v13
	v_fmac_f32_e32 v17, 0xb102e308, v4
	v_sub_f32_e32 v4, v13, v9
	v_fmamk_f32 v15, v14, 0x3e9b6dac, v231
	v_sub_f32_e32 v4, v5, v4
	v_add_f32_e32 v5, v16, v17
	v_fmaak_f32 v15, v14, v15, 0x3f2aaada
	v_sub_f32_e32 v9, v5, v16
	v_ldexp_f32 v16, v13, 1
	v_mul_f32_e32 v13, v13, v14
	v_mul_f32_e32 v13, v13, v15
	v_add_f32_e32 v14, v16, v13
	v_sub_f32_e32 v15, v14, v16
	v_ldexp_f32 v4, v4, 1
	v_sub_f32_e32 v13, v13, v15
	v_add_f32_e32 v4, v4, v13
	v_add_f32_e32 v13, v14, v4
	v_sub_f32_e32 v14, v13, v14
	v_sub_f32_e32 v4, v4, v14
	v_add_f32_e32 v14, v5, v13
	v_sub_f32_e32 v15, v14, v5
	v_sub_f32_e32 v16, v14, v15
	v_sub_f32_e32 v9, v17, v9
	v_sub_f32_e32 v5, v5, v16
	v_sub_f32_e32 v13, v13, v15
	v_add_f32_e32 v5, v13, v5
	v_add_f32_e32 v13, v9, v4
	v_sub_f32_e32 v15, v13, v9
	v_sub_f32_e32 v16, v13, v15
	v_sub_f32_e32 v9, v9, v16
	v_sub_f32_e32 v4, v4, v15
	v_add_f32_e32 v5, v13, v5
	v_add_f32_e32 v4, v4, v9
	v_add_f32_e32 v9, v14, v5
	v_sub_f32_e32 v13, v9, v14
	v_sub_f32_e32 v5, v5, v13
	v_add_f32_e32 v4, v4, v5
	v_add_f32_e32 v4, v9, v4
	v_cmp_neq_f32_e32 vcc, s6, v6
	v_mul_f32_e64 v5, |v8|, s7
	v_max_f32_e64 v8, -v8, 0
	v_cndmask_b32_e32 v4, v238, v4, vcc
	v_cmp_ngt_f32_e32 vcc, -1.0, v6
	v_exp_f32_e32 v3, v3
	s_nop 0
	v_cndmask_b32_e32 v4, v239, v4, vcc
	v_cmp_neq_f32_e32 vcc, -1.0, v6
	s_nop 1
	v_cndmask_b32_e32 v4, v240, v4, vcc
	v_cmp_lt_f32_e64 vcc, |v6|, s10
	s_nop 1
	v_cndmask_b32_e32 v4, v4, v6, vcc
	v_exp_f32_e32 v6, v5
	v_add_f32_e32 v4, v7, v4
	v_sub_f32_e32 v4, -0.5, v4
	v_mul_f32_e32 v4, 0x3fb8aa3b, v4
	v_add_f32_e32 v9, 1.0, v6
	v_exp_f32_e32 v7, v4
	v_add_f32_e32 v4, -1.0, v9
	v_sub_f32_e32 v5, v4, v9
	v_add_f32_e32 v5, 1.0, v5
	v_sub_f32_e32 v4, v6, v4
	v_add_f32_e32 v13, v4, v5
	v_frexp_mant_f32_e32 v4, v9
	v_cmp_gt_f32_e32 vcc, s8, v4
	v_cvt_f64_f32_e32 v[4:5], v9
	v_frexp_exp_i32_f64_e32 v4, v[4:5]
	v_subbrev_co_u32_e32 v4, vcc, 0, v4, vcc
	v_sub_u32_e32 v5, 0, v4
	v_ldexp_f32 v9, v9, v5
	v_ldexp_f32 v5, v13, v5
	v_add_f32_e32 v13, -1.0, v9
	v_add_f32_e32 v16, 1.0, v9
	v_add_f32_e32 v14, 1.0, v13
	v_add_f32_e32 v17, -1.0, v16
	v_sub_f32_e32 v14, v9, v14
	v_sub_f32_e32 v9, v9, v17
	v_add_f32_e32 v14, v5, v14
	v_add_f32_e32 v5, v5, v9
	v_add_f32_e32 v9, v16, v5
	v_rcp_f32_e32 v17, v9
	v_add_f32_e32 v15, v13, v14
	v_sub_f32_e32 v13, v15, v13
	v_sub_f32_e32 v13, v14, v13
	v_sub_f32_e32 v14, v9, v16
	v_sub_f32_e32 v5, v5, v14
	v_mul_f32_e32 v14, v15, v17
	v_mul_f32_e32 v16, v9, v14
	v_fma_f32 v18, v14, v9, -v16
	v_fmac_f32_e32 v18, v14, v5
	v_add_f32_e32 v19, v16, v18
	v_sub_f32_e32 v20, v15, v19
	v_sub_f32_e32 v15, v15, v20
	v_sub_f32_e32 v16, v19, v16
	v_sub_f32_e32 v15, v15, v19
	v_add_f32_e32 v13, v13, v15
	v_sub_f32_e32 v15, v16, v18
	v_add_f32_e32 v13, v15, v13
	v_add_f32_e32 v15, v20, v13
	v_mul_f32_e32 v16, v17, v15
	v_mul_f32_e32 v18, v9, v16
	v_fma_f32 v9, v16, v9, -v18
	v_fmac_f32_e32 v9, v16, v5
	v_sub_f32_e32 v5, v20, v15
	v_add_f32_e32 v5, v13, v5
	v_add_f32_e32 v13, v18, v9
	v_sub_f32_e32 v19, v15, v13
	v_sub_f32_e32 v15, v15, v19
	v_sub_f32_e32 v18, v13, v18
	v_sub_f32_e32 v13, v15, v13
	v_add_f32_e32 v5, v5, v13
	v_sub_f32_e32 v9, v18, v9
	v_cvt_f32_i32_e32 v4, v4
	v_add_f32_e32 v5, v9, v5
	v_add_f32_e32 v9, v14, v16
	v_add_f32_e32 v5, v19, v5
	v_sub_f32_e32 v13, v9, v14
	v_mul_f32_e32 v5, v17, v5
	v_sub_f32_e32 v13, v16, v13
	v_add_f32_e32 v5, v13, v5
	v_mul_f32_e32 v16, 0x3f317218, v4
	v_add_f32_e32 v13, v9, v5
	v_fma_f32 v17, v4, s9, -v16
	v_mul_f32_e32 v14, v13, v13
	v_fmac_f32_e32 v17, 0xb102e308, v4
	v_sub_f32_e32 v4, v13, v9
	v_fmamk_f32 v15, v14, 0x3e9b6dac, v231
	v_sub_f32_e32 v4, v5, v4
	v_add_f32_e32 v5, v16, v17
	v_fmaak_f32 v15, v14, v15, 0x3f2aaada
	v_sub_f32_e32 v9, v5, v16
	v_ldexp_f32 v16, v13, 1
	v_mul_f32_e32 v13, v13, v14
	v_mul_f32_e32 v13, v13, v15
	v_add_f32_e32 v14, v16, v13
	v_sub_f32_e32 v15, v14, v16
	v_ldexp_f32 v4, v4, 1
	v_sub_f32_e32 v13, v13, v15
	v_add_f32_e32 v4, v4, v13
	v_add_f32_e32 v13, v14, v4
	v_sub_f32_e32 v14, v13, v14
	v_sub_f32_e32 v4, v4, v14
	v_add_f32_e32 v14, v5, v13
	v_sub_f32_e32 v15, v14, v5
	v_sub_f32_e32 v16, v14, v15
	v_sub_f32_e32 v9, v17, v9
	v_sub_f32_e32 v5, v5, v16
	v_sub_f32_e32 v13, v13, v15
	v_add_f32_e32 v5, v13, v5
	v_add_f32_e32 v13, v9, v4
	v_sub_f32_e32 v15, v13, v9
	v_sub_f32_e32 v16, v13, v15
	v_sub_f32_e32 v9, v9, v16
	v_sub_f32_e32 v4, v4, v15
	v_add_f32_e32 v5, v13, v5
	v_add_f32_e32 v4, v4, v9
	v_add_f32_e32 v9, v14, v5
	v_sub_f32_e32 v13, v9, v14
	v_sub_f32_e32 v5, v5, v13
	v_add_f32_e32 v4, v4, v5
	v_add_f32_e32 v4, v9, v4
	v_cmp_neq_f32_e32 vcc, s6, v6
	s_nop 1
	v_cndmask_b32_e32 v4, v238, v4, vcc
	v_cmp_ngt_f32_e32 vcc, -1.0, v6
	s_nop 1
	v_cndmask_b32_e32 v4, v239, v4, vcc
	v_cmp_neq_f32_e32 vcc, -1.0, v6
	s_nop 1
	v_cndmask_b32_e32 v4, v240, v4, vcc
	v_cmp_lt_f32_e64 vcc, |v6|, s10
	s_nop 1
	v_cndmask_b32_e32 v4, v4, v6, vcc
	v_add_f32_e32 v4, v8, v4
	v_sub_f32_e32 v4, -0.5, v4
	v_mul_f32_e32 v4, 0x3fb8aa3b, v4
	v_exp_f32_e32 v5, v4
	v_mul_f32_e32 v4, 0xbfb8aa3b, v7
	v_exp_f32_e32 v4, v4
	ds_read_b128 v[6:9], v12 offset:176
	v_mul_f32_e32 v5, 0xbfb8aa3b, v5
	v_exp_f32_e32 v5, v5
	ds_write_b128 v75, v[2:5] offset:160
	ds_read_b128 v[2:5], v74 offset:176
	s_waitcnt lgkmcnt(0)
; template <int MODE, bool BIG = false> DI void gemm_tile(const Params& p, int tm, int tn, int kv, char* smem) {
;     ...
;   } else if constexpr (MODE == G_RWW) {
;     float4* W4 = (float4*)((float*)(p.ws + OFF_BUFA) + (size_t)m * 512 + col0);
;     const float4* w04 = (const float4*)(p.w0 + col0);
; #pragma unroll
;     for (int c4 = 0; c4 < 16; ++c4) {
;       float4 v = crow4[c4], ww = w04[c4];
;       float u[4] = {v.x + ww.x, v.y + ww.y, v.z + ww.z, v.w + ww.w};
; #pragma unroll
;       for (int e = 0; e < 4; ++e) {
;         const float z = -u[e];
;         const float sp = fmaxf(z, 0.f) + log1pf(__expf(-fabsf(z)));
;         u[e] = __expf(-__expf(-sp - 0.5f));
;       }
;       W4[c4] = make_float4(u[0], u[1], u[2], u[3]);
;     }
	v_add_f32_e32 v2, v6, v2
	v_mul_f32_e64 v6, |v2|, s7
	v_exp_f32_e32 v6, v6
	v_add_f32_e32 v4, v8, v4
	v_max_f32_e64 v8, -v2, 0
	v_add_f32_e32 v7, v7, v3
	v_add_f32_e32 v13, 1.0, v6
	v_add_f32_e32 v2, -1.0, v13
	v_sub_f32_e32 v3, v2, v13
	v_add_f32_e32 v3, 1.0, v3
	v_sub_f32_e32 v2, v6, v2
	v_add_f32_e32 v14, v2, v3
	v_frexp_mant_f32_e32 v2, v13
	v_cmp_gt_f32_e32 vcc, s8, v2
	v_cvt_f64_f32_e32 v[2:3], v13
	v_frexp_exp_i32_f64_e32 v2, v[2:3]
	v_subbrev_co_u32_e32 v2, vcc, 0, v2, vcc
	v_sub_u32_e32 v3, 0, v2
	v_ldexp_f32 v13, v13, v3
	v_ldexp_f32 v3, v14, v3
	v_add_f32_e32 v14, -1.0, v13
	v_add_f32_e32 v17, 1.0, v13
	v_add_f32_e32 v15, 1.0, v14
	v_add_f32_e32 v18, -1.0, v17
	v_sub_f32_e32 v15, v13, v15
	v_sub_f32_e32 v13, v13, v18
	v_add_f32_e32 v15, v3, v15
	v_add_f32_e32 v3, v3, v13
	v_add_f32_e32 v13, v17, v3
	v_rcp_f32_e32 v18, v13
	v_add_f32_e32 v16, v14, v15
	v_sub_f32_e32 v14, v16, v14
	v_sub_f32_e32 v14, v15, v14
	v_sub_f32_e32 v15, v13, v17
	v_sub_f32_e32 v3, v3, v15
	v_mul_f32_e32 v15, v16, v18
	v_mul_f32_e32 v17, v13, v15
	v_fma_f32 v19, v15, v13, -v17
	v_fmac_f32_e32 v19, v15, v3
	v_add_f32_e32 v20, v17, v19
	v_sub_f32_e32 v21, v16, v20
	v_sub_f32_e32 v16, v16, v21
	v_sub_f32_e32 v17, v20, v17
	v_sub_f32_e32 v16, v16, v20
	v_add_f32_e32 v14, v14, v16
	v_sub_f32_e32 v16, v17, v19
	v_add_f32_e32 v14, v16, v14
	v_add_f32_e32 v16, v21, v14
	v_mul_f32_e32 v17, v18, v16
	v_mul_f32_e32 v19, v13, v17
	v_fma_f32 v13, v17, v13, -v19
	v_fmac_f32_e32 v13, v17, v3
	v_sub_f32_e32 v3, v21, v16
	v_add_f32_e32 v3, v14, v3
	v_add_f32_e32 v14, v19, v13
	v_sub_f32_e32 v20, v16, v14
	v_sub_f32_e32 v16, v16, v20
	v_sub_f32_e32 v19, v14, v19
	v_sub_f32_e32 v14, v16, v14
	v_add_f32_e32 v3, v3, v14
	v_sub_f32_e32 v13, v19, v13
	v_cvt_f32_i32_e32 v2, v2
	v_add_f32_e32 v3, v13, v3
	v_add_f32_e32 v13, v15, v17
	v_add_f32_e32 v3, v20, v3
	v_sub_f32_e32 v14, v13, v15
	v_mul_f32_e32 v3, v18, v3
	v_sub_f32_e32 v14, v17, v14
	v_add_f32_e32 v3, v14, v3
	v_mul_f32_e32 v17, 0x3f317218, v2
	v_add_f32_e32 v14, v13, v3
	v_fma_f32 v18, v2, s9, -v17
	v_mul_f32_e32 v15, v14, v14
	v_fmac_f32_e32 v18, 0xb102e308, v2
	v_sub_f32_e32 v2, v14, v13
	v_fmamk_f32 v16, v15, 0x3e9b6dac, v231
	v_sub_f32_e32 v2, v3, v2
	v_add_f32_e32 v3, v17, v18
	v_fmaak_f32 v16, v15, v16, 0x3f2aaada
	v_sub_f32_e32 v13, v3, v17
	v_ldexp_f32 v17, v14, 1
	v_mul_f32_e32 v14, v14, v15
	v_mul_f32_e32 v14, v14, v16
	v_add_f32_e32 v15, v17, v14
	v_sub_f32_e32 v16, v15, v17
	v_ldexp_f32 v2, v2, 1
	v_sub_f32_e32 v14, v14, v16
	v_add_f32_e32 v2, v2, v14
	v_add_f32_e32 v14, v15, v2
	v_sub_f32_e32 v15, v14, v15
	v_sub_f32_e32 v2, v2, v15
	v_add_f32_e32 v15, v3, v14
	v_sub_f32_e32 v16, v15, v3
	v_sub_f32_e32 v17, v15, v16
	v_sub_f32_e32 v13, v18, v13
	v_sub_f32_e32 v3, v3, v17
	v_sub_f32_e32 v14, v14, v16
	v_add_f32_e32 v3, v14, v3
	v_add_f32_e32 v14, v13, v2
	v_sub_f32_e32 v16, v14, v13
	v_sub_f32_e32 v17, v14, v16
	v_sub_f32_e32 v13, v13, v17
	v_sub_f32_e32 v2, v2, v16
	v_add_f32_e32 v3, v14, v3
	v_add_f32_e32 v2, v2, v13
	v_add_f32_e32 v13, v15, v3
	v_sub_f32_e32 v14, v13, v15
	v_sub_f32_e32 v3, v3, v14
	v_add_f32_e32 v2, v2, v3
	v_add_f32_e32 v2, v13, v2
	v_cmp_neq_f32_e32 vcc, s6, v6
	v_mul_f32_e64 v3, |v7|, s7
	v_max_f32_e64 v7, -v7, 0
	v_cndmask_b32_e32 v2, v238, v2, vcc
	v_cmp_ngt_f32_e32 vcc, -1.0, v6
	s_nop 1
	v_cndmask_b32_e32 v2, v239, v2, vcc
	v_cmp_neq_f32_e32 vcc, -1.0, v6
	s_nop 1
	v_cndmask_b32_e32 v2, v240, v2, vcc
	v_cmp_lt_f32_e64 vcc, |v6|, s10
	s_nop 1
	v_cndmask_b32_e32 v2, v2, v6, vcc
	v_add_f32_e32 v2, v8, v2
	v_sub_f32_e32 v2, -0.5, v2
	v_mul_f32_e32 v2, 0x3fb8aa3b, v2
	v_exp_f32_e32 v6, v3
	v_exp_f32_e32 v2, v2
	v_add_f32_e32 v8, v9, v5
	v_add_f32_e32 v9, 1.0, v6
	v_mul_f32_e32 v5, 0xbfb8aa3b, v2
	v_add_f32_e32 v2, -1.0, v9
	v_sub_f32_e32 v3, v2, v9
	v_add_f32_e32 v3, 1.0, v3
	v_sub_f32_e32 v2, v6, v2
	v_add_f32_e32 v13, v2, v3
	v_frexp_mant_f32_e32 v2, v9
	v_cmp_gt_f32_e32 vcc, s8, v2
	v_cvt_f64_f32_e32 v[2:3], v9
	v_frexp_exp_i32_f64_e32 v2, v[2:3]
	v_subbrev_co_u32_e32 v2, vcc, 0, v2, vcc
	v_sub_u32_e32 v3, 0, v2
	v_ldexp_f32 v9, v9, v3
	v_ldexp_f32 v3, v13, v3
	v_add_f32_e32 v13, -1.0, v9
	v_add_f32_e32 v16, 1.0, v9
	v_add_f32_e32 v14, 1.0, v13
	v_add_f32_e32 v17, -1.0, v16
	v_sub_f32_e32 v14, v9, v14
	v_sub_f32_e32 v9, v9, v17
	v_add_f32_e32 v14, v3, v14
	v_add_f32_e32 v3, v3, v9
	v_add_f32_e32 v9, v16, v3
	v_rcp_f32_e32 v17, v9
	v_add_f32_e32 v15, v13, v14
	v_sub_f32_e32 v13, v15, v13
	v_sub_f32_e32 v13, v14, v13
	v_sub_f32_e32 v14, v9, v16
	v_sub_f32_e32 v3, v3, v14
	v_mul_f32_e32 v14, v15, v17
	v_mul_f32_e32 v16, v9, v14
	v_fma_f32 v18, v14, v9, -v16
	v_fmac_f32_e32 v18, v14, v3
	v_add_f32_e32 v19, v16, v18
	v_sub_f32_e32 v20, v15, v19
	v_sub_f32_e32 v15, v15, v20
	v_sub_f32_e32 v16, v19, v16
	v_sub_f32_e32 v15, v15, v19
	v_add_f32_e32 v13, v13, v15
	v_sub_f32_e32 v15, v16, v18
	v_add_f32_e32 v13, v15, v13
	v_add_f32_e32 v15, v20, v13
	v_mul_f32_e32 v16, v17, v15
	v_mul_f32_e32 v18, v9, v16
	v_fma_f32 v9, v16, v9, -v18
	v_fmac_f32_e32 v9, v16, v3
	v_sub_f32_e32 v3, v20, v15
	v_add_f32_e32 v3, v13, v3
	v_add_f32_e32 v13, v18, v9
	v_sub_f32_e32 v19, v15, v13
	v_sub_f32_e32 v15, v15, v19
	v_sub_f32_e32 v18, v13, v18
	v_sub_f32_e32 v13, v15, v13
	v_add_f32_e32 v3, v3, v13
	v_sub_f32_e32 v9, v18, v9
	v_cvt_f32_i32_e32 v2, v2
	v_add_f32_e32 v3, v9, v3
	v_add_f32_e32 v9, v14, v16
	v_add_f32_e32 v3, v19, v3
	v_sub_f32_e32 v13, v9, v14
	v_mul_f32_e32 v3, v17, v3
	v_sub_f32_e32 v13, v16, v13
	v_add_f32_e32 v3, v13, v3
	v_mul_f32_e32 v16, 0x3f317218, v2
	v_add_f32_e32 v13, v9, v3
	v_fma_f32 v17, v2, s9, -v16
	v_mul_f32_e32 v14, v13, v13
	v_fmac_f32_e32 v17, 0xb102e308, v2
; template <int MODE, bool BIG = false> DI void gemm_tile(const Params& p, int tm, int tn, int kv, char* smem) {
;     ...
;   } else if constexpr (MODE == G_RWW) {
;     float4* W4 = (float4*)((float*)(p.ws + OFF_BUFA) + (size_t)m * 512 + col0);
;     const float4* w04 = (const float4*)(p.w0 + col0);
; #pragma unroll
;     for (int c4 = 0; c4 < 16; ++c4) {
;       float4 v = crow4[c4], ww = w04[c4];
;       float u[4] = {v.x + ww.x, v.y + ww.y, v.z + ww.z, v.w + ww.w};
; #pragma unroll
;       for (int e = 0; e < 4; ++e) {
;         const float z = -u[e];
;         const float sp = fmaxf(z, 0.f) + log1pf(__expf(-fabsf(z)));
;         u[e] = __expf(-__expf(-sp - 0.5f));
;       }
;       W4[c4] = make_float4(u[0], u[1], u[2], u[3]);
;     }
	v_sub_f32_e32 v2, v13, v9
	v_fmamk_f32 v15, v14, 0x3e9b6dac, v231
	v_sub_f32_e32 v2, v3, v2
	v_add_f32_e32 v3, v16, v17
	v_fmaak_f32 v15, v14, v15, 0x3f2aaada
	v_sub_f32_e32 v9, v3, v16
	v_ldexp_f32 v16, v13, 1
	v_mul_f32_e32 v13, v13, v14
	v_mul_f32_e32 v13, v13, v15
	v_add_f32_e32 v14, v16, v13
	v_sub_f32_e32 v15, v14, v16
	v_ldexp_f32 v2, v2, 1
	v_sub_f32_e32 v13, v13, v15
	v_add_f32_e32 v2, v2, v13
	v_add_f32_e32 v13, v14, v2
	v_sub_f32_e32 v14, v13, v14
	v_sub_f32_e32 v2, v2, v14
	v_add_f32_e32 v14, v3, v13
	v_sub_f32_e32 v15, v14, v3
	v_sub_f32_e32 v16, v14, v15
	v_sub_f32_e32 v9, v17, v9
	v_sub_f32_e32 v3, v3, v16
	v_sub_f32_e32 v13, v13, v15
	v_add_f32_e32 v3, v13, v3
	v_add_f32_e32 v13, v9, v2
	v_sub_f32_e32 v15, v13, v9
	v_sub_f32_e32 v16, v13, v15
	v_sub_f32_e32 v9, v9, v16
	v_sub_f32_e32 v2, v2, v15
	v_add_f32_e32 v3, v13, v3
	v_add_f32_e32 v2, v2, v9
	v_add_f32_e32 v9, v14, v3
	v_sub_f32_e32 v13, v9, v14
	v_sub_f32_e32 v3, v3, v13
	v_add_f32_e32 v2, v2, v3
	v_add_f32_e32 v2, v9, v2
	v_cmp_neq_f32_e32 vcc, s6, v6
	s_nop 1
	v_cndmask_b32_e32 v2, v238, v2, vcc
	v_cmp_ngt_f32_e32 vcc, -1.0, v6
	s_nop 1
	v_cndmask_b32_e32 v2, v239, v2, vcc
	v_cmp_neq_f32_e32 vcc, -1.0, v6
	s_nop 1
	v_cndmask_b32_e32 v2, v240, v2, vcc
	v_cmp_lt_f32_e64 vcc, |v6|, s10
	s_nop 1
	v_cndmask_b32_e32 v2, v2, v6, vcc
	v_add_f32_e32 v2, v7, v2
	v_sub_f32_e32 v2, -0.5, v2
	v_mul_f32_e32 v2, 0x3fb8aa3b, v2
	v_exp_f32_e32 v3, v2
	v_mul_f32_e64 v2, |v4|, s7
	v_exp_f32_e32 v6, v2
	v_max_f32_e64 v7, -v4, 0
	v_exp_f32_e32 v2, v5
	v_mul_f32_e32 v3, 0xbfb8aa3b, v3
	v_add_f32_e32 v9, 1.0, v6
	v_add_f32_e32 v4, -1.0, v9
	v_sub_f32_e32 v5, v4, v9
	v_add_f32_e32 v5, 1.0, v5
	v_sub_f32_e32 v4, v6, v4
	v_add_f32_e32 v13, v4, v5
	v_frexp_mant_f32_e32 v4, v9
	v_cmp_gt_f32_e32 vcc, s8, v4
	v_cvt_f64_f32_e32 v[4:5], v9
	v_frexp_exp_i32_f64_e32 v4, v[4:5]
	v_subbrev_co_u32_e32 v4, vcc, 0, v4, vcc
	v_sub_u32_e32 v5, 0, v4
	v_ldexp_f32 v9, v9, v5
	v_ldexp_f32 v5, v13, v5
	v_add_f32_e32 v13, -1.0, v9
	v_add_f32_e32 v16, 1.0, v9
	v_add_f32_e32 v14, 1.0, v13
	v_add_f32_e32 v17, -1.0, v16
	v_sub_f32_e32 v14, v9, v14
	v_sub_f32_e32 v9, v9, v17
	v_add_f32_e32 v14, v5, v14
	v_add_f32_e32 v5, v5, v9
	v_add_f32_e32 v9, v16, v5
	v_rcp_f32_e32 v17, v9
	v_add_f32_e32 v15, v13, v14
	v_sub_f32_e32 v13, v15, v13
	v_sub_f32_e32 v13, v14, v13
	v_sub_f32_e32 v14, v9, v16
	v_sub_f32_e32 v5, v5, v14
	v_mul_f32_e32 v14, v15, v17
	v_mul_f32_e32 v16, v9, v14
	v_fma_f32 v18, v14, v9, -v16
	v_fmac_f32_e32 v18, v14, v5
	v_add_f32_e32 v19, v16, v18
	v_sub_f32_e32 v20, v15, v19
	v_sub_f32_e32 v15, v15, v20
	v_sub_f32_e32 v16, v19, v16
	v_sub_f32_e32 v15, v15, v19
	v_add_f32_e32 v13, v13, v15
	v_sub_f32_e32 v15, v16, v18
	v_add_f32_e32 v13, v15, v13
	v_add_f32_e32 v15, v20, v13
	v_mul_f32_e32 v16, v17, v15
	v_mul_f32_e32 v18, v9, v16
	v_fma_f32 v9, v16, v9, -v18
	v_fmac_f32_e32 v9, v16, v5
	v_sub_f32_e32 v5, v20, v15
	v_add_f32_e32 v5, v13, v5
	v_add_f32_e32 v13, v18, v9
	v_sub_f32_e32 v19, v15, v13
	v_sub_f32_e32 v15, v15, v19
	v_sub_f32_e32 v18, v13, v18
	v_sub_f32_e32 v13, v15, v13
	v_add_f32_e32 v5, v5, v13
	v_sub_f32_e32 v9, v18, v9
	v_cvt_f32_i32_e32 v4, v4
	v_add_f32_e32 v5, v9, v5
	v_add_f32_e32 v9, v14, v16
	v_add_f32_e32 v5, v19, v5
	v_sub_f32_e32 v13, v9, v14
	v_mul_f32_e32 v5, v17, v5
	v_sub_f32_e32 v13, v16, v13
	v_add_f32_e32 v5, v13, v5
	v_mul_f32_e32 v16, 0x3f317218, v4
	v_add_f32_e32 v13, v9, v5
	v_fma_f32 v17, v4, s9, -v16
	v_mul_f32_e32 v14, v13, v13
	v_fmac_f32_e32 v17, 0xb102e308, v4
	v_sub_f32_e32 v4, v13, v9
	v_fmamk_f32 v15, v14, 0x3e9b6dac, v231
	v_sub_f32_e32 v4, v5, v4
	v_add_f32_e32 v5, v16, v17
	v_fmaak_f32 v15, v14, v15, 0x3f2aaada
	v_sub_f32_e32 v9, v5, v16
	v_ldexp_f32 v16, v13, 1
	v_mul_f32_e32 v13, v13, v14
	v_mul_f32_e32 v13, v13, v15
	v_add_f32_e32 v14, v16, v13
	v_sub_f32_e32 v15, v14, v16
	v_ldexp_f32 v4, v4, 1
	v_sub_f32_e32 v13, v13, v15
	v_add_f32_e32 v4, v4, v13
	v_add_f32_e32 v13, v14, v4
	v_sub_f32_e32 v14, v13, v14
	v_sub_f32_e32 v4, v4, v14
	v_add_f32_e32 v14, v5, v13
	v_sub_f32_e32 v15, v14, v5
	v_sub_f32_e32 v16, v14, v15
	v_sub_f32_e32 v9, v17, v9
	v_sub_f32_e32 v5, v5, v16
	v_sub_f32_e32 v13, v13, v15
	v_add_f32_e32 v5, v13, v5
	v_add_f32_e32 v13, v9, v4
	v_sub_f32_e32 v15, v13, v9
	v_sub_f32_e32 v16, v13, v15
	v_sub_f32_e32 v9, v9, v16
	v_sub_f32_e32 v4, v4, v15
	v_add_f32_e32 v5, v13, v5
	v_add_f32_e32 v4, v4, v9
	v_add_f32_e32 v9, v14, v5
	v_sub_f32_e32 v13, v9, v14
	v_sub_f32_e32 v5, v5, v13
	v_add_f32_e32 v4, v4, v5
	v_add_f32_e32 v4, v9, v4
	v_cmp_neq_f32_e32 vcc, s6, v6
	v_mul_f32_e64 v5, |v8|, s7
	v_max_f32_e64 v8, -v8, 0
	v_cndmask_b32_e32 v4, v238, v4, vcc
	v_cmp_ngt_f32_e32 vcc, -1.0, v6
	v_exp_f32_e32 v3, v3
	s_nop 0
	v_cndmask_b32_e32 v4, v239, v4, vcc
	v_cmp_neq_f32_e32 vcc, -1.0, v6
	s_nop 1
	v_cndmask_b32_e32 v4, v240, v4, vcc
	v_cmp_lt_f32_e64 vcc, |v6|, s10
	s_nop 1
	v_cndmask_b32_e32 v4, v4, v6, vcc
	v_exp_f32_e32 v6, v5
	v_add_f32_e32 v4, v7, v4
	v_sub_f32_e32 v4, -0.5, v4
	v_mul_f32_e32 v4, 0x3fb8aa3b, v4
	v_add_f32_e32 v9, 1.0, v6
	v_exp_f32_e32 v7, v4
	v_add_f32_e32 v4, -1.0, v9
	v_sub_f32_e32 v5, v4, v9
	v_add_f32_e32 v5, 1.0, v5
	v_sub_f32_e32 v4, v6, v4
	v_add_f32_e32 v13, v4, v5
	v_frexp_mant_f32_e32 v4, v9
	v_cmp_gt_f32_e32 vcc, s8, v4
	v_cvt_f64_f32_e32 v[4:5], v9
	v_frexp_exp_i32_f64_e32 v4, v[4:5]
	v_subbrev_co_u32_e32 v4, vcc, 0, v4, vcc
	v_sub_u32_e32 v5, 0, v4
	v_ldexp_f32 v9, v9, v5
	v_ldexp_f32 v5, v13, v5
	v_add_f32_e32 v13, -1.0, v9
	v_add_f32_e32 v16, 1.0, v9
	v_add_f32_e32 v14, 1.0, v13
	v_add_f32_e32 v17, -1.0, v16
	v_sub_f32_e32 v14, v9, v14
	v_sub_f32_e32 v9, v9, v17
	v_add_f32_e32 v14, v5, v14
	v_add_f32_e32 v5, v5, v9
; template <int MODE, bool BIG = false> DI void gemm_tile(const Params& p, int tm, int tn, int kv, char* smem) {
;     ...
;   } else if constexpr (MODE == G_RWW) {
;     float4* W4 = (float4*)((float*)(p.ws + OFF_BUFA) + (size_t)m * 512 + col0);
;     const float4* w04 = (const float4*)(p.w0 + col0);
; #pragma unroll
;     for (int c4 = 0; c4 < 16; ++c4) {
;       float4 v = crow4[c4], ww = w04[c4];
;       float u[4] = {v.x + ww.x, v.y + ww.y, v.z + ww.z, v.w + ww.w};
; #pragma unroll
;       for (int e = 0; e < 4; ++e) {
;         const float z = -u[e];
;         const float sp = fmaxf(z, 0.f) + log1pf(__expf(-fabsf(z)));
;         u[e] = __expf(-__expf(-sp - 0.5f));
;       }
;       W4[c4] = make_float4(u[0], u[1], u[2], u[3]);
;     }
	v_add_f32_e32 v9, v16, v5
	v_rcp_f32_e32 v17, v9
	v_add_f32_e32 v15, v13, v14
	v_sub_f32_e32 v13, v15, v13
	v_sub_f32_e32 v13, v14, v13
	v_sub_f32_e32 v14, v9, v16
	v_sub_f32_e32 v5, v5, v14
	v_mul_f32_e32 v14, v15, v17
	v_mul_f32_e32 v16, v9, v14
	v_fma_f32 v18, v14, v9, -v16
	v_fmac_f32_e32 v18, v14, v5
	v_add_f32_e32 v19, v16, v18
	v_sub_f32_e32 v20, v15, v19
	v_sub_f32_e32 v15, v15, v20
	v_sub_f32_e32 v16, v19, v16
	v_sub_f32_e32 v15, v15, v19
	v_add_f32_e32 v13, v13, v15
	v_sub_f32_e32 v15, v16, v18
	v_add_f32_e32 v13, v15, v13
	v_add_f32_e32 v15, v20, v13
	v_mul_f32_e32 v16, v17, v15
	v_mul_f32_e32 v18, v9, v16
	v_fma_f32 v9, v16, v9, -v18
	v_fmac_f32_e32 v9, v16, v5
	v_sub_f32_e32 v5, v20, v15
	v_add_f32_e32 v5, v13, v5
	v_add_f32_e32 v13, v18, v9
	v_sub_f32_e32 v19, v15, v13
	v_sub_f32_e32 v15, v15, v19
	v_sub_f32_e32 v18, v13, v18
	v_sub_f32_e32 v13, v15, v13
	v_add_f32_e32 v5, v5, v13
	v_sub_f32_e32 v9, v18, v9
	v_cvt_f32_i32_e32 v4, v4
	v_add_f32_e32 v5, v9, v5
	v_add_f32_e32 v9, v14, v16
	v_add_f32_e32 v5, v19, v5
	v_sub_f32_e32 v13, v9, v14
	v_mul_f32_e32 v5, v17, v5
	v_sub_f32_e32 v13, v16, v13
	v_add_f32_e32 v5, v13, v5
	v_mul_f32_e32 v16, 0x3f317218, v4
	v_add_f32_e32 v13, v9, v5
	v_fma_f32 v17, v4, s9, -v16
	v_mul_f32_e32 v14, v13, v13
	v_fmac_f32_e32 v17, 0xb102e308, v4
	v_sub_f32_e32 v4, v13, v9
	v_fmamk_f32 v15, v14, 0x3e9b6dac, v231
	v_sub_f32_e32 v4, v5, v4
	v_add_f32_e32 v5, v16, v17
	v_fmaak_f32 v15, v14, v15, 0x3f2aaada
	v_sub_f32_e32 v9, v5, v16
	v_ldexp_f32 v16, v13, 1
	v_mul_f32_e32 v13, v13, v14
	v_mul_f32_e32 v13, v13, v15
	v_add_f32_e32 v14, v16, v13
	v_sub_f32_e32 v15, v14, v16
	v_ldexp_f32 v4, v4, 1
	v_sub_f32_e32 v13, v13, v15
	v_add_f32_e32 v4, v4, v13
	v_add_f32_e32 v13, v14, v4
	v_sub_f32_e32 v14, v13, v14
	v_sub_f32_e32 v4, v4, v14
	v_add_f32_e32 v14, v5, v13
	v_sub_f32_e32 v15, v14, v5
	v_sub_f32_e32 v16, v14, v15
	v_sub_f32_e32 v9, v17, v9
	v_sub_f32_e32 v5, v5, v16
	v_sub_f32_e32 v13, v13, v15
	v_add_f32_e32 v5, v13, v5
	v_add_f32_e32 v13, v9, v4
	v_sub_f32_e32 v15, v13, v9
	v_sub_f32_e32 v16, v13, v15
	v_sub_f32_e32 v9, v9, v16
	v_sub_f32_e32 v4, v4, v15
	v_add_f32_e32 v5, v13, v5
	v_add_f32_e32 v4, v4, v9
	v_add_f32_e32 v9, v14, v5
	v_sub_f32_e32 v13, v9, v14
	v_sub_f32_e32 v5, v5, v13
	v_add_f32_e32 v4, v4, v5
	v_add_f32_e32 v4, v9, v4
	v_cmp_neq_f32_e32 vcc, s6, v6
	s_nop 1
	v_cndmask_b32_e32 v4, v238, v4, vcc
	v_cmp_ngt_f32_e32 vcc, -1.0, v6
	s_nop 1
	v_cndmask_b32_e32 v4, v239, v4, vcc
	v_cmp_neq_f32_e32 vcc, -1.0, v6
	s_nop 1
	v_cndmask_b32_e32 v4, v240, v4, vcc
	v_cmp_lt_f32_e64 vcc, |v6|, s10
	s_nop 1
	v_cndmask_b32_e32 v4, v4, v6, vcc
	v_add_f32_e32 v4, v8, v4
	v_sub_f32_e32 v4, -0.5, v4
	v_mul_f32_e32 v4, 0x3fb8aa3b, v4
	v_exp_f32_e32 v5, v4
	v_mul_f32_e32 v4, 0xbfb8aa3b, v7
	v_exp_f32_e32 v4, v4
	ds_read_b128 v[6:9], v12 offset:192
	v_mul_f32_e32 v5, 0xbfb8aa3b, v5
	v_exp_f32_e32 v5, v5
	ds_write_b128 v75, v[2:5] offset:176
	ds_read_b128 v[2:5], v74 offset:192
	s_waitcnt lgkmcnt(0)
	v_add_f32_e32 v2, v6, v2
	v_mul_f32_e64 v6, |v2|, s7
	v_exp_f32_e32 v6, v6
	v_add_f32_e32 v4, v8, v4
	v_max_f32_e64 v8, -v2, 0
	v_add_f32_e32 v7, v7, v3
	v_add_f32_e32 v13, 1.0, v6
	v_add_f32_e32 v2, -1.0, v13
	v_sub_f32_e32 v3, v2, v13
	v_add_f32_e32 v3, 1.0, v3
	v_sub_f32_e32 v2, v6, v2
	v_add_f32_e32 v14, v2, v3
	v_frexp_mant_f32_e32 v2, v13
	v_cmp_gt_f32_e32 vcc, s8, v2
	v_cvt_f64_f32_e32 v[2:3], v13
	v_frexp_exp_i32_f64_e32 v2, v[2:3]
	v_subbrev_co_u32_e32 v2, vcc, 0, v2, vcc
	v_sub_u32_e32 v3, 0, v2
	v_ldexp_f32 v13, v13, v3
	v_ldexp_f32 v3, v14, v3
	v_add_f32_e32 v14, -1.0, v13
	v_add_f32_e32 v17, 1.0, v13
	v_add_f32_e32 v15, 1.0, v14
	v_add_f32_e32 v18, -1.0, v17
	v_sub_f32_e32 v15, v13, v15
	v_sub_f32_e32 v13, v13, v18
	v_add_f32_e32 v15, v3, v15
	v_add_f32_e32 v3, v3, v13
	v_add_f32_e32 v13, v17, v3
	v_rcp_f32_e32 v18, v13
	v_add_f32_e32 v16, v14, v15
	v_sub_f32_e32 v14, v16, v14
	v_sub_f32_e32 v14, v15, v14
	v_sub_f32_e32 v15, v13, v17
	v_sub_f32_e32 v3, v3, v15
	v_mul_f32_e32 v15, v16, v18
	v_mul_f32_e32 v17, v13, v15
	v_fma_f32 v19, v15, v13, -v17
	v_fmac_f32_e32 v19, v15, v3
	v_add_f32_e32 v20, v17, v19
	v_sub_f32_e32 v21, v16, v20
	v_sub_f32_e32 v16, v16, v21
	v_sub_f32_e32 v17, v20, v17
	v_sub_f32_e32 v16, v16, v20
	v_add_f32_e32 v14, v14, v16
	v_sub_f32_e32 v16, v17, v19
	v_add_f32_e32 v14, v16, v14
	v_add_f32_e32 v16, v21, v14
	v_mul_f32_e32 v17, v18, v16
	v_mul_f32_e32 v19, v13, v17
	v_fma_f32 v13, v17, v13, -v19
	v_fmac_f32_e32 v13, v17, v3
	v_sub_f32_e32 v3, v21, v16
	v_add_f32_e32 v3, v14, v3
	v_add_f32_e32 v14, v19, v13
	v_sub_f32_e32 v20, v16, v14
	v_sub_f32_e32 v16, v16, v20
	v_sub_f32_e32 v19, v14, v19
	v_sub_f32_e32 v14, v16, v14
	v_add_f32_e32 v3, v3, v14
	v_sub_f32_e32 v13, v19, v13
	v_cvt_f32_i32_e32 v2, v2
	v_add_f32_e32 v3, v13, v3
	v_add_f32_e32 v13, v15, v17
	v_add_f32_e32 v3, v20, v3
	v_sub_f32_e32 v14, v13, v15
	v_mul_f32_e32 v3, v18, v3
	v_sub_f32_e32 v14, v17, v14
	v_add_f32_e32 v3, v14, v3
	v_mul_f32_e32 v17, 0x3f317218, v2
	v_add_f32_e32 v14, v13, v3
	v_fma_f32 v18, v2, s9, -v17
	v_mul_f32_e32 v15, v14, v14
	v_fmac_f32_e32 v18, 0xb102e308, v2
	v_sub_f32_e32 v2, v14, v13
	v_fmamk_f32 v16, v15, 0x3e9b6dac, v231
	v_sub_f32_e32 v2, v3, v2
	v_add_f32_e32 v3, v17, v18
	v_fmaak_f32 v16, v15, v16, 0x3f2aaada
	v_sub_f32_e32 v13, v3, v17
	v_ldexp_f32 v17, v14, 1
	v_mul_f32_e32 v14, v14, v15
	v_mul_f32_e32 v14, v14, v16
	v_add_f32_e32 v15, v17, v14
	v_sub_f32_e32 v16, v15, v17
	v_ldexp_f32 v2, v2, 1
	v_sub_f32_e32 v14, v14, v16
	v_add_f32_e32 v2, v2, v14
	v_add_f32_e32 v14, v15, v2
	v_sub_f32_e32 v15, v14, v15
	v_sub_f32_e32 v2, v2, v15
	v_add_f32_e32 v15, v3, v14
; template <int MODE, bool BIG = false> DI void gemm_tile(const Params& p, int tm, int tn, int kv, char* smem) {
;     ...
;   } else if constexpr (MODE == G_RWW) {
;     float4* W4 = (float4*)((float*)(p.ws + OFF_BUFA) + (size_t)m * 512 + col0);
;     const float4* w04 = (const float4*)(p.w0 + col0);
; #pragma unroll
;     for (int c4 = 0; c4 < 16; ++c4) {
;       float4 v = crow4[c4], ww = w04[c4];
;       float u[4] = {v.x + ww.x, v.y + ww.y, v.z + ww.z, v.w + ww.w};
; #pragma unroll
;       for (int e = 0; e < 4; ++e) {
;         const float z = -u[e];
;         const float sp = fmaxf(z, 0.f) + log1pf(__expf(-fabsf(z)));
;         u[e] = __expf(-__expf(-sp - 0.5f));
;       }
;       W4[c4] = make_float4(u[0], u[1], u[2], u[3]);
;     }
	v_sub_f32_e32 v16, v15, v3
	v_sub_f32_e32 v17, v15, v16
	v_sub_f32_e32 v13, v18, v13
	v_sub_f32_e32 v3, v3, v17
	v_sub_f32_e32 v14, v14, v16
	v_add_f32_e32 v3, v14, v3
	v_add_f32_e32 v14, v13, v2
	v_sub_f32_e32 v16, v14, v13
	v_sub_f32_e32 v17, v14, v16
	v_sub_f32_e32 v13, v13, v17
	v_sub_f32_e32 v2, v2, v16
	v_add_f32_e32 v3, v14, v3
	v_add_f32_e32 v2, v2, v13
	v_add_f32_e32 v13, v15, v3
	v_sub_f32_e32 v14, v13, v15
	v_sub_f32_e32 v3, v3, v14
	v_add_f32_e32 v2, v2, v3
	v_add_f32_e32 v2, v13, v2
	v_cmp_neq_f32_e32 vcc, s6, v6
	v_mul_f32_e64 v3, |v7|, s7
	v_max_f32_e64 v7, -v7, 0
	v_cndmask_b32_e32 v2, v238, v2, vcc
	v_cmp_ngt_f32_e32 vcc, -1.0, v6
	s_nop 1
	v_cndmask_b32_e32 v2, v239, v2, vcc
	v_cmp_neq_f32_e32 vcc, -1.0, v6
	s_nop 1
	v_cndmask_b32_e32 v2, v240, v2, vcc
	v_cmp_lt_f32_e64 vcc, |v6|, s10
	s_nop 1
	v_cndmask_b32_e32 v2, v2, v6, vcc
	v_add_f32_e32 v2, v8, v2
	v_sub_f32_e32 v2, -0.5, v2
	v_mul_f32_e32 v2, 0x3fb8aa3b, v2
	v_exp_f32_e32 v6, v3
	v_exp_f32_e32 v2, v2
	v_add_f32_e32 v8, v9, v5
	v_add_f32_e32 v9, 1.0, v6
	v_mul_f32_e32 v5, 0xbfb8aa3b, v2
	v_add_f32_e32 v2, -1.0, v9
	v_sub_f32_e32 v3, v2, v9
	v_add_f32_e32 v3, 1.0, v3
	v_sub_f32_e32 v2, v6, v2
	v_add_f32_e32 v13, v2, v3
	v_frexp_mant_f32_e32 v2, v9
	v_cmp_gt_f32_e32 vcc, s8, v2
	v_cvt_f64_f32_e32 v[2:3], v9
	v_frexp_exp_i32_f64_e32 v2, v[2:3]
	v_subbrev_co_u32_e32 v2, vcc, 0, v2, vcc
	v_sub_u32_e32 v3, 0, v2
	v_ldexp_f32 v9, v9, v3
	v_ldexp_f32 v3, v13, v3
	v_add_f32_e32 v13, -1.0, v9
	v_add_f32_e32 v16, 1.0, v9
	v_add_f32_e32 v14, 1.0, v13
	v_add_f32_e32 v17, -1.0, v16
	v_sub_f32_e32 v14, v9, v14
	v_sub_f32_e32 v9, v9, v17
	v_add_f32_e32 v14, v3, v14
	v_add_f32_e32 v3, v3, v9
	v_add_f32_e32 v9, v16, v3
	v_rcp_f32_e32 v17, v9
	v_add_f32_e32 v15, v13, v14
	v_sub_f32_e32 v13, v15, v13
	v_sub_f32_e32 v13, v14, v13
	v_sub_f32_e32 v14, v9, v16
	v_sub_f32_e32 v3, v3, v14
	v_mul_f32_e32 v14, v15, v17
	v_mul_f32_e32 v16, v9, v14
	v_fma_f32 v18, v14, v9, -v16
	v_fmac_f32_e32 v18, v14, v3
	v_add_f32_e32 v19, v16, v18
	v_sub_f32_e32 v20, v15, v19
	v_sub_f32_e32 v15, v15, v20
	v_sub_f32_e32 v16, v19, v16
	v_sub_f32_e32 v15, v15, v19
	v_add_f32_e32 v13, v13, v15
	v_sub_f32_e32 v15, v16, v18
	v_add_f32_e32 v13, v15, v13
	v_add_f32_e32 v15, v20, v13
	v_mul_f32_e32 v16, v17, v15
	v_mul_f32_e32 v18, v9, v16
	v_fma_f32 v9, v16, v9, -v18
	v_fmac_f32_e32 v9, v16, v3
	v_sub_f32_e32 v3, v20, v15
	v_add_f32_e32 v3, v13, v3
	v_add_f32_e32 v13, v18, v9
	v_sub_f32_e32 v19, v15, v13
	v_sub_f32_e32 v15, v15, v19
	v_sub_f32_e32 v18, v13, v18
	v_sub_f32_e32 v13, v15, v13
	v_add_f32_e32 v3, v3, v13
	v_sub_f32_e32 v9, v18, v9
	v_cvt_f32_i32_e32 v2, v2
	v_add_f32_e32 v3, v9, v3
	v_add_f32_e32 v9, v14, v16
	v_add_f32_e32 v3, v19, v3
	v_sub_f32_e32 v13, v9, v14
	v_mul_f32_e32 v3, v17, v3
	v_sub_f32_e32 v13, v16, v13
	v_add_f32_e32 v3, v13, v3
	v_mul_f32_e32 v16, 0x3f317218, v2
	v_add_f32_e32 v13, v9, v3
	v_fma_f32 v17, v2, s9, -v16
	v_mul_f32_e32 v14, v13, v13
	v_fmac_f32_e32 v17, 0xb102e308, v2
	v_sub_f32_e32 v2, v13, v9
	v_fmamk_f32 v15, v14, 0x3e9b6dac, v231
	v_sub_f32_e32 v2, v3, v2
	v_add_f32_e32 v3, v16, v17
	v_fmaak_f32 v15, v14, v15, 0x3f2aaada
	v_sub_f32_e32 v9, v3, v16
	v_ldexp_f32 v16, v13, 1
	v_mul_f32_e32 v13, v13, v14
	v_mul_f32_e32 v13, v13, v15
	v_add_f32_e32 v14, v16, v13
	v_sub_f32_e32 v15, v14, v16
	v_ldexp_f32 v2, v2, 1
	v_sub_f32_e32 v13, v13, v15
	v_add_f32_e32 v2, v2, v13
	v_add_f32_e32 v13, v14, v2
	v_sub_f32_e32 v14, v13, v14
	v_sub_f32_e32 v2, v2, v14
	v_add_f32_e32 v14, v3, v13
	v_sub_f32_e32 v15, v14, v3
	v_sub_f32_e32 v16, v14, v15
	v_sub_f32_e32 v9, v17, v9
	v_sub_f32_e32 v3, v3, v16
	v_sub_f32_e32 v13, v13, v15
	v_add_f32_e32 v3, v13, v3
	v_add_f32_e32 v13, v9, v2
	v_sub_f32_e32 v15, v13, v9
	v_sub_f32_e32 v16, v13, v15
	v_sub_f32_e32 v9, v9, v16
	v_sub_f32_e32 v2, v2, v15
	v_add_f32_e32 v3, v13, v3
	v_add_f32_e32 v2, v2, v9
	v_add_f32_e32 v9, v14, v3
	v_sub_f32_e32 v13, v9, v14
	v_sub_f32_e32 v3, v3, v13
	v_add_f32_e32 v2, v2, v3
	v_add_f32_e32 v2, v9, v2
	v_cmp_neq_f32_e32 vcc, s6, v6
	s_nop 1
	v_cndmask_b32_e32 v2, v238, v2, vcc
	v_cmp_ngt_f32_e32 vcc, -1.0, v6
	s_nop 1
	v_cndmask_b32_e32 v2, v239, v2, vcc
	v_cmp_neq_f32_e32 vcc, -1.0, v6
	s_nop 1
	v_cndmask_b32_e32 v2, v240, v2, vcc
	v_cmp_lt_f32_e64 vcc, |v6|, s10
	s_nop 1
	v_cndmask_b32_e32 v2, v2, v6, vcc
	v_add_f32_e32 v2, v7, v2
	v_sub_f32_e32 v2, -0.5, v2
	v_mul_f32_e32 v2, 0x3fb8aa3b, v2
	v_exp_f32_e32 v3, v2
	v_mul_f32_e64 v2, |v4|, s7
	v_exp_f32_e32 v6, v2
	v_max_f32_e64 v7, -v4, 0
	v_exp_f32_e32 v2, v5
	v_mul_f32_e32 v3, 0xbfb8aa3b, v3
	v_add_f32_e32 v9, 1.0, v6
	v_add_f32_e32 v4, -1.0, v9
	v_sub_f32_e32 v5, v4, v9
	v_add_f32_e32 v5, 1.0, v5
	v_sub_f32_e32 v4, v6, v4
	v_add_f32_e32 v13, v4, v5
	v_frexp_mant_f32_e32 v4, v9
	v_cmp_gt_f32_e32 vcc, s8, v4
	v_cvt_f64_f32_e32 v[4:5], v9
	v_frexp_exp_i32_f64_e32 v4, v[4:5]
	v_subbrev_co_u32_e32 v4, vcc, 0, v4, vcc
	v_sub_u32_e32 v5, 0, v4
	v_ldexp_f32 v9, v9, v5
	v_ldexp_f32 v5, v13, v5
	v_add_f32_e32 v13, -1.0, v9
	v_add_f32_e32 v16, 1.0, v9
	v_add_f32_e32 v14, 1.0, v13
	v_add_f32_e32 v17, -1.0, v16
	v_sub_f32_e32 v14, v9, v14
	v_sub_f32_e32 v9, v9, v17
	v_add_f32_e32 v14, v5, v14
	v_add_f32_e32 v5, v5, v9
	v_add_f32_e32 v9, v16, v5
	v_rcp_f32_e32 v17, v9
	v_add_f32_e32 v15, v13, v14
	v_sub_f32_e32 v13, v15, v13
	v_sub_f32_e32 v13, v14, v13
	v_sub_f32_e32 v14, v9, v16
	v_sub_f32_e32 v5, v5, v14
	v_mul_f32_e32 v14, v15, v17
	v_mul_f32_e32 v16, v9, v14
	v_fma_f32 v18, v14, v9, -v16
	v_fmac_f32_e32 v18, v14, v5
	v_add_f32_e32 v19, v16, v18
	v_sub_f32_e32 v20, v15, v19
	v_sub_f32_e32 v15, v15, v20
	v_sub_f32_e32 v16, v19, v16
	v_sub_f32_e32 v15, v15, v19
; template <int MODE, bool BIG = false> DI void gemm_tile(const Params& p, int tm, int tn, int kv, char* smem) {
;     ...
;   } else if constexpr (MODE == G_RWW) {
;     float4* W4 = (float4*)((float*)(p.ws + OFF_BUFA) + (size_t)m * 512 + col0);
;     const float4* w04 = (const float4*)(p.w0 + col0);
; #pragma unroll
;     for (int c4 = 0; c4 < 16; ++c4) {
;       float4 v = crow4[c4], ww = w04[c4];
;       float u[4] = {v.x + ww.x, v.y + ww.y, v.z + ww.z, v.w + ww.w};
; #pragma unroll
;       for (int e = 0; e < 4; ++e) {
;         const float z = -u[e];
;         const float sp = fmaxf(z, 0.f) + log1pf(__expf(-fabsf(z)));
;         u[e] = __expf(-__expf(-sp - 0.5f));
;       }
;       W4[c4] = make_float4(u[0], u[1], u[2], u[3]);
;     }
	v_add_f32_e32 v13, v13, v15
	v_sub_f32_e32 v15, v16, v18
	v_add_f32_e32 v13, v15, v13
	v_add_f32_e32 v15, v20, v13
	v_mul_f32_e32 v16, v17, v15
	v_mul_f32_e32 v18, v9, v16
	v_fma_f32 v9, v16, v9, -v18
	v_fmac_f32_e32 v9, v16, v5
	v_sub_f32_e32 v5, v20, v15
	v_add_f32_e32 v5, v13, v5
	v_add_f32_e32 v13, v18, v9
	v_sub_f32_e32 v19, v15, v13
	v_sub_f32_e32 v15, v15, v19
	v_sub_f32_e32 v18, v13, v18
	v_sub_f32_e32 v13, v15, v13
	v_add_f32_e32 v5, v5, v13
	v_sub_f32_e32 v9, v18, v9
	v_cvt_f32_i32_e32 v4, v4
	v_add_f32_e32 v5, v9, v5
	v_add_f32_e32 v9, v14, v16
	v_add_f32_e32 v5, v19, v5
	v_sub_f32_e32 v13, v9, v14
	v_mul_f32_e32 v5, v17, v5
	v_sub_f32_e32 v13, v16, v13
	v_add_f32_e32 v5, v13, v5
	v_mul_f32_e32 v16, 0x3f317218, v4
	v_add_f32_e32 v13, v9, v5
	v_fma_f32 v17, v4, s9, -v16
	v_mul_f32_e32 v14, v13, v13
	v_fmac_f32_e32 v17, 0xb102e308, v4
	v_sub_f32_e32 v4, v13, v9
	v_fmamk_f32 v15, v14, 0x3e9b6dac, v231
	v_sub_f32_e32 v4, v5, v4
	v_add_f32_e32 v5, v16, v17
	v_fmaak_f32 v15, v14, v15, 0x3f2aaada
	v_sub_f32_e32 v9, v5, v16
	v_ldexp_f32 v16, v13, 1
	v_mul_f32_e32 v13, v13, v14
	v_mul_f32_e32 v13, v13, v15
	v_add_f32_e32 v14, v16, v13
	v_sub_f32_e32 v15, v14, v16
	v_ldexp_f32 v4, v4, 1
	v_sub_f32_e32 v13, v13, v15
	v_add_f32_e32 v4, v4, v13
	v_add_f32_e32 v13, v14, v4
	v_sub_f32_e32 v14, v13, v14
	v_sub_f32_e32 v4, v4, v14
	v_add_f32_e32 v14, v5, v13
	v_sub_f32_e32 v15, v14, v5
	v_sub_f32_e32 v16, v14, v15
	v_sub_f32_e32 v9, v17, v9
	v_sub_f32_e32 v5, v5, v16
	v_sub_f32_e32 v13, v13, v15
	v_add_f32_e32 v5, v13, v5
	v_add_f32_e32 v13, v9, v4
	v_sub_f32_e32 v15, v13, v9
	v_sub_f32_e32 v16, v13, v15
	v_sub_f32_e32 v9, v9, v16
	v_sub_f32_e32 v4, v4, v15
	v_add_f32_e32 v5, v13, v5
	v_add_f32_e32 v4, v4, v9
	v_add_f32_e32 v9, v14, v5
	v_sub_f32_e32 v13, v9, v14
	v_sub_f32_e32 v5, v5, v13
	v_add_f32_e32 v4, v4, v5
	v_add_f32_e32 v4, v9, v4
	v_cmp_neq_f32_e32 vcc, s6, v6
	v_mul_f32_e64 v5, |v8|, s7
	v_max_f32_e64 v8, -v8, 0
	v_cndmask_b32_e32 v4, v238, v4, vcc
	v_cmp_ngt_f32_e32 vcc, -1.0, v6
	v_exp_f32_e32 v3, v3
	s_nop 0
	v_cndmask_b32_e32 v4, v239, v4, vcc
	v_cmp_neq_f32_e32 vcc, -1.0, v6
	s_nop 1
	v_cndmask_b32_e32 v4, v240, v4, vcc
	v_cmp_lt_f32_e64 vcc, |v6|, s10
	s_nop 1
	v_cndmask_b32_e32 v4, v4, v6, vcc
	v_exp_f32_e32 v6, v5
	v_add_f32_e32 v4, v7, v4
	v_sub_f32_e32 v4, -0.5, v4
	v_mul_f32_e32 v4, 0x3fb8aa3b, v4
	v_add_f32_e32 v9, 1.0, v6
	v_exp_f32_e32 v7, v4
	v_add_f32_e32 v4, -1.0, v9
	v_sub_f32_e32 v5, v4, v9
	v_add_f32_e32 v5, 1.0, v5
	v_sub_f32_e32 v4, v6, v4
	v_add_f32_e32 v13, v4, v5
	v_frexp_mant_f32_e32 v4, v9
	v_cmp_gt_f32_e32 vcc, s8, v4
	v_cvt_f64_f32_e32 v[4:5], v9
	v_frexp_exp_i32_f64_e32 v4, v[4:5]
	v_subbrev_co_u32_e32 v4, vcc, 0, v4, vcc
	v_sub_u32_e32 v5, 0, v4
	v_ldexp_f32 v9, v9, v5
	v_ldexp_f32 v5, v13, v5
	v_add_f32_e32 v13, -1.0, v9
	v_add_f32_e32 v16, 1.0, v9
	v_add_f32_e32 v14, 1.0, v13
	v_add_f32_e32 v17, -1.0, v16
	v_sub_f32_e32 v14, v9, v14
	v_sub_f32_e32 v9, v9, v17
	v_add_f32_e32 v14, v5, v14
	v_add_f32_e32 v5, v5, v9
	v_add_f32_e32 v9, v16, v5
	v_rcp_f32_e32 v17, v9
	v_add_f32_e32 v15, v13, v14
	v_sub_f32_e32 v13, v15, v13
	v_sub_f32_e32 v13, v14, v13
	v_sub_f32_e32 v14, v9, v16
	v_sub_f32_e32 v5, v5, v14
	v_mul_f32_e32 v14, v15, v17
	v_mul_f32_e32 v16, v9, v14
	v_fma_f32 v18, v14, v9, -v16
	v_fmac_f32_e32 v18, v14, v5
	v_add_f32_e32 v19, v16, v18
	v_sub_f32_e32 v20, v15, v19
	v_sub_f32_e32 v15, v15, v20
	v_sub_f32_e32 v16, v19, v16
	v_sub_f32_e32 v15, v15, v19
	v_add_f32_e32 v13, v13, v15
	v_sub_f32_e32 v15, v16, v18
	v_add_f32_e32 v13, v15, v13
	v_add_f32_e32 v15, v20, v13
	v_mul_f32_e32 v16, v17, v15
	v_mul_f32_e32 v18, v9, v16
	v_fma_f32 v9, v16, v9, -v18
	v_fmac_f32_e32 v9, v16, v5
	v_sub_f32_e32 v5, v20, v15
	v_add_f32_e32 v5, v13, v5
	v_add_f32_e32 v13, v18, v9
	v_sub_f32_e32 v19, v15, v13
	v_sub_f32_e32 v15, v15, v19
	v_sub_f32_e32 v18, v13, v18
	v_sub_f32_e32 v13, v15, v13
	v_add_f32_e32 v5, v5, v13
	v_sub_f32_e32 v9, v18, v9
	v_cvt_f32_i32_e32 v4, v4
	v_add_f32_e32 v5, v9, v5
	v_add_f32_e32 v9, v14, v16
	v_add_f32_e32 v5, v19, v5
	v_sub_f32_e32 v13, v9, v14
	v_mul_f32_e32 v5, v17, v5
	v_sub_f32_e32 v13, v16, v13
	v_add_f32_e32 v5, v13, v5
	v_mul_f32_e32 v16, 0x3f317218, v4
	v_add_f32_e32 v13, v9, v5
	v_fma_f32 v17, v4, s9, -v16
	v_mul_f32_e32 v14, v13, v13
	v_fmac_f32_e32 v17, 0xb102e308, v4
	v_sub_f32_e32 v4, v13, v9
	v_fmamk_f32 v15, v14, 0x3e9b6dac, v231
	v_sub_f32_e32 v4, v5, v4
	v_add_f32_e32 v5, v16, v17
	v_fmaak_f32 v15, v14, v15, 0x3f2aaada
	v_sub_f32_e32 v9, v5, v16
	v_ldexp_f32 v16, v13, 1
	v_mul_f32_e32 v13, v13, v14
	v_mul_f32_e32 v13, v13, v15
	v_add_f32_e32 v14, v16, v13
	v_sub_f32_e32 v15, v14, v16
	v_ldexp_f32 v4, v4, 1
	v_sub_f32_e32 v13, v13, v15
	v_add_f32_e32 v4, v4, v13
	v_add_f32_e32 v13, v14, v4
	v_sub_f32_e32 v14, v13, v14
	v_sub_f32_e32 v4, v4, v14
	v_add_f32_e32 v14, v5, v13
	v_sub_f32_e32 v15, v14, v5
	v_sub_f32_e32 v16, v14, v15
	v_sub_f32_e32 v9, v17, v9
	v_sub_f32_e32 v5, v5, v16
	v_sub_f32_e32 v13, v13, v15
	v_add_f32_e32 v5, v13, v5
	v_add_f32_e32 v13, v9, v4
	v_sub_f32_e32 v15, v13, v9
	v_sub_f32_e32 v16, v13, v15
	v_sub_f32_e32 v9, v9, v16
	v_sub_f32_e32 v4, v4, v15
	v_add_f32_e32 v5, v13, v5
	v_add_f32_e32 v4, v4, v9
	v_add_f32_e32 v9, v14, v5
	v_sub_f32_e32 v13, v9, v14
	v_sub_f32_e32 v5, v5, v13
	v_add_f32_e32 v4, v4, v5
	v_add_f32_e32 v4, v9, v4
	v_cmp_neq_f32_e32 vcc, s6, v6
	s_nop 1
	v_cndmask_b32_e32 v4, v238, v4, vcc
	v_cmp_ngt_f32_e32 vcc, -1.0, v6
	s_nop 1
	v_cndmask_b32_e32 v4, v239, v4, vcc
	v_cmp_neq_f32_e32 vcc, -1.0, v6
	s_nop 1
	v_cndmask_b32_e32 v4, v240, v4, vcc
	v_cmp_lt_f32_e64 vcc, |v6|, s10
	s_nop 1
	v_cndmask_b32_e32 v4, v4, v6, vcc
	v_add_f32_e32 v4, v8, v4
	v_sub_f32_e32 v4, -0.5, v4
	v_mul_f32_e32 v4, 0x3fb8aa3b, v4
	v_exp_f32_e32 v5, v4
	v_mul_f32_e32 v4, 0xbfb8aa3b, v7
	v_exp_f32_e32 v4, v4
	ds_read_b128 v[6:9], v12 offset:208
	v_mul_f32_e32 v5, 0xbfb8aa3b, v5
	v_exp_f32_e32 v5, v5
	ds_write_b128 v75, v[2:5] offset:192
	ds_read_b128 v[2:5], v74 offset:208
	s_waitcnt lgkmcnt(0)
; template <int MODE, bool BIG = false> DI void gemm_tile(const Params& p, int tm, int tn, int kv, char* smem) {
;     ...
;   } else if constexpr (MODE == G_RWW) {
;     float4* W4 = (float4*)((float*)(p.ws + OFF_BUFA) + (size_t)m * 512 + col0);
;     const float4* w04 = (const float4*)(p.w0 + col0);
; #pragma unroll
;     for (int c4 = 0; c4 < 16; ++c4) {
;       float4 v = crow4[c4], ww = w04[c4];
;       float u[4] = {v.x + ww.x, v.y + ww.y, v.z + ww.z, v.w + ww.w};
; #pragma unroll
;       for (int e = 0; e < 4; ++e) {
;         const float z = -u[e];
;         const float sp = fmaxf(z, 0.f) + log1pf(__expf(-fabsf(z)));
;         u[e] = __expf(-__expf(-sp - 0.5f));
;       }
;       W4[c4] = make_float4(u[0], u[1], u[2], u[3]);
;     }
	v_add_f32_e32 v2, v6, v2
	v_mul_f32_e64 v6, |v2|, s7
	v_exp_f32_e32 v6, v6
	v_add_f32_e32 v4, v8, v4
	v_max_f32_e64 v8, -v2, 0
	v_add_f32_e32 v7, v7, v3
	v_add_f32_e32 v13, 1.0, v6
	v_add_f32_e32 v2, -1.0, v13
	v_sub_f32_e32 v3, v2, v13
	v_add_f32_e32 v3, 1.0, v3
	v_sub_f32_e32 v2, v6, v2
	v_add_f32_e32 v14, v2, v3
	v_frexp_mant_f32_e32 v2, v13
	v_cmp_gt_f32_e32 vcc, s8, v2
	v_cvt_f64_f32_e32 v[2:3], v13
	v_frexp_exp_i32_f64_e32 v2, v[2:3]
	v_subbrev_co_u32_e32 v2, vcc, 0, v2, vcc
	v_sub_u32_e32 v3, 0, v2
	v_ldexp_f32 v13, v13, v3
	v_ldexp_f32 v3, v14, v3
	v_add_f32_e32 v14, -1.0, v13
	v_add_f32_e32 v17, 1.0, v13
	v_add_f32_e32 v15, 1.0, v14
	v_add_f32_e32 v18, -1.0, v17
	v_sub_f32_e32 v15, v13, v15
	v_sub_f32_e32 v13, v13, v18
	v_add_f32_e32 v15, v3, v15
	v_add_f32_e32 v3, v3, v13
	v_add_f32_e32 v13, v17, v3
	v_rcp_f32_e32 v18, v13
	v_add_f32_e32 v16, v14, v15
	v_sub_f32_e32 v14, v16, v14
	v_sub_f32_e32 v14, v15, v14
	v_sub_f32_e32 v15, v13, v17
	v_sub_f32_e32 v3, v3, v15
	v_mul_f32_e32 v15, v16, v18
	v_mul_f32_e32 v17, v13, v15
	v_fma_f32 v19, v15, v13, -v17
	v_fmac_f32_e32 v19, v15, v3
	v_add_f32_e32 v20, v17, v19
	v_sub_f32_e32 v21, v16, v20
	v_sub_f32_e32 v16, v16, v21
	v_sub_f32_e32 v17, v20, v17
	v_sub_f32_e32 v16, v16, v20
	v_add_f32_e32 v14, v14, v16
	v_sub_f32_e32 v16, v17, v19
	v_add_f32_e32 v14, v16, v14
	v_add_f32_e32 v16, v21, v14
	v_mul_f32_e32 v17, v18, v16
	v_mul_f32_e32 v19, v13, v17
	v_fma_f32 v13, v17, v13, -v19
	v_fmac_f32_e32 v13, v17, v3
	v_sub_f32_e32 v3, v21, v16
	v_add_f32_e32 v3, v14, v3
	v_add_f32_e32 v14, v19, v13
	v_sub_f32_e32 v20, v16, v14
	v_sub_f32_e32 v16, v16, v20
	v_sub_f32_e32 v19, v14, v19
	v_sub_f32_e32 v14, v16, v14
	v_add_f32_e32 v3, v3, v14
	v_sub_f32_e32 v13, v19, v13
	v_cvt_f32_i32_e32 v2, v2
	v_add_f32_e32 v3, v13, v3
	v_add_f32_e32 v13, v15, v17
	v_add_f32_e32 v3, v20, v3
	v_sub_f32_e32 v14, v13, v15
	v_mul_f32_e32 v3, v18, v3
	v_sub_f32_e32 v14, v17, v14
	v_add_f32_e32 v3, v14, v3
	v_mul_f32_e32 v17, 0x3f317218, v2
	v_add_f32_e32 v14, v13, v3
	v_fma_f32 v18, v2, s9, -v17
	v_mul_f32_e32 v15, v14, v14
	v_fmac_f32_e32 v18, 0xb102e308, v2
	v_sub_f32_e32 v2, v14, v13
	v_fmamk_f32 v16, v15, 0x3e9b6dac, v231
	v_sub_f32_e32 v2, v3, v2
	v_add_f32_e32 v3, v17, v18
	v_fmaak_f32 v16, v15, v16, 0x3f2aaada
	v_sub_f32_e32 v13, v3, v17
	v_ldexp_f32 v17, v14, 1
	v_mul_f32_e32 v14, v14, v15
	v_mul_f32_e32 v14, v14, v16
	v_add_f32_e32 v15, v17, v14
	v_sub_f32_e32 v16, v15, v17
	v_ldexp_f32 v2, v2, 1
	v_sub_f32_e32 v14, v14, v16
	v_add_f32_e32 v2, v2, v14
	v_add_f32_e32 v14, v15, v2
	v_sub_f32_e32 v15, v14, v15
	v_sub_f32_e32 v2, v2, v15
	v_add_f32_e32 v15, v3, v14
	v_sub_f32_e32 v16, v15, v3
	v_sub_f32_e32 v17, v15, v16
	v_sub_f32_e32 v13, v18, v13
	v_sub_f32_e32 v3, v3, v17
	v_sub_f32_e32 v14, v14, v16
	v_add_f32_e32 v3, v14, v3
	v_add_f32_e32 v14, v13, v2
	v_sub_f32_e32 v16, v14, v13
	v_sub_f32_e32 v17, v14, v16
	v_sub_f32_e32 v13, v13, v17
	v_sub_f32_e32 v2, v2, v16
	v_add_f32_e32 v3, v14, v3
	v_add_f32_e32 v2, v2, v13
	v_add_f32_e32 v13, v15, v3
	v_sub_f32_e32 v14, v13, v15
	v_sub_f32_e32 v3, v3, v14
	v_add_f32_e32 v2, v2, v3
	v_add_f32_e32 v2, v13, v2
	v_cmp_neq_f32_e32 vcc, s6, v6
	v_mul_f32_e64 v3, |v7|, s7
	v_max_f32_e64 v7, -v7, 0
	v_cndmask_b32_e32 v2, v238, v2, vcc
	v_cmp_ngt_f32_e32 vcc, -1.0, v6
	s_nop 1
	v_cndmask_b32_e32 v2, v239, v2, vcc
	v_cmp_neq_f32_e32 vcc, -1.0, v6
	s_nop 1
	v_cndmask_b32_e32 v2, v240, v2, vcc
	v_cmp_lt_f32_e64 vcc, |v6|, s10
	s_nop 1
	v_cndmask_b32_e32 v2, v2, v6, vcc
	v_add_f32_e32 v2, v8, v2
	v_sub_f32_e32 v2, -0.5, v2
	v_mul_f32_e32 v2, 0x3fb8aa3b, v2
	v_exp_f32_e32 v6, v3
	v_exp_f32_e32 v2, v2
	v_add_f32_e32 v8, v9, v5
	v_add_f32_e32 v9, 1.0, v6
	v_mul_f32_e32 v5, 0xbfb8aa3b, v2
	v_add_f32_e32 v2, -1.0, v9
	v_sub_f32_e32 v3, v2, v9
	v_add_f32_e32 v3, 1.0, v3
	v_sub_f32_e32 v2, v6, v2
	v_add_f32_e32 v13, v2, v3
	v_frexp_mant_f32_e32 v2, v9
	v_cmp_gt_f32_e32 vcc, s8, v2
	v_cvt_f64_f32_e32 v[2:3], v9
	v_frexp_exp_i32_f64_e32 v2, v[2:3]
	v_subbrev_co_u32_e32 v2, vcc, 0, v2, vcc
	v_sub_u32_e32 v3, 0, v2
	v_ldexp_f32 v9, v9, v3
	v_ldexp_f32 v3, v13, v3
	v_add_f32_e32 v13, -1.0, v9
	v_add_f32_e32 v16, 1.0, v9
	v_add_f32_e32 v14, 1.0, v13
	v_add_f32_e32 v17, -1.0, v16
	v_sub_f32_e32 v14, v9, v14
	v_sub_f32_e32 v9, v9, v17
	v_add_f32_e32 v14, v3, v14
	v_add_f32_e32 v3, v3, v9
	v_add_f32_e32 v9, v16, v3
	v_rcp_f32_e32 v17, v9
	v_add_f32_e32 v15, v13, v14
	v_sub_f32_e32 v13, v15, v13
	v_sub_f32_e32 v13, v14, v13
	v_sub_f32_e32 v14, v9, v16
	v_sub_f32_e32 v3, v3, v14
	v_mul_f32_e32 v14, v15, v17
	v_mul_f32_e32 v16, v9, v14
	v_fma_f32 v18, v14, v9, -v16
	v_fmac_f32_e32 v18, v14, v3
	v_add_f32_e32 v19, v16, v18
	v_sub_f32_e32 v20, v15, v19
	v_sub_f32_e32 v15, v15, v20
	v_sub_f32_e32 v16, v19, v16
	v_sub_f32_e32 v15, v15, v19
	v_add_f32_e32 v13, v13, v15
	v_sub_f32_e32 v15, v16, v18
	v_add_f32_e32 v13, v15, v13
	v_add_f32_e32 v15, v20, v13
	v_mul_f32_e32 v16, v17, v15
	v_mul_f32_e32 v18, v9, v16
	v_fma_f32 v9, v16, v9, -v18
	v_fmac_f32_e32 v9, v16, v3
	v_sub_f32_e32 v3, v20, v15
	v_add_f32_e32 v3, v13, v3
	v_add_f32_e32 v13, v18, v9
	v_sub_f32_e32 v19, v15, v13
	v_sub_f32_e32 v15, v15, v19
	v_sub_f32_e32 v18, v13, v18
	v_sub_f32_e32 v13, v15, v13
	v_add_f32_e32 v3, v3, v13
	v_sub_f32_e32 v9, v18, v9
	v_cvt_f32_i32_e32 v2, v2
	v_add_f32_e32 v3, v9, v3
	v_add_f32_e32 v9, v14, v16
	v_add_f32_e32 v3, v19, v3
	v_sub_f32_e32 v13, v9, v14
	v_mul_f32_e32 v3, v17, v3
	v_sub_f32_e32 v13, v16, v13
	v_add_f32_e32 v3, v13, v3
	v_mul_f32_e32 v16, 0x3f317218, v2
	v_add_f32_e32 v13, v9, v3
	v_fma_f32 v17, v2, s9, -v16
	v_mul_f32_e32 v14, v13, v13
	v_fmac_f32_e32 v17, 0xb102e308, v2
; template <int MODE, bool BIG = false> DI void gemm_tile(const Params& p, int tm, int tn, int kv, char* smem) {
;     ...
;   } else if constexpr (MODE == G_RWW) {
;     float4* W4 = (float4*)((float*)(p.ws + OFF_BUFA) + (size_t)m * 512 + col0);
;     const float4* w04 = (const float4*)(p.w0 + col0);
; #pragma unroll
;     for (int c4 = 0; c4 < 16; ++c4) {
;       float4 v = crow4[c4], ww = w04[c4];
;       float u[4] = {v.x + ww.x, v.y + ww.y, v.z + ww.z, v.w + ww.w};
; #pragma unroll
;       for (int e = 0; e < 4; ++e) {
;         const float z = -u[e];
;         const float sp = fmaxf(z, 0.f) + log1pf(__expf(-fabsf(z)));
;         u[e] = __expf(-__expf(-sp - 0.5f));
;       }
;       W4[c4] = make_float4(u[0], u[1], u[2], u[3]);
;     }
	v_sub_f32_e32 v2, v13, v9
	v_fmamk_f32 v15, v14, 0x3e9b6dac, v231
	v_sub_f32_e32 v2, v3, v2
	v_add_f32_e32 v3, v16, v17
	v_fmaak_f32 v15, v14, v15, 0x3f2aaada
	v_sub_f32_e32 v9, v3, v16
	v_ldexp_f32 v16, v13, 1
	v_mul_f32_e32 v13, v13, v14
	v_mul_f32_e32 v13, v13, v15
	v_add_f32_e32 v14, v16, v13
	v_sub_f32_e32 v15, v14, v16
	v_ldexp_f32 v2, v2, 1
	v_sub_f32_e32 v13, v13, v15
	v_add_f32_e32 v2, v2, v13
	v_add_f32_e32 v13, v14, v2
	v_sub_f32_e32 v14, v13, v14
	v_sub_f32_e32 v2, v2, v14
	v_add_f32_e32 v14, v3, v13
	v_sub_f32_e32 v15, v14, v3
	v_sub_f32_e32 v16, v14, v15
	v_sub_f32_e32 v9, v17, v9
	v_sub_f32_e32 v3, v3, v16
	v_sub_f32_e32 v13, v13, v15
	v_add_f32_e32 v3, v13, v3
	v_add_f32_e32 v13, v9, v2
	v_sub_f32_e32 v15, v13, v9
	v_sub_f32_e32 v16, v13, v15
	v_sub_f32_e32 v9, v9, v16
	v_sub_f32_e32 v2, v2, v15
	v_add_f32_e32 v3, v13, v3
	v_add_f32_e32 v2, v2, v9
	v_add_f32_e32 v9, v14, v3
	v_sub_f32_e32 v13, v9, v14
	v_sub_f32_e32 v3, v3, v13
	v_add_f32_e32 v2, v2, v3
	v_add_f32_e32 v2, v9, v2
	v_cmp_neq_f32_e32 vcc, s6, v6
	s_nop 1
	v_cndmask_b32_e32 v2, v238, v2, vcc
	v_cmp_ngt_f32_e32 vcc, -1.0, v6
	s_nop 1
	v_cndmask_b32_e32 v2, v239, v2, vcc
	v_cmp_neq_f32_e32 vcc, -1.0, v6
	s_nop 1
	v_cndmask_b32_e32 v2, v240, v2, vcc
	v_cmp_lt_f32_e64 vcc, |v6|, s10
	s_nop 1
	v_cndmask_b32_e32 v2, v2, v6, vcc
	v_add_f32_e32 v2, v7, v2
	v_sub_f32_e32 v2, -0.5, v2
	v_mul_f32_e32 v2, 0x3fb8aa3b, v2
	v_exp_f32_e32 v3, v2
	v_mul_f32_e64 v2, |v4|, s7
	v_exp_f32_e32 v6, v2
	v_max_f32_e64 v7, -v4, 0
	v_exp_f32_e32 v2, v5
	v_mul_f32_e32 v3, 0xbfb8aa3b, v3
	v_add_f32_e32 v9, 1.0, v6
	v_add_f32_e32 v4, -1.0, v9
	v_sub_f32_e32 v5, v4, v9
	v_add_f32_e32 v5, 1.0, v5
	v_sub_f32_e32 v4, v6, v4
	v_add_f32_e32 v13, v4, v5
	v_frexp_mant_f32_e32 v4, v9
	v_cmp_gt_f32_e32 vcc, s8, v4
	v_cvt_f64_f32_e32 v[4:5], v9
	v_frexp_exp_i32_f64_e32 v4, v[4:5]
	v_subbrev_co_u32_e32 v4, vcc, 0, v4, vcc
	v_sub_u32_e32 v5, 0, v4
	v_ldexp_f32 v9, v9, v5
	v_ldexp_f32 v5, v13, v5
	v_add_f32_e32 v13, -1.0, v9
	v_add_f32_e32 v16, 1.0, v9
	v_add_f32_e32 v14, 1.0, v13
	v_add_f32_e32 v17, -1.0, v16
	v_sub_f32_e32 v14, v9, v14
	v_sub_f32_e32 v9, v9, v17
	v_add_f32_e32 v14, v5, v14
	v_add_f32_e32 v5, v5, v9
	v_add_f32_e32 v9, v16, v5
	v_rcp_f32_e32 v17, v9
	v_add_f32_e32 v15, v13, v14
	v_sub_f32_e32 v13, v15, v13
	v_sub_f32_e32 v13, v14, v13
	v_sub_f32_e32 v14, v9, v16
	v_sub_f32_e32 v5, v5, v14
	v_mul_f32_e32 v14, v15, v17
	v_mul_f32_e32 v16, v9, v14
	v_fma_f32 v18, v14, v9, -v16
	v_fmac_f32_e32 v18, v14, v5
	v_add_f32_e32 v19, v16, v18
	v_sub_f32_e32 v20, v15, v19
	v_sub_f32_e32 v15, v15, v20
	v_sub_f32_e32 v16, v19, v16
	v_sub_f32_e32 v15, v15, v19
	v_add_f32_e32 v13, v13, v15
	v_sub_f32_e32 v15, v16, v18
	v_add_f32_e32 v13, v15, v13
	v_add_f32_e32 v15, v20, v13
	v_mul_f32_e32 v16, v17, v15
	v_mul_f32_e32 v18, v9, v16
	v_fma_f32 v9, v16, v9, -v18
	v_fmac_f32_e32 v9, v16, v5
	v_sub_f32_e32 v5, v20, v15
	v_add_f32_e32 v5, v13, v5
	v_add_f32_e32 v13, v18, v9
	v_sub_f32_e32 v19, v15, v13
	v_sub_f32_e32 v15, v15, v19
	v_sub_f32_e32 v18, v13, v18
	v_sub_f32_e32 v13, v15, v13
	v_add_f32_e32 v5, v5, v13
	v_sub_f32_e32 v9, v18, v9
	v_cvt_f32_i32_e32 v4, v4
	v_add_f32_e32 v5, v9, v5
	v_add_f32_e32 v9, v14, v16
	v_add_f32_e32 v5, v19, v5
	v_sub_f32_e32 v13, v9, v14
	v_mul_f32_e32 v5, v17, v5
	v_sub_f32_e32 v13, v16, v13
	v_add_f32_e32 v5, v13, v5
	v_mul_f32_e32 v16, 0x3f317218, v4
	v_add_f32_e32 v13, v9, v5
	v_fma_f32 v17, v4, s9, -v16
	v_mul_f32_e32 v14, v13, v13
	v_fmac_f32_e32 v17, 0xb102e308, v4
	v_sub_f32_e32 v4, v13, v9
	v_fmamk_f32 v15, v14, 0x3e9b6dac, v231
	v_sub_f32_e32 v4, v5, v4
	v_add_f32_e32 v5, v16, v17
	v_fmaak_f32 v15, v14, v15, 0x3f2aaada
	v_sub_f32_e32 v9, v5, v16
	v_ldexp_f32 v16, v13, 1
	v_mul_f32_e32 v13, v13, v14
	v_mul_f32_e32 v13, v13, v15
	v_add_f32_e32 v14, v16, v13
	v_sub_f32_e32 v15, v14, v16
	v_ldexp_f32 v4, v4, 1
	v_sub_f32_e32 v13, v13, v15
	v_add_f32_e32 v4, v4, v13
	v_add_f32_e32 v13, v14, v4
	v_sub_f32_e32 v14, v13, v14
	v_sub_f32_e32 v4, v4, v14
	v_add_f32_e32 v14, v5, v13
	v_sub_f32_e32 v15, v14, v5
	v_sub_f32_e32 v16, v14, v15
	v_sub_f32_e32 v9, v17, v9
	v_sub_f32_e32 v5, v5, v16
	v_sub_f32_e32 v13, v13, v15
	v_add_f32_e32 v5, v13, v5
	v_add_f32_e32 v13, v9, v4
	v_sub_f32_e32 v15, v13, v9
	v_sub_f32_e32 v16, v13, v15
	v_sub_f32_e32 v9, v9, v16
	v_sub_f32_e32 v4, v4, v15
	v_add_f32_e32 v5, v13, v5
	v_add_f32_e32 v4, v4, v9
	v_add_f32_e32 v9, v14, v5
	v_sub_f32_e32 v13, v9, v14
	v_sub_f32_e32 v5, v5, v13
	v_add_f32_e32 v4, v4, v5
	v_add_f32_e32 v4, v9, v4
	v_cmp_neq_f32_e32 vcc, s6, v6
	v_mul_f32_e64 v5, |v8|, s7
	v_max_f32_e64 v8, -v8, 0
	v_cndmask_b32_e32 v4, v238, v4, vcc
	v_cmp_ngt_f32_e32 vcc, -1.0, v6
	v_exp_f32_e32 v3, v3
	s_nop 0
	v_cndmask_b32_e32 v4, v239, v4, vcc
	v_cmp_neq_f32_e32 vcc, -1.0, v6
	s_nop 1
	v_cndmask_b32_e32 v4, v240, v4, vcc
	v_cmp_lt_f32_e64 vcc, |v6|, s10
	s_nop 1
	v_cndmask_b32_e32 v4, v4, v6, vcc
	v_exp_f32_e32 v6, v5
	v_add_f32_e32 v4, v7, v4
	v_sub_f32_e32 v4, -0.5, v4
	v_mul_f32_e32 v4, 0x3fb8aa3b, v4
	v_add_f32_e32 v9, 1.0, v6
	v_exp_f32_e32 v7, v4
	v_add_f32_e32 v4, -1.0, v9
	v_sub_f32_e32 v5, v4, v9
	v_add_f32_e32 v5, 1.0, v5
	v_sub_f32_e32 v4, v6, v4
	v_add_f32_e32 v13, v4, v5
	v_frexp_mant_f32_e32 v4, v9
	v_cmp_gt_f32_e32 vcc, s8, v4
	v_cvt_f64_f32_e32 v[4:5], v9
	v_frexp_exp_i32_f64_e32 v4, v[4:5]
	v_subbrev_co_u32_e32 v4, vcc, 0, v4, vcc
	v_sub_u32_e32 v5, 0, v4
	v_ldexp_f32 v9, v9, v5
	v_ldexp_f32 v5, v13, v5
	v_add_f32_e32 v13, -1.0, v9
	v_add_f32_e32 v16, 1.0, v9
	v_add_f32_e32 v14, 1.0, v13
	v_add_f32_e32 v17, -1.0, v16
	v_sub_f32_e32 v14, v9, v14
	v_sub_f32_e32 v9, v9, v17
	v_add_f32_e32 v14, v5, v14
	v_add_f32_e32 v5, v5, v9
; template <int MODE, bool BIG = false> DI void gemm_tile(const Params& p, int tm, int tn, int kv, char* smem) {
;     ...
;   } else if constexpr (MODE == G_RWW) {
;     float4* W4 = (float4*)((float*)(p.ws + OFF_BUFA) + (size_t)m * 512 + col0);
;     const float4* w04 = (const float4*)(p.w0 + col0);
; #pragma unroll
;     for (int c4 = 0; c4 < 16; ++c4) {
;       float4 v = crow4[c4], ww = w04[c4];
;       float u[4] = {v.x + ww.x, v.y + ww.y, v.z + ww.z, v.w + ww.w};
; #pragma unroll
;       for (int e = 0; e < 4; ++e) {
;         const float z = -u[e];
;         const float sp = fmaxf(z, 0.f) + log1pf(__expf(-fabsf(z)));
;         u[e] = __expf(-__expf(-sp - 0.5f));
;       }
;       W4[c4] = make_float4(u[0], u[1], u[2], u[3]);
;     }
	v_add_f32_e32 v9, v16, v5
	v_rcp_f32_e32 v17, v9
	v_add_f32_e32 v15, v13, v14
	v_sub_f32_e32 v13, v15, v13
	v_sub_f32_e32 v13, v14, v13
	v_sub_f32_e32 v14, v9, v16
	v_sub_f32_e32 v5, v5, v14
	v_mul_f32_e32 v14, v15, v17
	v_mul_f32_e32 v16, v9, v14
	v_fma_f32 v18, v14, v9, -v16
	v_fmac_f32_e32 v18, v14, v5
	v_add_f32_e32 v19, v16, v18
	v_sub_f32_e32 v20, v15, v19
	v_sub_f32_e32 v15, v15, v20
	v_sub_f32_e32 v16, v19, v16
	v_sub_f32_e32 v15, v15, v19
	v_add_f32_e32 v13, v13, v15
	v_sub_f32_e32 v15, v16, v18
	v_add_f32_e32 v13, v15, v13
	v_add_f32_e32 v15, v20, v13
	v_mul_f32_e32 v16, v17, v15
	v_mul_f32_e32 v18, v9, v16
	v_fma_f32 v9, v16, v9, -v18
	v_fmac_f32_e32 v9, v16, v5
	v_sub_f32_e32 v5, v20, v15
	v_add_f32_e32 v5, v13, v5
	v_add_f32_e32 v13, v18, v9
	v_sub_f32_e32 v19, v15, v13
	v_sub_f32_e32 v15, v15, v19
	v_sub_f32_e32 v18, v13, v18
	v_sub_f32_e32 v13, v15, v13
	v_add_f32_e32 v5, v5, v13
	v_sub_f32_e32 v9, v18, v9
	v_cvt_f32_i32_e32 v4, v4
	v_add_f32_e32 v5, v9, v5
	v_add_f32_e32 v9, v14, v16
	v_add_f32_e32 v5, v19, v5
	v_sub_f32_e32 v13, v9, v14
	v_mul_f32_e32 v5, v17, v5
	v_sub_f32_e32 v13, v16, v13
	v_add_f32_e32 v5, v13, v5
	v_mul_f32_e32 v16, 0x3f317218, v4
	v_add_f32_e32 v13, v9, v5
	v_fma_f32 v17, v4, s9, -v16
	v_mul_f32_e32 v14, v13, v13
	v_fmac_f32_e32 v17, 0xb102e308, v4
	v_sub_f32_e32 v4, v13, v9
	v_fmamk_f32 v15, v14, 0x3e9b6dac, v231
	v_sub_f32_e32 v4, v5, v4
	v_add_f32_e32 v5, v16, v17
	v_fmaak_f32 v15, v14, v15, 0x3f2aaada
	v_sub_f32_e32 v9, v5, v16
	v_ldexp_f32 v16, v13, 1
	v_mul_f32_e32 v13, v13, v14
	v_mul_f32_e32 v13, v13, v15
	v_add_f32_e32 v14, v16, v13
	v_sub_f32_e32 v15, v14, v16
	v_ldexp_f32 v4, v4, 1
	v_sub_f32_e32 v13, v13, v15
	v_add_f32_e32 v4, v4, v13
	v_add_f32_e32 v13, v14, v4
	v_sub_f32_e32 v14, v13, v14
	v_sub_f32_e32 v4, v4, v14
	v_add_f32_e32 v14, v5, v13
	v_sub_f32_e32 v15, v14, v5
	v_sub_f32_e32 v16, v14, v15
	v_sub_f32_e32 v9, v17, v9
	v_sub_f32_e32 v5, v5, v16
	v_sub_f32_e32 v13, v13, v15
	v_add_f32_e32 v5, v13, v5
	v_add_f32_e32 v13, v9, v4
	v_sub_f32_e32 v15, v13, v9
	v_sub_f32_e32 v16, v13, v15
	v_sub_f32_e32 v9, v9, v16
	v_sub_f32_e32 v4, v4, v15
	v_add_f32_e32 v5, v13, v5
	v_add_f32_e32 v4, v4, v9
	v_add_f32_e32 v9, v14, v5
	v_sub_f32_e32 v13, v9, v14
	v_sub_f32_e32 v5, v5, v13
	v_add_f32_e32 v4, v4, v5
	v_add_f32_e32 v4, v9, v4
	v_cmp_neq_f32_e32 vcc, s6, v6
	s_nop 1
	v_cndmask_b32_e32 v4, v238, v4, vcc
	v_cmp_ngt_f32_e32 vcc, -1.0, v6
	s_nop 1
	v_cndmask_b32_e32 v4, v239, v4, vcc
	v_cmp_neq_f32_e32 vcc, -1.0, v6
	s_nop 1
	v_cndmask_b32_e32 v4, v240, v4, vcc
	v_cmp_lt_f32_e64 vcc, |v6|, s10
	s_nop 1
	v_cndmask_b32_e32 v4, v4, v6, vcc
	v_add_f32_e32 v4, v8, v4
	v_sub_f32_e32 v4, -0.5, v4
	v_mul_f32_e32 v4, 0x3fb8aa3b, v4
	v_exp_f32_e32 v5, v4
	v_mul_f32_e32 v4, 0xbfb8aa3b, v7
	v_exp_f32_e32 v4, v4
	ds_read_b128 v[6:9], v12 offset:224
	v_mul_f32_e32 v5, 0xbfb8aa3b, v5
	v_exp_f32_e32 v5, v5
	ds_write_b128 v75, v[2:5] offset:208
	ds_read_b128 v[2:5], v74 offset:224
	s_waitcnt lgkmcnt(0)
	v_add_f32_e32 v2, v6, v2
	v_mul_f32_e64 v6, |v2|, s7
	v_exp_f32_e32 v6, v6
	v_add_f32_e32 v4, v8, v4
	v_max_f32_e64 v8, -v2, 0
	v_add_f32_e32 v7, v7, v3
	v_add_f32_e32 v13, 1.0, v6
	v_add_f32_e32 v2, -1.0, v13
	v_sub_f32_e32 v3, v2, v13
	v_add_f32_e32 v3, 1.0, v3
	v_sub_f32_e32 v2, v6, v2
	v_add_f32_e32 v14, v2, v3
	v_frexp_mant_f32_e32 v2, v13
	v_cmp_gt_f32_e32 vcc, s8, v2
	v_cvt_f64_f32_e32 v[2:3], v13
	v_frexp_exp_i32_f64_e32 v2, v[2:3]
	v_subbrev_co_u32_e32 v2, vcc, 0, v2, vcc
	v_sub_u32_e32 v3, 0, v2
	v_ldexp_f32 v13, v13, v3
	v_ldexp_f32 v3, v14, v3
	v_add_f32_e32 v14, -1.0, v13
	v_add_f32_e32 v17, 1.0, v13
	v_add_f32_e32 v15, 1.0, v14
	v_add_f32_e32 v18, -1.0, v17
	v_sub_f32_e32 v15, v13, v15
	v_sub_f32_e32 v13, v13, v18
	v_add_f32_e32 v15, v3, v15
	v_add_f32_e32 v3, v3, v13
	v_add_f32_e32 v13, v17, v3
	v_rcp_f32_e32 v18, v13
	v_add_f32_e32 v16, v14, v15
	v_sub_f32_e32 v14, v16, v14
	v_sub_f32_e32 v14, v15, v14
	v_sub_f32_e32 v15, v13, v17
	v_sub_f32_e32 v3, v3, v15
	v_mul_f32_e32 v15, v16, v18
	v_mul_f32_e32 v17, v13, v15
	v_fma_f32 v19, v15, v13, -v17
	v_fmac_f32_e32 v19, v15, v3
	v_add_f32_e32 v20, v17, v19
	v_sub_f32_e32 v21, v16, v20
	v_sub_f32_e32 v16, v16, v21
	v_sub_f32_e32 v17, v20, v17
	v_sub_f32_e32 v16, v16, v20
	v_add_f32_e32 v14, v14, v16
	v_sub_f32_e32 v16, v17, v19
	v_add_f32_e32 v14, v16, v14
	v_add_f32_e32 v16, v21, v14
	v_mul_f32_e32 v17, v18, v16
	v_mul_f32_e32 v19, v13, v17
	v_fma_f32 v13, v17, v13, -v19
	v_fmac_f32_e32 v13, v17, v3
	v_sub_f32_e32 v3, v21, v16
	v_add_f32_e32 v3, v14, v3
	v_add_f32_e32 v14, v19, v13
	v_sub_f32_e32 v20, v16, v14
	v_sub_f32_e32 v16, v16, v20
	v_sub_f32_e32 v19, v14, v19
	v_sub_f32_e32 v14, v16, v14
	v_add_f32_e32 v3, v3, v14
	v_sub_f32_e32 v13, v19, v13
	v_cvt_f32_i32_e32 v2, v2
	v_add_f32_e32 v3, v13, v3
	v_add_f32_e32 v13, v15, v17
	v_add_f32_e32 v3, v20, v3
	v_sub_f32_e32 v14, v13, v15
	v_mul_f32_e32 v3, v18, v3
	v_sub_f32_e32 v14, v17, v14
	v_add_f32_e32 v3, v14, v3
	v_mul_f32_e32 v17, 0x3f317218, v2
	v_add_f32_e32 v14, v13, v3
	v_fma_f32 v18, v2, s9, -v17
	v_mul_f32_e32 v15, v14, v14
	v_fmac_f32_e32 v18, 0xb102e308, v2
	v_sub_f32_e32 v2, v14, v13
	v_fmamk_f32 v16, v15, 0x3e9b6dac, v231
	v_sub_f32_e32 v2, v3, v2
	v_add_f32_e32 v3, v17, v18
	v_fmaak_f32 v16, v15, v16, 0x3f2aaada
	v_sub_f32_e32 v13, v3, v17
	v_ldexp_f32 v17, v14, 1
	v_mul_f32_e32 v14, v14, v15
	v_mul_f32_e32 v14, v14, v16
	v_add_f32_e32 v15, v17, v14
	v_sub_f32_e32 v16, v15, v17
	v_ldexp_f32 v2, v2, 1
	v_sub_f32_e32 v14, v14, v16
	v_add_f32_e32 v2, v2, v14
	v_add_f32_e32 v14, v15, v2
	v_sub_f32_e32 v15, v14, v15
	v_sub_f32_e32 v2, v2, v15
	v_add_f32_e32 v15, v3, v14
; template <int MODE, bool BIG = false> DI void gemm_tile(const Params& p, int tm, int tn, int kv, char* smem) {
;     ...
;   } else if constexpr (MODE == G_RWW) {
;     float4* W4 = (float4*)((float*)(p.ws + OFF_BUFA) + (size_t)m * 512 + col0);
;     const float4* w04 = (const float4*)(p.w0 + col0);
; #pragma unroll
;     for (int c4 = 0; c4 < 16; ++c4) {
;       float4 v = crow4[c4], ww = w04[c4];
;       float u[4] = {v.x + ww.x, v.y + ww.y, v.z + ww.z, v.w + ww.w};
; #pragma unroll
;       for (int e = 0; e < 4; ++e) {
;         const float z = -u[e];
;         const float sp = fmaxf(z, 0.f) + log1pf(__expf(-fabsf(z)));
;         u[e] = __expf(-__expf(-sp - 0.5f));
;       }
;       W4[c4] = make_float4(u[0], u[1], u[2], u[3]);
;     }
	v_sub_f32_e32 v16, v15, v3
	v_sub_f32_e32 v17, v15, v16
	v_sub_f32_e32 v13, v18, v13
	v_sub_f32_e32 v3, v3, v17
	v_sub_f32_e32 v14, v14, v16
	v_add_f32_e32 v3, v14, v3
	v_add_f32_e32 v14, v13, v2
	v_sub_f32_e32 v16, v14, v13
	v_sub_f32_e32 v17, v14, v16
	v_sub_f32_e32 v13, v13, v17
	v_sub_f32_e32 v2, v2, v16
	v_add_f32_e32 v3, v14, v3
	v_add_f32_e32 v2, v2, v13
	v_add_f32_e32 v13, v15, v3
	v_sub_f32_e32 v14, v13, v15
	v_sub_f32_e32 v3, v3, v14
	v_add_f32_e32 v2, v2, v3
	v_add_f32_e32 v2, v13, v2
	v_cmp_neq_f32_e32 vcc, s6, v6
	v_mul_f32_e64 v3, |v7|, s7
	v_max_f32_e64 v7, -v7, 0
	v_cndmask_b32_e32 v2, v238, v2, vcc
	v_cmp_ngt_f32_e32 vcc, -1.0, v6
	s_nop 1
	v_cndmask_b32_e32 v2, v239, v2, vcc
	v_cmp_neq_f32_e32 vcc, -1.0, v6
	s_nop 1
	v_cndmask_b32_e32 v2, v240, v2, vcc
	v_cmp_lt_f32_e64 vcc, |v6|, s10
	s_nop 1
	v_cndmask_b32_e32 v2, v2, v6, vcc
	v_add_f32_e32 v2, v8, v2
	v_sub_f32_e32 v2, -0.5, v2
	v_mul_f32_e32 v2, 0x3fb8aa3b, v2
	v_exp_f32_e32 v6, v3
	v_exp_f32_e32 v2, v2
	v_add_f32_e32 v8, v9, v5
	v_add_f32_e32 v9, 1.0, v6
	v_mul_f32_e32 v5, 0xbfb8aa3b, v2
	v_add_f32_e32 v2, -1.0, v9
	v_sub_f32_e32 v3, v2, v9
	v_add_f32_e32 v3, 1.0, v3
	v_sub_f32_e32 v2, v6, v2
	v_add_f32_e32 v13, v2, v3
	v_frexp_mant_f32_e32 v2, v9
	v_cmp_gt_f32_e32 vcc, s8, v2
	v_cvt_f64_f32_e32 v[2:3], v9
	v_frexp_exp_i32_f64_e32 v2, v[2:3]
	v_subbrev_co_u32_e32 v2, vcc, 0, v2, vcc
	v_sub_u32_e32 v3, 0, v2
	v_ldexp_f32 v9, v9, v3
	v_ldexp_f32 v3, v13, v3
	v_add_f32_e32 v13, -1.0, v9
	v_add_f32_e32 v16, 1.0, v9
	v_add_f32_e32 v14, 1.0, v13
	v_add_f32_e32 v17, -1.0, v16
	v_sub_f32_e32 v14, v9, v14
	v_sub_f32_e32 v9, v9, v17
	v_add_f32_e32 v14, v3, v14
	v_add_f32_e32 v3, v3, v9
	v_add_f32_e32 v9, v16, v3
	v_rcp_f32_e32 v17, v9
	v_add_f32_e32 v15, v13, v14
	v_sub_f32_e32 v13, v15, v13
	v_sub_f32_e32 v13, v14, v13
	v_sub_f32_e32 v14, v9, v16
	v_sub_f32_e32 v3, v3, v14
	v_mul_f32_e32 v14, v15, v17
	v_mul_f32_e32 v16, v9, v14
	v_fma_f32 v18, v14, v9, -v16
	v_fmac_f32_e32 v18, v14, v3
	v_add_f32_e32 v19, v16, v18
	v_sub_f32_e32 v20, v15, v19
	v_sub_f32_e32 v15, v15, v20
	v_sub_f32_e32 v16, v19, v16
	v_sub_f32_e32 v15, v15, v19
	v_add_f32_e32 v13, v13, v15
	v_sub_f32_e32 v15, v16, v18
	v_add_f32_e32 v13, v15, v13
	v_add_f32_e32 v15, v20, v13
	v_mul_f32_e32 v16, v17, v15
	v_mul_f32_e32 v18, v9, v16
	v_fma_f32 v9, v16, v9, -v18
	v_fmac_f32_e32 v9, v16, v3
	v_sub_f32_e32 v3, v20, v15
	v_add_f32_e32 v3, v13, v3
	v_add_f32_e32 v13, v18, v9
	v_sub_f32_e32 v19, v15, v13
	v_sub_f32_e32 v15, v15, v19
	v_sub_f32_e32 v18, v13, v18
	v_sub_f32_e32 v13, v15, v13
	v_add_f32_e32 v3, v3, v13
	v_sub_f32_e32 v9, v18, v9
	v_cvt_f32_i32_e32 v2, v2
	v_add_f32_e32 v3, v9, v3
	v_add_f32_e32 v9, v14, v16
	v_add_f32_e32 v3, v19, v3
	v_sub_f32_e32 v13, v9, v14
	v_mul_f32_e32 v3, v17, v3
	v_sub_f32_e32 v13, v16, v13
	v_add_f32_e32 v3, v13, v3
	v_mul_f32_e32 v16, 0x3f317218, v2
	v_add_f32_e32 v13, v9, v3
	v_fma_f32 v17, v2, s9, -v16
	v_mul_f32_e32 v14, v13, v13
	v_fmac_f32_e32 v17, 0xb102e308, v2
	v_sub_f32_e32 v2, v13, v9
	v_fmamk_f32 v15, v14, 0x3e9b6dac, v231
	v_sub_f32_e32 v2, v3, v2
	v_add_f32_e32 v3, v16, v17
	v_fmaak_f32 v15, v14, v15, 0x3f2aaada
	v_sub_f32_e32 v9, v3, v16
	v_ldexp_f32 v16, v13, 1
	v_mul_f32_e32 v13, v13, v14
	v_mul_f32_e32 v13, v13, v15
	v_add_f32_e32 v14, v16, v13
	v_sub_f32_e32 v15, v14, v16
	v_ldexp_f32 v2, v2, 1
	v_sub_f32_e32 v13, v13, v15
	v_add_f32_e32 v2, v2, v13
	v_add_f32_e32 v13, v14, v2
	v_sub_f32_e32 v14, v13, v14
	v_sub_f32_e32 v2, v2, v14
	v_add_f32_e32 v14, v3, v13
	v_sub_f32_e32 v15, v14, v3
	v_sub_f32_e32 v16, v14, v15
	v_sub_f32_e32 v9, v17, v9
	v_sub_f32_e32 v3, v3, v16
	v_sub_f32_e32 v13, v13, v15
	v_add_f32_e32 v3, v13, v3
	v_add_f32_e32 v13, v9, v2
	v_sub_f32_e32 v15, v13, v9
	v_sub_f32_e32 v16, v13, v15
	v_sub_f32_e32 v9, v9, v16
	v_sub_f32_e32 v2, v2, v15
	v_add_f32_e32 v3, v13, v3
	v_add_f32_e32 v2, v2, v9
	v_add_f32_e32 v9, v14, v3
	v_sub_f32_e32 v13, v9, v14
	v_sub_f32_e32 v3, v3, v13
	v_add_f32_e32 v2, v2, v3
	v_add_f32_e32 v2, v9, v2
	v_cmp_neq_f32_e32 vcc, s6, v6
	s_nop 1
	v_cndmask_b32_e32 v2, v238, v2, vcc
	v_cmp_ngt_f32_e32 vcc, -1.0, v6
	s_nop 1
	v_cndmask_b32_e32 v2, v239, v2, vcc
	v_cmp_neq_f32_e32 vcc, -1.0, v6
	s_nop 1
	v_cndmask_b32_e32 v2, v240, v2, vcc
	v_cmp_lt_f32_e64 vcc, |v6|, s10
	s_nop 1
	v_cndmask_b32_e32 v2, v2, v6, vcc
	v_add_f32_e32 v2, v7, v2
	v_sub_f32_e32 v2, -0.5, v2
	v_mul_f32_e32 v2, 0x3fb8aa3b, v2
	v_exp_f32_e32 v3, v2
	v_mul_f32_e64 v2, |v4|, s7
	v_exp_f32_e32 v6, v2
	v_max_f32_e64 v7, -v4, 0
	v_exp_f32_e32 v2, v5
	v_mul_f32_e32 v3, 0xbfb8aa3b, v3
	v_add_f32_e32 v9, 1.0, v6
	v_add_f32_e32 v4, -1.0, v9
	v_sub_f32_e32 v5, v4, v9
	v_add_f32_e32 v5, 1.0, v5
	v_sub_f32_e32 v4, v6, v4
	v_add_f32_e32 v13, v4, v5
	v_frexp_mant_f32_e32 v4, v9
	v_cmp_gt_f32_e32 vcc, s8, v4
	v_cvt_f64_f32_e32 v[4:5], v9
	v_frexp_exp_i32_f64_e32 v4, v[4:5]
	v_subbrev_co_u32_e32 v4, vcc, 0, v4, vcc
	v_sub_u32_e32 v5, 0, v4
	v_ldexp_f32 v9, v9, v5
	v_ldexp_f32 v5, v13, v5
	v_add_f32_e32 v13, -1.0, v9
	v_add_f32_e32 v16, 1.0, v9
	v_add_f32_e32 v14, 1.0, v13
	v_add_f32_e32 v17, -1.0, v16
	v_sub_f32_e32 v14, v9, v14
	v_sub_f32_e32 v9, v9, v17
	v_add_f32_e32 v14, v5, v14
	v_add_f32_e32 v5, v5, v9
	v_add_f32_e32 v9, v16, v5
	v_rcp_f32_e32 v17, v9
	v_add_f32_e32 v15, v13, v14
	v_sub_f32_e32 v13, v15, v13
	v_sub_f32_e32 v13, v14, v13
	v_sub_f32_e32 v14, v9, v16
	v_sub_f32_e32 v5, v5, v14
	v_mul_f32_e32 v14, v15, v17
	v_mul_f32_e32 v16, v9, v14
	v_fma_f32 v18, v14, v9, -v16
	v_fmac_f32_e32 v18, v14, v5
	v_add_f32_e32 v19, v16, v18
	v_sub_f32_e32 v20, v15, v19
	v_sub_f32_e32 v15, v15, v20
	v_sub_f32_e32 v16, v19, v16
	v_sub_f32_e32 v15, v15, v19
; template <int MODE, bool BIG = false> DI void gemm_tile(const Params& p, int tm, int tn, int kv, char* smem) {
;     ...
;   } else if constexpr (MODE == G_RWW) {
;     float4* W4 = (float4*)((float*)(p.ws + OFF_BUFA) + (size_t)m * 512 + col0);
;     const float4* w04 = (const float4*)(p.w0 + col0);
; #pragma unroll
;     for (int c4 = 0; c4 < 16; ++c4) {
;       float4 v = crow4[c4], ww = w04[c4];
;       float u[4] = {v.x + ww.x, v.y + ww.y, v.z + ww.z, v.w + ww.w};
; #pragma unroll
;       for (int e = 0; e < 4; ++e) {
;         const float z = -u[e];
;         const float sp = fmaxf(z, 0.f) + log1pf(__expf(-fabsf(z)));
;         u[e] = __expf(-__expf(-sp - 0.5f));
;       }
;       W4[c4] = make_float4(u[0], u[1], u[2], u[3]);
;     }
	v_add_f32_e32 v13, v13, v15
	v_sub_f32_e32 v15, v16, v18
	v_add_f32_e32 v13, v15, v13
	v_add_f32_e32 v15, v20, v13
	v_mul_f32_e32 v16, v17, v15
	v_mul_f32_e32 v18, v9, v16
	v_fma_f32 v9, v16, v9, -v18
	v_fmac_f32_e32 v9, v16, v5
	v_sub_f32_e32 v5, v20, v15
	v_add_f32_e32 v5, v13, v5
	v_add_f32_e32 v13, v18, v9
	v_sub_f32_e32 v19, v15, v13
	v_sub_f32_e32 v15, v15, v19
	v_sub_f32_e32 v18, v13, v18
	v_sub_f32_e32 v13, v15, v13
	v_add_f32_e32 v5, v5, v13
	v_sub_f32_e32 v9, v18, v9
	v_cvt_f32_i32_e32 v4, v4
	v_add_f32_e32 v5, v9, v5
	v_add_f32_e32 v9, v14, v16
	v_add_f32_e32 v5, v19, v5
	v_sub_f32_e32 v13, v9, v14
	v_mul_f32_e32 v5, v17, v5
	v_sub_f32_e32 v13, v16, v13
	v_add_f32_e32 v5, v13, v5
	v_mul_f32_e32 v16, 0x3f317218, v4
	v_add_f32_e32 v13, v9, v5
	v_fma_f32 v17, v4, s9, -v16
	v_mul_f32_e32 v14, v13, v13
	v_fmac_f32_e32 v17, 0xb102e308, v4
	v_sub_f32_e32 v4, v13, v9
	v_fmamk_f32 v15, v14, 0x3e9b6dac, v231
	v_sub_f32_e32 v4, v5, v4
	v_add_f32_e32 v5, v16, v17
	v_fmaak_f32 v15, v14, v15, 0x3f2aaada
	v_sub_f32_e32 v9, v5, v16
	v_ldexp_f32 v16, v13, 1
	v_mul_f32_e32 v13, v13, v14
	v_mul_f32_e32 v13, v13, v15
	v_add_f32_e32 v14, v16, v13
	v_sub_f32_e32 v15, v14, v16
	v_ldexp_f32 v4, v4, 1
	v_sub_f32_e32 v13, v13, v15
	v_add_f32_e32 v4, v4, v13
	v_add_f32_e32 v13, v14, v4
	v_sub_f32_e32 v14, v13, v14
	v_sub_f32_e32 v4, v4, v14
	v_add_f32_e32 v14, v5, v13
	v_sub_f32_e32 v15, v14, v5
	v_sub_f32_e32 v16, v14, v15
	v_sub_f32_e32 v9, v17, v9
	v_sub_f32_e32 v5, v5, v16
	v_sub_f32_e32 v13, v13, v15
	v_add_f32_e32 v5, v13, v5
	v_add_f32_e32 v13, v9, v4
	v_sub_f32_e32 v15, v13, v9
	v_sub_f32_e32 v16, v13, v15
	v_sub_f32_e32 v9, v9, v16
	v_sub_f32_e32 v4, v4, v15
	v_add_f32_e32 v5, v13, v5
	v_add_f32_e32 v4, v4, v9
	v_add_f32_e32 v9, v14, v5
	v_sub_f32_e32 v13, v9, v14
	v_sub_f32_e32 v5, v5, v13
	v_add_f32_e32 v4, v4, v5
	v_add_f32_e32 v4, v9, v4
	v_cmp_neq_f32_e32 vcc, s6, v6
	v_mul_f32_e64 v5, |v8|, s7
	v_max_f32_e64 v8, -v8, 0
	v_cndmask_b32_e32 v4, v238, v4, vcc
	v_cmp_ngt_f32_e32 vcc, -1.0, v6
	v_exp_f32_e32 v3, v3
	s_nop 0
	v_cndmask_b32_e32 v4, v239, v4, vcc
	v_cmp_neq_f32_e32 vcc, -1.0, v6
	s_nop 1
	v_cndmask_b32_e32 v4, v240, v4, vcc
	v_cmp_lt_f32_e64 vcc, |v6|, s10
	s_nop 1
	v_cndmask_b32_e32 v4, v4, v6, vcc
	v_exp_f32_e32 v6, v5
	v_add_f32_e32 v4, v7, v4
	v_sub_f32_e32 v4, -0.5, v4
	v_mul_f32_e32 v4, 0x3fb8aa3b, v4
	v_add_f32_e32 v9, 1.0, v6
	v_exp_f32_e32 v7, v4
	v_add_f32_e32 v4, -1.0, v9
	v_sub_f32_e32 v5, v4, v9
	v_add_f32_e32 v5, 1.0, v5
	v_sub_f32_e32 v4, v6, v4
	v_add_f32_e32 v13, v4, v5
	v_frexp_mant_f32_e32 v4, v9
	v_cmp_gt_f32_e32 vcc, s8, v4
	v_cvt_f64_f32_e32 v[4:5], v9
	v_frexp_exp_i32_f64_e32 v4, v[4:5]
	v_subbrev_co_u32_e32 v4, vcc, 0, v4, vcc
	v_sub_u32_e32 v5, 0, v4
	v_ldexp_f32 v9, v9, v5
	v_ldexp_f32 v5, v13, v5
	v_add_f32_e32 v13, -1.0, v9
	v_add_f32_e32 v16, 1.0, v9
	v_add_f32_e32 v14, 1.0, v13
	v_add_f32_e32 v17, -1.0, v16
	v_sub_f32_e32 v14, v9, v14
	v_sub_f32_e32 v9, v9, v17
	v_add_f32_e32 v14, v5, v14
	v_add_f32_e32 v5, v5, v9
	v_add_f32_e32 v9, v16, v5
	v_rcp_f32_e32 v17, v9
	v_add_f32_e32 v15, v13, v14
	v_sub_f32_e32 v13, v15, v13
	v_sub_f32_e32 v13, v14, v13
	v_sub_f32_e32 v14, v9, v16
	v_sub_f32_e32 v5, v5, v14
	v_mul_f32_e32 v14, v15, v17
	v_mul_f32_e32 v16, v9, v14
	v_fma_f32 v18, v14, v9, -v16
	v_fmac_f32_e32 v18, v14, v5
	v_add_f32_e32 v19, v16, v18
	v_sub_f32_e32 v20, v15, v19
	v_sub_f32_e32 v15, v15, v20
	v_sub_f32_e32 v16, v19, v16
	v_sub_f32_e32 v15, v15, v19
	v_add_f32_e32 v13, v13, v15
	v_sub_f32_e32 v15, v16, v18
	v_add_f32_e32 v13, v15, v13
	v_add_f32_e32 v15, v20, v13
	v_mul_f32_e32 v16, v17, v15
	v_mul_f32_e32 v18, v9, v16
	v_fma_f32 v9, v16, v9, -v18
	v_fmac_f32_e32 v9, v16, v5
	v_sub_f32_e32 v5, v20, v15
	v_add_f32_e32 v5, v13, v5
	v_add_f32_e32 v13, v18, v9
	v_sub_f32_e32 v19, v15, v13
	v_sub_f32_e32 v15, v15, v19
	v_sub_f32_e32 v18, v13, v18
	v_sub_f32_e32 v13, v15, v13
	v_add_f32_e32 v5, v5, v13
	v_sub_f32_e32 v9, v18, v9
	v_cvt_f32_i32_e32 v4, v4
	v_add_f32_e32 v5, v9, v5
	v_add_f32_e32 v9, v14, v16
	v_add_f32_e32 v5, v19, v5
	v_sub_f32_e32 v13, v9, v14
	v_mul_f32_e32 v5, v17, v5
	v_sub_f32_e32 v13, v16, v13
	v_add_f32_e32 v5, v13, v5
	v_mul_f32_e32 v16, 0x3f317218, v4
	v_add_f32_e32 v13, v9, v5
	v_fma_f32 v17, v4, s9, -v16
	v_mul_f32_e32 v14, v13, v13
	v_fmac_f32_e32 v17, 0xb102e308, v4
	v_sub_f32_e32 v4, v13, v9
	v_fmamk_f32 v15, v14, 0x3e9b6dac, v231
	v_sub_f32_e32 v4, v5, v4
	v_add_f32_e32 v5, v16, v17
	v_fmaak_f32 v15, v14, v15, 0x3f2aaada
	v_sub_f32_e32 v9, v5, v16
	v_ldexp_f32 v16, v13, 1
	v_mul_f32_e32 v13, v13, v14
	v_mul_f32_e32 v13, v13, v15
	v_add_f32_e32 v14, v16, v13
	v_sub_f32_e32 v15, v14, v16
	v_ldexp_f32 v4, v4, 1
	v_sub_f32_e32 v13, v13, v15
	v_add_f32_e32 v4, v4, v13
	v_add_f32_e32 v13, v14, v4
	v_sub_f32_e32 v14, v13, v14
	v_sub_f32_e32 v4, v4, v14
	v_add_f32_e32 v14, v5, v13
	v_sub_f32_e32 v15, v14, v5
	v_sub_f32_e32 v16, v14, v15
	v_sub_f32_e32 v9, v17, v9
	v_sub_f32_e32 v5, v5, v16
	v_sub_f32_e32 v13, v13, v15
	v_add_f32_e32 v5, v13, v5
	v_add_f32_e32 v13, v9, v4
	v_sub_f32_e32 v15, v13, v9
	v_sub_f32_e32 v16, v13, v15
	v_sub_f32_e32 v9, v9, v16
	v_sub_f32_e32 v4, v4, v15
	v_add_f32_e32 v5, v13, v5
	v_add_f32_e32 v4, v4, v9
	v_add_f32_e32 v9, v14, v5
	v_sub_f32_e32 v13, v9, v14
	v_sub_f32_e32 v5, v5, v13
	v_add_f32_e32 v4, v4, v5
	v_add_f32_e32 v4, v9, v4
	v_cmp_neq_f32_e32 vcc, s6, v6
	s_nop 1
	v_cndmask_b32_e32 v4, v238, v4, vcc
	v_cmp_ngt_f32_e32 vcc, -1.0, v6
	s_nop 1
	v_cndmask_b32_e32 v4, v239, v4, vcc
	v_cmp_neq_f32_e32 vcc, -1.0, v6
	s_nop 1
	v_cndmask_b32_e32 v4, v240, v4, vcc
	v_cmp_lt_f32_e64 vcc, |v6|, s10
	s_nop 1
	v_cndmask_b32_e32 v4, v4, v6, vcc
	v_add_f32_e32 v4, v8, v4
	v_sub_f32_e32 v4, -0.5, v4
	v_mul_f32_e32 v4, 0x3fb8aa3b, v4
	v_exp_f32_e32 v5, v4
	v_mul_f32_e32 v4, 0xbfb8aa3b, v7
	v_exp_f32_e32 v4, v4
	ds_read_b128 v[6:9], v12 offset:240
	v_mul_f32_e32 v5, 0xbfb8aa3b, v5
	v_exp_f32_e32 v5, v5
	ds_write_b128 v75, v[2:5] offset:224
	ds_read_b128 v[2:5], v74 offset:240
	s_waitcnt lgkmcnt(0)
; template <int MODE, bool BIG = false> DI void gemm_tile(const Params& p, int tm, int tn, int kv, char* smem) {
;     ...
;   } else if constexpr (MODE == G_RWW) {
;     float4* W4 = (float4*)((float*)(p.ws + OFF_BUFA) + (size_t)m * 512 + col0);
;     const float4* w04 = (const float4*)(p.w0 + col0);
; #pragma unroll
;     for (int c4 = 0; c4 < 16; ++c4) {
;       float4 v = crow4[c4], ww = w04[c4];
;       float u[4] = {v.x + ww.x, v.y + ww.y, v.z + ww.z, v.w + ww.w};
; #pragma unroll
;       for (int e = 0; e < 4; ++e) {
;         const float z = -u[e];
;         const float sp = fmaxf(z, 0.f) + log1pf(__expf(-fabsf(z)));
;         u[e] = __expf(-__expf(-sp - 0.5f));
;       }
;       W4[c4] = make_float4(u[0], u[1], u[2], u[3]);
;     }
	v_add_f32_e32 v0, v6, v2
	v_mul_f32_e64 v2, |v0|, s7
	v_exp_f32_e32 v6, v2
	v_add_f32_e32 v4, v8, v4
	v_add_f32_e32 v7, v7, v3
	v_max_f32_e64 v0, -v0, 0
	v_add_f32_e32 v8, 1.0, v6
	v_add_f32_e32 v2, -1.0, v8
	v_sub_f32_e32 v3, v2, v8
	v_add_f32_e32 v3, 1.0, v3
	v_sub_f32_e32 v2, v6, v2
	v_add_f32_e32 v12, v2, v3
	v_frexp_mant_f32_e32 v2, v8
	v_cmp_gt_f32_e32 vcc, s8, v2
	v_cvt_f64_f32_e32 v[2:3], v8
	v_frexp_exp_i32_f64_e32 v2, v[2:3]
	v_subbrev_co_u32_e32 v2, vcc, 0, v2, vcc
	v_sub_u32_e32 v3, 0, v2
	v_ldexp_f32 v8, v8, v3
	v_ldexp_f32 v3, v12, v3
	v_add_f32_e32 v12, -1.0, v8
	v_add_f32_e32 v15, 1.0, v8
	v_add_f32_e32 v13, 1.0, v12
	v_add_f32_e32 v16, -1.0, v15
	v_sub_f32_e32 v13, v8, v13
	v_sub_f32_e32 v8, v8, v16
	v_add_f32_e32 v13, v3, v13
	v_add_f32_e32 v3, v3, v8
	v_add_f32_e32 v8, v15, v3
	v_rcp_f32_e32 v16, v8
	v_add_f32_e32 v14, v12, v13
	v_sub_f32_e32 v12, v14, v12
	v_sub_f32_e32 v12, v13, v12
	v_sub_f32_e32 v13, v8, v15
	v_sub_f32_e32 v3, v3, v13
	v_mul_f32_e32 v13, v14, v16
	v_mul_f32_e32 v15, v8, v13
	v_fma_f32 v17, v13, v8, -v15
	v_fmac_f32_e32 v17, v13, v3
	v_add_f32_e32 v18, v15, v17
	v_sub_f32_e32 v19, v14, v18
	v_sub_f32_e32 v14, v14, v19
	v_sub_f32_e32 v15, v18, v15
	v_sub_f32_e32 v14, v14, v18
	v_add_f32_e32 v12, v12, v14
	v_sub_f32_e32 v14, v15, v17
	v_add_f32_e32 v12, v14, v12
	v_add_f32_e32 v14, v19, v12
	v_mul_f32_e32 v15, v16, v14
	v_mul_f32_e32 v17, v8, v15
	v_fma_f32 v8, v15, v8, -v17
	v_fmac_f32_e32 v8, v15, v3
	v_sub_f32_e32 v3, v19, v14
	v_add_f32_e32 v3, v12, v3
	v_add_f32_e32 v12, v17, v8
	v_sub_f32_e32 v18, v14, v12
	v_sub_f32_e32 v14, v14, v18
	v_sub_f32_e32 v17, v12, v17
	v_sub_f32_e32 v12, v14, v12
	v_add_f32_e32 v3, v3, v12
	v_sub_f32_e32 v8, v17, v8
	v_cvt_f32_i32_e32 v2, v2
	v_add_f32_e32 v3, v8, v3
	v_add_f32_e32 v8, v13, v15
	v_add_f32_e32 v3, v18, v3
	v_sub_f32_e32 v12, v8, v13
	v_mul_f32_e32 v3, v16, v3
	v_sub_f32_e32 v12, v15, v12
	v_add_f32_e32 v3, v12, v3
	v_mul_f32_e32 v15, 0x3f317218, v2
	v_add_f32_e32 v12, v8, v3
	v_fma_f32 v16, v2, s9, -v15
	v_mul_f32_e32 v13, v12, v12
	v_fmac_f32_e32 v16, 0xb102e308, v2
	v_sub_f32_e32 v2, v12, v8
	v_fmamk_f32 v14, v13, 0x3e9b6dac, v231
	v_sub_f32_e32 v2, v3, v2
	v_add_f32_e32 v3, v15, v16
	v_fmaak_f32 v14, v13, v14, 0x3f2aaada
	v_sub_f32_e32 v8, v3, v15
	v_ldexp_f32 v15, v12, 1
	v_mul_f32_e32 v12, v12, v13
	v_mul_f32_e32 v12, v12, v14
	v_add_f32_e32 v13, v15, v12
	v_sub_f32_e32 v14, v13, v15
	v_ldexp_f32 v2, v2, 1
	v_sub_f32_e32 v12, v12, v14
	v_add_f32_e32 v2, v2, v12
	v_add_f32_e32 v12, v13, v2
	v_sub_f32_e32 v13, v12, v13
	v_sub_f32_e32 v2, v2, v13
	v_add_f32_e32 v13, v3, v12
	v_sub_f32_e32 v14, v13, v3
	v_sub_f32_e32 v15, v13, v14
	v_sub_f32_e32 v8, v16, v8
	v_sub_f32_e32 v3, v3, v15
	v_sub_f32_e32 v12, v12, v14
	v_add_f32_e32 v3, v12, v3
	v_add_f32_e32 v12, v8, v2
	v_sub_f32_e32 v14, v12, v8
	v_sub_f32_e32 v15, v12, v14
	v_sub_f32_e32 v8, v8, v15
	v_sub_f32_e32 v2, v2, v14
	v_add_f32_e32 v3, v12, v3
	v_add_f32_e32 v2, v2, v8
	v_add_f32_e32 v8, v13, v3
	v_sub_f32_e32 v12, v8, v13
	v_sub_f32_e32 v3, v3, v12
	v_add_f32_e32 v2, v2, v3
	v_add_f32_e32 v2, v8, v2
	v_cmp_neq_f32_e32 vcc, s6, v6
	v_add_f32_e32 v8, v9, v5
	v_max_f32_e64 v5, -v7, 0
	v_cndmask_b32_e32 v2, v238, v2, vcc
	v_cmp_ngt_f32_e32 vcc, -1.0, v6
	s_nop 1
	v_cndmask_b32_e32 v2, v239, v2, vcc
	v_cmp_neq_f32_e32 vcc, -1.0, v6
	s_nop 1
	v_cndmask_b32_e32 v2, v240, v2, vcc
	v_cmp_lt_f32_e64 vcc, |v6|, s10
	s_nop 1
	v_cndmask_b32_e32 v2, v2, v6, vcc
	v_add_f32_e32 v0, v0, v2
	v_mul_f32_e64 v2, |v7|, s7
	v_exp_f32_e32 v6, v2
	v_sub_f32_e32 v0, -0.5, v0
	v_mul_f32_e32 v0, 0x3fb8aa3b, v0
	v_exp_f32_e32 v0, v0
	v_add_f32_e32 v7, 1.0, v6
	v_add_f32_e32 v2, -1.0, v7
	v_sub_f32_e32 v3, v2, v7
	v_add_f32_e32 v3, 1.0, v3
	v_sub_f32_e32 v2, v6, v2
	v_add_f32_e32 v9, v2, v3
	v_frexp_mant_f32_e32 v2, v7
	v_cmp_gt_f32_e32 vcc, s8, v2
	v_cvt_f64_f32_e32 v[2:3], v7
	v_frexp_exp_i32_f64_e32 v2, v[2:3]
	v_subbrev_co_u32_e32 v2, vcc, 0, v2, vcc
	v_sub_u32_e32 v3, 0, v2
	v_ldexp_f32 v7, v7, v3
	v_ldexp_f32 v3, v9, v3
	v_add_f32_e32 v9, -1.0, v7
	v_add_f32_e32 v14, 1.0, v7
	v_add_f32_e32 v12, 1.0, v9
	v_add_f32_e32 v15, -1.0, v14
	v_sub_f32_e32 v12, v7, v12
	v_sub_f32_e32 v7, v7, v15
	v_add_f32_e32 v12, v3, v12
	v_add_f32_e32 v3, v3, v7
	v_add_f32_e32 v7, v14, v3
	v_rcp_f32_e32 v15, v7
	v_add_f32_e32 v13, v9, v12
	v_sub_f32_e32 v9, v13, v9
	v_sub_f32_e32 v9, v12, v9
	v_sub_f32_e32 v12, v7, v14
	v_sub_f32_e32 v3, v3, v12
	v_mul_f32_e32 v12, v13, v15
	v_mul_f32_e32 v14, v7, v12
	v_fma_f32 v16, v12, v7, -v14
	v_fmac_f32_e32 v16, v12, v3
	v_add_f32_e32 v17, v14, v16
	v_sub_f32_e32 v18, v13, v17
	v_sub_f32_e32 v13, v13, v18
	v_sub_f32_e32 v14, v17, v14
	v_sub_f32_e32 v13, v13, v17
	v_add_f32_e32 v9, v9, v13
	v_sub_f32_e32 v13, v14, v16
	v_add_f32_e32 v9, v13, v9
	v_add_f32_e32 v13, v18, v9
	v_mul_f32_e32 v14, v15, v13
	v_mul_f32_e32 v16, v7, v14
	v_fma_f32 v7, v14, v7, -v16
	v_fmac_f32_e32 v7, v14, v3
	v_sub_f32_e32 v3, v18, v13
	v_add_f32_e32 v3, v9, v3
	v_add_f32_e32 v9, v16, v7
	v_sub_f32_e32 v17, v13, v9
	v_sub_f32_e32 v13, v13, v17
	v_sub_f32_e32 v16, v9, v16
	v_sub_f32_e32 v9, v13, v9
	v_add_f32_e32 v3, v3, v9
	v_sub_f32_e32 v7, v16, v7
	v_cvt_f32_i32_e32 v2, v2
	v_add_f32_e32 v3, v7, v3
	v_add_f32_e32 v7, v12, v14
	v_add_f32_e32 v3, v17, v3
	v_sub_f32_e32 v9, v7, v12
	v_mul_f32_e32 v3, v15, v3
	v_sub_f32_e32 v9, v14, v9
	v_add_f32_e32 v3, v9, v3
	v_mul_f32_e32 v14, 0x3f317218, v2
	v_add_f32_e32 v9, v7, v3
	v_fma_f32 v15, v2, s9, -v14
	v_mul_f32_e32 v12, v9, v9
	v_fmac_f32_e32 v15, 0xb102e308, v2
	v_sub_f32_e32 v2, v9, v7
	v_fmamk_f32 v13, v12, 0x3e9b6dac, v231
	v_sub_f32_e32 v2, v3, v2
	v_add_f32_e32 v3, v14, v15
; template <int MODE, bool BIG = false> DI void gemm_tile(const Params& p, int tm, int tn, int kv, char* smem) {
;     ...
;   } else if constexpr (MODE == G_RWW) {
;     float4* W4 = (float4*)((float*)(p.ws + OFF_BUFA) + (size_t)m * 512 + col0);
;     const float4* w04 = (const float4*)(p.w0 + col0);
; #pragma unroll
;     for (int c4 = 0; c4 < 16; ++c4) {
;       float4 v = crow4[c4], ww = w04[c4];
;       float u[4] = {v.x + ww.x, v.y + ww.y, v.z + ww.z, v.w + ww.w};
; #pragma unroll
;       for (int e = 0; e < 4; ++e) {
;         const float z = -u[e];
;         const float sp = fmaxf(z, 0.f) + log1pf(__expf(-fabsf(z)));
;         u[e] = __expf(-__expf(-sp - 0.5f));
;       }
;       W4[c4] = make_float4(u[0], u[1], u[2], u[3]);
;     }
	v_fmaak_f32 v13, v12, v13, 0x3f2aaada
	v_sub_f32_e32 v7, v3, v14
	v_ldexp_f32 v14, v9, 1
	v_mul_f32_e32 v9, v9, v12
	v_mul_f32_e32 v9, v9, v13
	v_add_f32_e32 v12, v14, v9
	v_sub_f32_e32 v13, v12, v14
	v_ldexp_f32 v2, v2, 1
	v_sub_f32_e32 v9, v9, v13
	v_add_f32_e32 v2, v2, v9
	v_add_f32_e32 v9, v12, v2
	v_sub_f32_e32 v12, v9, v12
	v_sub_f32_e32 v2, v2, v12
	v_add_f32_e32 v12, v3, v9
	v_sub_f32_e32 v13, v12, v3
	v_sub_f32_e32 v14, v12, v13
	v_sub_f32_e32 v7, v15, v7
	v_sub_f32_e32 v3, v3, v14
	v_sub_f32_e32 v9, v9, v13
	v_add_f32_e32 v3, v9, v3
	v_add_f32_e32 v9, v7, v2
	v_sub_f32_e32 v13, v9, v7
	v_sub_f32_e32 v14, v9, v13
	v_sub_f32_e32 v7, v7, v14
	v_sub_f32_e32 v2, v2, v13
	v_add_f32_e32 v3, v9, v3
	v_add_f32_e32 v2, v2, v7
	v_add_f32_e32 v7, v12, v3
	v_sub_f32_e32 v9, v7, v12
	v_sub_f32_e32 v3, v3, v9
	v_add_f32_e32 v2, v2, v3
	v_add_f32_e32 v2, v7, v2
	v_cmp_neq_f32_e32 vcc, s6, v6
	v_mul_f32_e32 v0, 0xbfb8aa3b, v0
	s_nop 0
	v_cndmask_b32_e32 v2, v238, v2, vcc
	v_cmp_ngt_f32_e32 vcc, -1.0, v6
	s_nop 1
	v_cndmask_b32_e32 v2, v239, v2, vcc
	v_cmp_neq_f32_e32 vcc, -1.0, v6
	s_nop 1
	v_cndmask_b32_e32 v2, v240, v2, vcc
	v_cmp_lt_f32_e64 vcc, |v6|, s10
	s_nop 1
	v_cndmask_b32_e32 v2, v2, v6, vcc
	v_add_f32_e32 v2, v5, v2
	v_sub_f32_e32 v2, -0.5, v2
	v_mul_f32_e32 v2, 0x3fb8aa3b, v2
	v_exp_f32_e32 v3, v2
	v_mul_f32_e64 v2, |v4|, s7
	v_exp_f32_e32 v6, v2
	v_exp_f32_e32 v2, v0
	v_mul_f32_e32 v0, 0xbfb8aa3b, v3
	v_max_f32_e64 v3, -v4, 0
	v_add_f32_e32 v7, 1.0, v6
	v_add_f32_e32 v4, -1.0, v7
	v_sub_f32_e32 v5, v4, v7
	v_add_f32_e32 v5, 1.0, v5
	v_sub_f32_e32 v4, v6, v4
	v_add_f32_e32 v9, v4, v5
	v_frexp_mant_f32_e32 v4, v7
	v_cmp_gt_f32_e32 vcc, s8, v4
	v_cvt_f64_f32_e32 v[4:5], v7
	v_frexp_exp_i32_f64_e32 v4, v[4:5]
	v_subbrev_co_u32_e32 v4, vcc, 0, v4, vcc
	v_sub_u32_e32 v5, 0, v4
	v_ldexp_f32 v7, v7, v5
	v_ldexp_f32 v5, v9, v5
	v_add_f32_e32 v9, -1.0, v7
	v_add_f32_e32 v14, 1.0, v7
	v_add_f32_e32 v12, 1.0, v9
	v_add_f32_e32 v15, -1.0, v14
	v_sub_f32_e32 v12, v7, v12
	v_sub_f32_e32 v7, v7, v15
	v_add_f32_e32 v12, v5, v12
	v_add_f32_e32 v5, v5, v7
	v_add_f32_e32 v7, v14, v5
	v_rcp_f32_e32 v15, v7
	v_add_f32_e32 v13, v9, v12
	v_sub_f32_e32 v9, v13, v9
	v_sub_f32_e32 v9, v12, v9
	v_sub_f32_e32 v12, v7, v14
	v_sub_f32_e32 v5, v5, v12
	v_mul_f32_e32 v12, v13, v15
	v_mul_f32_e32 v14, v7, v12
	v_fma_f32 v16, v12, v7, -v14
	v_fmac_f32_e32 v16, v12, v5
	v_add_f32_e32 v17, v14, v16
	v_sub_f32_e32 v18, v13, v17
	v_sub_f32_e32 v13, v13, v18
	v_sub_f32_e32 v14, v17, v14
	v_sub_f32_e32 v13, v13, v17
	v_add_f32_e32 v9, v9, v13
	v_sub_f32_e32 v13, v14, v16
	v_add_f32_e32 v9, v13, v9
	v_add_f32_e32 v13, v18, v9
	v_mul_f32_e32 v14, v15, v13
	v_mul_f32_e32 v16, v7, v14
	v_fma_f32 v7, v14, v7, -v16
	v_fmac_f32_e32 v7, v14, v5
	v_sub_f32_e32 v5, v18, v13
	v_add_f32_e32 v5, v9, v5
	v_add_f32_e32 v9, v16, v7
	v_sub_f32_e32 v17, v13, v9
	v_sub_f32_e32 v13, v13, v17
	v_sub_f32_e32 v16, v9, v16
	v_sub_f32_e32 v9, v13, v9
	v_add_f32_e32 v5, v5, v9
	v_sub_f32_e32 v7, v16, v7
	v_cvt_f32_i32_e32 v4, v4
	v_add_f32_e32 v5, v7, v5
	v_add_f32_e32 v7, v12, v14
	v_add_f32_e32 v5, v17, v5
	v_sub_f32_e32 v9, v7, v12
	v_mul_f32_e32 v5, v15, v5
	v_sub_f32_e32 v9, v14, v9
	v_add_f32_e32 v5, v9, v5
	v_mul_f32_e32 v14, 0x3f317218, v4
	v_add_f32_e32 v9, v7, v5
	v_fma_f32 v15, v4, s9, -v14
	v_mul_f32_e32 v12, v9, v9
	v_fmac_f32_e32 v15, 0xb102e308, v4
	v_sub_f32_e32 v4, v9, v7
	v_fmamk_f32 v13, v12, 0x3e9b6dac, v231
	v_sub_f32_e32 v4, v5, v4
	v_add_f32_e32 v5, v14, v15
	v_fmaak_f32 v13, v12, v13, 0x3f2aaada
	v_sub_f32_e32 v7, v5, v14
	v_ldexp_f32 v14, v9, 1
	v_mul_f32_e32 v9, v9, v12
	v_mul_f32_e32 v9, v9, v13
	v_add_f32_e32 v12, v14, v9
	v_sub_f32_e32 v13, v12, v14
	v_ldexp_f32 v4, v4, 1
	v_sub_f32_e32 v9, v9, v13
	v_add_f32_e32 v4, v4, v9
	v_add_f32_e32 v9, v12, v4
	v_sub_f32_e32 v12, v9, v12
	v_sub_f32_e32 v4, v4, v12
	v_add_f32_e32 v12, v5, v9
	v_sub_f32_e32 v13, v12, v5
	v_sub_f32_e32 v14, v12, v13
	v_sub_f32_e32 v7, v15, v7
	v_sub_f32_e32 v5, v5, v14
	v_sub_f32_e32 v9, v9, v13
	v_add_f32_e32 v5, v9, v5
	v_add_f32_e32 v9, v7, v4
	v_sub_f32_e32 v13, v9, v7
	v_sub_f32_e32 v14, v9, v13
	v_sub_f32_e32 v7, v7, v14
	v_sub_f32_e32 v4, v4, v13
	v_add_f32_e32 v5, v9, v5
	v_add_f32_e32 v4, v4, v7
	v_add_f32_e32 v7, v12, v5
	v_sub_f32_e32 v9, v7, v12
	v_sub_f32_e32 v5, v5, v9
	v_add_f32_e32 v4, v4, v5
	v_add_f32_e32 v4, v7, v4
	v_cmp_neq_f32_e32 vcc, s6, v6
	s_nop 1
	v_cndmask_b32_e32 v4, v238, v4, vcc
	v_cmp_ngt_f32_e32 vcc, -1.0, v6
	s_nop 1
	v_cndmask_b32_e32 v4, v239, v4, vcc
	v_cmp_neq_f32_e32 vcc, -1.0, v6
	s_nop 1
	v_cndmask_b32_e32 v4, v240, v4, vcc
	v_cmp_lt_f32_e64 vcc, |v6|, s10
	s_nop 1
	v_cndmask_b32_e32 v4, v4, v6, vcc
	v_add_f32_e32 v3, v3, v4
	v_mul_f32_e64 v4, |v8|, s7
	v_exp_f32_e32 v6, v4
	v_sub_f32_e32 v3, -0.5, v3
	v_mul_f32_e32 v3, 0x3fb8aa3b, v3
	v_exp_f32_e32 v7, v3
	v_max_f32_e64 v3, -v8, 0
	v_add_f32_e32 v8, 1.0, v6
	v_add_f32_e32 v4, -1.0, v8
	v_sub_f32_e32 v5, v4, v8
	v_add_f32_e32 v5, 1.0, v5
	v_sub_f32_e32 v4, v6, v4
	v_add_f32_e32 v9, v4, v5
	v_frexp_mant_f32_e32 v4, v8
	v_cmp_gt_f32_e32 vcc, s8, v4
	v_cvt_f64_f32_e32 v[4:5], v8
	v_frexp_exp_i32_f64_e32 v4, v[4:5]
	v_subbrev_co_u32_e32 v4, vcc, 0, v4, vcc
	v_sub_u32_e32 v5, 0, v4
	v_ldexp_f32 v8, v8, v5
	v_ldexp_f32 v5, v9, v5
	v_add_f32_e32 v9, -1.0, v8
	v_add_f32_e32 v14, 1.0, v8
	v_add_f32_e32 v12, 1.0, v9
	v_add_f32_e32 v15, -1.0, v14
	v_sub_f32_e32 v12, v8, v12
	v_sub_f32_e32 v8, v8, v15
	v_add_f32_e32 v12, v5, v12
	v_add_f32_e32 v5, v5, v8
	v_add_f32_e32 v8, v14, v5
	v_rcp_f32_e32 v15, v8
	v_add_f32_e32 v13, v9, v12
	v_sub_f32_e32 v9, v13, v9
	v_sub_f32_e32 v9, v12, v9
	v_sub_f32_e32 v12, v8, v14
; template <int MODE, bool BIG = false> DI void gemm_tile(const Params& p, int tm, int tn, int kv, char* smem) {
;     ...
;   } else if constexpr (MODE == G_RWW) {
;     float4* W4 = (float4*)((float*)(p.ws + OFF_BUFA) + (size_t)m * 512 + col0);
;     const float4* w04 = (const float4*)(p.w0 + col0);
; #pragma unroll
;     for (int c4 = 0; c4 < 16; ++c4) {
;       float4 v = crow4[c4], ww = w04[c4];
;       float u[4] = {v.x + ww.x, v.y + ww.y, v.z + ww.z, v.w + ww.w};
; #pragma unroll
;       for (int e = 0; e < 4; ++e) {
;         const float z = -u[e];
;         const float sp = fmaxf(z, 0.f) + log1pf(__expf(-fabsf(z)));
;         u[e] = __expf(-__expf(-sp - 0.5f));
;       }
;       W4[c4] = make_float4(u[0], u[1], u[2], u[3]);
;     }
	v_sub_f32_e32 v5, v5, v12
	v_mul_f32_e32 v12, v13, v15
	v_mul_f32_e32 v14, v8, v12
	v_fma_f32 v16, v12, v8, -v14
	v_fmac_f32_e32 v16, v12, v5
	v_add_f32_e32 v17, v14, v16
	v_sub_f32_e32 v18, v13, v17
	v_sub_f32_e32 v13, v13, v18
	v_sub_f32_e32 v14, v17, v14
	v_sub_f32_e32 v13, v13, v17
	v_add_f32_e32 v9, v9, v13
	v_sub_f32_e32 v13, v14, v16
	v_add_f32_e32 v9, v13, v9
	v_add_f32_e32 v13, v18, v9
	v_mul_f32_e32 v14, v15, v13
	v_mul_f32_e32 v16, v8, v14
	v_fma_f32 v8, v14, v8, -v16
	v_fmac_f32_e32 v8, v14, v5
	v_sub_f32_e32 v5, v18, v13
	v_add_f32_e32 v5, v9, v5
	v_add_f32_e32 v9, v16, v8
	v_sub_f32_e32 v17, v13, v9
	v_sub_f32_e32 v13, v13, v17
	v_sub_f32_e32 v16, v9, v16
	v_sub_f32_e32 v9, v13, v9
	v_add_f32_e32 v5, v5, v9
	v_sub_f32_e32 v8, v16, v8
	v_cvt_f32_i32_e32 v4, v4
	v_add_f32_e32 v5, v8, v5
	v_add_f32_e32 v8, v12, v14
	v_add_f32_e32 v5, v17, v5
	v_sub_f32_e32 v9, v8, v12
	v_mul_f32_e32 v5, v15, v5
	v_sub_f32_e32 v9, v14, v9
	v_add_f32_e32 v5, v9, v5
	v_mul_f32_e32 v14, 0x3f317218, v4
	v_add_f32_e32 v9, v8, v5
	v_fma_f32 v15, v4, s9, -v14
	v_mul_f32_e32 v12, v9, v9
	v_fmac_f32_e32 v15, 0xb102e308, v4
	v_sub_f32_e32 v4, v9, v8
	v_fmamk_f32 v13, v12, 0x3e9b6dac, v231
	v_sub_f32_e32 v4, v5, v4
	v_add_f32_e32 v5, v14, v15
	v_fmaak_f32 v13, v12, v13, 0x3f2aaada
	v_sub_f32_e32 v8, v5, v14
	v_ldexp_f32 v14, v9, 1
	v_mul_f32_e32 v9, v9, v12
	v_mul_f32_e32 v9, v9, v13
	v_add_f32_e32 v12, v14, v9
	v_sub_f32_e32 v13, v12, v14
	v_ldexp_f32 v4, v4, 1
	v_sub_f32_e32 v9, v9, v13
	v_add_f32_e32 v4, v4, v9
	v_add_f32_e32 v9, v12, v4
	v_sub_f32_e32 v12, v9, v12
	v_sub_f32_e32 v4, v4, v12
	v_add_f32_e32 v12, v5, v9
	v_sub_f32_e32 v13, v12, v5
	v_sub_f32_e32 v14, v12, v13
	v_sub_f32_e32 v8, v15, v8
	v_sub_f32_e32 v5, v5, v14
	v_sub_f32_e32 v9, v9, v13
	v_add_f32_e32 v5, v9, v5
	v_add_f32_e32 v9, v8, v4
	v_sub_f32_e32 v13, v9, v8
	v_sub_f32_e32 v14, v9, v13
	v_sub_f32_e32 v8, v8, v14
	v_sub_f32_e32 v4, v4, v13
	v_add_f32_e32 v5, v9, v5
	v_add_f32_e32 v4, v4, v8
	v_add_f32_e32 v8, v12, v5
	v_sub_f32_e32 v9, v8, v12
	v_sub_f32_e32 v5, v5, v9
	v_add_f32_e32 v4, v4, v5
	v_add_f32_e32 v4, v8, v4
	v_cmp_neq_f32_e32 vcc, s6, v6
	s_mov_b32 s6, s88
	s_mov_b32 s7, s86
	v_cndmask_b32_e32 v4, v238, v4, vcc
	v_cmp_ngt_f32_e32 vcc, -1.0, v6
	s_mov_b32 s8, s85
	s_nop 0
	v_cndmask_b32_e32 v4, v239, v4, vcc
	v_cmp_neq_f32_e32 vcc, -1.0, v6
	s_nop 1
	v_cndmask_b32_e32 v4, v240, v4, vcc
	v_cmp_lt_f32_e64 vcc, |v6|, s10
	s_nop 1
	v_cndmask_b32_e32 v4, v4, v6, vcc
	v_add_f32_e32 v3, v3, v4
	v_sub_f32_e32 v3, -0.5, v3
	v_mul_f32_e32 v3, 0x3fb8aa3b, v3
	v_exp_f32_e32 v5, v3
	v_exp_f32_e32 v3, v0
	v_mul_f32_e32 v0, 0xbfb8aa3b, v7
	v_exp_f32_e32 v4, v0
	v_mul_f32_e32 v0, 0xbfb8aa3b, v5
	v_exp_f32_e32 v5, v0
	ds_write_b128 v75, v[2:5] offset:240
	s_waitcnt lgkmcnt(0)
	s_barrier
	v_lshrrev_b32_e32 v66, 5, v173
	v_lshrrev_b32_e32 v69, 1, v173
	v_sub_u32_e32 v68, v66, v69
	v_lshlrev_b32_e32 v68, 11, v68
	v_and_b32_e32 v69, 1, v173
	v_lshlrev_b32_e32 v69, 8, v69
	v_sub_u32_e32 v68, v68, v69
	v_and_b32_e32 v69, 31, v173
	v_lshl_add_u32 v68, v69, 4, v68
	v_mul_u32_u24_e32 v66, 0x210, v66
	v_lshl_add_u32 v66, v69, 4, v66
	v_ashrrev_i32_e32 v69, 31, v68
	v_lshl_add_u64 v[68:69], v[10:11], 0, v[68:69]
	v_mov_b32_e32 v70, 0x4000
	v_mov_b32_e32 v71, 0
	ds_read_b128 v[2:5], v66
	ds_read_b128 v[6:9], v66 offset:4224
	ds_read_b128 v[10:13], v66 offset:8448
	ds_read_b128 v[14:17], v66 offset:12672
	ds_read_b128 v[18:21], v66 offset:16896
	ds_read_b128 v[22:25], v66 offset:21120
	ds_read_b128 v[26:29], v66 offset:25344
	ds_read_b128 v[30:33], v66 offset:29568
	s_waitcnt lgkmcnt(7)
	global_store_dwordx4 v[68:69], v[2:5], off
	v_lshl_add_u64 v[68:69], v[70:71], 0, v[68:69]
	ds_read_b128 v[34:37], v66 offset:33792
	s_waitcnt lgkmcnt(7)
	global_store_dwordx4 v[68:69], v[6:9], off
	v_lshl_add_u64 v[68:69], v[70:71], 0, v[68:69]
	ds_read_b128 v[38:41], v66 offset:38016
	s_waitcnt lgkmcnt(7)
	global_store_dwordx4 v[68:69], v[10:13], off
	v_lshl_add_u64 v[68:69], v[70:71], 0, v[68:69]
	ds_read_b128 v[42:45], v66 offset:42240
	s_waitcnt lgkmcnt(7)
	global_store_dwordx4 v[68:69], v[14:17], off
	v_lshl_add_u64 v[68:69], v[70:71], 0, v[68:69]
	ds_read_b128 v[46:49], v66 offset:46464
	s_waitcnt lgkmcnt(7)
	global_store_dwordx4 v[68:69], v[18:21], off
	v_lshl_add_u64 v[68:69], v[70:71], 0, v[68:69]
	ds_read_b128 v[50:53], v66 offset:50688
	s_waitcnt lgkmcnt(7)
	global_store_dwordx4 v[68:69], v[22:25], off
	v_lshl_add_u64 v[68:69], v[70:71], 0, v[68:69]
	ds_read_b128 v[54:57], v66 offset:54912
	s_waitcnt lgkmcnt(7)
	global_store_dwordx4 v[68:69], v[26:29], off
	v_lshl_add_u64 v[68:69], v[70:71], 0, v[68:69]
	ds_read_b128 v[58:61], v66 offset:59136
	s_waitcnt lgkmcnt(7)
	global_store_dwordx4 v[68:69], v[30:33], off
	v_lshl_add_u64 v[68:69], v[70:71], 0, v[68:69]
	ds_read_b128 v[62:65], v66 offset:63360
	s_waitcnt lgkmcnt(7)
	global_store_dwordx4 v[68:69], v[34:37], off
	v_lshl_add_u64 v[68:69], v[70:71], 0, v[68:69]
	s_waitcnt lgkmcnt(6)
	global_store_dwordx4 v[68:69], v[38:41], off
	v_lshl_add_u64 v[68:69], v[70:71], 0, v[68:69]
	s_waitcnt lgkmcnt(5)
	global_store_dwordx4 v[68:69], v[42:45], off
	v_lshl_add_u64 v[68:69], v[70:71], 0, v[68:69]
	s_waitcnt lgkmcnt(4)
	global_store_dwordx4 v[68:69], v[46:49], off
	v_lshl_add_u64 v[68:69], v[70:71], 0, v[68:69]
	s_waitcnt lgkmcnt(3)
	global_store_dwordx4 v[68:69], v[50:53], off
	v_lshl_add_u64 v[68:69], v[70:71], 0, v[68:69]
	s_waitcnt lgkmcnt(2)
	global_store_dwordx4 v[68:69], v[54:57], off
	v_lshl_add_u64 v[68:69], v[70:71], 0, v[68:69]
	s_waitcnt lgkmcnt(1)
	global_store_dwordx4 v[68:69], v[58:61], off
	v_lshl_add_u64 v[68:69], v[70:71], 0, v[68:69]
	s_waitcnt lgkmcnt(0)
	global_store_dwordx4 v[68:69], v[62:65], off
	v_lshl_add_u64 v[68:69], v[70:71], 0, v[68:69]
	s_cbranch_scc1 .LBB0_343

; DI void t0_item(const Params& p, int item, char* smem) {
;     ...
;   const int c = tid & 63, kp = tid >> 6;
;   const int rc = grp < 8 ? grp * 64 + c : (grp < 16 ? 512 + (grp - 8) * 64 + c : 1600 + c);
;   const float* wc = p.w_in + 1304 + rc;
;   float a = 0.f;
; #pragma unroll 8
;   for (int k = kp * 256; k < kp * 256 + 256; ++k) a += xs[k] * wc[(size_t)k * 3096];
;   __syncthreads();
;   red[tid] = a;
;   __syncthreads();
;   if (tid < 64) {
;     const float v = red[tid] + red[tid + 64] + red[tid + 128] + red[tid + 192];
;     ((float*)(p.ws + OFF_T0))[(size_t)(b * 17 + grp) * 64 + tid] = v * (1.f - p.mu[rc]);
;   }
.LBB0_382:
	s_mov_b64 s[4:5], 0x3060
	v_add_co_u32_e32 v22, vcc, 0xfffead60, v4
	s_nop 1
	v_addc_co_u32_e32 v23, vcc, -1, v5, vcc
	s_movk_i32 s1, 8
.Lt0_dot_loop:
	global_load_dword v30, v[22:23], off
	v_lshl_add_u64 v[22:23], v[22:23], 0, s[4:5]
	global_load_dword v31, v[22:23], off
	v_lshl_add_u64 v[22:23], v[22:23], 0, s[4:5]
	global_load_dword v32, v[22:23], off
	v_lshl_add_u64 v[22:23], v[22:23], 0, s[4:5]
	global_load_dword v33, v[22:23], off
	v_lshl_add_u64 v[22:23], v[22:23], 0, s[4:5]
	global_load_dword v34, v[22:23], off
	v_lshl_add_u64 v[22:23], v[22:23], 0, s[4:5]
	global_load_dword v35, v[22:23], off
	v_lshl_add_u64 v[22:23], v[22:23], 0, s[4:5]
	global_load_dword v36, v[22:23], off
	v_lshl_add_u64 v[22:23], v[22:23], 0, s[4:5]
	global_load_dword v37, v[22:23], off
	v_lshl_add_u64 v[22:23], v[22:23], 0, s[4:5]
	global_load_dword v38, v[22:23], off
	v_lshl_add_u64 v[22:23], v[22:23], 0, s[4:5]
	global_load_dword v39, v[22:23], off
	v_lshl_add_u64 v[22:23], v[22:23], 0, s[4:5]
	global_load_dword v40, v[22:23], off
	v_lshl_add_u64 v[22:23], v[22:23], 0, s[4:5]
	global_load_dword v41, v[22:23], off
	v_lshl_add_u64 v[22:23], v[22:23], 0, s[4:5]
	global_load_dword v42, v[22:23], off
	v_lshl_add_u64 v[22:23], v[22:23], 0, s[4:5]
	global_load_dword v43, v[22:23], off
	v_lshl_add_u64 v[22:23], v[22:23], 0, s[4:5]
	global_load_dword v44, v[22:23], off
	v_lshl_add_u64 v[22:23], v[22:23], 0, s[4:5]
	global_load_dword v45, v[22:23], off
	v_lshl_add_u64 v[22:23], v[22:23], 0, s[4:5]
	global_load_dword v46, v[22:23], off
	v_lshl_add_u64 v[22:23], v[22:23], 0, s[4:5]
	global_load_dword v47, v[22:23], off
	v_lshl_add_u64 v[22:23], v[22:23], 0, s[4:5]
	global_load_dword v48, v[22:23], off
	v_lshl_add_u64 v[22:23], v[22:23], 0, s[4:5]
	global_load_dword v49, v[22:23], off
	v_lshl_add_u64 v[22:23], v[22:23], 0, s[4:5]
	global_load_dword v50, v[22:23], off
	v_lshl_add_u64 v[22:23], v[22:23], 0, s[4:5]
	global_load_dword v51, v[22:23], off
	v_lshl_add_u64 v[22:23], v[22:23], 0, s[4:5]
	global_load_dword v52, v[22:23], off
	v_lshl_add_u64 v[22:23], v[22:23], 0, s[4:5]
	global_load_dword v53, v[22:23], off
	v_lshl_add_u64 v[22:23], v[22:23], 0, s[4:5]
	global_load_dword v54, v[22:23], off
	v_lshl_add_u64 v[22:23], v[22:23], 0, s[4:5]
	global_load_dword v55, v[22:23], off
	v_lshl_add_u64 v[22:23], v[22:23], 0, s[4:5]
	global_load_dword v56, v[22:23], off
	v_lshl_add_u64 v[22:23], v[22:23], 0, s[4:5]
	global_load_dword v57, v[22:23], off
	v_lshl_add_u64 v[22:23], v[22:23], 0, s[4:5]
	global_load_dword v58, v[22:23], off
	v_lshl_add_u64 v[22:23], v[22:23], 0, s[4:5]
	global_load_dword v59, v[22:23], off
	v_lshl_add_u64 v[22:23], v[22:23], 0, s[4:5]
	global_load_dword v60, v[22:23], off
	v_lshl_add_u64 v[22:23], v[22:23], 0, s[4:5]
	global_load_dword v61, v[22:23], off
	v_lshl_add_u64 v[22:23], v[22:23], 0, s[4:5]
	ds_read_b128 v[24:27], v11
	ds_read_b128 v[62:65], v11 offset:16
	s_waitcnt vmcnt(31) lgkmcnt(1)
	v_fmac_f32_e32 v13, v24, v30
	s_waitcnt vmcnt(30)
	v_mul_f32_e32 v21, v25, v31
	v_add_f32_e32 v13, v13, v21
	s_waitcnt vmcnt(29)
	v_mul_f32_e32 v21, v26, v32
	v_add_f32_e32 v13, v13, v21
	s_waitcnt vmcnt(28)
	v_mul_f32_e32 v21, v27, v33
	v_add_f32_e32 v13, v13, v21
	ds_read_b128 v[24:27], v11 offset:32
	s_waitcnt vmcnt(27) lgkmcnt(1)
	v_mul_f32_e32 v21, v62, v34
	v_add_f32_e32 v13, v13, v21
	s_waitcnt vmcnt(26)
	v_mul_f32_e32 v21, v63, v35
	v_add_f32_e32 v13, v13, v21
	s_waitcnt vmcnt(25)
	v_mul_f32_e32 v21, v64, v36
	v_add_f32_e32 v13, v13, v21
	s_waitcnt vmcnt(24)
	v_fmac_f32_e32 v13, v65, v37
	ds_read_b128 v[62:65], v11 offset:48
	s_waitcnt vmcnt(23) lgkmcnt(1)
	v_fmac_f32_e32 v13, v24, v38
	s_waitcnt vmcnt(22)
	v_mul_f32_e32 v21, v25, v39
	v_add_f32_e32 v13, v13, v21
	s_waitcnt vmcnt(21)
	v_mul_f32_e32 v21, v26, v40
	v_add_f32_e32 v13, v13, v21
	s_waitcnt vmcnt(20)
	v_mul_f32_e32 v21, v27, v41
	v_add_f32_e32 v13, v13, v21
	ds_read_b128 v[24:27], v11 offset:64
	s_waitcnt vmcnt(19) lgkmcnt(1)
	v_mul_f32_e32 v21, v62, v42
	v_add_f32_e32 v13, v13, v21
	s_waitcnt vmcnt(18)
	v_mul_f32_e32 v21, v63, v43
	v_add_f32_e32 v13, v13, v21
	s_waitcnt vmcnt(17)
	v_mul_f32_e32 v21, v64, v44
	v_add_f32_e32 v13, v13, v21
	s_waitcnt vmcnt(16)
	v_fmac_f32_e32 v13, v65, v45
	ds_read_b128 v[62:65], v11 offset:80
	s_waitcnt vmcnt(15) lgkmcnt(1)
	v_fmac_f32_e32 v13, v24, v46
	s_waitcnt vmcnt(14)
	v_mul_f32_e32 v21, v25, v47
	v_add_f32_e32 v13, v13, v21
	s_waitcnt vmcnt(13)
	v_mul_f32_e32 v21, v26, v48
	v_add_f32_e32 v13, v13, v21
	s_waitcnt vmcnt(12)
	v_mul_f32_e32 v21, v27, v49
	v_add_f32_e32 v13, v13, v21
	ds_read_b128 v[24:27], v11 offset:96
	s_waitcnt vmcnt(11) lgkmcnt(1)
	v_mul_f32_e32 v21, v62, v50
	v_add_f32_e32 v13, v13, v21
	s_waitcnt vmcnt(10)
	v_mul_f32_e32 v21, v63, v51
	v_add_f32_e32 v13, v13, v21
	s_waitcnt vmcnt(9)
	v_mul_f32_e32 v21, v64, v52
	v_add_f32_e32 v13, v13, v21
	s_waitcnt vmcnt(8)
	v_fmac_f32_e32 v13, v65, v53
	ds_read_b128 v[62:65], v11 offset:112
	s_waitcnt vmcnt(7) lgkmcnt(1)
	v_fmac_f32_e32 v13, v24, v54
	s_waitcnt vmcnt(6)
	v_mul_f32_e32 v21, v25, v55
	v_add_f32_e32 v13, v13, v21
	s_waitcnt vmcnt(5)
	v_mul_f32_e32 v21, v26, v56
	v_add_f32_e32 v13, v13, v21
	s_waitcnt vmcnt(4)
	v_mul_f32_e32 v21, v27, v57
	v_add_f32_e32 v13, v13, v21
	s_waitcnt vmcnt(3) lgkmcnt(0)
	v_mul_f32_e32 v21, v62, v58
	v_add_f32_e32 v13, v13, v21
	s_waitcnt vmcnt(2)
	v_mul_f32_e32 v21, v63, v59
	v_add_f32_e32 v13, v13, v21
	s_waitcnt vmcnt(1)
	v_mul_f32_e32 v21, v64, v60
	v_add_f32_e32 v13, v13, v21
	s_waitcnt vmcnt(0)
	v_fmac_f32_e32 v13, v65, v61
	v_add_u32_e32 v11, 0x80, v11
	s_sub_i32 s1, s1, 1
	s_cmp_lg_u32 s1, 0
	s_cbranch_scc1 .Lt0_dot_loop
	s_or_b64 exec, exec, s[2:3]
	s_barrier
	ds_write_b32 v166, v13 offset:4096
	s_waitcnt lgkmcnt(0)
	s_barrier
	s_mov_b64 s[2:3], exec
	v_readlane_b32 s4, v254, 32
	v_readlane_b32 s5, v254, 33
	s_and_b64 s[4:5], s[2:3], s[4:5]
	s_mov_b64 exec, s[4:5]
	s_cbranch_execz .LBB0_368
	v_lshl_add_u64 v[2:3], v[2:3], 2, s[72:73]
	global_load_dword v11, v[2:3], off
	ds_read2st64_b32 v[2:3], v166 offset0:16 offset1:17
	ds_read2st64_b32 v[4:5], v166 offset0:18 offset1:19
	s_ashr_i32 s1, s0, 31
	s_lshl_b64 s[0:1], s[0:1], 8
	s_waitcnt lgkmcnt(1)
	v_add_f32_e32 v2, v2, v3
	s_waitcnt lgkmcnt(0)
	v_add_f32_e32 v2, v2, v4
	v_add_f32_e32 v2, v2, v5
	s_waitcnt vmcnt(0)
	v_sub_f32_e32 v3, 1.0, v11
	v_mul_f32_e32 v4, v2, v3
	v_lshl_add_u64 v[2:3], v[198:199], 0, s[0:1]
	global_store_dword v[2:3], v4, off
	s_branch .LBB0_368
